# stack: P0 MLP-first overlap + unrolled P9 bias-table prologue + FFT exchange ds_writes sunk to their producers
# speedup vs baseline: 1.0131x; 1.0034x over previous
; __device__ __forceinline__ f2 cmulw(f2 a, float wr, float wi) { const f2 s = __builtin_shufflevector(a, a, 1, 0); return s * (f2){-wi, wi} + a * (f2){wr, wr}; }
; __device__ __forceinline__ void fft32(f2 (&x)[32]) {
;     constexpr float TWR[32] = {TWR_LIST}; constexpr float TWI[32] = {TWI_LIST};
; #pragma unroll
;     for (int h = 16; h >= 1; h >>= 1) {
; #pragma unroll
;         for (int i0 = 0; i0 < 32; i0 += 2 * h) {
; #pragma unroll
;             for (int j = 0; j < h; ++j) {
;                 const int i = i0 + j, k = i + h, m = j * (32 / h);
;                 const f2 a = x[i], b = x[k], d = a - b;
;                 x[i] = a + b;
;                 if (m == 0) x[k] = d;
;                 else if (m == 16) x[k] = (f2){d.y, -d.x};
;                 else x[k] = cmulw(d, TWR[m], TWI[m]);
;             }
;         }
;     }
; }
.LBB0_339:
	v_pk_add_f32 v[72:73], v[68:69], v[38:39] neg_lo:[0,1] neg_hi:[0,1]
	v_pk_add_f32 v[38:39], v[38:39], v[68:69]
	v_pk_add_f32 v[68:69], v[40:41], v[0:1]
	v_pk_add_f32 v[0:1], v[0:1], v[40:41] neg_lo:[0,1] neg_hi:[0,1]
	s_mov_b32 s94, s63
	v_pk_mul_f32 v[40:41], v[0:1], s[46:47]
	s_mov_b32 s65, s60
	v_pk_fma_f32 v[0:1], v[0:1], s[52:53], v[40:41] op_sel:[0,0,1] op_sel_hi:[1,0,0]
	v_pk_add_f32 v[40:41], v[42:43], v[2:3]
	v_pk_add_f32 v[2:3], v[2:3], v[42:43] neg_lo:[0,1] neg_hi:[0,1]
	s_mov_b32 s20, s59
	v_pk_mul_f32 v[42:43], v[2:3], s[54:55]
	s_mov_b32 s67, s56
	v_pk_fma_f32 v[2:3], v[2:3], s[56:57], v[42:43] op_sel:[0,0,1] op_sel_hi:[1,0,0]
	v_pk_add_f32 v[42:43], v[44:45], v[4:5]
	v_pk_add_f32 v[4:5], v[4:5], v[44:45] neg_lo:[0,1] neg_hi:[0,1]
	s_mov_b32 s6, s55
	v_pk_mul_f32 v[44:45], v[4:5], s[58:59]
	s_mov_b32 s79, s52
	v_pk_fma_f32 v[4:5], v[4:5], s[60:61], v[44:45] op_sel:[0,0,1] op_sel_hi:[1,0,0]
	v_pk_add_f32 v[44:45], v[46:47], v[6:7]
	v_pk_add_f32 v[6:7], v[6:7], v[46:47] neg_lo:[0,1] neg_hi:[0,1]
	s_mov_b32 s76, s47
	v_pk_mul_f32 v[46:47], v[6:7], s[62:63]
	v_lshrrev_b32_e32 v16, 4, v12
	v_pk_fma_f32 v[6:7], v[6:7], s[94:95], v[46:47] op_sel:[0,0,1] op_sel_hi:[1,0,0]
	v_pk_add_f32 v[46:47], v[48:49], v[8:9]
	v_pk_add_f32 v[8:9], v[8:9], v[48:49] neg_lo:[0,1] neg_hi:[0,1]
	v_lshl_add_u32 v213, v12, 3, 0
	v_pk_mul_f32 v[48:49], v[8:9], s[64:65]
	v_add_u32_e32 v212, 0x10800, v213
	v_pk_fma_f32 v[8:9], v[8:9], s[20:21], v[48:49] op_sel:[0,0,1] op_sel_hi:[1,0,0]
	v_pk_add_f32 v[48:49], v[50:51], v[10:11]
	v_pk_add_f32 v[10:11], v[10:11], v[50:51] neg_lo:[0,1] neg_hi:[0,1]
	s_cmp_lt_u32 s10, 2
	v_pk_mul_f32 v[50:51], v[10:11], s[66:67]
	s_nop 0
	v_pk_fma_f32 v[10:11], v[10:11], s[6:7], v[50:51] op_sel:[0,0,1] op_sel_hi:[1,0,0]
	v_pk_add_f32 v[50:51], v[52:53], v[14:15]
	v_pk_add_f32 v[14:15], v[14:15], v[52:53] neg_lo:[0,1] neg_hi:[0,1]
	s_nop 0
	v_pk_mul_f32 v[52:53], v[14:15], s[78:79]
	s_nop 0
	v_pk_fma_f32 v[14:15], v[14:15], s[76:77], v[52:53] op_sel:[0,0,1] op_sel_hi:[1,0,0]
	v_pk_add_f32 v[52:53], v[54:55], v[22:23]
	v_pk_add_f32 v[22:23], v[22:23], v[54:55] neg_lo:[0,1] neg_hi:[0,1]
	s_nop 0
	v_xor_b32_e32 v55, 0x80000000, v22
	v_mov_b32_e32 v54, v23
	v_pk_add_f32 v[22:23], v[56:57], v[24:25]
	v_pk_add_f32 v[24:25], v[24:25], v[56:57] neg_lo:[0,1] neg_hi:[0,1]
	s_nop 0
	v_pk_mul_f32 v[56:57], v[24:25], s[78:79]
	s_nop 0
	v_pk_fma_f32 v[24:25], v[24:25], s[76:77], v[56:57] op_sel:[0,0,1] op_sel_hi:[1,0,0] neg_lo:[1,0,0] neg_hi:[1,0,0]
	v_pk_add_f32 v[56:57], v[58:59], v[26:27]
	v_pk_add_f32 v[26:27], v[26:27], v[58:59] neg_lo:[0,1] neg_hi:[0,1]
	s_nop 0
	v_pk_mul_f32 v[58:59], v[26:27], s[66:67]
	s_nop 0
	v_pk_fma_f32 v[26:27], v[26:27], s[6:7], v[58:59] op_sel:[0,0,1] op_sel_hi:[1,0,0] neg_lo:[1,0,0] neg_hi:[1,0,0]
	v_pk_add_f32 v[58:59], v[60:61], v[28:29]
	v_pk_add_f32 v[28:29], v[28:29], v[60:61] neg_lo:[0,1] neg_hi:[0,1]
	s_nop 0
	v_pk_mul_f32 v[60:61], v[28:29], s[64:65]
	s_nop 0
	v_pk_fma_f32 v[28:29], v[28:29], s[20:21], v[60:61] op_sel:[0,0,1] op_sel_hi:[1,0,0] neg_lo:[1,0,0] neg_hi:[1,0,0]
	v_pk_add_f32 v[60:61], v[62:63], v[30:31]
	v_pk_add_f32 v[30:31], v[30:31], v[62:63] neg_lo:[0,1] neg_hi:[0,1]
	s_nop 0
	v_pk_mul_f32 v[62:63], v[30:31], s[62:63]
	s_nop 0
	v_pk_fma_f32 v[30:31], v[30:31], s[94:95], v[62:63] op_sel:[0,0,1] op_sel_hi:[1,0,0] neg_lo:[1,0,0] neg_hi:[1,0,0]
	v_pk_add_f32 v[62:63], v[64:65], v[32:33]
	v_pk_add_f32 v[32:33], v[32:33], v[64:65] neg_lo:[0,1] neg_hi:[0,1]
	s_nop 0
	v_pk_mul_f32 v[64:65], v[32:33], s[58:59]
	s_nop 0
	v_pk_fma_f32 v[32:33], v[32:33], s[60:61], v[64:65] op_sel:[0,0,1] op_sel_hi:[1,0,0] neg_lo:[1,0,0] neg_hi:[1,0,0]
	v_pk_add_f32 v[64:65], v[66:67], v[34:35]
	v_pk_add_f32 v[34:35], v[34:35], v[66:67] neg_lo:[0,1] neg_hi:[0,1]
	s_nop 0
	v_pk_mul_f32 v[66:67], v[34:35], s[54:55]
	s_nop 0
	v_pk_fma_f32 v[34:35], v[34:35], s[56:57], v[66:67] op_sel:[0,0,1] op_sel_hi:[1,0,0] neg_lo:[1,0,0] neg_hi:[1,0,0]
	v_pk_add_f32 v[66:67], v[70:71], v[36:37]
	v_pk_add_f32 v[36:37], v[36:37], v[70:71] neg_lo:[0,1] neg_hi:[0,1]
	s_nop 0
	v_pk_mul_f32 v[70:71], v[36:37], s[46:47]
	s_nop 0
	v_pk_fma_f32 v[36:37], v[36:37], s[52:53], v[70:71] op_sel:[0,0,1] op_sel_hi:[1,0,0] neg_lo:[1,0,0] neg_hi:[1,0,0]
	v_pk_add_f32 v[70:71], v[38:39], v[52:53] neg_lo:[0,1] neg_hi:[0,1]
	v_pk_add_f32 v[38:39], v[52:53], v[38:39]
	v_pk_add_f32 v[52:53], v[22:23], v[68:69]
	v_pk_add_f32 v[22:23], v[68:69], v[22:23] neg_lo:[0,1] neg_hi:[0,1]
	s_nop 0
	v_pk_mul_f32 v[68:69], v[22:23], s[54:55]
	s_nop 0
	v_pk_fma_f32 v[22:23], v[22:23], s[56:57], v[68:69] op_sel:[0,0,1] op_sel_hi:[1,0,0]
	v_pk_add_f32 v[68:69], v[56:57], v[40:41]
	v_pk_add_f32 v[40:41], v[40:41], v[56:57] neg_lo:[0,1] neg_hi:[0,1]
	s_nop 0
	v_pk_mul_f32 v[56:57], v[40:41], s[62:63]
	s_nop 0
	v_pk_fma_f32 v[40:41], v[40:41], s[94:95], v[56:57] op_sel:[0,0,1] op_sel_hi:[1,0,0]
	v_pk_add_f32 v[56:57], v[58:59], v[42:43]
	v_pk_add_f32 v[42:43], v[42:43], v[58:59] neg_lo:[0,1] neg_hi:[0,1]
	s_nop 0
	v_pk_mul_f32 v[58:59], v[42:43], s[66:67]
	s_nop 0
	v_pk_fma_f32 v[42:43], v[42:43], s[6:7], v[58:59] op_sel:[0,0,1] op_sel_hi:[1,0,0]
	v_pk_add_f32 v[58:59], v[60:61], v[44:45]
	v_pk_add_f32 v[44:45], v[44:45], v[60:61] neg_lo:[0,1] neg_hi:[0,1]
	s_nop 0
	v_xor_b32_e32 v61, 0x80000000, v44
	v_mov_b32_e32 v60, v45
	v_pk_add_f32 v[44:45], v[62:63], v[46:47]
	v_pk_add_f32 v[46:47], v[46:47], v[62:63] neg_lo:[0,1] neg_hi:[0,1]
	s_nop 0
	v_pk_mul_f32 v[62:63], v[46:47], s[66:67]
	s_nop 0
	v_pk_fma_f32 v[46:47], v[46:47], s[6:7], v[62:63] op_sel:[0,0,1] op_sel_hi:[1,0,0] neg_lo:[1,0,0] neg_hi:[1,0,0]
	v_pk_add_f32 v[62:63], v[64:65], v[48:49]
; __device__ __forceinline__ f2 cmulw(f2 a, float wr, float wi) { const f2 s = __builtin_shufflevector(a, a, 1, 0); return s * (f2){-wi, wi} + a * (f2){wr, wr}; }
; __device__ __forceinline__ void fft32(f2 (&x)[32]) {
;     constexpr float TWR[32] = {TWR_LIST}; constexpr float TWI[32] = {TWI_LIST};
; #pragma unroll
;     for (int h = 16; h >= 1; h >>= 1) {
; #pragma unroll
;         for (int i0 = 0; i0 < 32; i0 += 2 * h) {
; #pragma unroll
;             for (int j = 0; j < h; ++j) {
;                 const int i = i0 + j, k = i + h, m = j * (32 / h);
;                 const f2 a = x[i], b = x[k], d = a - b;
;                 x[i] = a + b;
;                 if (m == 0) x[k] = d;
;                 else if (m == 16) x[k] = (f2){d.y, -d.x};
;                 else x[k] = cmulw(d, TWR[m], TWI[m]);
;             }
;         }
;     }
; }
	v_pk_add_f32 v[48:49], v[48:49], v[64:65] neg_lo:[0,1] neg_hi:[0,1]
	s_nop 0
	v_pk_mul_f32 v[64:65], v[48:49], s[62:63]
	s_nop 0
	v_pk_fma_f32 v[48:49], v[48:49], s[94:95], v[64:65] op_sel:[0,0,1] op_sel_hi:[1,0,0] neg_lo:[1,0,0] neg_hi:[1,0,0]
	v_pk_add_f32 v[64:65], v[66:67], v[50:51]
	v_pk_add_f32 v[50:51], v[50:51], v[66:67] neg_lo:[0,1] neg_hi:[0,1]
	s_nop 0
	v_pk_mul_f32 v[66:67], v[50:51], s[54:55]
	s_nop 0
	v_pk_fma_f32 v[50:51], v[50:51], s[56:57], v[66:67] op_sel:[0,0,1] op_sel_hi:[1,0,0] neg_lo:[1,0,0] neg_hi:[1,0,0]
	v_pk_add_f32 v[66:67], v[72:73], v[54:55] neg_lo:[0,1] neg_hi:[0,1]
	v_pk_add_f32 v[54:55], v[54:55], v[72:73]
	v_pk_add_f32 v[72:73], v[24:25], v[0:1]
	v_pk_add_f32 v[0:1], v[0:1], v[24:25] neg_lo:[0,1] neg_hi:[0,1]
	s_nop 0
	v_pk_mul_f32 v[24:25], v[0:1], s[54:55]
	s_nop 0
	v_pk_fma_f32 v[0:1], v[0:1], s[56:57], v[24:25] op_sel:[0,0,1] op_sel_hi:[1,0,0]
	v_pk_add_f32 v[24:25], v[26:27], v[2:3]
	v_pk_add_f32 v[2:3], v[2:3], v[26:27] neg_lo:[0,1] neg_hi:[0,1]
	s_nop 0
	v_pk_mul_f32 v[26:27], v[2:3], s[62:63]
	s_nop 0
	v_pk_fma_f32 v[2:3], v[2:3], s[94:95], v[26:27] op_sel:[0,0,1] op_sel_hi:[1,0,0]
	v_pk_add_f32 v[26:27], v[28:29], v[4:5]
	v_pk_add_f32 v[4:5], v[4:5], v[28:29] neg_lo:[0,1] neg_hi:[0,1]
	s_nop 0
	v_pk_mul_f32 v[28:29], v[4:5], s[66:67]
	s_nop 0
	v_pk_fma_f32 v[4:5], v[4:5], s[6:7], v[28:29] op_sel:[0,0,1] op_sel_hi:[1,0,0]
	v_pk_add_f32 v[28:29], v[30:31], v[6:7]
	v_pk_add_f32 v[6:7], v[6:7], v[30:31] neg_lo:[0,1] neg_hi:[0,1]
	s_nop 0
	v_xor_b32_e32 v31, 0x80000000, v6
	v_mov_b32_e32 v30, v7
	v_pk_add_f32 v[6:7], v[32:33], v[8:9]
	v_pk_add_f32 v[8:9], v[8:9], v[32:33] neg_lo:[0,1] neg_hi:[0,1]
	s_nop 0
	v_pk_mul_f32 v[32:33], v[8:9], s[66:67]
	s_nop 0
	v_pk_fma_f32 v[8:9], v[8:9], s[6:7], v[32:33] op_sel:[0,0,1] op_sel_hi:[1,0,0] neg_lo:[1,0,0] neg_hi:[1,0,0]
	v_pk_add_f32 v[32:33], v[34:35], v[10:11]
	v_pk_add_f32 v[10:11], v[10:11], v[34:35] neg_lo:[0,1] neg_hi:[0,1]
	s_movk_i32 s7, 0x1080
	v_pk_mul_f32 v[34:35], v[10:11], s[62:63]
	v_mul_lo_u32 v16, v16, s7
	v_pk_fma_f32 v[10:11], v[10:11], s[94:95], v[34:35] op_sel:[0,0,1] op_sel_hi:[1,0,0] neg_lo:[1,0,0] neg_hi:[1,0,0]
	v_pk_add_f32 v[34:35], v[36:37], v[14:15]
	v_pk_add_f32 v[14:15], v[14:15], v[36:37] neg_lo:[0,1] neg_hi:[0,1]
	s_nop 0
	v_pk_mul_f32 v[36:37], v[14:15], s[54:55]
	s_nop 0
	v_pk_fma_f32 v[14:15], v[14:15], s[56:57], v[36:37] op_sel:[0,0,1] op_sel_hi:[1,0,0] neg_lo:[1,0,0] neg_hi:[1,0,0]
	v_pk_add_f32 v[36:37], v[38:39], v[58:59] neg_lo:[0,1] neg_hi:[0,1]
	v_pk_add_f32 v[38:39], v[58:59], v[38:39]
	v_pk_add_f32 v[58:59], v[44:45], v[52:53]
	v_pk_add_f32 v[44:45], v[52:53], v[44:45] neg_lo:[0,1] neg_hi:[0,1]
	s_nop 0
	v_pk_mul_f32 v[52:53], v[44:45], s[62:63]
	s_nop 0
	v_pk_fma_f32 v[44:45], v[44:45], s[94:95], v[52:53] op_sel:[0,0,1] op_sel_hi:[1,0,0]
	v_pk_add_f32 v[52:53], v[62:63], v[68:69]
	v_pk_add_f32 v[62:63], v[68:69], v[62:63] neg_lo:[0,1] neg_hi:[0,1]
	s_nop 0
	v_xor_b32_e32 v69, 0x80000000, v62
	v_mov_b32_e32 v68, v63
	v_pk_add_f32 v[62:63], v[64:65], v[56:57]
	v_pk_add_f32 v[56:57], v[56:57], v[64:65] neg_lo:[0,1] neg_hi:[0,1]
	s_nop 0
	v_pk_mul_f32 v[64:65], v[56:57], s[62:63]
	s_nop 0
	v_pk_fma_f32 v[56:57], v[56:57], s[94:95], v[64:65] op_sel:[0,0,1] op_sel_hi:[1,0,0] neg_lo:[1,0,0] neg_hi:[1,0,0]
	v_pk_add_f32 v[64:65], v[70:71], v[60:61] neg_lo:[0,1] neg_hi:[0,1]
	v_pk_add_f32 v[60:61], v[60:61], v[70:71]
	v_pk_add_f32 v[70:71], v[46:47], v[22:23]
	v_pk_add_f32 v[22:23], v[22:23], v[46:47] neg_lo:[0,1] neg_hi:[0,1]
	s_nop 0
	v_pk_mul_f32 v[46:47], v[22:23], s[62:63]
	s_nop 0
	v_pk_fma_f32 v[22:23], v[22:23], s[94:95], v[46:47] op_sel:[0,0,1] op_sel_hi:[1,0,0]
	v_pk_add_f32 v[46:47], v[48:49], v[40:41]
	v_pk_add_f32 v[40:41], v[40:41], v[48:49] neg_lo:[0,1] neg_hi:[0,1]
	s_nop 0
	v_xor_b32_e32 v49, 0x80000000, v40
	v_mov_b32_e32 v48, v41
	v_pk_add_f32 v[40:41], v[50:51], v[42:43]
	v_pk_add_f32 v[42:43], v[42:43], v[50:51] neg_lo:[0,1] neg_hi:[0,1]
	s_nop 0
	v_pk_mul_f32 v[50:51], v[42:43], s[62:63]
	s_nop 0
	v_pk_fma_f32 v[42:43], v[42:43], s[94:95], v[50:51] op_sel:[0,0,1] op_sel_hi:[1,0,0] neg_lo:[1,0,0] neg_hi:[1,0,0]
	v_pk_add_f32 v[50:51], v[54:55], v[28:29] neg_lo:[0,1] neg_hi:[0,1]
	v_pk_add_f32 v[28:29], v[28:29], v[54:55]
	v_pk_add_f32 v[54:55], v[6:7], v[72:73]
	v_pk_add_f32 v[6:7], v[72:73], v[6:7] neg_lo:[0,1] neg_hi:[0,1]
	s_nop 0
	v_pk_mul_f32 v[72:73], v[6:7], s[62:63]
	s_nop 0
	v_pk_fma_f32 v[6:7], v[6:7], s[94:95], v[72:73] op_sel:[0,0,1] op_sel_hi:[1,0,0]
	v_pk_add_f32 v[72:73], v[32:33], v[24:25]
	v_pk_add_f32 v[24:25], v[24:25], v[32:33] neg_lo:[0,1] neg_hi:[0,1]
	s_nop 0
	v_xor_b32_e32 v33, 0x80000000, v24
	v_mov_b32_e32 v32, v25
	v_pk_add_f32 v[24:25], v[34:35], v[26:27]
	v_pk_add_f32 v[26:27], v[26:27], v[34:35] neg_lo:[0,1] neg_hi:[0,1]
	s_nop 0
	v_pk_mul_f32 v[34:35], v[26:27], s[62:63]
	s_nop 0
	v_pk_fma_f32 v[26:27], v[26:27], s[94:95], v[34:35] op_sel:[0,0,1] op_sel_hi:[1,0,0] neg_lo:[1,0,0] neg_hi:[1,0,0]
	v_pk_add_f32 v[34:35], v[66:67], v[30:31] neg_lo:[0,1] neg_hi:[0,1]
	v_pk_add_f32 v[30:31], v[66:67], v[30:31]
	v_pk_add_f32 v[66:67], v[8:9], v[0:1]
	v_pk_add_f32 v[0:1], v[0:1], v[8:9] neg_lo:[0,1] neg_hi:[0,1]
	s_nop 0
	v_pk_mul_f32 v[8:9], v[0:1], s[62:63]
	s_nop 0
	v_pk_fma_f32 v[0:1], v[0:1], s[94:95], v[8:9] op_sel:[0,0,1] op_sel_hi:[1,0,0]
	v_pk_add_f32 v[8:9], v[10:11], v[2:3]
	v_pk_add_f32 v[2:3], v[2:3], v[10:11] neg_lo:[0,1] neg_hi:[0,1]
	s_nop 0
	v_xor_b32_e32 v11, 0x80000000, v2
	v_mov_b32_e32 v10, v3
	v_pk_add_f32 v[2:3], v[14:15], v[4:5]
	v_pk_add_f32 v[4:5], v[4:5], v[14:15] neg_lo:[0,1] neg_hi:[0,1]
	s_nop 0
	v_pk_mul_f32 v[14:15], v[4:5], s[62:63]
	s_nop 0
; __device__ __forceinline__ f2 cmulw(f2 a, float wr, float wi) { const f2 s = __builtin_shufflevector(a, a, 1, 0); return s * (f2){-wi, wi} + a * (f2){wr, wr}; }
; __device__ __forceinline__ void fft32(f2 (&x)[32]) {
;     constexpr float TWR[32] = {TWR_LIST}; constexpr float TWI[32] = {TWI_LIST};
; #pragma unroll
;     for (int h = 16; h >= 1; h >>= 1) {
; #pragma unroll
;         for (int i0 = 0; i0 < 32; i0 += 2 * h) {
; #pragma unroll
;             for (int j = 0; j < h; ++j) {
;                 const int i = i0 + j, k = i + h, m = j * (32 / h);
;                 const f2 a = x[i], b = x[k], d = a - b;
;                 x[i] = a + b;
;                 if (m == 0) x[k] = d;
;                 else if (m == 16) x[k] = (f2){d.y, -d.x};
;                 else x[k] = cmulw(d, TWR[m], TWI[m]);
;             }
;         }
;     }
; }
; __device__ __forceinline__ void fft_forward(f2 (&x)[32], LAS f2* X, int t, LAS const float* W1, LAS const M2C* MC) {
;     ...
;     { const float wr = W1[0], wi = W1[1]; twiddle32<false>(x, wr * wr - wi * wi, 2.f * wr * wi); }
	v_pk_fma_f32 v[4:5], v[4:5], s[94:95], v[14:15] op_sel:[0,0,1] op_sel_hi:[1,0,0] neg_lo:[1,0,0] neg_hi:[1,0,0]
	v_pk_add_f32 v[14:15], v[38:39], v[52:53] neg_lo:[0,1] neg_hi:[0,1]
	v_pk_add_f32 v[38:39], v[52:53], v[38:39]
	v_pk_add_f32 v[52:53], v[62:63], v[58:59]
	v_pk_add_f32 v[58:59], v[58:59], v[62:63] neg_lo:[0,1] neg_hi:[0,1]
	s_nop 0
	v_xor_b32_e32 v63, 0x80000000, v58
	v_mov_b32_e32 v62, v59
	v_pk_add_f32 v[58:59], v[36:37], v[68:69] neg_lo:[0,1] neg_hi:[0,1]
	v_pk_add_f32 v[36:37], v[36:37], v[68:69]
	v_pk_add_f32 v[68:69], v[56:57], v[44:45]
	v_pk_add_f32 v[44:45], v[44:45], v[56:57] neg_lo:[0,1] neg_hi:[0,1]
	s_nop 0
	v_xor_b32_e32 v57, 0x80000000, v44
	v_mov_b32_e32 v56, v45
	v_pk_add_f32 v[44:45], v[60:61], v[46:47] neg_lo:[0,1] neg_hi:[0,1]
	v_pk_add_f32 v[46:47], v[60:61], v[46:47]
	v_pk_add_f32 v[60:61], v[40:41], v[70:71]
	v_pk_add_f32 v[40:41], v[70:71], v[40:41] neg_lo:[0,1] neg_hi:[0,1]
	s_nop 0
	v_xor_b32_e32 v71, 0x80000000, v40
	v_mov_b32_e32 v70, v41
	v_pk_add_f32 v[40:41], v[64:65], v[48:49] neg_lo:[0,1] neg_hi:[0,1]
	v_pk_add_f32 v[48:49], v[64:65], v[48:49]
	v_pk_add_f32 v[64:65], v[42:43], v[22:23]
	v_pk_add_f32 v[22:23], v[22:23], v[42:43] neg_lo:[0,1] neg_hi:[0,1]
	s_nop 0
	v_xor_b32_e32 v43, 0x80000000, v22
	v_mov_b32_e32 v42, v23
	v_pk_add_f32 v[22:23], v[28:29], v[72:73] neg_lo:[0,1] neg_hi:[0,1]
	v_pk_add_f32 v[28:29], v[28:29], v[72:73]
	v_pk_add_f32 v[72:73], v[24:25], v[54:55]
	v_pk_add_f32 v[24:25], v[54:55], v[24:25] neg_lo:[0,1] neg_hi:[0,1]
	s_nop 0
	v_xor_b32_e32 v55, 0x80000000, v24
	v_mov_b32_e32 v54, v25
	v_pk_add_f32 v[24:25], v[50:51], v[32:33] neg_lo:[0,1] neg_hi:[0,1]
	v_pk_add_f32 v[32:33], v[50:51], v[32:33]
	v_pk_add_f32 v[50:51], v[26:27], v[6:7]
	v_pk_add_f32 v[6:7], v[6:7], v[26:27] neg_lo:[0,1] neg_hi:[0,1]
	s_nop 0
	v_xor_b32_e32 v27, 0x80000000, v6
	v_mov_b32_e32 v26, v7
	v_pk_add_f32 v[6:7], v[30:31], v[8:9] neg_lo:[0,1] neg_hi:[0,1]
	v_pk_add_f32 v[8:9], v[30:31], v[8:9]
	v_pk_add_f32 v[30:31], v[2:3], v[66:67]
	v_pk_add_f32 v[2:3], v[66:67], v[2:3] neg_lo:[0,1] neg_hi:[0,1]
	s_nop 0
	v_xor_b32_e32 v67, 0x80000000, v2
	v_mov_b32_e32 v66, v3
	v_pk_add_f32 v[2:3], v[34:35], v[10:11] neg_lo:[0,1] neg_hi:[0,1]
	v_pk_add_f32 v[10:11], v[34:35], v[10:11]
	v_pk_add_f32 v[34:35], v[4:5], v[0:1]
	v_pk_add_f32 v[0:1], v[0:1], v[4:5] neg_lo:[0,1] neg_hi:[0,1]
	s_nop 0
	v_xor_b32_e32 v5, 0x80000000, v0
	v_mov_b32_e32 v4, v1
	v_pk_add_f32 v[0:1], v[52:53], v[38:39]
	v_pk_add_f32 v[38:39], v[38:39], v[52:53] neg_lo:[0,1] neg_hi:[0,1]
	v_pk_add_f32 v[52:53], v[14:15], v[62:63]
	v_pk_add_f32 v[14:15], v[14:15], v[62:63] neg_lo:[0,1] neg_hi:[0,1]
	v_pk_add_f32 v[62:63], v[36:37], v[68:69]
	v_pk_add_f32 v[36:37], v[36:37], v[68:69] neg_lo:[0,1] neg_hi:[0,1]
	v_pk_add_f32 v[68:69], v[58:59], v[56:57]
	v_pk_add_f32 v[56:57], v[58:59], v[56:57] neg_lo:[0,1] neg_hi:[0,1]
	v_pk_add_f32 v[58:59], v[46:47], v[60:61]
	v_pk_add_f32 v[46:47], v[46:47], v[60:61] neg_lo:[0,1] neg_hi:[0,1]
	v_pk_add_f32 v[60:61], v[44:45], v[70:71]
	v_pk_add_f32 v[44:45], v[44:45], v[70:71] neg_lo:[0,1] neg_hi:[0,1]
	v_pk_add_f32 v[70:71], v[48:49], v[64:65]
	v_pk_add_f32 v[48:49], v[48:49], v[64:65] neg_lo:[0,1] neg_hi:[0,1]
	v_pk_add_f32 v[64:65], v[40:41], v[42:43]
	v_pk_add_f32 v[40:41], v[40:41], v[42:43] neg_lo:[0,1] neg_hi:[0,1]
	v_pk_add_f32 v[42:43], v[28:29], v[72:73]
	v_pk_add_f32 v[28:29], v[28:29], v[72:73] neg_lo:[0,1] neg_hi:[0,1]
	v_pk_add_f32 v[72:73], v[22:23], v[54:55]
	v_pk_add_f32 v[22:23], v[22:23], v[54:55] neg_lo:[0,1] neg_hi:[0,1]
	v_pk_add_f32 v[54:55], v[32:33], v[50:51]
	v_pk_add_f32 v[32:33], v[32:33], v[50:51] neg_lo:[0,1] neg_hi:[0,1]
	v_pk_add_f32 v[50:51], v[24:25], v[26:27]
	v_pk_add_f32 v[24:25], v[24:25], v[26:27] neg_lo:[0,1] neg_hi:[0,1]
	v_pk_add_f32 v[26:27], v[8:9], v[30:31]
	v_pk_add_f32 v[8:9], v[8:9], v[30:31] neg_lo:[0,1] neg_hi:[0,1]
	v_pk_add_f32 v[30:31], v[6:7], v[66:67]
	v_pk_add_f32 v[6:7], v[6:7], v[66:67] neg_lo:[0,1] neg_hi:[0,1]
	v_pk_add_f32 v[66:67], v[10:11], v[34:35]
	v_pk_add_f32 v[10:11], v[10:11], v[34:35] neg_lo:[0,1] neg_hi:[0,1]
	v_pk_add_f32 v[34:35], v[2:3], v[4:5]
	v_pk_add_f32 v[2:3], v[2:3], v[4:5] neg_lo:[0,1] neg_hi:[0,1]
	ds_read_b64 v[4:5], v211
	s_waitcnt lgkmcnt(0)
; #define LAS __attribute__((address_space(3)))
; template <bool CONJ> __device__ __forceinline__ void twiddle32(f2 (&x)[32], float wr, float wi) {
;     asm volatile("" : "+v"(wr), "+v"(wi));
;     f2 c = (f2){wr, CONJ ? -wi : wi}; const f2 w = c;
; #pragma unroll
;     for (int k = 1; k < 32; ++k) { const int p = brev5(k); x[p] = cmulr(x[p], c); if (k < 31) c = cmulr(c, w); }
; }
; __device__ __forceinline__ void fft_forward(f2 (&x)[32], LAS f2* X, int t, LAS const float* W1, LAS const M2C* MC) {
;     ...
;     { const float wr = W1[0], wi = W1[1]; twiddle32<false>(x, wr * wr - wi * wi, 2.f * wr * wi); }
;     LAS f2* wp = X + t; LAS const f2* rp = X + (t >> 4) * XP + (t & 15); LAS f2* wp1 = wp + 16 * XP; LAS const f2* rp1 = rp + 256;
;     asm volatile("" : "+v"(wp), "+v"(rp), "+v"(wp1), "+v"(rp1));
; #pragma unroll
;     for (int k = 0; k < 16; ++k) { wp[k * XP] = x[brev5(k)]; wp1[k * XP] = x[brev5(k + 16)]; }
	v_pk_mul_f32 v[74:75], v[4:5], v[4:5]
	v_add_f32_e32 v4, v4, v4
	v_sub_f32_e32 v74, v74, v75
	v_mul_f32_e32 v75, v4, v5
	s_nop 0
	v_pk_mul_f32 v[4:5], v[42:43], v[74:75] op_sel_hi:[1,0]
	s_nop 0
	v_pk_fma_f32 v[4:5], v[42:43], v[74:75], v[4:5] op_sel:[1,1,0] op_sel_hi:[0,1,1] neg_lo:[0,1,0]
	ds_write_b64 v213, v[4:5] offset:4224
	v_pk_mul_f32 v[42:43], v[74:75], v[74:75] op_sel_hi:[1,0]
	s_nop 0
	v_pk_fma_f32 v[42:43], v[74:75], v[74:75], v[42:43] op_sel:[1,1,0] op_sel_hi:[0,1,1] neg_lo:[0,1,0]
	s_nop 0
	v_pk_mul_f32 v[76:77], v[58:59], v[42:43] op_sel_hi:[1,0]
	s_nop 0
	v_pk_fma_f32 v[58:59], v[58:59], v[42:43], v[76:77] op_sel:[1,1,0] op_sel_hi:[0,1,1] neg_lo:[0,1,0]
	ds_write_b64 v213, v[58:59] offset:8448
	v_pk_mul_f32 v[76:77], v[42:43], v[74:75] op_sel_hi:[1,0]
	s_nop 0
	v_pk_fma_f32 v[42:43], v[42:43], v[74:75], v[76:77] op_sel:[1,1,0] op_sel_hi:[0,1,1] neg_lo:[0,1,0]
	s_nop 0
	v_pk_mul_f32 v[76:77], v[26:27], v[42:43] op_sel_hi:[1,0]
	s_nop 0
	v_pk_fma_f32 v[26:27], v[26:27], v[42:43], v[76:77] op_sel:[1,1,0] op_sel_hi:[0,1,1] neg_lo:[0,1,0]
	ds_write_b64 v213, v[26:27] offset:12672
	v_pk_mul_f32 v[76:77], v[42:43], v[74:75] op_sel_hi:[1,0]
	s_nop 0
	v_pk_fma_f32 v[42:43], v[42:43], v[74:75], v[76:77] op_sel:[1,1,0] op_sel_hi:[0,1,1] neg_lo:[0,1,0]
	s_nop 0
	v_pk_mul_f32 v[76:77], v[62:63], v[42:43] op_sel_hi:[1,0]
	s_nop 0
	v_pk_fma_f32 v[62:63], v[62:63], v[42:43], v[76:77] op_sel:[1,1,0] op_sel_hi:[0,1,1] neg_lo:[0,1,0]
	ds_write_b64 v213, v[62:63] offset:16896
	v_pk_mul_f32 v[76:77], v[42:43], v[74:75] op_sel_hi:[1,0]
	s_nop 0
	v_pk_fma_f32 v[42:43], v[42:43], v[74:75], v[76:77] op_sel:[1,1,0] op_sel_hi:[0,1,1] neg_lo:[0,1,0]
	s_nop 0
	v_pk_mul_f32 v[76:77], v[54:55], v[42:43] op_sel_hi:[1,0]
	s_nop 0
	v_pk_fma_f32 v[54:55], v[54:55], v[42:43], v[76:77] op_sel:[1,1,0] op_sel_hi:[0,1,1] neg_lo:[0,1,0]
	ds_write_b64 v213, v[54:55] offset:21120
	v_pk_mul_f32 v[76:77], v[42:43], v[74:75] op_sel_hi:[1,0]
	s_nop 0
	v_pk_fma_f32 v[42:43], v[42:43], v[74:75], v[76:77] op_sel:[1,1,0] op_sel_hi:[0,1,1] neg_lo:[0,1,0]
	s_nop 0
	v_pk_mul_f32 v[76:77], v[70:71], v[42:43] op_sel_hi:[1,0]
	s_nop 0
	v_pk_fma_f32 v[70:71], v[70:71], v[42:43], v[76:77] op_sel:[1,1,0] op_sel_hi:[0,1,1] neg_lo:[0,1,0]
	ds_write_b64 v213, v[70:71] offset:25344
	v_pk_mul_f32 v[76:77], v[42:43], v[74:75] op_sel_hi:[1,0]
	s_nop 0
	v_pk_fma_f32 v[42:43], v[42:43], v[74:75], v[76:77] op_sel:[1,1,0] op_sel_hi:[0,1,1] neg_lo:[0,1,0]
	s_nop 0
	v_pk_mul_f32 v[76:77], v[66:67], v[42:43] op_sel_hi:[1,0]
	s_nop 0
	v_pk_fma_f32 v[66:67], v[66:67], v[42:43], v[76:77] op_sel:[1,1,0] op_sel_hi:[0,1,1] neg_lo:[0,1,0]
	ds_write_b64 v213, v[66:67] offset:29568
	v_pk_mul_f32 v[76:77], v[42:43], v[74:75] op_sel_hi:[1,0]
	s_nop 0
	v_pk_fma_f32 v[42:43], v[42:43], v[74:75], v[76:77] op_sel:[1,1,0] op_sel_hi:[0,1,1] neg_lo:[0,1,0]
	s_nop 0
	v_pk_mul_f32 v[76:77], v[52:53], v[42:43] op_sel_hi:[1,0]
	s_nop 0
	v_pk_fma_f32 v[52:53], v[52:53], v[42:43], v[76:77] op_sel:[1,1,0] op_sel_hi:[0,1,1] neg_lo:[0,1,0]
	ds_write_b64 v213, v[52:53] offset:33792
	v_pk_mul_f32 v[76:77], v[42:43], v[74:75] op_sel_hi:[1,0]
	s_nop 0
	v_pk_fma_f32 v[42:43], v[42:43], v[74:75], v[76:77] op_sel:[1,1,0] op_sel_hi:[0,1,1] neg_lo:[0,1,0]
	s_nop 0
	v_pk_mul_f32 v[76:77], v[72:73], v[42:43] op_sel_hi:[1,0]
	s_nop 0
	v_pk_fma_f32 v[72:73], v[72:73], v[42:43], v[76:77] op_sel:[1,1,0] op_sel_hi:[0,1,1] neg_lo:[0,1,0]
	ds_write_b64 v213, v[72:73] offset:38016
	v_pk_mul_f32 v[76:77], v[42:43], v[74:75] op_sel_hi:[1,0]
	s_nop 0
	v_pk_fma_f32 v[42:43], v[42:43], v[74:75], v[76:77] op_sel:[1,1,0] op_sel_hi:[0,1,1] neg_lo:[0,1,0]
	s_nop 0
	v_pk_mul_f32 v[76:77], v[60:61], v[42:43] op_sel_hi:[1,0]
	s_nop 0
	v_pk_fma_f32 v[60:61], v[60:61], v[42:43], v[76:77] op_sel:[1,1,0] op_sel_hi:[0,1,1] neg_lo:[0,1,0]
	ds_write_b64 v213, v[60:61] offset:42240
	v_pk_mul_f32 v[76:77], v[42:43], v[74:75] op_sel_hi:[1,0]
	s_nop 0
	v_pk_fma_f32 v[42:43], v[42:43], v[74:75], v[76:77] op_sel:[1,1,0] op_sel_hi:[0,1,1] neg_lo:[0,1,0]
	s_nop 0
	v_pk_mul_f32 v[76:77], v[30:31], v[42:43] op_sel_hi:[1,0]
	s_nop 0
	v_pk_fma_f32 v[30:31], v[30:31], v[42:43], v[76:77] op_sel:[1,1,0] op_sel_hi:[0,1,1] neg_lo:[0,1,0]
	ds_write_b64 v213, v[30:31] offset:46464
	v_pk_mul_f32 v[76:77], v[42:43], v[74:75] op_sel_hi:[1,0]
	s_nop 0
	v_pk_fma_f32 v[42:43], v[42:43], v[74:75], v[76:77] op_sel:[1,1,0] op_sel_hi:[0,1,1] neg_lo:[0,1,0]
	s_nop 0
	v_pk_mul_f32 v[76:77], v[68:69], v[42:43] op_sel_hi:[1,0]
	s_nop 0
	v_pk_fma_f32 v[68:69], v[68:69], v[42:43], v[76:77] op_sel:[1,1,0] op_sel_hi:[0,1,1] neg_lo:[0,1,0]
	ds_write_b64 v213, v[68:69] offset:50688
	v_pk_mul_f32 v[76:77], v[42:43], v[74:75] op_sel_hi:[1,0]
	s_nop 0
	v_pk_fma_f32 v[42:43], v[42:43], v[74:75], v[76:77] op_sel:[1,1,0] op_sel_hi:[0,1,1] neg_lo:[0,1,0]
	s_nop 0
	v_pk_mul_f32 v[76:77], v[50:51], v[42:43] op_sel_hi:[1,0]
	s_nop 0
	v_pk_fma_f32 v[50:51], v[50:51], v[42:43], v[76:77] op_sel:[1,1,0] op_sel_hi:[0,1,1] neg_lo:[0,1,0]
	ds_write_b64 v213, v[50:51] offset:54912
	v_pk_mul_f32 v[76:77], v[42:43], v[74:75] op_sel_hi:[1,0]
	s_nop 0
	v_pk_fma_f32 v[42:43], v[42:43], v[74:75], v[76:77] op_sel:[1,1,0] op_sel_hi:[0,1,1] neg_lo:[0,1,0]
	s_nop 0
	v_pk_mul_f32 v[76:77], v[64:65], v[42:43] op_sel_hi:[1,0]
	s_nop 0
	v_pk_fma_f32 v[64:65], v[64:65], v[42:43], v[76:77] op_sel:[1,1,0] op_sel_hi:[0,1,1] neg_lo:[0,1,0]
	ds_write_b64 v213, v[64:65] offset:59136
	v_pk_mul_f32 v[76:77], v[42:43], v[74:75] op_sel_hi:[1,0]
	s_nop 0
	v_pk_fma_f32 v[42:43], v[42:43], v[74:75], v[76:77] op_sel:[1,1,0] op_sel_hi:[0,1,1] neg_lo:[0,1,0]
	s_nop 0
	v_pk_mul_f32 v[76:77], v[34:35], v[42:43] op_sel_hi:[1,0]
	s_nop 0
; #define LAS __attribute__((address_space(3)))
; #define LBAR() do { asm volatile("s_waitcnt lgkmcnt(0)" ::: "memory"); __builtin_amdgcn_s_barrier(); asm volatile("" ::: "memory"); } while (0)
; template <bool CONJ> __device__ __forceinline__ void twiddle32(f2 (&x)[32], float wr, float wi) {
;     asm volatile("" : "+v"(wr), "+v"(wi));
;     f2 c = (f2){wr, CONJ ? -wi : wi}; const f2 w = c;
; #pragma unroll
;     for (int k = 1; k < 32; ++k) { const int p = brev5(k); x[p] = cmulr(x[p], c); if (k < 31) c = cmulr(c, w); }
; }
; __device__ __forceinline__ void fft_forward(f2 (&x)[32], LAS f2* X, int t, LAS const float* W1, LAS const M2C* MC) {
;     ...
;     LAS f2* wp = X + t; LAS const f2* rp = X + (t >> 4) * XP + (t & 15); LAS f2* wp1 = wp + 16 * XP; LAS const f2* rp1 = rp + 256;
;     asm volatile("" : "+v"(wp), "+v"(rp), "+v"(wp1), "+v"(rp1));
; #pragma unroll
;     for (int k = 0; k < 16; ++k) { wp[k * XP] = x[brev5(k)]; wp1[k * XP] = x[brev5(k + 16)]; }
;     LBAR();
	v_pk_fma_f32 v[34:35], v[34:35], v[42:43], v[76:77] op_sel:[1,1,0] op_sel_hi:[0,1,1] neg_lo:[0,1,0]
	ds_write_b64 v213, v[34:35] offset:63360
	v_pk_mul_f32 v[76:77], v[42:43], v[74:75] op_sel_hi:[1,0]
	s_nop 0
	v_pk_fma_f32 v[42:43], v[42:43], v[74:75], v[76:77] op_sel:[1,1,0] op_sel_hi:[0,1,1] neg_lo:[0,1,0]
	s_nop 0
	v_pk_mul_f32 v[76:77], v[38:39], v[42:43] op_sel_hi:[1,0]
	s_nop 0
	v_pk_fma_f32 v[38:39], v[38:39], v[42:43], v[76:77] op_sel:[1,1,0] op_sel_hi:[0,1,1] neg_lo:[0,1,0]
	ds_write_b64 v212, v[38:39]
	v_pk_mul_f32 v[76:77], v[42:43], v[74:75] op_sel_hi:[1,0]
	s_nop 0
	v_pk_fma_f32 v[42:43], v[42:43], v[74:75], v[76:77] op_sel:[1,1,0] op_sel_hi:[0,1,1] neg_lo:[0,1,0]
	s_nop 0
	v_pk_mul_f32 v[76:77], v[28:29], v[42:43] op_sel_hi:[1,0]
	s_nop 0
	v_pk_fma_f32 v[28:29], v[28:29], v[42:43], v[76:77] op_sel:[1,1,0] op_sel_hi:[0,1,1] neg_lo:[0,1,0]
	ds_write_b64 v212, v[28:29] offset:4224
	v_pk_mul_f32 v[76:77], v[42:43], v[74:75] op_sel_hi:[1,0]
	s_nop 0
	v_pk_fma_f32 v[42:43], v[42:43], v[74:75], v[76:77] op_sel:[1,1,0] op_sel_hi:[0,1,1] neg_lo:[0,1,0]
	s_nop 0
	v_pk_mul_f32 v[76:77], v[46:47], v[42:43] op_sel_hi:[1,0]
	s_nop 0
	v_pk_fma_f32 v[46:47], v[46:47], v[42:43], v[76:77] op_sel:[1,1,0] op_sel_hi:[0,1,1] neg_lo:[0,1,0]
	ds_write_b64 v212, v[46:47] offset:8448
	v_pk_mul_f32 v[76:77], v[42:43], v[74:75] op_sel_hi:[1,0]
	s_nop 0
	v_pk_fma_f32 v[42:43], v[42:43], v[74:75], v[76:77] op_sel:[1,1,0] op_sel_hi:[0,1,1] neg_lo:[0,1,0]
	s_nop 0
	v_pk_mul_f32 v[76:77], v[8:9], v[42:43] op_sel_hi:[1,0]
	s_nop 0
	v_pk_fma_f32 v[8:9], v[8:9], v[42:43], v[76:77] op_sel:[1,1,0] op_sel_hi:[0,1,1] neg_lo:[0,1,0]
	ds_write_b64 v212, v[8:9] offset:12672
	v_pk_mul_f32 v[76:77], v[42:43], v[74:75] op_sel_hi:[1,0]
	s_nop 0
	v_pk_fma_f32 v[42:43], v[42:43], v[74:75], v[76:77] op_sel:[1,1,0] op_sel_hi:[0,1,1] neg_lo:[0,1,0]
	s_nop 0
	v_pk_mul_f32 v[76:77], v[36:37], v[42:43] op_sel_hi:[1,0]
	s_nop 0
	v_pk_fma_f32 v[36:37], v[36:37], v[42:43], v[76:77] op_sel:[1,1,0] op_sel_hi:[0,1,1] neg_lo:[0,1,0]
	ds_write_b64 v212, v[36:37] offset:16896
	v_pk_mul_f32 v[76:77], v[42:43], v[74:75] op_sel_hi:[1,0]
	s_nop 0
	v_pk_fma_f32 v[42:43], v[42:43], v[74:75], v[76:77] op_sel:[1,1,0] op_sel_hi:[0,1,1] neg_lo:[0,1,0]
	s_nop 0
	v_pk_mul_f32 v[76:77], v[32:33], v[42:43] op_sel_hi:[1,0]
	s_nop 0
	v_pk_fma_f32 v[32:33], v[32:33], v[42:43], v[76:77] op_sel:[1,1,0] op_sel_hi:[0,1,1] neg_lo:[0,1,0]
	ds_write_b64 v212, v[32:33] offset:21120
	v_pk_mul_f32 v[76:77], v[42:43], v[74:75] op_sel_hi:[1,0]
	s_nop 0
	v_pk_fma_f32 v[42:43], v[42:43], v[74:75], v[76:77] op_sel:[1,1,0] op_sel_hi:[0,1,1] neg_lo:[0,1,0]
	s_nop 0
	v_pk_mul_f32 v[76:77], v[48:49], v[42:43] op_sel_hi:[1,0]
	s_nop 0
	v_pk_fma_f32 v[48:49], v[48:49], v[42:43], v[76:77] op_sel:[1,1,0] op_sel_hi:[0,1,1] neg_lo:[0,1,0]
	ds_write_b64 v212, v[48:49] offset:25344
	v_pk_mul_f32 v[76:77], v[42:43], v[74:75] op_sel_hi:[1,0]
	s_nop 0
	v_pk_fma_f32 v[42:43], v[42:43], v[74:75], v[76:77] op_sel:[1,1,0] op_sel_hi:[0,1,1] neg_lo:[0,1,0]
	s_nop 0
	v_pk_mul_f32 v[76:77], v[10:11], v[42:43] op_sel_hi:[1,0]
	s_nop 0
	v_pk_fma_f32 v[10:11], v[10:11], v[42:43], v[76:77] op_sel:[1,1,0] op_sel_hi:[0,1,1] neg_lo:[0,1,0]
	ds_write_b64 v212, v[10:11] offset:29568
	v_pk_mul_f32 v[76:77], v[42:43], v[74:75] op_sel_hi:[1,0]
	s_nop 0
	v_pk_fma_f32 v[42:43], v[42:43], v[74:75], v[76:77] op_sel:[1,1,0] op_sel_hi:[0,1,1] neg_lo:[0,1,0]
	s_nop 0
	v_pk_mul_f32 v[76:77], v[14:15], v[42:43] op_sel_hi:[1,0]
	s_nop 0
	v_pk_fma_f32 v[14:15], v[14:15], v[42:43], v[76:77] op_sel:[1,1,0] op_sel_hi:[0,1,1] neg_lo:[0,1,0]
	ds_write_b64 v212, v[14:15] offset:33792
	v_pk_mul_f32 v[76:77], v[42:43], v[74:75] op_sel_hi:[1,0]
	s_nop 0
	v_pk_fma_f32 v[42:43], v[42:43], v[74:75], v[76:77] op_sel:[1,1,0] op_sel_hi:[0,1,1] neg_lo:[0,1,0]
	s_nop 0
	v_pk_mul_f32 v[76:77], v[22:23], v[42:43] op_sel_hi:[1,0]
	s_nop 0
	v_pk_fma_f32 v[22:23], v[22:23], v[42:43], v[76:77] op_sel:[1,1,0] op_sel_hi:[0,1,1] neg_lo:[0,1,0]
	ds_write_b64 v212, v[22:23] offset:38016
	v_pk_mul_f32 v[76:77], v[42:43], v[74:75] op_sel_hi:[1,0]
	s_nop 0
	v_pk_fma_f32 v[42:43], v[42:43], v[74:75], v[76:77] op_sel:[1,1,0] op_sel_hi:[0,1,1] neg_lo:[0,1,0]
	s_nop 0
	v_pk_mul_f32 v[76:77], v[44:45], v[42:43] op_sel_hi:[1,0]
	s_nop 0
	v_pk_fma_f32 v[44:45], v[44:45], v[42:43], v[76:77] op_sel:[1,1,0] op_sel_hi:[0,1,1] neg_lo:[0,1,0]
	ds_write_b64 v212, v[44:45] offset:42240
	v_pk_mul_f32 v[76:77], v[42:43], v[74:75] op_sel_hi:[1,0]
	s_nop 0
	v_pk_fma_f32 v[42:43], v[42:43], v[74:75], v[76:77] op_sel:[1,1,0] op_sel_hi:[0,1,1] neg_lo:[0,1,0]
	s_nop 0
	v_pk_mul_f32 v[76:77], v[6:7], v[42:43] op_sel_hi:[1,0]
	s_nop 0
	v_pk_fma_f32 v[6:7], v[6:7], v[42:43], v[76:77] op_sel:[1,1,0] op_sel_hi:[0,1,1] neg_lo:[0,1,0]
	ds_write_b64 v212, v[6:7] offset:46464
	v_pk_mul_f32 v[76:77], v[42:43], v[74:75] op_sel_hi:[1,0]
	s_nop 0
	v_pk_fma_f32 v[42:43], v[42:43], v[74:75], v[76:77] op_sel:[1,1,0] op_sel_hi:[0,1,1] neg_lo:[0,1,0]
	s_nop 0
	v_pk_mul_f32 v[76:77], v[56:57], v[42:43] op_sel_hi:[1,0]
	s_nop 0
	v_pk_fma_f32 v[56:57], v[56:57], v[42:43], v[76:77] op_sel:[1,1,0] op_sel_hi:[0,1,1] neg_lo:[0,1,0]
	ds_write_b64 v212, v[56:57] offset:50688
	v_pk_mul_f32 v[76:77], v[42:43], v[74:75] op_sel_hi:[1,0]
	s_nop 0
	v_pk_fma_f32 v[42:43], v[42:43], v[74:75], v[76:77] op_sel:[1,1,0] op_sel_hi:[0,1,1] neg_lo:[0,1,0]
	s_nop 0
	v_pk_mul_f32 v[76:77], v[24:25], v[42:43] op_sel_hi:[1,0]
	s_nop 0
	v_pk_fma_f32 v[24:25], v[24:25], v[42:43], v[76:77] op_sel:[1,1,0] op_sel_hi:[0,1,1] neg_lo:[0,1,0]
	ds_write_b64 v212, v[24:25] offset:54912
	v_pk_mul_f32 v[76:77], v[42:43], v[74:75] op_sel_hi:[1,0]
	s_nop 0
	v_pk_fma_f32 v[42:43], v[42:43], v[74:75], v[76:77] op_sel:[1,1,0] op_sel_hi:[0,1,1] neg_lo:[0,1,0]
	s_nop 0
	v_pk_mul_f32 v[76:77], v[40:41], v[42:43] op_sel_hi:[1,0]
	s_nop 0
	v_pk_fma_f32 v[40:41], v[40:41], v[42:43], v[76:77] op_sel:[1,1,0] op_sel_hi:[0,1,1] neg_lo:[0,1,0]
	ds_write_b64 v212, v[40:41] offset:59136
	v_pk_mul_f32 v[76:77], v[42:43], v[74:75] op_sel_hi:[1,0]
	s_nop 0
	v_pk_fma_f32 v[42:43], v[42:43], v[74:75], v[76:77] op_sel:[1,1,0] op_sel_hi:[0,1,1] neg_lo:[0,1,0]
	s_nop 0
	v_pk_mul_f32 v[74:75], v[2:3], v[42:43] op_sel_hi:[1,0]
	s_nop 0
	v_pk_fma_f32 v[2:3], v[2:3], v[42:43], v[74:75] op_sel:[1,1,0] op_sel_hi:[0,1,1] neg_lo:[0,1,0]
	ds_write_b64 v212, v[2:3] offset:63360
	v_and_b32_e32 v42, 15, v12
	v_lshlrev_b32_e32 v42, 3, v42
	v_add3_u32 v214, 0, v16, v42
	v_add_u32_e32 v215, 0x800, v214
	v_mov_b32_e32 v16, v213
	v_mov_b32_e32 v42, v212
	v_mov_b32_e32 v74, v214
	v_mov_b32_e32 v75, v215
	ds_write_b64 v213, v[0:1]
	s_waitcnt lgkmcnt(0)
	s_barrier
; __device__ __forceinline__ f2 cmulw(f2 a, float wr, float wi) { const f2 s = __builtin_shufflevector(a, a, 1, 0); return s * (f2){-wi, wi} + a * (f2){wr, wr}; }
; #define LBAR() do { asm volatile("s_waitcnt lgkmcnt(0)" ::: "memory"); __builtin_amdgcn_s_barrier(); asm volatile("" ::: "memory"); } while (0)
; __device__ __forceinline__ void fft32(f2 (&x)[32]) {
;     constexpr float TWR[32] = {TWR_LIST}; constexpr float TWI[32] = {TWI_LIST};
; #pragma unroll
;     for (int h = 16; h >= 1; h >>= 1) {
; #pragma unroll
;         for (int i0 = 0; i0 < 32; i0 += 2 * h) {
; #pragma unroll
;             for (int j = 0; j < h; ++j) {
;                 const int i = i0 + j, k = i + h, m = j * (32 / h);
;                 const f2 a = x[i], b = x[k], d = a - b;
;                 x[i] = a + b;
;                 if (m == 0) x[k] = d;
;                 else if (m == 16) x[k] = (f2){d.y, -d.x};
;                 else x[k] = cmulw(d, TWR[m], TWI[m]);
;             }
;         }
;     }
; }
; __device__ __forceinline__ void fft_forward(f2 (&x)[32], LAS f2* X, int t, LAS const float* W1, LAS const M2C* MC) {
;     ...
; #pragma unroll
;     for (int m = 0; m < 16; ++m) { x[m] = rp[16 * m]; x[m + 16] = rp1[16 * m]; }
;     LBAR();
;     fft32(x);
	ds_read2_b64 v[0:3], v74 offset1:16
	ds_read2_b64 v[4:7], v75 offset1:16
	ds_read2_b64 v[8:11], v74 offset0:32 offset1:48
	ds_read2_b64 v[22:25], v75 offset0:32 offset1:48
	ds_read2_b64 v[26:29], v74 offset0:64 offset1:80
	ds_read2_b64 v[30:33], v75 offset0:64 offset1:80
	ds_read2_b64 v[34:37], v74 offset0:96 offset1:112
	ds_read2_b64 v[38:41], v75 offset0:96 offset1:112
	ds_read2_b64 v[42:45], v74 offset0:128 offset1:144
	ds_read2_b64 v[46:49], v75 offset0:128 offset1:144
	ds_read2_b64 v[50:53], v74 offset0:160 offset1:176
	ds_read2_b64 v[54:57], v75 offset0:160 offset1:176
	ds_read2_b64 v[58:61], v74 offset0:192 offset1:208
	ds_read2_b64 v[62:65], v75 offset0:192 offset1:208
	ds_read2_b64 v[66:69], v74 offset0:224 offset1:240
	ds_read2_b64 v[70:73], v75 offset0:224 offset1:240
	s_waitcnt lgkmcnt(14)
	v_pk_add_f32 v[14:15], v[0:1], v[4:5] neg_lo:[0,1] neg_hi:[0,1]
	v_pk_add_f32 v[0:1], v[0:1], v[4:5]
	v_pk_add_f32 v[4:5], v[2:3], v[6:7]
	v_pk_add_f32 v[2:3], v[2:3], v[6:7] neg_lo:[0,1] neg_hi:[0,1]
	s_waitcnt lgkmcnt(0)
	s_barrier
	v_pk_mul_f32 v[6:7], v[2:3], s[46:47]
	s_nop 0
	v_pk_fma_f32 v[2:3], v[2:3], s[52:53], v[6:7] op_sel:[0,0,1] op_sel_hi:[1,0,0]
	s_waitcnt lgkmcnt(12)
	v_pk_add_f32 v[6:7], v[8:9], v[22:23]
	v_pk_add_f32 v[8:9], v[8:9], v[22:23] neg_lo:[0,1] neg_hi:[0,1]
	s_nop 0
	v_pk_mul_f32 v[22:23], v[8:9], s[54:55]
	s_nop 0
	v_pk_fma_f32 v[8:9], v[8:9], s[56:57], v[22:23] op_sel:[0,0,1] op_sel_hi:[1,0,0]
	v_pk_add_f32 v[22:23], v[10:11], v[24:25]
	v_pk_add_f32 v[10:11], v[10:11], v[24:25] neg_lo:[0,1] neg_hi:[0,1]
	s_nop 0
	v_pk_mul_f32 v[24:25], v[10:11], s[58:59]
	s_nop 0
	v_pk_fma_f32 v[10:11], v[10:11], s[60:61], v[24:25] op_sel:[0,0,1] op_sel_hi:[1,0,0]
	s_waitcnt lgkmcnt(10)
	v_pk_add_f32 v[24:25], v[26:27], v[30:31]
	v_pk_add_f32 v[26:27], v[26:27], v[30:31] neg_lo:[0,1] neg_hi:[0,1]
	s_nop 0
	v_pk_mul_f32 v[30:31], v[26:27], s[62:63]
	s_nop 0
	v_pk_fma_f32 v[26:27], v[26:27], s[94:95], v[30:31] op_sel:[0,0,1] op_sel_hi:[1,0,0]
	v_pk_add_f32 v[30:31], v[28:29], v[32:33]
	v_pk_add_f32 v[28:29], v[28:29], v[32:33] neg_lo:[0,1] neg_hi:[0,1]
	s_nop 0
	v_pk_mul_f32 v[32:33], v[28:29], s[64:65]
	s_nop 0
	v_pk_fma_f32 v[28:29], v[28:29], s[20:21], v[32:33] op_sel:[0,0,1] op_sel_hi:[1,0,0]
	s_waitcnt lgkmcnt(8)
	v_pk_add_f32 v[32:33], v[34:35], v[38:39]
	v_pk_add_f32 v[34:35], v[34:35], v[38:39] neg_lo:[0,1] neg_hi:[0,1]
	s_nop 0
	v_pk_mul_f32 v[38:39], v[34:35], s[66:67]
	s_nop 0
	v_pk_fma_f32 v[34:35], v[34:35], s[6:7], v[38:39] op_sel:[0,0,1] op_sel_hi:[1,0,0]
	v_pk_add_f32 v[38:39], v[36:37], v[40:41]
	v_pk_add_f32 v[36:37], v[36:37], v[40:41] neg_lo:[0,1] neg_hi:[0,1]
	s_nop 0
	v_pk_mul_f32 v[40:41], v[36:37], s[78:79]
	s_nop 0
	v_pk_fma_f32 v[36:37], v[36:37], s[76:77], v[40:41] op_sel:[0,0,1] op_sel_hi:[1,0,0]
	s_waitcnt lgkmcnt(6)
	v_pk_add_f32 v[40:41], v[42:43], v[46:47]
	v_pk_add_f32 v[42:43], v[42:43], v[46:47] neg_lo:[0,1] neg_hi:[0,1]
	s_nop 0
	v_xor_b32_e32 v47, 0x80000000, v42
	v_mov_b32_e32 v46, v43
	v_pk_add_f32 v[42:43], v[44:45], v[48:49]
	v_pk_add_f32 v[44:45], v[44:45], v[48:49] neg_lo:[0,1] neg_hi:[0,1]
	s_nop 0
	v_pk_mul_f32 v[48:49], v[44:45], s[78:79]
	s_nop 0
	v_pk_fma_f32 v[44:45], v[44:45], s[76:77], v[48:49] op_sel:[0,0,1] op_sel_hi:[1,0,0] neg_lo:[1,0,0] neg_hi:[1,0,0]
	s_waitcnt lgkmcnt(4)
	v_pk_add_f32 v[48:49], v[50:51], v[54:55]
	v_pk_add_f32 v[50:51], v[50:51], v[54:55] neg_lo:[0,1] neg_hi:[0,1]
	s_nop 0
	v_pk_mul_f32 v[54:55], v[50:51], s[66:67]
	s_nop 0
	v_pk_fma_f32 v[50:51], v[50:51], s[6:7], v[54:55] op_sel:[0,0,1] op_sel_hi:[1,0,0] neg_lo:[1,0,0] neg_hi:[1,0,0]
	v_pk_add_f32 v[54:55], v[52:53], v[56:57]
	v_pk_add_f32 v[52:53], v[52:53], v[56:57] neg_lo:[0,1] neg_hi:[0,1]
	s_nop 0
	v_pk_mul_f32 v[56:57], v[52:53], s[64:65]
	s_nop 0
	v_pk_fma_f32 v[52:53], v[52:53], s[20:21], v[56:57] op_sel:[0,0,1] op_sel_hi:[1,0,0] neg_lo:[1,0,0] neg_hi:[1,0,0]
	s_waitcnt lgkmcnt(2)
	v_pk_add_f32 v[56:57], v[58:59], v[62:63]
	v_pk_add_f32 v[58:59], v[58:59], v[62:63] neg_lo:[0,1] neg_hi:[0,1]
	s_nop 0
	v_pk_mul_f32 v[62:63], v[58:59], s[62:63]
	s_nop 0
	v_pk_fma_f32 v[58:59], v[58:59], s[94:95], v[62:63] op_sel:[0,0,1] op_sel_hi:[1,0,0] neg_lo:[1,0,0] neg_hi:[1,0,0]
	v_pk_add_f32 v[62:63], v[60:61], v[64:65]
	v_pk_add_f32 v[60:61], v[60:61], v[64:65] neg_lo:[0,1] neg_hi:[0,1]
	s_nop 0
	v_pk_mul_f32 v[64:65], v[60:61], s[58:59]
	s_nop 0
	v_pk_fma_f32 v[60:61], v[60:61], s[60:61], v[64:65] op_sel:[0,0,1] op_sel_hi:[1,0,0] neg_lo:[1,0,0] neg_hi:[1,0,0]
	s_waitcnt lgkmcnt(0)
; __device__ __forceinline__ f2 cmulw(f2 a, float wr, float wi) { const f2 s = __builtin_shufflevector(a, a, 1, 0); return s * (f2){-wi, wi} + a * (f2){wr, wr}; }
; __device__ __forceinline__ void fft32(f2 (&x)[32]) {
;     constexpr float TWR[32] = {TWR_LIST}; constexpr float TWI[32] = {TWI_LIST};
; #pragma unroll
;     for (int h = 16; h >= 1; h >>= 1) {
; #pragma unroll
;         for (int i0 = 0; i0 < 32; i0 += 2 * h) {
; #pragma unroll
;             for (int j = 0; j < h; ++j) {
;                 const int i = i0 + j, k = i + h, m = j * (32 / h);
;                 const f2 a = x[i], b = x[k], d = a - b;
;                 x[i] = a + b;
;                 if (m == 0) x[k] = d;
;                 else if (m == 16) x[k] = (f2){d.y, -d.x};
;                 else x[k] = cmulw(d, TWR[m], TWI[m]);
;             }
;         }
;     }
; }
	v_pk_add_f32 v[64:65], v[66:67], v[70:71]
	v_pk_add_f32 v[66:67], v[66:67], v[70:71] neg_lo:[0,1] neg_hi:[0,1]
	s_nop 0
	v_pk_mul_f32 v[70:71], v[66:67], s[54:55]
	s_nop 0
	v_pk_fma_f32 v[66:67], v[66:67], s[56:57], v[70:71] op_sel:[0,0,1] op_sel_hi:[1,0,0] neg_lo:[1,0,0] neg_hi:[1,0,0]
	v_pk_add_f32 v[70:71], v[68:69], v[72:73]
	v_pk_add_f32 v[68:69], v[68:69], v[72:73] neg_lo:[0,1] neg_hi:[0,1]
	s_nop 0
	v_pk_mul_f32 v[72:73], v[68:69], s[46:47]
	s_nop 0
	v_pk_fma_f32 v[68:69], v[68:69], s[52:53], v[72:73] op_sel:[0,0,1] op_sel_hi:[1,0,0] neg_lo:[1,0,0] neg_hi:[1,0,0]
	v_pk_add_f32 v[72:73], v[0:1], v[40:41] neg_lo:[0,1] neg_hi:[0,1]
	v_pk_add_f32 v[0:1], v[0:1], v[40:41]
	v_pk_add_f32 v[40:41], v[4:5], v[42:43]
	v_pk_add_f32 v[4:5], v[4:5], v[42:43] neg_lo:[0,1] neg_hi:[0,1]
	s_nop 0
	v_pk_mul_f32 v[42:43], v[4:5], s[54:55]
	s_nop 0
	v_pk_fma_f32 v[4:5], v[4:5], s[56:57], v[42:43] op_sel:[0,0,1] op_sel_hi:[1,0,0]
	v_pk_add_f32 v[42:43], v[6:7], v[48:49]
	v_pk_add_f32 v[6:7], v[6:7], v[48:49] neg_lo:[0,1] neg_hi:[0,1]
	s_nop 0
	v_pk_mul_f32 v[48:49], v[6:7], s[62:63]
	s_nop 0
	v_pk_fma_f32 v[6:7], v[6:7], s[94:95], v[48:49] op_sel:[0,0,1] op_sel_hi:[1,0,0]
	v_pk_add_f32 v[48:49], v[22:23], v[54:55]
	v_pk_add_f32 v[22:23], v[22:23], v[54:55] neg_lo:[0,1] neg_hi:[0,1]
	s_nop 0
	v_pk_mul_f32 v[54:55], v[22:23], s[66:67]
	s_nop 0
	v_pk_fma_f32 v[22:23], v[22:23], s[6:7], v[54:55] op_sel:[0,0,1] op_sel_hi:[1,0,0]
	v_pk_add_f32 v[54:55], v[24:25], v[56:57]
	v_pk_add_f32 v[24:25], v[24:25], v[56:57] neg_lo:[0,1] neg_hi:[0,1]
	s_nop 0
	v_xor_b32_e32 v57, 0x80000000, v24
	v_mov_b32_e32 v56, v25
	v_pk_add_f32 v[24:25], v[30:31], v[62:63]
	v_pk_add_f32 v[30:31], v[30:31], v[62:63] neg_lo:[0,1] neg_hi:[0,1]
	s_nop 0
	v_pk_mul_f32 v[62:63], v[30:31], s[66:67]
	s_nop 0
	v_pk_fma_f32 v[30:31], v[30:31], s[6:7], v[62:63] op_sel:[0,0,1] op_sel_hi:[1,0,0] neg_lo:[1,0,0] neg_hi:[1,0,0]
	v_pk_add_f32 v[62:63], v[32:33], v[64:65]
	v_pk_add_f32 v[32:33], v[32:33], v[64:65] neg_lo:[0,1] neg_hi:[0,1]
	s_nop 0
	v_pk_mul_f32 v[64:65], v[32:33], s[62:63]
	s_nop 0
	v_pk_fma_f32 v[32:33], v[32:33], s[94:95], v[64:65] op_sel:[0,0,1] op_sel_hi:[1,0,0] neg_lo:[1,0,0] neg_hi:[1,0,0]
	v_pk_add_f32 v[64:65], v[38:39], v[70:71]
	v_pk_add_f32 v[38:39], v[38:39], v[70:71] neg_lo:[0,1] neg_hi:[0,1]
	s_nop 0
	v_pk_mul_f32 v[70:71], v[38:39], s[54:55]
	s_nop 0
	v_pk_fma_f32 v[38:39], v[38:39], s[56:57], v[70:71] op_sel:[0,0,1] op_sel_hi:[1,0,0] neg_lo:[1,0,0] neg_hi:[1,0,0]
	v_pk_add_f32 v[70:71], v[14:15], v[46:47] neg_lo:[0,1] neg_hi:[0,1]
	v_pk_add_f32 v[14:15], v[14:15], v[46:47]
	v_pk_add_f32 v[46:47], v[2:3], v[44:45]
	v_pk_add_f32 v[2:3], v[2:3], v[44:45] neg_lo:[0,1] neg_hi:[0,1]
	s_nop 0
	v_pk_mul_f32 v[44:45], v[2:3], s[54:55]
	s_nop 0
	v_pk_fma_f32 v[2:3], v[2:3], s[56:57], v[44:45] op_sel:[0,0,1] op_sel_hi:[1,0,0]
	v_pk_add_f32 v[44:45], v[8:9], v[50:51]
	v_pk_add_f32 v[8:9], v[8:9], v[50:51] neg_lo:[0,1] neg_hi:[0,1]
	s_nop 0
	v_pk_mul_f32 v[50:51], v[8:9], s[62:63]
	s_nop 0
	v_pk_fma_f32 v[8:9], v[8:9], s[94:95], v[50:51] op_sel:[0,0,1] op_sel_hi:[1,0,0]
	v_pk_add_f32 v[50:51], v[10:11], v[52:53]
	v_pk_add_f32 v[10:11], v[10:11], v[52:53] neg_lo:[0,1] neg_hi:[0,1]
	s_nop 0
	v_pk_mul_f32 v[52:53], v[10:11], s[66:67]
	s_nop 0
	v_pk_fma_f32 v[10:11], v[10:11], s[6:7], v[52:53] op_sel:[0,0,1] op_sel_hi:[1,0,0]
	v_pk_add_f32 v[52:53], v[26:27], v[58:59]
	v_pk_add_f32 v[26:27], v[26:27], v[58:59] neg_lo:[0,1] neg_hi:[0,1]
	s_nop 0
	v_xor_b32_e32 v59, 0x80000000, v26
	v_mov_b32_e32 v58, v27
	v_pk_add_f32 v[26:27], v[28:29], v[60:61]
	v_pk_add_f32 v[28:29], v[28:29], v[60:61] neg_lo:[0,1] neg_hi:[0,1]
	s_nop 0
	v_pk_mul_f32 v[60:61], v[28:29], s[66:67]
	s_nop 0
	v_pk_fma_f32 v[28:29], v[28:29], s[6:7], v[60:61] op_sel:[0,0,1] op_sel_hi:[1,0,0] neg_lo:[1,0,0] neg_hi:[1,0,0]
	v_pk_add_f32 v[60:61], v[34:35], v[66:67]
	v_pk_add_f32 v[34:35], v[34:35], v[66:67] neg_lo:[0,1] neg_hi:[0,1]
	s_mov_b64 s[6:7], -1
	v_pk_mul_f32 v[66:67], v[34:35], s[62:63]
	s_nop 0
	v_pk_fma_f32 v[34:35], v[34:35], s[94:95], v[66:67] op_sel:[0,0,1] op_sel_hi:[1,0,0] neg_lo:[1,0,0] neg_hi:[1,0,0]
	v_pk_add_f32 v[66:67], v[36:37], v[68:69]
	v_pk_add_f32 v[36:37], v[36:37], v[68:69] neg_lo:[0,1] neg_hi:[0,1]
	s_nop 0
	v_pk_mul_f32 v[68:69], v[36:37], s[54:55]
	s_nop 0
	v_pk_fma_f32 v[36:37], v[36:37], s[56:57], v[68:69] op_sel:[0,0,1] op_sel_hi:[1,0,0] neg_lo:[1,0,0] neg_hi:[1,0,0]
	v_pk_add_f32 v[68:69], v[0:1], v[54:55] neg_lo:[0,1] neg_hi:[0,1]
	v_pk_add_f32 v[0:1], v[0:1], v[54:55]
	v_pk_add_f32 v[54:55], v[40:41], v[24:25]
	v_pk_add_f32 v[24:25], v[40:41], v[24:25] neg_lo:[0,1] neg_hi:[0,1]
	s_nop 0
	v_pk_mul_f32 v[40:41], v[24:25], s[62:63]
	s_nop 0
	v_pk_fma_f32 v[24:25], v[24:25], s[94:95], v[40:41] op_sel:[0,0,1] op_sel_hi:[1,0,0]
	v_pk_add_f32 v[40:41], v[42:43], v[62:63]
	v_pk_add_f32 v[42:43], v[42:43], v[62:63] neg_lo:[0,1] neg_hi:[0,1]
	s_nop 0
	v_xor_b32_e32 v63, 0x80000000, v42
	v_mov_b32_e32 v62, v43
	v_pk_add_f32 v[42:43], v[48:49], v[64:65]
	v_pk_add_f32 v[48:49], v[48:49], v[64:65] neg_lo:[0,1] neg_hi:[0,1]
	s_nop 0
	v_pk_mul_f32 v[64:65], v[48:49], s[62:63]
	s_nop 0
	v_pk_fma_f32 v[48:49], v[48:49], s[94:95], v[64:65] op_sel:[0,0,1] op_sel_hi:[1,0,0] neg_lo:[1,0,0] neg_hi:[1,0,0]
	v_pk_add_f32 v[64:65], v[72:73], v[56:57] neg_lo:[0,1] neg_hi:[0,1]
	v_pk_add_f32 v[56:57], v[72:73], v[56:57]
	v_pk_add_f32 v[72:73], v[4:5], v[30:31]
	v_pk_add_f32 v[4:5], v[4:5], v[30:31] neg_lo:[0,1] neg_hi:[0,1]
	s_nop 0
	v_pk_mul_f32 v[30:31], v[4:5], s[62:63]
	s_nop 0
	v_pk_fma_f32 v[4:5], v[4:5], s[94:95], v[30:31] op_sel:[0,0,1] op_sel_hi:[1,0,0]
	v_pk_add_f32 v[30:31], v[6:7], v[32:33]
; #define LAS __attribute__((address_space(3)))
; __device__ __forceinline__ f2 cmulw(f2 a, float wr, float wi) { const f2 s = __builtin_shufflevector(a, a, 1, 0); return s * (f2){-wi, wi} + a * (f2){wr, wr}; }
; #define LBAR() do { asm volatile("s_waitcnt lgkmcnt(0)" ::: "memory"); __builtin_amdgcn_s_barrier(); asm volatile("" ::: "memory"); } while (0)
; __device__ __forceinline__ void fft32(f2 (&x)[32]) {
;     constexpr float TWR[32] = {TWR_LIST}; constexpr float TWI[32] = {TWI_LIST};
; #pragma unroll
;     for (int h = 16; h >= 1; h >>= 1) {
; #pragma unroll
;         for (int i0 = 0; i0 < 32; i0 += 2 * h) {
; #pragma unroll
;             for (int j = 0; j < h; ++j) {
;                 const int i = i0 + j, k = i + h, m = j * (32 / h);
;                 const f2 a = x[i], b = x[k], d = a - b;
;                 x[i] = a + b;
;                 if (m == 0) x[k] = d;
;                 else if (m == 16) x[k] = (f2){d.y, -d.x};
;                 else x[k] = cmulw(d, TWR[m], TWI[m]);
;             }
;         }
;     }
; }
; __device__ __forceinline__ void fft_forward(f2 (&x)[32], LAS f2* X, int t, LAS const float* W1, LAS const M2C* MC) {
;     fft32(x);
;     { const float wr = W1[0], wi = W1[1]; twiddle32<false>(x, wr * wr - wi * wi, 2.f * wr * wi); }
;     LAS f2* wp = X + t; LAS const f2* rp = X + (t >> 4) * XP + (t & 15); LAS f2* wp1 = wp + 16 * XP; LAS const f2* rp1 = rp + 256;
;     asm volatile("" : "+v"(wp), "+v"(rp), "+v"(wp1), "+v"(rp1));
; #pragma unroll
;     for (int k = 0; k < 16; ++k) { wp[k * XP] = x[brev5(k)]; wp1[k * XP] = x[brev5(k + 16)]; }
;     LBAR();
; #pragma unroll
;     for (int m = 0; m < 16; ++m) { x[m] = rp[16 * m]; x[m + 16] = rp1[16 * m]; }
;     LBAR();
;     fft32(x);
;     const M2C c = m2c_load(MC); const f2 t8 = (f2){c.t8r, c.t8i}, t4 = (f2){c.t4r, c.t4i}, t2 = (f2){c.t2r, c.t2i};
	v_pk_add_f32 v[6:7], v[6:7], v[32:33] neg_lo:[0,1] neg_hi:[0,1]
	s_nop 0
	v_xor_b32_e32 v33, 0x80000000, v6
	v_mov_b32_e32 v32, v7
	v_pk_add_f32 v[6:7], v[22:23], v[38:39]
	v_pk_add_f32 v[22:23], v[22:23], v[38:39] neg_lo:[0,1] neg_hi:[0,1]
	s_nop 0
	v_pk_mul_f32 v[38:39], v[22:23], s[62:63]
	s_nop 0
	v_pk_fma_f32 v[22:23], v[22:23], s[94:95], v[38:39] op_sel:[0,0,1] op_sel_hi:[1,0,0] neg_lo:[1,0,0] neg_hi:[1,0,0]
	v_pk_add_f32 v[38:39], v[14:15], v[52:53] neg_lo:[0,1] neg_hi:[0,1]
	v_pk_add_f32 v[14:15], v[14:15], v[52:53]
	v_pk_add_f32 v[52:53], v[46:47], v[26:27]
	v_pk_add_f32 v[26:27], v[46:47], v[26:27] neg_lo:[0,1] neg_hi:[0,1]
	s_nop 0
	v_pk_mul_f32 v[46:47], v[26:27], s[62:63]
	s_nop 0
	v_pk_fma_f32 v[26:27], v[26:27], s[94:95], v[46:47] op_sel:[0,0,1] op_sel_hi:[1,0,0]
	v_pk_add_f32 v[46:47], v[44:45], v[60:61]
	v_pk_add_f32 v[44:45], v[44:45], v[60:61] neg_lo:[0,1] neg_hi:[0,1]
	s_nop 0
	v_xor_b32_e32 v61, 0x80000000, v44
	v_mov_b32_e32 v60, v45
	v_pk_add_f32 v[44:45], v[50:51], v[66:67]
	v_pk_add_f32 v[50:51], v[50:51], v[66:67] neg_lo:[0,1] neg_hi:[0,1]
	v_pk_add_f32 v[74:75], v[52:53], v[44:45]
	v_pk_mul_f32 v[66:67], v[50:51], s[62:63]
	s_nop 0
	v_pk_fma_f32 v[50:51], v[50:51], s[94:95], v[66:67] op_sel:[0,0,1] op_sel_hi:[1,0,0] neg_lo:[1,0,0] neg_hi:[1,0,0]
	v_pk_add_f32 v[66:67], v[70:71], v[58:59] neg_lo:[0,1] neg_hi:[0,1]
	v_pk_add_f32 v[58:59], v[70:71], v[58:59]
	v_pk_add_f32 v[70:71], v[2:3], v[28:29]
	v_pk_add_f32 v[2:3], v[2:3], v[28:29] neg_lo:[0,1] neg_hi:[0,1]
	s_nop 0
	v_pk_mul_f32 v[28:29], v[2:3], s[62:63]
	s_nop 0
	v_pk_fma_f32 v[2:3], v[2:3], s[94:95], v[28:29] op_sel:[0,0,1] op_sel_hi:[1,0,0]
	v_pk_add_f32 v[28:29], v[8:9], v[34:35]
	v_pk_add_f32 v[8:9], v[8:9], v[34:35] neg_lo:[0,1] neg_hi:[0,1]
	s_nop 0
	v_xor_b32_e32 v35, 0x80000000, v8
	v_mov_b32_e32 v34, v9
	v_pk_add_f32 v[8:9], v[10:11], v[36:37]
	v_pk_add_f32 v[10:11], v[10:11], v[36:37] neg_lo:[0,1] neg_hi:[0,1]
	s_nop 0
	v_pk_mul_f32 v[36:37], v[10:11], s[62:63]
	s_nop 0
	v_pk_fma_f32 v[10:11], v[10:11], s[94:95], v[36:37] op_sel:[0,0,1] op_sel_hi:[1,0,0] neg_lo:[1,0,0] neg_hi:[1,0,0]
	v_pk_add_f32 v[36:37], v[0:1], v[40:41] neg_lo:[0,1] neg_hi:[0,1]
	v_pk_add_f32 v[0:1], v[0:1], v[40:41]
	v_pk_add_f32 v[40:41], v[54:55], v[42:43]
	v_pk_add_f32 v[42:43], v[54:55], v[42:43] neg_lo:[0,1] neg_hi:[0,1]
	v_pk_add_f32 v[78:79], v[0:1], v[40:41] neg_lo:[0,1] neg_hi:[0,1]
	v_xor_b32_e32 v55, 0x80000000, v42
	v_mov_b32_e32 v54, v43
	v_pk_add_f32 v[42:43], v[68:69], v[62:63] neg_lo:[0,1] neg_hi:[0,1]
	v_pk_add_f32 v[62:63], v[68:69], v[62:63]
	v_pk_add_f32 v[68:69], v[24:25], v[48:49]
	v_pk_add_f32 v[24:25], v[24:25], v[48:49] neg_lo:[0,1] neg_hi:[0,1]
	v_pk_add_f32 v[82:83], v[36:37], v[54:55] neg_lo:[0,1] neg_hi:[0,1]
	v_xor_b32_e32 v49, 0x80000000, v24
	v_mov_b32_e32 v48, v25
	v_pk_add_f32 v[24:25], v[56:57], v[30:31] neg_lo:[0,1] neg_hi:[0,1]
	v_pk_add_f32 v[30:31], v[56:57], v[30:31]
	v_pk_add_f32 v[56:57], v[72:73], v[6:7]
	v_pk_add_f32 v[6:7], v[72:73], v[6:7] neg_lo:[0,1] neg_hi:[0,1]
	v_pk_add_f32 v[80:81], v[42:43], v[48:49]
	v_xor_b32_e32 v73, 0x80000000, v6
	v_mov_b32_e32 v72, v7
	v_pk_add_f32 v[6:7], v[64:65], v[32:33] neg_lo:[0,1] neg_hi:[0,1]
	v_pk_add_f32 v[32:33], v[64:65], v[32:33]
	v_pk_add_f32 v[64:65], v[4:5], v[22:23]
	v_pk_add_f32 v[4:5], v[4:5], v[22:23] neg_lo:[0,1] neg_hi:[0,1]
	v_pk_add_f32 v[84:85], v[42:43], v[48:49] neg_lo:[0,1] neg_hi:[0,1]
	v_xor_b32_e32 v23, 0x80000000, v4
	v_mov_b32_e32 v22, v5
	v_pk_add_f32 v[4:5], v[14:15], v[46:47] neg_lo:[0,1] neg_hi:[0,1]
	v_pk_add_f32 v[46:47], v[14:15], v[46:47]
	v_pk_add_f32 v[14:15], v[52:53], v[44:45] neg_lo:[0,1] neg_hi:[0,1]
	v_pk_add_f32 v[52:53], v[38:39], v[60:61] neg_lo:[0,1] neg_hi:[0,1]
	v_xor_b32_e32 v45, 0x80000000, v14
	v_mov_b32_e32 v44, v15
	v_pk_add_f32 v[38:39], v[38:39], v[60:61]
	v_pk_add_f32 v[60:61], v[26:27], v[50:51]
	v_pk_add_f32 v[14:15], v[26:27], v[50:51] neg_lo:[0,1] neg_hi:[0,1]
	v_pk_add_f32 v[50:51], v[58:59], v[28:29] neg_lo:[0,1] neg_hi:[0,1]
	v_pk_add_f32 v[28:29], v[58:59], v[28:29]
	v_pk_add_f32 v[58:59], v[70:71], v[8:9]
	v_pk_add_f32 v[8:9], v[70:71], v[8:9] neg_lo:[0,1] neg_hi:[0,1]
	v_xor_b32_e32 v27, 0x80000000, v14
	v_xor_b32_e32 v71, 0x80000000, v8
	v_mov_b32_e32 v70, v9
	v_pk_add_f32 v[8:9], v[66:67], v[34:35] neg_lo:[0,1] neg_hi:[0,1]
	v_pk_add_f32 v[34:35], v[66:67], v[34:35]
	v_pk_add_f32 v[66:67], v[2:3], v[10:11]
	v_pk_add_f32 v[2:3], v[2:3], v[10:11] neg_lo:[0,1] neg_hi:[0,1]
	v_mov_b32_e32 v26, v15
	v_xor_b32_e32 v11, 0x80000000, v2
	v_mov_b32_e32 v10, v3
	v_pk_add_f32 v[14:15], v[0:1], v[40:41]
	v_pk_add_f32 v[40:41], v[36:37], v[54:55]
	v_pk_add_f32 v[36:37], v[30:31], v[56:57]
	v_pk_add_f32 v[30:31], v[30:31], v[56:57] neg_lo:[0,1] neg_hi:[0,1]
	v_pk_add_f32 v[42:43], v[24:25], v[72:73]
	v_pk_add_f32 v[86:87], v[24:25], v[72:73] neg_lo:[0,1] neg_hi:[0,1]
	v_pk_add_f32 v[24:25], v[32:33], v[64:65]
	v_pk_add_f32 v[88:89], v[32:33], v[64:65] neg_lo:[0,1] neg_hi:[0,1]
	v_pk_add_f32 v[48:49], v[6:7], v[22:23]
	v_pk_add_f32 v[22:23], v[6:7], v[22:23] neg_lo:[0,1] neg_hi:[0,1]
	v_pk_add_f32 v[32:33], v[46:47], v[74:75]
	v_pk_add_f32 v[46:47], v[46:47], v[74:75] neg_lo:[0,1] neg_hi:[0,1]
	v_pk_add_f32 v[56:57], v[4:5], v[44:45]
	v_pk_add_f32 v[74:75], v[4:5], v[44:45] neg_lo:[0,1] neg_hi:[0,1]
	v_pk_add_f32 v[64:65], v[50:51], v[70:71]
	v_pk_add_f32 v[50:51], v[50:51], v[70:71] neg_lo:[0,1] neg_hi:[0,1]
	v_pk_add_f32 v[70:71], v[34:35], v[66:67]
	v_pk_add_f32 v[34:35], v[34:35], v[66:67] neg_lo:[0,1] neg_hi:[0,1]
	v_pk_add_f32 v[66:67], v[8:9], v[10:11]
	v_pk_add_f32 v[92:93], v[8:9], v[10:11] neg_lo:[0,1] neg_hi:[0,1]
	ds_read_b128 v[8:11], v151
	ds_read_b128 v[0:3], v151 offset:16
	ds_read_b128 v[4:7], v151 offset:32
	v_pk_add_f32 v[44:45], v[38:39], v[60:61]
	v_pk_add_f32 v[90:91], v[38:39], v[60:61] neg_lo:[0,1] neg_hi:[0,1]
	v_pk_add_f32 v[60:61], v[28:29], v[58:59]
	v_pk_add_f32 v[58:59], v[28:29], v[58:59] neg_lo:[0,1] neg_hi:[0,1]
	s_waitcnt lgkmcnt(2)
; template <bool CONJ> __device__ __forceinline__ void twiddle32(f2 (&x)[32], float wr, float wi) {
;     asm volatile("" : "+v"(wr), "+v"(wi));
;     f2 c = (f2){wr, CONJ ? -wi : wi}; const f2 w = c;
; #pragma unroll
;     for (int k = 1; k < 32; ++k) { const int p = brev5(k); x[p] = cmulr(x[p], c); if (k < 31) c = cmulr(c, w); }
; }
	v_pk_add_f32 v[38:39], v[52:53], v[26:27]
	v_pk_mul_f32 v[28:29], v[32:33], v[8:9] op_sel_hi:[1,0]
	v_pk_add_f32 v[26:27], v[52:53], v[26:27] neg_lo:[0,1] neg_hi:[0,1]
	v_pk_fma_f32 v[52:53], v[32:33], v[8:9], v[28:29] op_sel:[1,1,0] op_sel_hi:[0,1,1] neg_lo:[0,1,0]
	v_pk_mul_f32 v[28:29], v[8:9], v[8:9] op_sel_hi:[1,0]
	v_pk_add_f32 v[54:55], v[62:63], v[68:69]
	v_pk_fma_f32 v[28:29], v[8:9], v[8:9], v[28:29] op_sel:[1,1,0] op_sel_hi:[0,1,1] neg_lo:[0,1,0]
	v_pk_add_f32 v[62:63], v[62:63], v[68:69] neg_lo:[0,1] neg_hi:[0,1]
	v_pk_mul_f32 v[32:33], v[36:37], v[28:29] op_sel_hi:[1,0]
	s_nop 0
	v_pk_fma_f32 v[36:37], v[36:37], v[28:29], v[32:33] op_sel:[1,1,0] op_sel_hi:[0,1,1] neg_lo:[0,1,0]
	v_pk_mul_f32 v[32:33], v[28:29], v[8:9] op_sel_hi:[1,0]
	s_nop 0
	v_pk_fma_f32 v[28:29], v[28:29], v[8:9], v[32:33] op_sel:[1,1,0] op_sel_hi:[0,1,1] neg_lo:[0,1,0]
	s_nop 0
	v_pk_mul_f32 v[32:33], v[60:61], v[28:29] op_sel_hi:[1,0]
	s_nop 0
	v_pk_fma_f32 v[68:69], v[60:61], v[28:29], v[32:33] op_sel:[1,1,0] op_sel_hi:[0,1,1] neg_lo:[0,1,0]
	v_pk_mul_f32 v[32:33], v[28:29], v[8:9] op_sel_hi:[1,0]
	s_nop 0
	v_pk_fma_f32 v[32:33], v[28:29], v[8:9], v[32:33] op_sel:[1,1,0] op_sel_hi:[0,1,1] neg_lo:[0,1,0]
	s_nop 0
	v_pk_mul_f32 v[28:29], v[54:55], v[32:33] op_sel_hi:[1,0]
	s_nop 0
	v_pk_fma_f32 v[28:29], v[54:55], v[32:33], v[28:29] op_sel:[1,1,0] op_sel_hi:[0,1,1] neg_lo:[0,1,0]
	v_pk_mul_f32 v[54:55], v[32:33], v[8:9] op_sel_hi:[1,0]
	s_nop 0
	v_pk_fma_f32 v[32:33], v[32:33], v[8:9], v[54:55] op_sel:[1,1,0] op_sel_hi:[0,1,1] neg_lo:[0,1,0]
	s_nop 0
	v_pk_mul_f32 v[54:55], v[44:45], v[32:33] op_sel_hi:[1,0]
	s_nop 0
	v_pk_fma_f32 v[60:61], v[44:45], v[32:33], v[54:55] op_sel:[1,1,0] op_sel_hi:[0,1,1] neg_lo:[0,1,0]
	v_pk_mul_f32 v[44:45], v[32:33], v[8:9] op_sel_hi:[1,0]
	s_nop 0
	v_pk_fma_f32 v[32:33], v[32:33], v[8:9], v[44:45] op_sel:[1,1,0] op_sel_hi:[0,1,1] neg_lo:[0,1,0]
	s_nop 0
	v_pk_mul_f32 v[44:45], v[24:25], v[32:33] op_sel_hi:[1,0]
	s_nop 0
	v_pk_fma_f32 v[44:45], v[24:25], v[32:33], v[44:45] op_sel:[1,1,0] op_sel_hi:[0,1,1] neg_lo:[0,1,0]
	v_pk_mul_f32 v[24:25], v[32:33], v[8:9] op_sel_hi:[1,0]
	s_nop 0
	v_pk_fma_f32 v[24:25], v[32:33], v[8:9], v[24:25] op_sel:[1,1,0] op_sel_hi:[0,1,1] neg_lo:[0,1,0]
	s_nop 0
	v_pk_mul_f32 v[32:33], v[70:71], v[24:25] op_sel_hi:[1,0]
	s_nop 0
	v_pk_fma_f32 v[76:77], v[70:71], v[24:25], v[32:33] op_sel:[1,1,0] op_sel_hi:[0,1,1] neg_lo:[0,1,0]
	v_pk_mul_f32 v[32:33], v[24:25], v[8:9] op_sel_hi:[1,0]
	s_nop 0
	v_pk_fma_f32 v[32:33], v[24:25], v[8:9], v[32:33] op_sel:[1,1,0] op_sel_hi:[0,1,1] neg_lo:[0,1,0]
	s_nop 0
	v_pk_mul_f32 v[24:25], v[40:41], v[32:33] op_sel_hi:[1,0]
	s_nop 0
	v_pk_fma_f32 v[24:25], v[40:41], v[32:33], v[24:25] op_sel:[1,1,0] op_sel_hi:[0,1,1] neg_lo:[0,1,0]
	v_pk_mul_f32 v[40:41], v[32:33], v[8:9] op_sel_hi:[1,0]
	s_nop 0
	v_pk_fma_f32 v[32:33], v[32:33], v[8:9], v[40:41] op_sel:[1,1,0] op_sel_hi:[0,1,1] neg_lo:[0,1,0]
	s_nop 0
	v_pk_mul_f32 v[40:41], v[56:57], v[32:33] op_sel_hi:[1,0]
	s_nop 0
	v_pk_fma_f32 v[56:57], v[56:57], v[32:33], v[40:41] op_sel:[1,1,0] op_sel_hi:[0,1,1] neg_lo:[0,1,0]
	v_pk_mul_f32 v[40:41], v[32:33], v[8:9] op_sel_hi:[1,0]
	s_nop 0
	v_pk_fma_f32 v[32:33], v[32:33], v[8:9], v[40:41] op_sel:[1,1,0] op_sel_hi:[0,1,1] neg_lo:[0,1,0]
	s_nop 0
	v_pk_mul_f32 v[40:41], v[42:43], v[32:33] op_sel_hi:[1,0]
	s_nop 0
	v_pk_fma_f32 v[40:41], v[42:43], v[32:33], v[40:41] op_sel:[1,1,0] op_sel_hi:[0,1,1] neg_lo:[0,1,0]
	v_pk_mul_f32 v[42:43], v[32:33], v[8:9] op_sel_hi:[1,0]
	s_nop 0
	v_pk_fma_f32 v[32:33], v[32:33], v[8:9], v[42:43] op_sel:[1,1,0] op_sel_hi:[0,1,1] neg_lo:[0,1,0]
	s_nop 0
	v_pk_mul_f32 v[42:43], v[64:65], v[32:33] op_sel_hi:[1,0]
	s_nop 0
	v_pk_fma_f32 v[72:73], v[64:65], v[32:33], v[42:43] op_sel:[1,1,0] op_sel_hi:[0,1,1] neg_lo:[0,1,0]
	v_pk_mul_f32 v[42:43], v[32:33], v[8:9] op_sel_hi:[1,0]
	s_nop 0
	v_pk_fma_f32 v[42:43], v[32:33], v[8:9], v[42:43] op_sel:[1,1,0] op_sel_hi:[0,1,1] neg_lo:[0,1,0]
	s_nop 0
	v_pk_mul_f32 v[32:33], v[80:81], v[42:43] op_sel_hi:[1,0]
	v_pk_mul_f32 v[54:55], v[42:43], v[8:9] op_sel_hi:[1,0]
	s_nop 0
	v_pk_fma_f32 v[32:33], v[80:81], v[42:43], v[32:33] op_sel:[1,1,0] op_sel_hi:[0,1,1] neg_lo:[0,1,0]
	v_pk_fma_f32 v[42:43], v[42:43], v[8:9], v[54:55] op_sel:[1,1,0] op_sel_hi:[0,1,1] neg_lo:[0,1,0]
	s_nop 0
	v_pk_mul_f32 v[54:55], v[38:39], v[42:43] op_sel_hi:[1,0]
	s_nop 0
	v_pk_fma_f32 v[64:65], v[38:39], v[42:43], v[54:55] op_sel:[1,1,0] op_sel_hi:[0,1,1] neg_lo:[0,1,0]
	v_pk_mul_f32 v[38:39], v[42:43], v[8:9] op_sel_hi:[1,0]
	s_nop 0
	v_pk_fma_f32 v[38:39], v[42:43], v[8:9], v[38:39] op_sel:[1,1,0] op_sel_hi:[0,1,1] neg_lo:[0,1,0]
	s_nop 0
	v_pk_mul_f32 v[42:43], v[48:49], v[38:39] op_sel_hi:[1,0]
	s_nop 0
	v_pk_fma_f32 v[48:49], v[48:49], v[38:39], v[42:43] op_sel:[1,1,0] op_sel_hi:[0,1,1] neg_lo:[0,1,0]
	v_pk_mul_f32 v[42:43], v[38:39], v[8:9] op_sel_hi:[1,0]
	s_nop 0
	v_pk_fma_f32 v[38:39], v[38:39], v[8:9], v[42:43] op_sel:[1,1,0] op_sel_hi:[0,1,1] neg_lo:[0,1,0]
	s_nop 0
	v_pk_mul_f32 v[42:43], v[66:67], v[38:39] op_sel_hi:[1,0]
	s_nop 0
	v_pk_fma_f32 v[80:81], v[66:67], v[38:39], v[42:43] op_sel:[1,1,0] op_sel_hi:[0,1,1] neg_lo:[0,1,0]
	v_pk_mul_f32 v[42:43], v[38:39], v[8:9] op_sel_hi:[1,0]
	s_nop 0
	v_pk_fma_f32 v[38:39], v[38:39], v[8:9], v[42:43] op_sel:[1,1,0] op_sel_hi:[0,1,1] neg_lo:[0,1,0]
	s_nop 0
	v_pk_mul_f32 v[42:43], v[78:79], v[38:39] op_sel_hi:[1,0]
	s_nop 0
	v_pk_fma_f32 v[94:95], v[78:79], v[38:39], v[42:43] op_sel:[1,1,0] op_sel_hi:[0,1,1] neg_lo:[0,1,0]
	v_pk_mul_f32 v[42:43], v[38:39], v[8:9] op_sel_hi:[1,0]
	s_nop 0
	v_pk_fma_f32 v[38:39], v[38:39], v[8:9], v[42:43] op_sel:[1,1,0] op_sel_hi:[0,1,1] neg_lo:[0,1,0]
; __device__ __forceinline__ float lx1(float v) { return __int_as_float(__builtin_amdgcn_update_dpp(0, __float_as_int(v), 0xB1, 0xF, 0xF, true)); }
; __device__ __forceinline__ float lx2(float v) { return __int_as_float(__builtin_amdgcn_update_dpp(0, __float_as_int(v), 0x4E, 0xF, 0xF, true)); }
; __device__ __forceinline__ float lx4(float v) { return __int_as_float(__builtin_amdgcn_ds_swizzle(__float_as_int(v), 0x101F)); }
; __device__ __forceinline__ float lx8(float v) { return __int_as_float(__builtin_amdgcn_update_dpp(0, __float_as_int(v), 0x128, 0xF, 0xF, true)); }
; template <bool CONJ> __device__ __forceinline__ void twiddle32(f2 (&x)[32], float wr, float wi) {
;     asm volatile("" : "+v"(wr), "+v"(wi));
;     f2 c = (f2){wr, CONJ ? -wi : wi}; const f2 w = c;
; #pragma unroll
;     for (int k = 1; k < 32; ++k) { const int p = brev5(k); x[p] = cmulr(x[p], c); if (k < 31) c = cmulr(c, w); }
; }
; __device__ __forceinline__ void fft_forward(f2 (&x)[32], LAS f2* X, int t, LAS const float* W1, LAS const M2C* MC) {
;     ...
; #pragma unroll
;     for (int p = 0; p < 32; ++p) {
;         f2 v = x[p], pr;
;         pr = (f2){lx8(v.x), lx8(v.y)}; v = cmulr(pr + v * c.s8, t8);
;         pr = (f2){lx4(v.x), lx4(v.y)}; v = cmulr(pr + v * c.s4, t4);
;         pr = (f2){lx2(v.x), lx2(v.y)}; v = cmulr(pr + v * c.s2, t2);
;         pr = (f2){lx1(v.x), lx1(v.y)}; x[p] = pr + v * c.s1;
;     }
	s_nop 0
	v_pk_mul_f32 v[42:43], v[46:47], v[38:39] op_sel_hi:[1,0]
	s_nop 0
	v_pk_fma_f32 v[54:55], v[46:47], v[38:39], v[42:43] op_sel:[1,1,0] op_sel_hi:[0,1,1] neg_lo:[0,1,0]
	v_pk_mul_f32 v[42:43], v[38:39], v[8:9] op_sel_hi:[1,0]
	s_nop 0
	v_pk_fma_f32 v[42:43], v[38:39], v[8:9], v[42:43] op_sel:[1,1,0] op_sel_hi:[0,1,1] neg_lo:[0,1,0]
	s_nop 0
	v_pk_mul_f32 v[38:39], v[30:31], v[42:43] op_sel_hi:[1,0]
	s_nop 0
	v_pk_fma_f32 v[38:39], v[30:31], v[42:43], v[38:39] op_sel:[1,1,0] op_sel_hi:[0,1,1] neg_lo:[0,1,0]
	v_pk_mul_f32 v[30:31], v[42:43], v[8:9] op_sel_hi:[1,0]
	s_nop 0
	v_pk_fma_f32 v[30:31], v[42:43], v[8:9], v[30:31] op_sel:[1,1,0] op_sel_hi:[0,1,1] neg_lo:[0,1,0]
	s_nop 0
	v_pk_mul_f32 v[42:43], v[58:59], v[30:31] op_sel_hi:[1,0]
	s_nop 0
	v_pk_fma_f32 v[70:71], v[58:59], v[30:31], v[42:43] op_sel:[1,1,0] op_sel_hi:[0,1,1] neg_lo:[0,1,0]
	v_pk_mul_f32 v[42:43], v[30:31], v[8:9] op_sel_hi:[1,0]
	s_nop 0
	v_pk_fma_f32 v[42:43], v[30:31], v[8:9], v[42:43] op_sel:[1,1,0] op_sel_hi:[0,1,1] neg_lo:[0,1,0]
	s_nop 0
	v_pk_mul_f32 v[30:31], v[62:63], v[42:43] op_sel_hi:[1,0]
	v_pk_mul_f32 v[46:47], v[42:43], v[8:9] op_sel_hi:[1,0]
	s_nop 0
	v_pk_fma_f32 v[30:31], v[62:63], v[42:43], v[30:31] op_sel:[1,1,0] op_sel_hi:[0,1,1] neg_lo:[0,1,0]
	v_pk_fma_f32 v[42:43], v[42:43], v[8:9], v[46:47] op_sel:[1,1,0] op_sel_hi:[0,1,1] neg_lo:[0,1,0]
	s_nop 0
	v_pk_mul_f32 v[46:47], v[90:91], v[42:43] op_sel_hi:[1,0]
	s_nop 0
	v_pk_fma_f32 v[62:63], v[90:91], v[42:43], v[46:47] op_sel:[1,1,0] op_sel_hi:[0,1,1] neg_lo:[0,1,0]
	v_pk_mul_f32 v[46:47], v[42:43], v[8:9] op_sel_hi:[1,0]
	s_nop 0
	v_pk_fma_f32 v[42:43], v[42:43], v[8:9], v[46:47] op_sel:[1,1,0] op_sel_hi:[0,1,1] neg_lo:[0,1,0]
	s_nop 0
	v_pk_mul_f32 v[46:47], v[88:89], v[42:43] op_sel_hi:[1,0]
	v_pk_mul_f32 v[58:59], v[42:43], v[8:9] op_sel_hi:[1,0]
	s_nop 0
	v_pk_fma_f32 v[46:47], v[88:89], v[42:43], v[46:47] op_sel:[1,1,0] op_sel_hi:[0,1,1] neg_lo:[0,1,0]
	v_pk_fma_f32 v[42:43], v[42:43], v[8:9], v[58:59] op_sel:[1,1,0] op_sel_hi:[0,1,1] neg_lo:[0,1,0]
	s_nop 0
	v_pk_mul_f32 v[58:59], v[34:35], v[42:43] op_sel_hi:[1,0]
	s_nop 0
	v_pk_fma_f32 v[78:79], v[34:35], v[42:43], v[58:59] op_sel:[1,1,0] op_sel_hi:[0,1,1] neg_lo:[0,1,0]
	v_pk_mul_f32 v[34:35], v[42:43], v[8:9] op_sel_hi:[1,0]
	s_nop 0
	v_pk_fma_f32 v[34:35], v[42:43], v[8:9], v[34:35] op_sel:[1,1,0] op_sel_hi:[0,1,1] neg_lo:[0,1,0]
	s_nop 0
	v_pk_mul_f32 v[42:43], v[82:83], v[34:35] op_sel_hi:[1,0]
	s_nop 0
	v_pk_fma_f32 v[88:89], v[82:83], v[34:35], v[42:43] op_sel:[1,1,0] op_sel_hi:[0,1,1] neg_lo:[0,1,0]
	v_pk_mul_f32 v[42:43], v[34:35], v[8:9] op_sel_hi:[1,0]
	s_nop 0
	v_pk_fma_f32 v[34:35], v[34:35], v[8:9], v[42:43] op_sel:[1,1,0] op_sel_hi:[0,1,1] neg_lo:[0,1,0]
	s_nop 0
	v_pk_mul_f32 v[42:43], v[74:75], v[34:35] op_sel_hi:[1,0]
	s_nop 0
	v_pk_fma_f32 v[58:59], v[74:75], v[34:35], v[42:43] op_sel:[1,1,0] op_sel_hi:[0,1,1] neg_lo:[0,1,0]
	v_pk_mul_f32 v[42:43], v[34:35], v[8:9] op_sel_hi:[1,0]
	s_nop 0
	v_pk_fma_f32 v[34:35], v[34:35], v[8:9], v[42:43] op_sel:[1,1,0] op_sel_hi:[0,1,1] neg_lo:[0,1,0]
	s_nop 0
	v_pk_mul_f32 v[42:43], v[86:87], v[34:35] op_sel_hi:[1,0]
	v_pk_mul_f32 v[66:67], v[34:35], v[8:9] op_sel_hi:[1,0]
	s_nop 0
	v_pk_fma_f32 v[42:43], v[86:87], v[34:35], v[42:43] op_sel:[1,1,0] op_sel_hi:[0,1,1] neg_lo:[0,1,0]
	v_pk_fma_f32 v[34:35], v[34:35], v[8:9], v[66:67] op_sel:[1,1,0] op_sel_hi:[0,1,1] neg_lo:[0,1,0]
	s_nop 0
	v_pk_mul_f32 v[66:67], v[50:51], v[34:35] op_sel_hi:[1,0]
	s_nop 0
	v_pk_fma_f32 v[74:75], v[50:51], v[34:35], v[66:67] op_sel:[1,1,0] op_sel_hi:[0,1,1] neg_lo:[0,1,0]
	v_pk_mul_f32 v[50:51], v[34:35], v[8:9] op_sel_hi:[1,0]
	s_nop 0
	v_pk_fma_f32 v[50:51], v[34:35], v[8:9], v[50:51] op_sel:[1,1,0] op_sel_hi:[0,1,1] neg_lo:[0,1,0]
	s_nop 0
	v_pk_mul_f32 v[34:35], v[84:85], v[50:51] op_sel_hi:[1,0]
	v_pk_mul_f32 v[66:67], v[50:51], v[8:9] op_sel_hi:[1,0]
	s_nop 0
	v_pk_fma_f32 v[34:35], v[84:85], v[50:51], v[34:35] op_sel:[1,1,0] op_sel_hi:[0,1,1] neg_lo:[0,1,0]
	v_pk_fma_f32 v[50:51], v[50:51], v[8:9], v[66:67] op_sel:[1,1,0] op_sel_hi:[0,1,1] neg_lo:[0,1,0]
	s_nop 0
	v_pk_mul_f32 v[66:67], v[26:27], v[50:51] op_sel_hi:[1,0]
	s_nop 0
	v_pk_fma_f32 v[66:67], v[26:27], v[50:51], v[66:67] op_sel:[1,1,0] op_sel_hi:[0,1,1] neg_lo:[0,1,0]
	v_pk_mul_f32 v[26:27], v[50:51], v[8:9] op_sel_hi:[1,0]
	s_nop 0
	v_pk_fma_f32 v[26:27], v[50:51], v[8:9], v[26:27] op_sel:[1,1,0] op_sel_hi:[0,1,1] neg_lo:[0,1,0]
	s_nop 0
	v_pk_mul_f32 v[50:51], v[22:23], v[26:27] op_sel_hi:[1,0]
	s_nop 0
	v_pk_fma_f32 v[50:51], v[22:23], v[26:27], v[50:51] op_sel:[1,1,0] op_sel_hi:[0,1,1] neg_lo:[0,1,0]
	v_pk_mul_f32 v[22:23], v[26:27], v[8:9] op_sel_hi:[1,0]
	s_nop 0
	v_pk_fma_f32 v[8:9], v[26:27], v[8:9], v[22:23] op_sel:[1,1,0] op_sel_hi:[0,1,1] neg_lo:[0,1,0]
	s_nop 0
	v_pk_mul_f32 v[22:23], v[92:93], v[8:9] op_sel_hi:[1,0]
	s_nop 0
	v_pk_fma_f32 v[82:83], v[92:93], v[8:9], v[22:23] op_sel:[1,1,0] op_sel_hi:[0,1,1] neg_lo:[0,1,0]
	s_waitcnt lgkmcnt(0)
	v_mov_b32_e32 v8, v7
	v_mov_b32_dpp v22, v14 row_ror:8 row_mask:0xf bank_mask:0xf bound_ctrl:1
	v_mov_b32_dpp v23, v15 row_ror:8 row_mask:0xf bank_mask:0xf bound_ctrl:1
	v_pk_fma_f32 v[14:15], v[14:15], v[4:5], v[22:23] op_sel_hi:[1,0,1]
	s_nop 0
	v_pk_mul_f32 v[22:23], v[14:15], v[10:11] op_sel_hi:[1,0]
	s_nop 0
	v_pk_fma_f32 v[14:15], v[14:15], v[10:11], v[22:23] op_sel:[1,1,0] op_sel_hi:[0,1,1] neg_lo:[0,1,0]
	ds_swizzle_b32 v22, v14 offset:swizzle(SWAP,4)
	ds_swizzle_b32 v23, v15 offset:swizzle(SWAP,4)
	s_waitcnt lgkmcnt(0)
; __device__ __forceinline__ float lx1(float v) { return __int_as_float(__builtin_amdgcn_update_dpp(0, __float_as_int(v), 0xB1, 0xF, 0xF, true)); }
; __device__ __forceinline__ float lx2(float v) { return __int_as_float(__builtin_amdgcn_update_dpp(0, __float_as_int(v), 0x4E, 0xF, 0xF, true)); }
; __device__ __forceinline__ float lx4(float v) { return __int_as_float(__builtin_amdgcn_ds_swizzle(__float_as_int(v), 0x101F)); }
; __device__ __forceinline__ float lx8(float v) { return __int_as_float(__builtin_amdgcn_update_dpp(0, __float_as_int(v), 0x128, 0xF, 0xF, true)); }
; __device__ __forceinline__ void fft_forward(f2 (&x)[32], LAS f2* X, int t, LAS const float* W1, LAS const M2C* MC) {
;     ...
; #pragma unroll
;     for (int p = 0; p < 32; ++p) {
;         f2 v = x[p], pr;
;         pr = (f2){lx8(v.x), lx8(v.y)}; v = cmulr(pr + v * c.s8, t8);
;         pr = (f2){lx4(v.x), lx4(v.y)}; v = cmulr(pr + v * c.s4, t4);
;         pr = (f2){lx2(v.x), lx2(v.y)}; v = cmulr(pr + v * c.s2, t2);
;         pr = (f2){lx1(v.x), lx1(v.y)}; x[p] = pr + v * c.s1;
;     }
	v_pk_fma_f32 v[14:15], v[4:5], v[14:15], v[22:23] op_sel:[1,0,0]
	s_nop 0
	v_pk_mul_f32 v[22:23], v[14:15], v[0:1] op_sel_hi:[1,0]
	s_nop 0
	v_pk_fma_f32 v[14:15], v[14:15], v[0:1], v[22:23] op_sel:[1,1,0] op_sel_hi:[0,1,1] neg_lo:[0,1,0]
	s_nop 1
	v_mov_b32_dpp v22, v14 quad_perm:[2,3,0,1] row_mask:0xf bank_mask:0xf bound_ctrl:1
	v_mov_b32_dpp v23, v15 quad_perm:[2,3,0,1] row_mask:0xf bank_mask:0xf bound_ctrl:1
	v_pk_fma_f32 v[14:15], v[6:7], v[14:15], v[22:23] op_sel_hi:[0,1,1]
	v_pk_mul_f32 v[22:23], v[14:15], v[2:3] op_sel_hi:[1,0]
	s_nop 0
	v_pk_fma_f32 v[14:15], v[14:15], v[2:3], v[22:23] op_sel:[1,1,0] op_sel_hi:[0,1,1] neg_lo:[0,1,0]
	s_nop 1
	v_mov_b32_dpp v22, v14 quad_perm:[1,0,3,2] row_mask:0xf bank_mask:0xf bound_ctrl:1
	v_mov_b32_dpp v23, v15 quad_perm:[1,0,3,2] row_mask:0xf bank_mask:0xf bound_ctrl:1
	v_pk_fma_f32 v[14:15], v[8:9], v[14:15], v[22:23] op_sel_hi:[0,1,1]
	v_mov_b32_dpp v22, v94 row_ror:8 row_mask:0xf bank_mask:0xf bound_ctrl:1
	v_mov_b32_dpp v23, v95 row_ror:8 row_mask:0xf bank_mask:0xf bound_ctrl:1
	v_pk_fma_f32 v[22:23], v[4:5], v[94:95], v[22:23] op_sel_hi:[0,1,1]
	v_pk_mul_f32 v[26:27], v[22:23], v[10:11] op_sel_hi:[1,0]
	s_nop 0
	v_pk_fma_f32 v[22:23], v[22:23], v[10:11], v[26:27] op_sel:[1,1,0] op_sel_hi:[0,1,1] neg_lo:[0,1,0]
	ds_swizzle_b32 v26, v22 offset:swizzle(SWAP,4)
	ds_swizzle_b32 v27, v23 offset:swizzle(SWAP,4)
	s_waitcnt lgkmcnt(0)
	v_pk_fma_f32 v[22:23], v[4:5], v[22:23], v[26:27] op_sel:[1,0,0]
	s_nop 0
	v_pk_mul_f32 v[26:27], v[22:23], v[0:1] op_sel_hi:[1,0]
	s_nop 0
	v_pk_fma_f32 v[22:23], v[22:23], v[0:1], v[26:27] op_sel:[1,1,0] op_sel_hi:[0,1,1] neg_lo:[0,1,0]
	s_nop 1
	v_mov_b32_dpp v26, v22 quad_perm:[2,3,0,1] row_mask:0xf bank_mask:0xf bound_ctrl:1
	v_mov_b32_dpp v27, v23 quad_perm:[2,3,0,1] row_mask:0xf bank_mask:0xf bound_ctrl:1
	v_pk_fma_f32 v[22:23], v[6:7], v[22:23], v[26:27] op_sel_hi:[0,1,1]
	v_pk_mul_f32 v[26:27], v[22:23], v[2:3] op_sel_hi:[1,0]
	s_nop 0
	v_pk_fma_f32 v[22:23], v[22:23], v[2:3], v[26:27] op_sel:[1,1,0] op_sel_hi:[0,1,1] neg_lo:[0,1,0]
	s_nop 1
	v_mov_b32_dpp v26, v22 quad_perm:[1,0,3,2] row_mask:0xf bank_mask:0xf bound_ctrl:1
	v_mov_b32_dpp v27, v23 quad_perm:[1,0,3,2] row_mask:0xf bank_mask:0xf bound_ctrl:1
	v_pk_fma_f32 v[22:23], v[8:9], v[22:23], v[26:27] op_sel_hi:[0,1,1]
	v_mov_b32_dpp v26, v24 row_ror:8 row_mask:0xf bank_mask:0xf bound_ctrl:1
	v_mov_b32_dpp v27, v25 row_ror:8 row_mask:0xf bank_mask:0xf bound_ctrl:1
	v_pk_fma_f32 v[24:25], v[4:5], v[24:25], v[26:27] op_sel_hi:[0,1,1]
	v_pk_mul_f32 v[26:27], v[24:25], v[10:11] op_sel_hi:[1,0]
	s_nop 0
	v_pk_fma_f32 v[24:25], v[24:25], v[10:11], v[26:27] op_sel:[1,1,0] op_sel_hi:[0,1,1] neg_lo:[0,1,0]
	ds_swizzle_b32 v26, v24 offset:swizzle(SWAP,4)
	ds_swizzle_b32 v27, v25 offset:swizzle(SWAP,4)
	s_waitcnt lgkmcnt(0)
	v_pk_fma_f32 v[24:25], v[4:5], v[24:25], v[26:27] op_sel:[1,0,0]
	s_nop 0
	v_pk_mul_f32 v[26:27], v[24:25], v[0:1] op_sel_hi:[1,0]
	s_nop 0
	v_pk_fma_f32 v[24:25], v[24:25], v[0:1], v[26:27] op_sel:[1,1,0] op_sel_hi:[0,1,1] neg_lo:[0,1,0]
	s_nop 1
	v_mov_b32_dpp v26, v24 quad_perm:[2,3,0,1] row_mask:0xf bank_mask:0xf bound_ctrl:1
	v_mov_b32_dpp v27, v25 quad_perm:[2,3,0,1] row_mask:0xf bank_mask:0xf bound_ctrl:1
	v_pk_fma_f32 v[24:25], v[6:7], v[24:25], v[26:27] op_sel_hi:[0,1,1]
	v_pk_mul_f32 v[26:27], v[24:25], v[2:3] op_sel_hi:[1,0]
	s_nop 0
	v_pk_fma_f32 v[24:25], v[24:25], v[2:3], v[26:27] op_sel:[1,1,0] op_sel_hi:[0,1,1] neg_lo:[0,1,0]
	s_nop 1
	v_mov_b32_dpp v26, v24 quad_perm:[1,0,3,2] row_mask:0xf bank_mask:0xf bound_ctrl:1
	v_mov_b32_dpp v27, v25 quad_perm:[1,0,3,2] row_mask:0xf bank_mask:0xf bound_ctrl:1
	v_pk_fma_f32 v[24:25], v[8:9], v[24:25], v[26:27] op_sel_hi:[0,1,1]
	v_mov_b32_dpp v26, v88 row_ror:8 row_mask:0xf bank_mask:0xf bound_ctrl:1
	v_mov_b32_dpp v27, v89 row_ror:8 row_mask:0xf bank_mask:0xf bound_ctrl:1
	v_pk_fma_f32 v[26:27], v[4:5], v[88:89], v[26:27] op_sel_hi:[0,1,1]
	v_pk_mul_f32 v[84:85], v[26:27], v[10:11] op_sel_hi:[1,0]
	s_nop 0
	v_pk_fma_f32 v[26:27], v[26:27], v[10:11], v[84:85] op_sel:[1,1,0] op_sel_hi:[0,1,1] neg_lo:[0,1,0]
	ds_swizzle_b32 v84, v26 offset:swizzle(SWAP,4)
	ds_swizzle_b32 v85, v27 offset:swizzle(SWAP,4)
	s_waitcnt lgkmcnt(0)
	v_pk_fma_f32 v[26:27], v[4:5], v[26:27], v[84:85] op_sel:[1,0,0]
	s_nop 0
	v_pk_mul_f32 v[84:85], v[26:27], v[0:1] op_sel_hi:[1,0]
	s_nop 0
	v_pk_fma_f32 v[26:27], v[26:27], v[0:1], v[84:85] op_sel:[1,1,0] op_sel_hi:[0,1,1] neg_lo:[0,1,0]
	s_nop 1
	v_mov_b32_dpp v84, v26 quad_perm:[2,3,0,1] row_mask:0xf bank_mask:0xf bound_ctrl:1
	v_mov_b32_dpp v85, v27 quad_perm:[2,3,0,1] row_mask:0xf bank_mask:0xf bound_ctrl:1
	v_pk_fma_f32 v[26:27], v[6:7], v[26:27], v[84:85] op_sel_hi:[0,1,1]
	v_pk_mul_f32 v[84:85], v[26:27], v[2:3] op_sel_hi:[1,0]
	s_nop 0
	v_pk_fma_f32 v[26:27], v[26:27], v[2:3], v[84:85] op_sel:[1,1,0] op_sel_hi:[0,1,1] neg_lo:[0,1,0]
	s_nop 1
	v_mov_b32_dpp v84, v26 quad_perm:[1,0,3,2] row_mask:0xf bank_mask:0xf bound_ctrl:1
	v_mov_b32_dpp v85, v27 quad_perm:[1,0,3,2] row_mask:0xf bank_mask:0xf bound_ctrl:1
	v_pk_fma_f32 v[26:27], v[8:9], v[26:27], v[84:85] op_sel_hi:[0,1,1]
	v_mov_b32_dpp v84, v28 row_ror:8 row_mask:0xf bank_mask:0xf bound_ctrl:1
	v_mov_b32_dpp v85, v29 row_ror:8 row_mask:0xf bank_mask:0xf bound_ctrl:1
	v_pk_fma_f32 v[28:29], v[4:5], v[28:29], v[84:85] op_sel_hi:[0,1,1]
	v_pk_mul_f32 v[84:85], v[28:29], v[10:11] op_sel_hi:[1,0]
	s_nop 0
	v_pk_fma_f32 v[28:29], v[28:29], v[10:11], v[84:85] op_sel:[1,1,0] op_sel_hi:[0,1,1] neg_lo:[0,1,0]
	ds_swizzle_b32 v84, v28 offset:swizzle(SWAP,4)
	ds_swizzle_b32 v85, v29 offset:swizzle(SWAP,4)
	s_waitcnt lgkmcnt(0)
; __device__ __forceinline__ float lx1(float v) { return __int_as_float(__builtin_amdgcn_update_dpp(0, __float_as_int(v), 0xB1, 0xF, 0xF, true)); }
; __device__ __forceinline__ float lx2(float v) { return __int_as_float(__builtin_amdgcn_update_dpp(0, __float_as_int(v), 0x4E, 0xF, 0xF, true)); }
; __device__ __forceinline__ float lx4(float v) { return __int_as_float(__builtin_amdgcn_ds_swizzle(__float_as_int(v), 0x101F)); }
; __device__ __forceinline__ float lx8(float v) { return __int_as_float(__builtin_amdgcn_update_dpp(0, __float_as_int(v), 0x128, 0xF, 0xF, true)); }
; __device__ __forceinline__ void fft_forward(f2 (&x)[32], LAS f2* X, int t, LAS const float* W1, LAS const M2C* MC) {
;     ...
; #pragma unroll
;     for (int p = 0; p < 32; ++p) {
;         f2 v = x[p], pr;
;         pr = (f2){lx8(v.x), lx8(v.y)}; v = cmulr(pr + v * c.s8, t8);
;         pr = (f2){lx4(v.x), lx4(v.y)}; v = cmulr(pr + v * c.s4, t4);
;         pr = (f2){lx2(v.x), lx2(v.y)}; v = cmulr(pr + v * c.s2, t2);
;         pr = (f2){lx1(v.x), lx1(v.y)}; x[p] = pr + v * c.s1;
;     }
	v_pk_fma_f32 v[28:29], v[4:5], v[28:29], v[84:85] op_sel:[1,0,0]
	s_nop 0
	v_pk_mul_f32 v[84:85], v[28:29], v[0:1] op_sel_hi:[1,0]
	s_nop 0
	v_pk_fma_f32 v[28:29], v[28:29], v[0:1], v[84:85] op_sel:[1,1,0] op_sel_hi:[0,1,1] neg_lo:[0,1,0]
	s_nop 1
	v_mov_b32_dpp v84, v28 quad_perm:[2,3,0,1] row_mask:0xf bank_mask:0xf bound_ctrl:1
	v_mov_b32_dpp v85, v29 quad_perm:[2,3,0,1] row_mask:0xf bank_mask:0xf bound_ctrl:1
	v_pk_fma_f32 v[28:29], v[6:7], v[28:29], v[84:85] op_sel_hi:[0,1,1]
	v_pk_mul_f32 v[84:85], v[28:29], v[2:3] op_sel_hi:[1,0]
	s_nop 0
	v_pk_fma_f32 v[28:29], v[28:29], v[2:3], v[84:85] op_sel:[1,1,0] op_sel_hi:[0,1,1] neg_lo:[0,1,0]
	s_nop 1
	v_mov_b32_dpp v84, v28 quad_perm:[1,0,3,2] row_mask:0xf bank_mask:0xf bound_ctrl:1
	v_mov_b32_dpp v85, v29 quad_perm:[1,0,3,2] row_mask:0xf bank_mask:0xf bound_ctrl:1
	v_pk_fma_f32 v[28:29], v[8:9], v[28:29], v[84:85] op_sel_hi:[0,1,1]
	v_mov_b32_dpp v84, v30 row_ror:8 row_mask:0xf bank_mask:0xf bound_ctrl:1
	v_mov_b32_dpp v85, v31 row_ror:8 row_mask:0xf bank_mask:0xf bound_ctrl:1
	v_pk_fma_f32 v[30:31], v[4:5], v[30:31], v[84:85] op_sel_hi:[0,1,1]
	v_pk_mul_f32 v[84:85], v[30:31], v[10:11] op_sel_hi:[1,0]
	s_nop 0
	v_pk_fma_f32 v[30:31], v[30:31], v[10:11], v[84:85] op_sel:[1,1,0] op_sel_hi:[0,1,1] neg_lo:[0,1,0]
	ds_swizzle_b32 v84, v30 offset:swizzle(SWAP,4)
	ds_swizzle_b32 v85, v31 offset:swizzle(SWAP,4)
	s_waitcnt lgkmcnt(0)
	v_pk_fma_f32 v[30:31], v[4:5], v[30:31], v[84:85] op_sel:[1,0,0]
	s_nop 0
	v_pk_mul_f32 v[84:85], v[30:31], v[0:1] op_sel_hi:[1,0]
	s_nop 0
	v_pk_fma_f32 v[30:31], v[30:31], v[0:1], v[84:85] op_sel:[1,1,0] op_sel_hi:[0,1,1] neg_lo:[0,1,0]
	s_nop 1
	v_mov_b32_dpp v84, v30 quad_perm:[2,3,0,1] row_mask:0xf bank_mask:0xf bound_ctrl:1
	v_mov_b32_dpp v85, v31 quad_perm:[2,3,0,1] row_mask:0xf bank_mask:0xf bound_ctrl:1
	v_pk_fma_f32 v[30:31], v[6:7], v[30:31], v[84:85] op_sel_hi:[0,1,1]
	v_pk_mul_f32 v[84:85], v[30:31], v[2:3] op_sel_hi:[1,0]
	s_nop 0
	v_pk_fma_f32 v[30:31], v[30:31], v[2:3], v[84:85] op_sel:[1,1,0] op_sel_hi:[0,1,1] neg_lo:[0,1,0]
	s_nop 1
	v_mov_b32_dpp v84, v30 quad_perm:[1,0,3,2] row_mask:0xf bank_mask:0xf bound_ctrl:1
	v_mov_b32_dpp v85, v31 quad_perm:[1,0,3,2] row_mask:0xf bank_mask:0xf bound_ctrl:1
	v_pk_fma_f32 v[30:31], v[8:9], v[30:31], v[84:85] op_sel_hi:[0,1,1]
	v_mov_b32_dpp v84, v32 row_ror:8 row_mask:0xf bank_mask:0xf bound_ctrl:1
	v_mov_b32_dpp v85, v33 row_ror:8 row_mask:0xf bank_mask:0xf bound_ctrl:1
	v_pk_fma_f32 v[32:33], v[4:5], v[32:33], v[84:85] op_sel_hi:[0,1,1]
	v_pk_mul_f32 v[84:85], v[32:33], v[10:11] op_sel_hi:[1,0]
	s_nop 0
	v_pk_fma_f32 v[32:33], v[32:33], v[10:11], v[84:85] op_sel:[1,1,0] op_sel_hi:[0,1,1] neg_lo:[0,1,0]
	ds_swizzle_b32 v84, v32 offset:swizzle(SWAP,4)
	ds_swizzle_b32 v85, v33 offset:swizzle(SWAP,4)
	s_waitcnt lgkmcnt(0)
	v_pk_fma_f32 v[32:33], v[4:5], v[32:33], v[84:85] op_sel:[1,0,0]
	s_nop 0
	v_pk_mul_f32 v[84:85], v[32:33], v[0:1] op_sel_hi:[1,0]
	s_nop 0
	v_pk_fma_f32 v[32:33], v[32:33], v[0:1], v[84:85] op_sel:[1,1,0] op_sel_hi:[0,1,1] neg_lo:[0,1,0]
	s_nop 1
	v_mov_b32_dpp v84, v32 quad_perm:[2,3,0,1] row_mask:0xf bank_mask:0xf bound_ctrl:1
	v_mov_b32_dpp v85, v33 quad_perm:[2,3,0,1] row_mask:0xf bank_mask:0xf bound_ctrl:1
	v_pk_fma_f32 v[32:33], v[6:7], v[32:33], v[84:85] op_sel_hi:[0,1,1]
	v_pk_mul_f32 v[84:85], v[32:33], v[2:3] op_sel_hi:[1,0]
	s_nop 0
	v_pk_fma_f32 v[32:33], v[32:33], v[2:3], v[84:85] op_sel:[1,1,0] op_sel_hi:[0,1,1] neg_lo:[0,1,0]
	s_nop 1
	v_mov_b32_dpp v84, v32 quad_perm:[1,0,3,2] row_mask:0xf bank_mask:0xf bound_ctrl:1
	v_mov_b32_dpp v85, v33 quad_perm:[1,0,3,2] row_mask:0xf bank_mask:0xf bound_ctrl:1
	v_pk_fma_f32 v[32:33], v[8:9], v[32:33], v[84:85] op_sel_hi:[0,1,1]
	v_mov_b32_dpp v84, v34 row_ror:8 row_mask:0xf bank_mask:0xf bound_ctrl:1
	v_mov_b32_dpp v85, v35 row_ror:8 row_mask:0xf bank_mask:0xf bound_ctrl:1
	v_pk_fma_f32 v[34:35], v[4:5], v[34:35], v[84:85] op_sel_hi:[0,1,1]
	v_pk_mul_f32 v[84:85], v[34:35], v[10:11] op_sel_hi:[1,0]
	s_nop 0
	v_pk_fma_f32 v[34:35], v[34:35], v[10:11], v[84:85] op_sel:[1,1,0] op_sel_hi:[0,1,1] neg_lo:[0,1,0]
	ds_swizzle_b32 v84, v34 offset:swizzle(SWAP,4)
	ds_swizzle_b32 v85, v35 offset:swizzle(SWAP,4)
	s_waitcnt lgkmcnt(0)
	v_pk_fma_f32 v[34:35], v[4:5], v[34:35], v[84:85] op_sel:[1,0,0]
	s_nop 0
	v_pk_mul_f32 v[84:85], v[34:35], v[0:1] op_sel_hi:[1,0]
	s_nop 0
	v_pk_fma_f32 v[34:35], v[34:35], v[0:1], v[84:85] op_sel:[1,1,0] op_sel_hi:[0,1,1] neg_lo:[0,1,0]
	s_nop 1
	v_mov_b32_dpp v84, v34 quad_perm:[2,3,0,1] row_mask:0xf bank_mask:0xf bound_ctrl:1
	v_mov_b32_dpp v85, v35 quad_perm:[2,3,0,1] row_mask:0xf bank_mask:0xf bound_ctrl:1
	v_pk_fma_f32 v[34:35], v[6:7], v[34:35], v[84:85] op_sel_hi:[0,1,1]
	v_pk_mul_f32 v[84:85], v[34:35], v[2:3] op_sel_hi:[1,0]
	s_nop 0
	v_pk_fma_f32 v[34:35], v[34:35], v[2:3], v[84:85] op_sel:[1,1,0] op_sel_hi:[0,1,1] neg_lo:[0,1,0]
	s_nop 1
	v_mov_b32_dpp v84, v34 quad_perm:[1,0,3,2] row_mask:0xf bank_mask:0xf bound_ctrl:1
	v_mov_b32_dpp v85, v35 quad_perm:[1,0,3,2] row_mask:0xf bank_mask:0xf bound_ctrl:1
	v_pk_fma_f32 v[34:35], v[8:9], v[34:35], v[84:85] op_sel_hi:[0,1,1]
	v_mov_b32_dpp v84, v36 row_ror:8 row_mask:0xf bank_mask:0xf bound_ctrl:1
	v_mov_b32_dpp v85, v37 row_ror:8 row_mask:0xf bank_mask:0xf bound_ctrl:1
	v_pk_fma_f32 v[36:37], v[4:5], v[36:37], v[84:85] op_sel_hi:[0,1,1]
	v_pk_mul_f32 v[84:85], v[36:37], v[10:11] op_sel_hi:[1,0]
	s_nop 0
	v_pk_fma_f32 v[36:37], v[36:37], v[10:11], v[84:85] op_sel:[1,1,0] op_sel_hi:[0,1,1] neg_lo:[0,1,0]
	ds_swizzle_b32 v84, v36 offset:swizzle(SWAP,4)
	ds_swizzle_b32 v85, v37 offset:swizzle(SWAP,4)
	s_waitcnt lgkmcnt(0)
; __device__ __forceinline__ float lx1(float v) { return __int_as_float(__builtin_amdgcn_update_dpp(0, __float_as_int(v), 0xB1, 0xF, 0xF, true)); }
; __device__ __forceinline__ float lx2(float v) { return __int_as_float(__builtin_amdgcn_update_dpp(0, __float_as_int(v), 0x4E, 0xF, 0xF, true)); }
; __device__ __forceinline__ float lx4(float v) { return __int_as_float(__builtin_amdgcn_ds_swizzle(__float_as_int(v), 0x101F)); }
; __device__ __forceinline__ float lx8(float v) { return __int_as_float(__builtin_amdgcn_update_dpp(0, __float_as_int(v), 0x128, 0xF, 0xF, true)); }
; __device__ __forceinline__ void fft_forward(f2 (&x)[32], LAS f2* X, int t, LAS const float* W1, LAS const M2C* MC) {
;     ...
; #pragma unroll
;     for (int p = 0; p < 32; ++p) {
;         f2 v = x[p], pr;
;         pr = (f2){lx8(v.x), lx8(v.y)}; v = cmulr(pr + v * c.s8, t8);
;         pr = (f2){lx4(v.x), lx4(v.y)}; v = cmulr(pr + v * c.s4, t4);
;         pr = (f2){lx2(v.x), lx2(v.y)}; v = cmulr(pr + v * c.s2, t2);
;         pr = (f2){lx1(v.x), lx1(v.y)}; x[p] = pr + v * c.s1;
;     }
	v_pk_fma_f32 v[36:37], v[4:5], v[36:37], v[84:85] op_sel:[1,0,0]
	s_nop 0
	v_pk_mul_f32 v[84:85], v[36:37], v[0:1] op_sel_hi:[1,0]
	s_nop 0
	v_pk_fma_f32 v[36:37], v[36:37], v[0:1], v[84:85] op_sel:[1,1,0] op_sel_hi:[0,1,1] neg_lo:[0,1,0]
	s_nop 1
	v_mov_b32_dpp v84, v36 quad_perm:[2,3,0,1] row_mask:0xf bank_mask:0xf bound_ctrl:1
	v_mov_b32_dpp v85, v37 quad_perm:[2,3,0,1] row_mask:0xf bank_mask:0xf bound_ctrl:1
	v_pk_fma_f32 v[36:37], v[6:7], v[36:37], v[84:85] op_sel_hi:[0,1,1]
	v_pk_mul_f32 v[84:85], v[36:37], v[2:3] op_sel_hi:[1,0]
	s_nop 0
	v_pk_fma_f32 v[36:37], v[36:37], v[2:3], v[84:85] op_sel:[1,1,0] op_sel_hi:[0,1,1] neg_lo:[0,1,0]
	s_nop 1
	v_mov_b32_dpp v84, v36 quad_perm:[1,0,3,2] row_mask:0xf bank_mask:0xf bound_ctrl:1
	v_mov_b32_dpp v85, v37 quad_perm:[1,0,3,2] row_mask:0xf bank_mask:0xf bound_ctrl:1
	v_pk_fma_f32 v[36:37], v[8:9], v[36:37], v[84:85] op_sel_hi:[0,1,1]
	v_mov_b32_dpp v84, v38 row_ror:8 row_mask:0xf bank_mask:0xf bound_ctrl:1
	v_mov_b32_dpp v85, v39 row_ror:8 row_mask:0xf bank_mask:0xf bound_ctrl:1
	v_pk_fma_f32 v[38:39], v[4:5], v[38:39], v[84:85] op_sel_hi:[0,1,1]
	v_pk_mul_f32 v[84:85], v[38:39], v[10:11] op_sel_hi:[1,0]
	s_nop 0
	v_pk_fma_f32 v[38:39], v[38:39], v[10:11], v[84:85] op_sel:[1,1,0] op_sel_hi:[0,1,1] neg_lo:[0,1,0]
	ds_swizzle_b32 v84, v38 offset:swizzle(SWAP,4)
	ds_swizzle_b32 v85, v39 offset:swizzle(SWAP,4)
	s_waitcnt lgkmcnt(0)
	v_pk_fma_f32 v[38:39], v[4:5], v[38:39], v[84:85] op_sel:[1,0,0]
	s_nop 0
	v_pk_mul_f32 v[84:85], v[38:39], v[0:1] op_sel_hi:[1,0]
	s_nop 0
	v_pk_fma_f32 v[38:39], v[38:39], v[0:1], v[84:85] op_sel:[1,1,0] op_sel_hi:[0,1,1] neg_lo:[0,1,0]
	s_nop 1
	v_mov_b32_dpp v84, v38 quad_perm:[2,3,0,1] row_mask:0xf bank_mask:0xf bound_ctrl:1
	v_mov_b32_dpp v85, v39 quad_perm:[2,3,0,1] row_mask:0xf bank_mask:0xf bound_ctrl:1
	v_pk_fma_f32 v[38:39], v[6:7], v[38:39], v[84:85] op_sel_hi:[0,1,1]
	v_pk_mul_f32 v[84:85], v[38:39], v[2:3] op_sel_hi:[1,0]
	s_nop 0
	v_pk_fma_f32 v[38:39], v[38:39], v[2:3], v[84:85] op_sel:[1,1,0] op_sel_hi:[0,1,1] neg_lo:[0,1,0]
	s_nop 1
	v_mov_b32_dpp v84, v38 quad_perm:[1,0,3,2] row_mask:0xf bank_mask:0xf bound_ctrl:1
	v_mov_b32_dpp v85, v39 quad_perm:[1,0,3,2] row_mask:0xf bank_mask:0xf bound_ctrl:1
	v_pk_fma_f32 v[38:39], v[8:9], v[38:39], v[84:85] op_sel_hi:[0,1,1]
	v_mov_b32_dpp v84, v40 row_ror:8 row_mask:0xf bank_mask:0xf bound_ctrl:1
	v_mov_b32_dpp v85, v41 row_ror:8 row_mask:0xf bank_mask:0xf bound_ctrl:1
	v_pk_fma_f32 v[40:41], v[4:5], v[40:41], v[84:85] op_sel_hi:[0,1,1]
	v_pk_mul_f32 v[84:85], v[40:41], v[10:11] op_sel_hi:[1,0]
	s_nop 0
	v_pk_fma_f32 v[40:41], v[40:41], v[10:11], v[84:85] op_sel:[1,1,0] op_sel_hi:[0,1,1] neg_lo:[0,1,0]
	ds_swizzle_b32 v84, v40 offset:swizzle(SWAP,4)
	ds_swizzle_b32 v85, v41 offset:swizzle(SWAP,4)
	s_waitcnt lgkmcnt(0)
	v_pk_fma_f32 v[40:41], v[4:5], v[40:41], v[84:85] op_sel:[1,0,0]
	s_nop 0
	v_pk_mul_f32 v[84:85], v[40:41], v[0:1] op_sel_hi:[1,0]
	s_nop 0
	v_pk_fma_f32 v[40:41], v[40:41], v[0:1], v[84:85] op_sel:[1,1,0] op_sel_hi:[0,1,1] neg_lo:[0,1,0]
	s_nop 1
	v_mov_b32_dpp v84, v40 quad_perm:[2,3,0,1] row_mask:0xf bank_mask:0xf bound_ctrl:1
	v_mov_b32_dpp v85, v41 quad_perm:[2,3,0,1] row_mask:0xf bank_mask:0xf bound_ctrl:1
	v_pk_fma_f32 v[40:41], v[6:7], v[40:41], v[84:85] op_sel_hi:[0,1,1]
	v_pk_mul_f32 v[84:85], v[40:41], v[2:3] op_sel_hi:[1,0]
	s_nop 0
	v_pk_fma_f32 v[40:41], v[40:41], v[2:3], v[84:85] op_sel:[1,1,0] op_sel_hi:[0,1,1] neg_lo:[0,1,0]
	s_nop 1
	v_mov_b32_dpp v84, v40 quad_perm:[1,0,3,2] row_mask:0xf bank_mask:0xf bound_ctrl:1
	v_mov_b32_dpp v85, v41 quad_perm:[1,0,3,2] row_mask:0xf bank_mask:0xf bound_ctrl:1
	v_pk_fma_f32 v[40:41], v[8:9], v[40:41], v[84:85] op_sel_hi:[0,1,1]
	v_mov_b32_dpp v84, v42 row_ror:8 row_mask:0xf bank_mask:0xf bound_ctrl:1
	v_mov_b32_dpp v85, v43 row_ror:8 row_mask:0xf bank_mask:0xf bound_ctrl:1
	v_pk_fma_f32 v[42:43], v[4:5], v[42:43], v[84:85] op_sel_hi:[0,1,1]
	v_pk_mul_f32 v[84:85], v[42:43], v[10:11] op_sel_hi:[1,0]
	s_nop 0
	v_pk_fma_f32 v[42:43], v[42:43], v[10:11], v[84:85] op_sel:[1,1,0] op_sel_hi:[0,1,1] neg_lo:[0,1,0]
	ds_swizzle_b32 v84, v42 offset:swizzle(SWAP,4)
	ds_swizzle_b32 v85, v43 offset:swizzle(SWAP,4)
	s_waitcnt lgkmcnt(0)
	v_pk_fma_f32 v[42:43], v[4:5], v[42:43], v[84:85] op_sel:[1,0,0]
	s_nop 0
	v_pk_mul_f32 v[84:85], v[42:43], v[0:1] op_sel_hi:[1,0]
	s_nop 0
	v_pk_fma_f32 v[42:43], v[42:43], v[0:1], v[84:85] op_sel:[1,1,0] op_sel_hi:[0,1,1] neg_lo:[0,1,0]
	s_nop 1
	v_mov_b32_dpp v84, v42 quad_perm:[2,3,0,1] row_mask:0xf bank_mask:0xf bound_ctrl:1
	v_mov_b32_dpp v85, v43 quad_perm:[2,3,0,1] row_mask:0xf bank_mask:0xf bound_ctrl:1
	v_pk_fma_f32 v[42:43], v[6:7], v[42:43], v[84:85] op_sel_hi:[0,1,1]
	v_pk_mul_f32 v[84:85], v[42:43], v[2:3] op_sel_hi:[1,0]
	s_nop 0
	v_pk_fma_f32 v[42:43], v[42:43], v[2:3], v[84:85] op_sel:[1,1,0] op_sel_hi:[0,1,1] neg_lo:[0,1,0]
	s_nop 1
	v_mov_b32_dpp v84, v42 quad_perm:[1,0,3,2] row_mask:0xf bank_mask:0xf bound_ctrl:1
	v_mov_b32_dpp v85, v43 quad_perm:[1,0,3,2] row_mask:0xf bank_mask:0xf bound_ctrl:1
	v_pk_fma_f32 v[42:43], v[8:9], v[42:43], v[84:85] op_sel_hi:[0,1,1]
	v_mov_b32_dpp v84, v44 row_ror:8 row_mask:0xf bank_mask:0xf bound_ctrl:1
	v_mov_b32_dpp v85, v45 row_ror:8 row_mask:0xf bank_mask:0xf bound_ctrl:1
	v_pk_fma_f32 v[44:45], v[4:5], v[44:45], v[84:85] op_sel_hi:[0,1,1]
	v_pk_mul_f32 v[84:85], v[44:45], v[10:11] op_sel_hi:[1,0]
	s_nop 0
	v_pk_fma_f32 v[44:45], v[44:45], v[10:11], v[84:85] op_sel:[1,1,0] op_sel_hi:[0,1,1] neg_lo:[0,1,0]
	ds_swizzle_b32 v84, v44 offset:swizzle(SWAP,4)
	ds_swizzle_b32 v85, v45 offset:swizzle(SWAP,4)
	s_waitcnt lgkmcnt(0)
; __device__ __forceinline__ float lx1(float v) { return __int_as_float(__builtin_amdgcn_update_dpp(0, __float_as_int(v), 0xB1, 0xF, 0xF, true)); }
; __device__ __forceinline__ float lx2(float v) { return __int_as_float(__builtin_amdgcn_update_dpp(0, __float_as_int(v), 0x4E, 0xF, 0xF, true)); }
; __device__ __forceinline__ float lx4(float v) { return __int_as_float(__builtin_amdgcn_ds_swizzle(__float_as_int(v), 0x101F)); }
; __device__ __forceinline__ float lx8(float v) { return __int_as_float(__builtin_amdgcn_update_dpp(0, __float_as_int(v), 0x128, 0xF, 0xF, true)); }
; __device__ __forceinline__ void fft_forward(f2 (&x)[32], LAS f2* X, int t, LAS const float* W1, LAS const M2C* MC) {
;     ...
; #pragma unroll
;     for (int p = 0; p < 32; ++p) {
;         f2 v = x[p], pr;
;         pr = (f2){lx8(v.x), lx8(v.y)}; v = cmulr(pr + v * c.s8, t8);
;         pr = (f2){lx4(v.x), lx4(v.y)}; v = cmulr(pr + v * c.s4, t4);
;         pr = (f2){lx2(v.x), lx2(v.y)}; v = cmulr(pr + v * c.s2, t2);
;         pr = (f2){lx1(v.x), lx1(v.y)}; x[p] = pr + v * c.s1;
;     }
	v_pk_fma_f32 v[44:45], v[4:5], v[44:45], v[84:85] op_sel:[1,0,0]
	s_nop 0
	v_pk_mul_f32 v[84:85], v[44:45], v[0:1] op_sel_hi:[1,0]
	s_nop 0
	v_pk_fma_f32 v[44:45], v[44:45], v[0:1], v[84:85] op_sel:[1,1,0] op_sel_hi:[0,1,1] neg_lo:[0,1,0]
	s_nop 1
	v_mov_b32_dpp v84, v44 quad_perm:[2,3,0,1] row_mask:0xf bank_mask:0xf bound_ctrl:1
	v_mov_b32_dpp v85, v45 quad_perm:[2,3,0,1] row_mask:0xf bank_mask:0xf bound_ctrl:1
	v_pk_fma_f32 v[44:45], v[6:7], v[44:45], v[84:85] op_sel_hi:[0,1,1]
	v_pk_mul_f32 v[84:85], v[44:45], v[2:3] op_sel_hi:[1,0]
	s_nop 0
	v_pk_fma_f32 v[44:45], v[44:45], v[2:3], v[84:85] op_sel:[1,1,0] op_sel_hi:[0,1,1] neg_lo:[0,1,0]
	s_nop 1
	v_mov_b32_dpp v84, v44 quad_perm:[1,0,3,2] row_mask:0xf bank_mask:0xf bound_ctrl:1
	v_mov_b32_dpp v85, v45 quad_perm:[1,0,3,2] row_mask:0xf bank_mask:0xf bound_ctrl:1
	v_pk_fma_f32 v[44:45], v[8:9], v[44:45], v[84:85] op_sel_hi:[0,1,1]
	v_mov_b32_dpp v84, v46 row_ror:8 row_mask:0xf bank_mask:0xf bound_ctrl:1
	v_mov_b32_dpp v85, v47 row_ror:8 row_mask:0xf bank_mask:0xf bound_ctrl:1
	v_pk_fma_f32 v[46:47], v[4:5], v[46:47], v[84:85] op_sel_hi:[0,1,1]
	v_pk_mul_f32 v[84:85], v[46:47], v[10:11] op_sel_hi:[1,0]
	s_nop 0
	v_pk_fma_f32 v[46:47], v[46:47], v[10:11], v[84:85] op_sel:[1,1,0] op_sel_hi:[0,1,1] neg_lo:[0,1,0]
	ds_swizzle_b32 v84, v46 offset:swizzle(SWAP,4)
	ds_swizzle_b32 v85, v47 offset:swizzle(SWAP,4)
	s_waitcnt lgkmcnt(0)
	v_pk_fma_f32 v[46:47], v[4:5], v[46:47], v[84:85] op_sel:[1,0,0]
	s_nop 0
	v_pk_mul_f32 v[84:85], v[46:47], v[0:1] op_sel_hi:[1,0]
	s_nop 0
	v_pk_fma_f32 v[46:47], v[46:47], v[0:1], v[84:85] op_sel:[1,1,0] op_sel_hi:[0,1,1] neg_lo:[0,1,0]
	s_nop 1
	v_mov_b32_dpp v84, v46 quad_perm:[2,3,0,1] row_mask:0xf bank_mask:0xf bound_ctrl:1
	v_mov_b32_dpp v85, v47 quad_perm:[2,3,0,1] row_mask:0xf bank_mask:0xf bound_ctrl:1
	v_pk_fma_f32 v[46:47], v[6:7], v[46:47], v[84:85] op_sel_hi:[0,1,1]
	v_pk_mul_f32 v[84:85], v[46:47], v[2:3] op_sel_hi:[1,0]
	s_nop 0
	v_pk_fma_f32 v[46:47], v[46:47], v[2:3], v[84:85] op_sel:[1,1,0] op_sel_hi:[0,1,1] neg_lo:[0,1,0]
	s_nop 1
	v_mov_b32_dpp v84, v46 quad_perm:[1,0,3,2] row_mask:0xf bank_mask:0xf bound_ctrl:1
	v_mov_b32_dpp v85, v47 quad_perm:[1,0,3,2] row_mask:0xf bank_mask:0xf bound_ctrl:1
	v_pk_fma_f32 v[46:47], v[8:9], v[46:47], v[84:85] op_sel_hi:[0,1,1]
	v_mov_b32_dpp v84, v48 row_ror:8 row_mask:0xf bank_mask:0xf bound_ctrl:1
	v_mov_b32_dpp v85, v49 row_ror:8 row_mask:0xf bank_mask:0xf bound_ctrl:1
	v_pk_fma_f32 v[48:49], v[4:5], v[48:49], v[84:85] op_sel_hi:[0,1,1]
	v_pk_mul_f32 v[84:85], v[48:49], v[10:11] op_sel_hi:[1,0]
	s_nop 0
	v_pk_fma_f32 v[48:49], v[48:49], v[10:11], v[84:85] op_sel:[1,1,0] op_sel_hi:[0,1,1] neg_lo:[0,1,0]
	ds_swizzle_b32 v84, v48 offset:swizzle(SWAP,4)
	ds_swizzle_b32 v85, v49 offset:swizzle(SWAP,4)
	s_waitcnt lgkmcnt(0)
	v_pk_fma_f32 v[48:49], v[4:5], v[48:49], v[84:85] op_sel:[1,0,0]
	s_nop 0
	v_pk_mul_f32 v[84:85], v[48:49], v[0:1] op_sel_hi:[1,0]
	s_nop 0
	v_pk_fma_f32 v[48:49], v[48:49], v[0:1], v[84:85] op_sel:[1,1,0] op_sel_hi:[0,1,1] neg_lo:[0,1,0]
	s_nop 1
	v_mov_b32_dpp v84, v48 quad_perm:[2,3,0,1] row_mask:0xf bank_mask:0xf bound_ctrl:1
	v_mov_b32_dpp v85, v49 quad_perm:[2,3,0,1] row_mask:0xf bank_mask:0xf bound_ctrl:1
	v_pk_fma_f32 v[48:49], v[6:7], v[48:49], v[84:85] op_sel_hi:[0,1,1]
	v_pk_mul_f32 v[84:85], v[48:49], v[2:3] op_sel_hi:[1,0]
	s_nop 0
	v_pk_fma_f32 v[48:49], v[48:49], v[2:3], v[84:85] op_sel:[1,1,0] op_sel_hi:[0,1,1] neg_lo:[0,1,0]
	s_nop 1
	v_mov_b32_dpp v84, v48 quad_perm:[1,0,3,2] row_mask:0xf bank_mask:0xf bound_ctrl:1
	v_mov_b32_dpp v85, v49 quad_perm:[1,0,3,2] row_mask:0xf bank_mask:0xf bound_ctrl:1
	v_pk_fma_f32 v[48:49], v[8:9], v[48:49], v[84:85] op_sel_hi:[0,1,1]
	v_mov_b32_dpp v84, v50 row_ror:8 row_mask:0xf bank_mask:0xf bound_ctrl:1
	v_mov_b32_dpp v85, v51 row_ror:8 row_mask:0xf bank_mask:0xf bound_ctrl:1
	v_pk_fma_f32 v[50:51], v[4:5], v[50:51], v[84:85] op_sel_hi:[0,1,1]
	v_pk_mul_f32 v[84:85], v[50:51], v[10:11] op_sel_hi:[1,0]
	s_nop 0
	v_pk_fma_f32 v[50:51], v[50:51], v[10:11], v[84:85] op_sel:[1,1,0] op_sel_hi:[0,1,1] neg_lo:[0,1,0]
	ds_swizzle_b32 v84, v50 offset:swizzle(SWAP,4)
	ds_swizzle_b32 v85, v51 offset:swizzle(SWAP,4)
	s_waitcnt lgkmcnt(0)
	v_pk_fma_f32 v[50:51], v[4:5], v[50:51], v[84:85] op_sel:[1,0,0]
	s_nop 0
	v_pk_mul_f32 v[84:85], v[50:51], v[0:1] op_sel_hi:[1,0]
	s_nop 0
	v_pk_fma_f32 v[50:51], v[50:51], v[0:1], v[84:85] op_sel:[1,1,0] op_sel_hi:[0,1,1] neg_lo:[0,1,0]
	s_nop 1
	v_mov_b32_dpp v84, v50 quad_perm:[2,3,0,1] row_mask:0xf bank_mask:0xf bound_ctrl:1
	v_mov_b32_dpp v85, v51 quad_perm:[2,3,0,1] row_mask:0xf bank_mask:0xf bound_ctrl:1
	v_pk_fma_f32 v[50:51], v[6:7], v[50:51], v[84:85] op_sel_hi:[0,1,1]
	v_pk_mul_f32 v[84:85], v[50:51], v[2:3] op_sel_hi:[1,0]
	s_nop 0
	v_pk_fma_f32 v[50:51], v[50:51], v[2:3], v[84:85] op_sel:[1,1,0] op_sel_hi:[0,1,1] neg_lo:[0,1,0]
	s_nop 1
	v_mov_b32_dpp v84, v50 quad_perm:[1,0,3,2] row_mask:0xf bank_mask:0xf bound_ctrl:1
	v_mov_b32_dpp v85, v51 quad_perm:[1,0,3,2] row_mask:0xf bank_mask:0xf bound_ctrl:1
	v_pk_fma_f32 v[50:51], v[8:9], v[50:51], v[84:85] op_sel_hi:[0,1,1]
	v_mov_b32_dpp v84, v52 row_ror:8 row_mask:0xf bank_mask:0xf bound_ctrl:1
	v_mov_b32_dpp v85, v53 row_ror:8 row_mask:0xf bank_mask:0xf bound_ctrl:1
	v_pk_fma_f32 v[52:53], v[4:5], v[52:53], v[84:85] op_sel_hi:[0,1,1]
	v_pk_mul_f32 v[84:85], v[52:53], v[10:11] op_sel_hi:[1,0]
	s_nop 0
	v_pk_fma_f32 v[52:53], v[52:53], v[10:11], v[84:85] op_sel:[1,1,0] op_sel_hi:[0,1,1] neg_lo:[0,1,0]
	ds_swizzle_b32 v84, v52 offset:swizzle(SWAP,4)
	ds_swizzle_b32 v85, v53 offset:swizzle(SWAP,4)
	s_waitcnt lgkmcnt(0)
; __device__ __forceinline__ float lx1(float v) { return __int_as_float(__builtin_amdgcn_update_dpp(0, __float_as_int(v), 0xB1, 0xF, 0xF, true)); }
; __device__ __forceinline__ float lx2(float v) { return __int_as_float(__builtin_amdgcn_update_dpp(0, __float_as_int(v), 0x4E, 0xF, 0xF, true)); }
; __device__ __forceinline__ float lx4(float v) { return __int_as_float(__builtin_amdgcn_ds_swizzle(__float_as_int(v), 0x101F)); }
; __device__ __forceinline__ float lx8(float v) { return __int_as_float(__builtin_amdgcn_update_dpp(0, __float_as_int(v), 0x128, 0xF, 0xF, true)); }
; __device__ __forceinline__ void fft_forward(f2 (&x)[32], LAS f2* X, int t, LAS const float* W1, LAS const M2C* MC) {
;     ...
; #pragma unroll
;     for (int p = 0; p < 32; ++p) {
;         f2 v = x[p], pr;
;         pr = (f2){lx8(v.x), lx8(v.y)}; v = cmulr(pr + v * c.s8, t8);
;         pr = (f2){lx4(v.x), lx4(v.y)}; v = cmulr(pr + v * c.s4, t4);
;         pr = (f2){lx2(v.x), lx2(v.y)}; v = cmulr(pr + v * c.s2, t2);
;         pr = (f2){lx1(v.x), lx1(v.y)}; x[p] = pr + v * c.s1;
;     }
	v_pk_fma_f32 v[52:53], v[4:5], v[52:53], v[84:85] op_sel:[1,0,0]
	s_nop 0
	v_pk_mul_f32 v[84:85], v[52:53], v[0:1] op_sel_hi:[1,0]
	s_nop 0
	v_pk_fma_f32 v[52:53], v[52:53], v[0:1], v[84:85] op_sel:[1,1,0] op_sel_hi:[0,1,1] neg_lo:[0,1,0]
	s_nop 1
	v_mov_b32_dpp v84, v52 quad_perm:[2,3,0,1] row_mask:0xf bank_mask:0xf bound_ctrl:1
	v_mov_b32_dpp v85, v53 quad_perm:[2,3,0,1] row_mask:0xf bank_mask:0xf bound_ctrl:1
	v_pk_fma_f32 v[52:53], v[6:7], v[52:53], v[84:85] op_sel_hi:[0,1,1]
	v_pk_mul_f32 v[84:85], v[52:53], v[2:3] op_sel_hi:[1,0]
	s_nop 0
	v_pk_fma_f32 v[52:53], v[52:53], v[2:3], v[84:85] op_sel:[1,1,0] op_sel_hi:[0,1,1] neg_lo:[0,1,0]
	s_nop 1
	v_mov_b32_dpp v84, v52 quad_perm:[1,0,3,2] row_mask:0xf bank_mask:0xf bound_ctrl:1
	v_mov_b32_dpp v85, v53 quad_perm:[1,0,3,2] row_mask:0xf bank_mask:0xf bound_ctrl:1
	v_pk_fma_f32 v[52:53], v[8:9], v[52:53], v[84:85] op_sel_hi:[0,1,1]
	v_mov_b32_dpp v84, v54 row_ror:8 row_mask:0xf bank_mask:0xf bound_ctrl:1
	v_mov_b32_dpp v85, v55 row_ror:8 row_mask:0xf bank_mask:0xf bound_ctrl:1
	v_pk_fma_f32 v[54:55], v[4:5], v[54:55], v[84:85] op_sel_hi:[0,1,1]
	v_pk_mul_f32 v[84:85], v[54:55], v[10:11] op_sel_hi:[1,0]
	s_nop 0
	v_pk_fma_f32 v[54:55], v[54:55], v[10:11], v[84:85] op_sel:[1,1,0] op_sel_hi:[0,1,1] neg_lo:[0,1,0]
	ds_swizzle_b32 v84, v54 offset:swizzle(SWAP,4)
	ds_swizzle_b32 v85, v55 offset:swizzle(SWAP,4)
	s_waitcnt lgkmcnt(0)
	v_pk_fma_f32 v[54:55], v[4:5], v[54:55], v[84:85] op_sel:[1,0,0]
	s_nop 0
	v_pk_mul_f32 v[84:85], v[54:55], v[0:1] op_sel_hi:[1,0]
	s_nop 0
	v_pk_fma_f32 v[54:55], v[54:55], v[0:1], v[84:85] op_sel:[1,1,0] op_sel_hi:[0,1,1] neg_lo:[0,1,0]
	s_nop 1
	v_mov_b32_dpp v84, v54 quad_perm:[2,3,0,1] row_mask:0xf bank_mask:0xf bound_ctrl:1
	v_mov_b32_dpp v85, v55 quad_perm:[2,3,0,1] row_mask:0xf bank_mask:0xf bound_ctrl:1
	v_pk_fma_f32 v[54:55], v[6:7], v[54:55], v[84:85] op_sel_hi:[0,1,1]
	v_pk_mul_f32 v[84:85], v[54:55], v[2:3] op_sel_hi:[1,0]
	s_nop 0
	v_pk_fma_f32 v[54:55], v[54:55], v[2:3], v[84:85] op_sel:[1,1,0] op_sel_hi:[0,1,1] neg_lo:[0,1,0]
	s_nop 1
	v_mov_b32_dpp v84, v54 quad_perm:[1,0,3,2] row_mask:0xf bank_mask:0xf bound_ctrl:1
	v_mov_b32_dpp v85, v55 quad_perm:[1,0,3,2] row_mask:0xf bank_mask:0xf bound_ctrl:1
	v_pk_fma_f32 v[54:55], v[8:9], v[54:55], v[84:85] op_sel_hi:[0,1,1]
	v_mov_b32_dpp v84, v56 row_ror:8 row_mask:0xf bank_mask:0xf bound_ctrl:1
	v_mov_b32_dpp v85, v57 row_ror:8 row_mask:0xf bank_mask:0xf bound_ctrl:1
	v_pk_fma_f32 v[56:57], v[4:5], v[56:57], v[84:85] op_sel_hi:[0,1,1]
	v_pk_mul_f32 v[84:85], v[56:57], v[10:11] op_sel_hi:[1,0]
	s_nop 0
	v_pk_fma_f32 v[56:57], v[56:57], v[10:11], v[84:85] op_sel:[1,1,0] op_sel_hi:[0,1,1] neg_lo:[0,1,0]
	ds_swizzle_b32 v84, v56 offset:swizzle(SWAP,4)
	ds_swizzle_b32 v85, v57 offset:swizzle(SWAP,4)
	s_waitcnt lgkmcnt(0)
	v_pk_fma_f32 v[56:57], v[4:5], v[56:57], v[84:85] op_sel:[1,0,0]
	s_nop 0
	v_pk_mul_f32 v[84:85], v[56:57], v[0:1] op_sel_hi:[1,0]
	s_nop 0
	v_pk_fma_f32 v[56:57], v[56:57], v[0:1], v[84:85] op_sel:[1,1,0] op_sel_hi:[0,1,1] neg_lo:[0,1,0]
	s_nop 1
	v_mov_b32_dpp v84, v56 quad_perm:[2,3,0,1] row_mask:0xf bank_mask:0xf bound_ctrl:1
	v_mov_b32_dpp v85, v57 quad_perm:[2,3,0,1] row_mask:0xf bank_mask:0xf bound_ctrl:1
	v_pk_fma_f32 v[56:57], v[6:7], v[56:57], v[84:85] op_sel_hi:[0,1,1]
	v_pk_mul_f32 v[84:85], v[56:57], v[2:3] op_sel_hi:[1,0]
	s_nop 0
	v_pk_fma_f32 v[56:57], v[56:57], v[2:3], v[84:85] op_sel:[1,1,0] op_sel_hi:[0,1,1] neg_lo:[0,1,0]
	s_nop 1
	v_mov_b32_dpp v84, v56 quad_perm:[1,0,3,2] row_mask:0xf bank_mask:0xf bound_ctrl:1
	v_mov_b32_dpp v85, v57 quad_perm:[1,0,3,2] row_mask:0xf bank_mask:0xf bound_ctrl:1
	v_pk_fma_f32 v[56:57], v[8:9], v[56:57], v[84:85] op_sel_hi:[0,1,1]
	v_mov_b32_dpp v84, v58 row_ror:8 row_mask:0xf bank_mask:0xf bound_ctrl:1
	v_mov_b32_dpp v85, v59 row_ror:8 row_mask:0xf bank_mask:0xf bound_ctrl:1
	v_pk_fma_f32 v[58:59], v[4:5], v[58:59], v[84:85] op_sel_hi:[0,1,1]
	v_pk_mul_f32 v[84:85], v[58:59], v[10:11] op_sel_hi:[1,0]
	s_nop 0
	v_pk_fma_f32 v[58:59], v[58:59], v[10:11], v[84:85] op_sel:[1,1,0] op_sel_hi:[0,1,1] neg_lo:[0,1,0]
	ds_swizzle_b32 v84, v58 offset:swizzle(SWAP,4)
	ds_swizzle_b32 v85, v59 offset:swizzle(SWAP,4)
	s_waitcnt lgkmcnt(0)
	v_pk_fma_f32 v[58:59], v[4:5], v[58:59], v[84:85] op_sel:[1,0,0]
	s_nop 0
	v_pk_mul_f32 v[84:85], v[58:59], v[0:1] op_sel_hi:[1,0]
	s_nop 0
	v_pk_fma_f32 v[58:59], v[58:59], v[0:1], v[84:85] op_sel:[1,1,0] op_sel_hi:[0,1,1] neg_lo:[0,1,0]
	s_nop 1
	v_mov_b32_dpp v84, v58 quad_perm:[2,3,0,1] row_mask:0xf bank_mask:0xf bound_ctrl:1
	v_mov_b32_dpp v85, v59 quad_perm:[2,3,0,1] row_mask:0xf bank_mask:0xf bound_ctrl:1
	v_pk_fma_f32 v[58:59], v[6:7], v[58:59], v[84:85] op_sel_hi:[0,1,1]
	v_pk_mul_f32 v[84:85], v[58:59], v[2:3] op_sel_hi:[1,0]
	s_nop 0
	v_pk_fma_f32 v[58:59], v[58:59], v[2:3], v[84:85] op_sel:[1,1,0] op_sel_hi:[0,1,1] neg_lo:[0,1,0]
	s_nop 1
	v_mov_b32_dpp v84, v58 quad_perm:[1,0,3,2] row_mask:0xf bank_mask:0xf bound_ctrl:1
	v_mov_b32_dpp v85, v59 quad_perm:[1,0,3,2] row_mask:0xf bank_mask:0xf bound_ctrl:1
	v_pk_fma_f32 v[58:59], v[8:9], v[58:59], v[84:85] op_sel_hi:[0,1,1]
	v_mov_b32_dpp v84, v60 row_ror:8 row_mask:0xf bank_mask:0xf bound_ctrl:1
	v_mov_b32_dpp v85, v61 row_ror:8 row_mask:0xf bank_mask:0xf bound_ctrl:1
	v_pk_fma_f32 v[60:61], v[4:5], v[60:61], v[84:85] op_sel_hi:[0,1,1]
	v_pk_mul_f32 v[84:85], v[60:61], v[10:11] op_sel_hi:[1,0]
	s_nop 0
	v_pk_fma_f32 v[60:61], v[60:61], v[10:11], v[84:85] op_sel:[1,1,0] op_sel_hi:[0,1,1] neg_lo:[0,1,0]
	ds_swizzle_b32 v84, v60 offset:swizzle(SWAP,4)
	ds_swizzle_b32 v85, v61 offset:swizzle(SWAP,4)
	s_waitcnt lgkmcnt(0)
; __device__ __forceinline__ float lx1(float v) { return __int_as_float(__builtin_amdgcn_update_dpp(0, __float_as_int(v), 0xB1, 0xF, 0xF, true)); }
; __device__ __forceinline__ float lx2(float v) { return __int_as_float(__builtin_amdgcn_update_dpp(0, __float_as_int(v), 0x4E, 0xF, 0xF, true)); }
; __device__ __forceinline__ float lx4(float v) { return __int_as_float(__builtin_amdgcn_ds_swizzle(__float_as_int(v), 0x101F)); }
; __device__ __forceinline__ float lx8(float v) { return __int_as_float(__builtin_amdgcn_update_dpp(0, __float_as_int(v), 0x128, 0xF, 0xF, true)); }
; __device__ __forceinline__ void fft_forward(f2 (&x)[32], LAS f2* X, int t, LAS const float* W1, LAS const M2C* MC) {
;     ...
; #pragma unroll
;     for (int p = 0; p < 32; ++p) {
;         f2 v = x[p], pr;
;         pr = (f2){lx8(v.x), lx8(v.y)}; v = cmulr(pr + v * c.s8, t8);
;         pr = (f2){lx4(v.x), lx4(v.y)}; v = cmulr(pr + v * c.s4, t4);
;         pr = (f2){lx2(v.x), lx2(v.y)}; v = cmulr(pr + v * c.s2, t2);
;         pr = (f2){lx1(v.x), lx1(v.y)}; x[p] = pr + v * c.s1;
;     }
	v_pk_fma_f32 v[60:61], v[4:5], v[60:61], v[84:85] op_sel:[1,0,0]
	s_nop 0
	v_pk_mul_f32 v[84:85], v[60:61], v[0:1] op_sel_hi:[1,0]
	s_nop 0
	v_pk_fma_f32 v[60:61], v[60:61], v[0:1], v[84:85] op_sel:[1,1,0] op_sel_hi:[0,1,1] neg_lo:[0,1,0]
	s_nop 1
	v_mov_b32_dpp v84, v60 quad_perm:[2,3,0,1] row_mask:0xf bank_mask:0xf bound_ctrl:1
	v_mov_b32_dpp v85, v61 quad_perm:[2,3,0,1] row_mask:0xf bank_mask:0xf bound_ctrl:1
	v_pk_fma_f32 v[60:61], v[6:7], v[60:61], v[84:85] op_sel_hi:[0,1,1]
	v_pk_mul_f32 v[84:85], v[60:61], v[2:3] op_sel_hi:[1,0]
	s_nop 0
	v_pk_fma_f32 v[60:61], v[60:61], v[2:3], v[84:85] op_sel:[1,1,0] op_sel_hi:[0,1,1] neg_lo:[0,1,0]
	s_nop 1
	v_mov_b32_dpp v84, v60 quad_perm:[1,0,3,2] row_mask:0xf bank_mask:0xf bound_ctrl:1
	v_mov_b32_dpp v85, v61 quad_perm:[1,0,3,2] row_mask:0xf bank_mask:0xf bound_ctrl:1
	v_pk_fma_f32 v[60:61], v[8:9], v[60:61], v[84:85] op_sel_hi:[0,1,1]
	v_mov_b32_dpp v84, v62 row_ror:8 row_mask:0xf bank_mask:0xf bound_ctrl:1
	v_mov_b32_dpp v85, v63 row_ror:8 row_mask:0xf bank_mask:0xf bound_ctrl:1
	v_pk_fma_f32 v[62:63], v[4:5], v[62:63], v[84:85] op_sel_hi:[0,1,1]
	v_pk_mul_f32 v[84:85], v[62:63], v[10:11] op_sel_hi:[1,0]
	s_nop 0
	v_pk_fma_f32 v[62:63], v[62:63], v[10:11], v[84:85] op_sel:[1,1,0] op_sel_hi:[0,1,1] neg_lo:[0,1,0]
	ds_swizzle_b32 v84, v62 offset:swizzle(SWAP,4)
	ds_swizzle_b32 v85, v63 offset:swizzle(SWAP,4)
	s_waitcnt lgkmcnt(0)
	v_pk_fma_f32 v[62:63], v[4:5], v[62:63], v[84:85] op_sel:[1,0,0]
	s_nop 0
	v_pk_mul_f32 v[84:85], v[62:63], v[0:1] op_sel_hi:[1,0]
	s_nop 0
	v_pk_fma_f32 v[62:63], v[62:63], v[0:1], v[84:85] op_sel:[1,1,0] op_sel_hi:[0,1,1] neg_lo:[0,1,0]
	s_nop 1
	v_mov_b32_dpp v84, v62 quad_perm:[2,3,0,1] row_mask:0xf bank_mask:0xf bound_ctrl:1
	v_mov_b32_dpp v85, v63 quad_perm:[2,3,0,1] row_mask:0xf bank_mask:0xf bound_ctrl:1
	v_pk_fma_f32 v[62:63], v[6:7], v[62:63], v[84:85] op_sel_hi:[0,1,1]
	v_pk_mul_f32 v[84:85], v[62:63], v[2:3] op_sel_hi:[1,0]
	s_nop 0
	v_pk_fma_f32 v[62:63], v[62:63], v[2:3], v[84:85] op_sel:[1,1,0] op_sel_hi:[0,1,1] neg_lo:[0,1,0]
	s_nop 1
	v_mov_b32_dpp v84, v62 quad_perm:[1,0,3,2] row_mask:0xf bank_mask:0xf bound_ctrl:1
	v_mov_b32_dpp v85, v63 quad_perm:[1,0,3,2] row_mask:0xf bank_mask:0xf bound_ctrl:1
	v_pk_fma_f32 v[62:63], v[8:9], v[62:63], v[84:85] op_sel_hi:[0,1,1]
	v_mov_b32_dpp v84, v64 row_ror:8 row_mask:0xf bank_mask:0xf bound_ctrl:1
	v_mov_b32_dpp v85, v65 row_ror:8 row_mask:0xf bank_mask:0xf bound_ctrl:1
	v_pk_fma_f32 v[64:65], v[4:5], v[64:65], v[84:85] op_sel_hi:[0,1,1]
	v_pk_mul_f32 v[84:85], v[64:65], v[10:11] op_sel_hi:[1,0]
	s_nop 0
	v_pk_fma_f32 v[64:65], v[64:65], v[10:11], v[84:85] op_sel:[1,1,0] op_sel_hi:[0,1,1] neg_lo:[0,1,0]
	ds_swizzle_b32 v84, v64 offset:swizzle(SWAP,4)
	ds_swizzle_b32 v85, v65 offset:swizzle(SWAP,4)
	s_waitcnt lgkmcnt(0)
	v_pk_fma_f32 v[64:65], v[4:5], v[64:65], v[84:85] op_sel:[1,0,0]
	s_nop 0
	v_pk_mul_f32 v[84:85], v[64:65], v[0:1] op_sel_hi:[1,0]
	s_nop 0
	v_pk_fma_f32 v[64:65], v[64:65], v[0:1], v[84:85] op_sel:[1,1,0] op_sel_hi:[0,1,1] neg_lo:[0,1,0]
	s_nop 1
	v_mov_b32_dpp v84, v64 quad_perm:[2,3,0,1] row_mask:0xf bank_mask:0xf bound_ctrl:1
	v_mov_b32_dpp v85, v65 quad_perm:[2,3,0,1] row_mask:0xf bank_mask:0xf bound_ctrl:1
	v_pk_fma_f32 v[64:65], v[6:7], v[64:65], v[84:85] op_sel_hi:[0,1,1]
	v_pk_mul_f32 v[84:85], v[64:65], v[2:3] op_sel_hi:[1,0]
	s_nop 0
	v_pk_fma_f32 v[64:65], v[64:65], v[2:3], v[84:85] op_sel:[1,1,0] op_sel_hi:[0,1,1] neg_lo:[0,1,0]
	s_nop 1
	v_mov_b32_dpp v84, v64 quad_perm:[1,0,3,2] row_mask:0xf bank_mask:0xf bound_ctrl:1
	v_mov_b32_dpp v85, v65 quad_perm:[1,0,3,2] row_mask:0xf bank_mask:0xf bound_ctrl:1
	v_pk_fma_f32 v[64:65], v[8:9], v[64:65], v[84:85] op_sel_hi:[0,1,1]
	v_mov_b32_dpp v84, v66 row_ror:8 row_mask:0xf bank_mask:0xf bound_ctrl:1
	v_mov_b32_dpp v85, v67 row_ror:8 row_mask:0xf bank_mask:0xf bound_ctrl:1
	v_pk_fma_f32 v[66:67], v[4:5], v[66:67], v[84:85] op_sel_hi:[0,1,1]
	v_pk_mul_f32 v[84:85], v[66:67], v[10:11] op_sel_hi:[1,0]
	s_nop 0
	v_pk_fma_f32 v[66:67], v[66:67], v[10:11], v[84:85] op_sel:[1,1,0] op_sel_hi:[0,1,1] neg_lo:[0,1,0]
	ds_swizzle_b32 v84, v66 offset:swizzle(SWAP,4)
	ds_swizzle_b32 v85, v67 offset:swizzle(SWAP,4)
	s_waitcnt lgkmcnt(0)
	v_pk_fma_f32 v[66:67], v[4:5], v[66:67], v[84:85] op_sel:[1,0,0]
	s_nop 0
	v_pk_mul_f32 v[84:85], v[66:67], v[0:1] op_sel_hi:[1,0]
	s_nop 0
	v_pk_fma_f32 v[66:67], v[66:67], v[0:1], v[84:85] op_sel:[1,1,0] op_sel_hi:[0,1,1] neg_lo:[0,1,0]
	s_nop 1
	v_mov_b32_dpp v84, v66 quad_perm:[2,3,0,1] row_mask:0xf bank_mask:0xf bound_ctrl:1
	v_mov_b32_dpp v85, v67 quad_perm:[2,3,0,1] row_mask:0xf bank_mask:0xf bound_ctrl:1
	v_pk_fma_f32 v[66:67], v[6:7], v[66:67], v[84:85] op_sel_hi:[0,1,1]
	v_pk_mul_f32 v[84:85], v[66:67], v[2:3] op_sel_hi:[1,0]
	s_nop 0
	v_pk_fma_f32 v[66:67], v[66:67], v[2:3], v[84:85] op_sel:[1,1,0] op_sel_hi:[0,1,1] neg_lo:[0,1,0]
	s_nop 1
	v_mov_b32_dpp v84, v66 quad_perm:[1,0,3,2] row_mask:0xf bank_mask:0xf bound_ctrl:1
	v_mov_b32_dpp v85, v67 quad_perm:[1,0,3,2] row_mask:0xf bank_mask:0xf bound_ctrl:1
	v_pk_fma_f32 v[66:67], v[8:9], v[66:67], v[84:85] op_sel_hi:[0,1,1]
	v_mov_b32_dpp v84, v68 row_ror:8 row_mask:0xf bank_mask:0xf bound_ctrl:1
	v_mov_b32_dpp v85, v69 row_ror:8 row_mask:0xf bank_mask:0xf bound_ctrl:1
	v_pk_fma_f32 v[68:69], v[4:5], v[68:69], v[84:85] op_sel_hi:[0,1,1]
	v_pk_mul_f32 v[84:85], v[68:69], v[10:11] op_sel_hi:[1,0]
	s_nop 0
	v_pk_fma_f32 v[68:69], v[68:69], v[10:11], v[84:85] op_sel:[1,1,0] op_sel_hi:[0,1,1] neg_lo:[0,1,0]
	ds_swizzle_b32 v84, v68 offset:swizzle(SWAP,4)
	ds_swizzle_b32 v85, v69 offset:swizzle(SWAP,4)
	s_waitcnt lgkmcnt(0)
; __device__ __forceinline__ float lx1(float v) { return __int_as_float(__builtin_amdgcn_update_dpp(0, __float_as_int(v), 0xB1, 0xF, 0xF, true)); }
; __device__ __forceinline__ float lx2(float v) { return __int_as_float(__builtin_amdgcn_update_dpp(0, __float_as_int(v), 0x4E, 0xF, 0xF, true)); }
; __device__ __forceinline__ float lx4(float v) { return __int_as_float(__builtin_amdgcn_ds_swizzle(__float_as_int(v), 0x101F)); }
; __device__ __forceinline__ float lx8(float v) { return __int_as_float(__builtin_amdgcn_update_dpp(0, __float_as_int(v), 0x128, 0xF, 0xF, true)); }
; __device__ __forceinline__ void fft_forward(f2 (&x)[32], LAS f2* X, int t, LAS const float* W1, LAS const M2C* MC) {
;     ...
; #pragma unroll
;     for (int p = 0; p < 32; ++p) {
;         f2 v = x[p], pr;
;         pr = (f2){lx8(v.x), lx8(v.y)}; v = cmulr(pr + v * c.s8, t8);
;         pr = (f2){lx4(v.x), lx4(v.y)}; v = cmulr(pr + v * c.s4, t4);
;         pr = (f2){lx2(v.x), lx2(v.y)}; v = cmulr(pr + v * c.s2, t2);
;         pr = (f2){lx1(v.x), lx1(v.y)}; x[p] = pr + v * c.s1;
;     }
	v_pk_fma_f32 v[68:69], v[4:5], v[68:69], v[84:85] op_sel:[1,0,0]
	s_nop 0
	v_pk_mul_f32 v[84:85], v[68:69], v[0:1] op_sel_hi:[1,0]
	s_nop 0
	v_pk_fma_f32 v[68:69], v[68:69], v[0:1], v[84:85] op_sel:[1,1,0] op_sel_hi:[0,1,1] neg_lo:[0,1,0]
	s_nop 1
	v_mov_b32_dpp v84, v68 quad_perm:[2,3,0,1] row_mask:0xf bank_mask:0xf bound_ctrl:1
	v_mov_b32_dpp v85, v69 quad_perm:[2,3,0,1] row_mask:0xf bank_mask:0xf bound_ctrl:1
	v_pk_fma_f32 v[68:69], v[6:7], v[68:69], v[84:85] op_sel_hi:[0,1,1]
	v_pk_mul_f32 v[84:85], v[68:69], v[2:3] op_sel_hi:[1,0]
	s_nop 0
	v_pk_fma_f32 v[68:69], v[68:69], v[2:3], v[84:85] op_sel:[1,1,0] op_sel_hi:[0,1,1] neg_lo:[0,1,0]
	s_nop 1
	v_mov_b32_dpp v84, v68 quad_perm:[1,0,3,2] row_mask:0xf bank_mask:0xf bound_ctrl:1
	v_mov_b32_dpp v85, v69 quad_perm:[1,0,3,2] row_mask:0xf bank_mask:0xf bound_ctrl:1
	v_pk_fma_f32 v[68:69], v[8:9], v[68:69], v[84:85] op_sel_hi:[0,1,1]
	v_mov_b32_dpp v84, v70 row_ror:8 row_mask:0xf bank_mask:0xf bound_ctrl:1
	v_mov_b32_dpp v85, v71 row_ror:8 row_mask:0xf bank_mask:0xf bound_ctrl:1
	v_pk_fma_f32 v[70:71], v[4:5], v[70:71], v[84:85] op_sel_hi:[0,1,1]
	v_pk_mul_f32 v[84:85], v[70:71], v[10:11] op_sel_hi:[1,0]
	s_nop 0
	v_pk_fma_f32 v[70:71], v[70:71], v[10:11], v[84:85] op_sel:[1,1,0] op_sel_hi:[0,1,1] neg_lo:[0,1,0]
	ds_swizzle_b32 v84, v70 offset:swizzle(SWAP,4)
	ds_swizzle_b32 v85, v71 offset:swizzle(SWAP,4)
	s_waitcnt lgkmcnt(0)
	v_pk_fma_f32 v[70:71], v[4:5], v[70:71], v[84:85] op_sel:[1,0,0]
	s_nop 0
	v_pk_mul_f32 v[84:85], v[70:71], v[0:1] op_sel_hi:[1,0]
	s_nop 0
	v_pk_fma_f32 v[70:71], v[70:71], v[0:1], v[84:85] op_sel:[1,1,0] op_sel_hi:[0,1,1] neg_lo:[0,1,0]
	s_nop 1
	v_mov_b32_dpp v84, v70 quad_perm:[2,3,0,1] row_mask:0xf bank_mask:0xf bound_ctrl:1
	v_mov_b32_dpp v85, v71 quad_perm:[2,3,0,1] row_mask:0xf bank_mask:0xf bound_ctrl:1
	v_pk_fma_f32 v[70:71], v[6:7], v[70:71], v[84:85] op_sel_hi:[0,1,1]
	v_pk_mul_f32 v[84:85], v[70:71], v[2:3] op_sel_hi:[1,0]
	s_nop 0
	v_pk_fma_f32 v[70:71], v[70:71], v[2:3], v[84:85] op_sel:[1,1,0] op_sel_hi:[0,1,1] neg_lo:[0,1,0]
	s_nop 1
	v_mov_b32_dpp v84, v70 quad_perm:[1,0,3,2] row_mask:0xf bank_mask:0xf bound_ctrl:1
	v_mov_b32_dpp v85, v71 quad_perm:[1,0,3,2] row_mask:0xf bank_mask:0xf bound_ctrl:1
	v_pk_fma_f32 v[70:71], v[8:9], v[70:71], v[84:85] op_sel_hi:[0,1,1]
	v_mov_b32_dpp v84, v72 row_ror:8 row_mask:0xf bank_mask:0xf bound_ctrl:1
	v_mov_b32_dpp v85, v73 row_ror:8 row_mask:0xf bank_mask:0xf bound_ctrl:1
	v_pk_fma_f32 v[72:73], v[4:5], v[72:73], v[84:85] op_sel_hi:[0,1,1]
	v_pk_mul_f32 v[84:85], v[72:73], v[10:11] op_sel_hi:[1,0]
	s_nop 0
	v_pk_fma_f32 v[72:73], v[72:73], v[10:11], v[84:85] op_sel:[1,1,0] op_sel_hi:[0,1,1] neg_lo:[0,1,0]
	ds_swizzle_b32 v84, v72 offset:swizzle(SWAP,4)
	ds_swizzle_b32 v85, v73 offset:swizzle(SWAP,4)
	s_waitcnt lgkmcnt(0)
	v_pk_fma_f32 v[72:73], v[4:5], v[72:73], v[84:85] op_sel:[1,0,0]
	s_nop 0
	v_pk_mul_f32 v[84:85], v[72:73], v[0:1] op_sel_hi:[1,0]
	s_nop 0
	v_pk_fma_f32 v[72:73], v[72:73], v[0:1], v[84:85] op_sel:[1,1,0] op_sel_hi:[0,1,1] neg_lo:[0,1,0]
	s_nop 1
	v_mov_b32_dpp v84, v72 quad_perm:[2,3,0,1] row_mask:0xf bank_mask:0xf bound_ctrl:1
	v_mov_b32_dpp v85, v73 quad_perm:[2,3,0,1] row_mask:0xf bank_mask:0xf bound_ctrl:1
	v_pk_fma_f32 v[72:73], v[6:7], v[72:73], v[84:85] op_sel_hi:[0,1,1]
	v_pk_mul_f32 v[84:85], v[72:73], v[2:3] op_sel_hi:[1,0]
	s_nop 0
	v_pk_fma_f32 v[72:73], v[72:73], v[2:3], v[84:85] op_sel:[1,1,0] op_sel_hi:[0,1,1] neg_lo:[0,1,0]
	s_nop 1
	v_mov_b32_dpp v84, v72 quad_perm:[1,0,3,2] row_mask:0xf bank_mask:0xf bound_ctrl:1
	v_mov_b32_dpp v85, v73 quad_perm:[1,0,3,2] row_mask:0xf bank_mask:0xf bound_ctrl:1
	v_pk_fma_f32 v[72:73], v[8:9], v[72:73], v[84:85] op_sel_hi:[0,1,1]
	v_mov_b32_dpp v84, v74 row_ror:8 row_mask:0xf bank_mask:0xf bound_ctrl:1
	v_mov_b32_dpp v85, v75 row_ror:8 row_mask:0xf bank_mask:0xf bound_ctrl:1
	v_pk_fma_f32 v[74:75], v[4:5], v[74:75], v[84:85] op_sel_hi:[0,1,1]
	v_pk_mul_f32 v[84:85], v[74:75], v[10:11] op_sel_hi:[1,0]
	s_nop 0
	v_pk_fma_f32 v[74:75], v[74:75], v[10:11], v[84:85] op_sel:[1,1,0] op_sel_hi:[0,1,1] neg_lo:[0,1,0]
	ds_swizzle_b32 v84, v74 offset:swizzle(SWAP,4)
	ds_swizzle_b32 v85, v75 offset:swizzle(SWAP,4)
	s_waitcnt lgkmcnt(0)
	v_pk_fma_f32 v[74:75], v[4:5], v[74:75], v[84:85] op_sel:[1,0,0]
	s_nop 0
	v_pk_mul_f32 v[84:85], v[74:75], v[0:1] op_sel_hi:[1,0]
	s_nop 0
	v_pk_fma_f32 v[74:75], v[74:75], v[0:1], v[84:85] op_sel:[1,1,0] op_sel_hi:[0,1,1] neg_lo:[0,1,0]
	s_nop 1
	v_mov_b32_dpp v84, v74 quad_perm:[2,3,0,1] row_mask:0xf bank_mask:0xf bound_ctrl:1
	v_mov_b32_dpp v85, v75 quad_perm:[2,3,0,1] row_mask:0xf bank_mask:0xf bound_ctrl:1
	v_pk_fma_f32 v[74:75], v[6:7], v[74:75], v[84:85] op_sel_hi:[0,1,1]
	v_pk_mul_f32 v[84:85], v[74:75], v[2:3] op_sel_hi:[1,0]
	s_nop 0
	v_pk_fma_f32 v[74:75], v[74:75], v[2:3], v[84:85] op_sel:[1,1,0] op_sel_hi:[0,1,1] neg_lo:[0,1,0]
	s_nop 1
	v_mov_b32_dpp v84, v74 quad_perm:[1,0,3,2] row_mask:0xf bank_mask:0xf bound_ctrl:1
	v_mov_b32_dpp v85, v75 quad_perm:[1,0,3,2] row_mask:0xf bank_mask:0xf bound_ctrl:1
	v_pk_fma_f32 v[74:75], v[8:9], v[74:75], v[84:85] op_sel_hi:[0,1,1]
	v_mov_b32_dpp v84, v76 row_ror:8 row_mask:0xf bank_mask:0xf bound_ctrl:1
	v_mov_b32_dpp v85, v77 row_ror:8 row_mask:0xf bank_mask:0xf bound_ctrl:1
	v_pk_fma_f32 v[76:77], v[4:5], v[76:77], v[84:85] op_sel_hi:[0,1,1]
	v_pk_mul_f32 v[84:85], v[76:77], v[10:11] op_sel_hi:[1,0]
	s_nop 0
	v_pk_fma_f32 v[76:77], v[76:77], v[10:11], v[84:85] op_sel:[1,1,0] op_sel_hi:[0,1,1] neg_lo:[0,1,0]
	ds_swizzle_b32 v84, v76 offset:swizzle(SWAP,4)
	ds_swizzle_b32 v85, v77 offset:swizzle(SWAP,4)
	s_waitcnt lgkmcnt(0)
; __device__ __forceinline__ float lx1(float v) { return __int_as_float(__builtin_amdgcn_update_dpp(0, __float_as_int(v), 0xB1, 0xF, 0xF, true)); }
; __device__ __forceinline__ float lx2(float v) { return __int_as_float(__builtin_amdgcn_update_dpp(0, __float_as_int(v), 0x4E, 0xF, 0xF, true)); }
; __device__ __forceinline__ float lx4(float v) { return __int_as_float(__builtin_amdgcn_ds_swizzle(__float_as_int(v), 0x101F)); }
; __device__ __forceinline__ float lx8(float v) { return __int_as_float(__builtin_amdgcn_update_dpp(0, __float_as_int(v), 0x128, 0xF, 0xF, true)); }
; __device__ __forceinline__ void fft_forward(f2 (&x)[32], LAS f2* X, int t, LAS const float* W1, LAS const M2C* MC) {
;     ...
; #pragma unroll
;     for (int p = 0; p < 32; ++p) {
;         f2 v = x[p], pr;
;         pr = (f2){lx8(v.x), lx8(v.y)}; v = cmulr(pr + v * c.s8, t8);
;         pr = (f2){lx4(v.x), lx4(v.y)}; v = cmulr(pr + v * c.s4, t4);
;         pr = (f2){lx2(v.x), lx2(v.y)}; v = cmulr(pr + v * c.s2, t2);
;         pr = (f2){lx1(v.x), lx1(v.y)}; x[p] = pr + v * c.s1;
;     }
; template <int VAR> __device__ __forceinline__ void hyena_conv_phase(const Frame& F, const bf16* ZT, const bf16* GT, const float* conv_w, const float* conv_b, const float* skip, float* gscr, float* zscr, bf16* UT) {
;     ...
;             if (job < 2) {
	v_pk_fma_f32 v[76:77], v[4:5], v[76:77], v[84:85] op_sel:[1,0,0]
	s_nop 0
	v_pk_mul_f32 v[84:85], v[76:77], v[0:1] op_sel_hi:[1,0]
	s_nop 0
	v_pk_fma_f32 v[76:77], v[76:77], v[0:1], v[84:85] op_sel:[1,1,0] op_sel_hi:[0,1,1] neg_lo:[0,1,0]
	s_nop 1
	v_mov_b32_dpp v84, v76 quad_perm:[2,3,0,1] row_mask:0xf bank_mask:0xf bound_ctrl:1
	v_mov_b32_dpp v85, v77 quad_perm:[2,3,0,1] row_mask:0xf bank_mask:0xf bound_ctrl:1
	v_pk_fma_f32 v[76:77], v[6:7], v[76:77], v[84:85] op_sel_hi:[0,1,1]
	v_pk_mul_f32 v[84:85], v[76:77], v[2:3] op_sel_hi:[1,0]
	s_nop 0
	v_pk_fma_f32 v[76:77], v[76:77], v[2:3], v[84:85] op_sel:[1,1,0] op_sel_hi:[0,1,1] neg_lo:[0,1,0]
	s_nop 1
	v_mov_b32_dpp v84, v76 quad_perm:[1,0,3,2] row_mask:0xf bank_mask:0xf bound_ctrl:1
	v_mov_b32_dpp v85, v77 quad_perm:[1,0,3,2] row_mask:0xf bank_mask:0xf bound_ctrl:1
	v_pk_fma_f32 v[76:77], v[8:9], v[76:77], v[84:85] op_sel_hi:[0,1,1]
	v_mov_b32_dpp v84, v78 row_ror:8 row_mask:0xf bank_mask:0xf bound_ctrl:1
	v_mov_b32_dpp v85, v79 row_ror:8 row_mask:0xf bank_mask:0xf bound_ctrl:1
	v_pk_fma_f32 v[78:79], v[4:5], v[78:79], v[84:85] op_sel_hi:[0,1,1]
	v_pk_mul_f32 v[84:85], v[78:79], v[10:11] op_sel_hi:[1,0]
	s_nop 0
	v_pk_fma_f32 v[78:79], v[78:79], v[10:11], v[84:85] op_sel:[1,1,0] op_sel_hi:[0,1,1] neg_lo:[0,1,0]
	ds_swizzle_b32 v84, v78 offset:swizzle(SWAP,4)
	ds_swizzle_b32 v85, v79 offset:swizzle(SWAP,4)
	s_waitcnt lgkmcnt(0)
	v_pk_fma_f32 v[78:79], v[4:5], v[78:79], v[84:85] op_sel:[1,0,0]
	s_nop 0
	v_pk_mul_f32 v[84:85], v[78:79], v[0:1] op_sel_hi:[1,0]
	s_nop 0
	v_pk_fma_f32 v[78:79], v[78:79], v[0:1], v[84:85] op_sel:[1,1,0] op_sel_hi:[0,1,1] neg_lo:[0,1,0]
	s_nop 1
	v_mov_b32_dpp v84, v78 quad_perm:[2,3,0,1] row_mask:0xf bank_mask:0xf bound_ctrl:1
	v_mov_b32_dpp v85, v79 quad_perm:[2,3,0,1] row_mask:0xf bank_mask:0xf bound_ctrl:1
	v_pk_fma_f32 v[78:79], v[6:7], v[78:79], v[84:85] op_sel_hi:[0,1,1]
	v_pk_mul_f32 v[84:85], v[78:79], v[2:3] op_sel_hi:[1,0]
	s_nop 0
	v_pk_fma_f32 v[78:79], v[78:79], v[2:3], v[84:85] op_sel:[1,1,0] op_sel_hi:[0,1,1] neg_lo:[0,1,0]
	s_nop 1
	v_mov_b32_dpp v84, v78 quad_perm:[1,0,3,2] row_mask:0xf bank_mask:0xf bound_ctrl:1
	v_mov_b32_dpp v85, v79 quad_perm:[1,0,3,2] row_mask:0xf bank_mask:0xf bound_ctrl:1
	v_pk_fma_f32 v[78:79], v[8:9], v[78:79], v[84:85] op_sel_hi:[0,1,1]
	v_mov_b32_dpp v84, v80 row_ror:8 row_mask:0xf bank_mask:0xf bound_ctrl:1
	v_mov_b32_dpp v85, v81 row_ror:8 row_mask:0xf bank_mask:0xf bound_ctrl:1
	v_pk_fma_f32 v[80:81], v[4:5], v[80:81], v[84:85] op_sel_hi:[0,1,1]
	v_pk_mul_f32 v[84:85], v[80:81], v[10:11] op_sel_hi:[1,0]
	s_nop 0
	v_pk_fma_f32 v[80:81], v[80:81], v[10:11], v[84:85] op_sel:[1,1,0] op_sel_hi:[0,1,1] neg_lo:[0,1,0]
	ds_swizzle_b32 v84, v80 offset:swizzle(SWAP,4)
	ds_swizzle_b32 v85, v81 offset:swizzle(SWAP,4)
	s_waitcnt lgkmcnt(0)
	v_pk_fma_f32 v[80:81], v[4:5], v[80:81], v[84:85] op_sel:[1,0,0]
	s_nop 0
	v_pk_mul_f32 v[84:85], v[80:81], v[0:1] op_sel_hi:[1,0]
	s_nop 0
	v_pk_fma_f32 v[80:81], v[80:81], v[0:1], v[84:85] op_sel:[1,1,0] op_sel_hi:[0,1,1] neg_lo:[0,1,0]
	s_nop 1
	v_mov_b32_dpp v84, v80 quad_perm:[2,3,0,1] row_mask:0xf bank_mask:0xf bound_ctrl:1
	v_mov_b32_dpp v85, v81 quad_perm:[2,3,0,1] row_mask:0xf bank_mask:0xf bound_ctrl:1
	v_pk_fma_f32 v[80:81], v[6:7], v[80:81], v[84:85] op_sel_hi:[0,1,1]
	v_pk_mul_f32 v[84:85], v[80:81], v[2:3] op_sel_hi:[1,0]
	s_nop 0
	v_pk_fma_f32 v[80:81], v[80:81], v[2:3], v[84:85] op_sel:[1,1,0] op_sel_hi:[0,1,1] neg_lo:[0,1,0]
	s_nop 1
	v_mov_b32_dpp v84, v80 quad_perm:[1,0,3,2] row_mask:0xf bank_mask:0xf bound_ctrl:1
	v_mov_b32_dpp v85, v81 quad_perm:[1,0,3,2] row_mask:0xf bank_mask:0xf bound_ctrl:1
	v_pk_fma_f32 v[80:81], v[8:9], v[80:81], v[84:85] op_sel_hi:[0,1,1]
	v_mov_b32_dpp v84, v82 row_ror:8 row_mask:0xf bank_mask:0xf bound_ctrl:1
	v_mov_b32_dpp v85, v83 row_ror:8 row_mask:0xf bank_mask:0xf bound_ctrl:1
	v_pk_fma_f32 v[82:83], v[4:5], v[82:83], v[84:85] op_sel_hi:[0,1,1]
	v_pk_mul_f32 v[84:85], v[82:83], v[10:11] op_sel_hi:[1,0]
	s_nop 0
	v_pk_fma_f32 v[10:11], v[82:83], v[10:11], v[84:85] op_sel:[1,1,0] op_sel_hi:[0,1,1] neg_lo:[0,1,0]
	ds_swizzle_b32 v82, v10 offset:swizzle(SWAP,4)
	ds_swizzle_b32 v83, v11 offset:swizzle(SWAP,4)
	s_waitcnt lgkmcnt(0)
	v_pk_fma_f32 v[4:5], v[4:5], v[10:11], v[82:83] op_sel:[1,0,0]
	s_nop 0
	v_pk_mul_f32 v[10:11], v[4:5], v[0:1] op_sel_hi:[1,0]
	s_nop 0
	v_pk_fma_f32 v[0:1], v[4:5], v[0:1], v[10:11] op_sel:[1,1,0] op_sel_hi:[0,1,1] neg_lo:[0,1,0]
	s_nop 1
	v_mov_b32_dpp v4, v0 quad_perm:[2,3,0,1] row_mask:0xf bank_mask:0xf bound_ctrl:1
	v_mov_b32_dpp v5, v1 quad_perm:[2,3,0,1] row_mask:0xf bank_mask:0xf bound_ctrl:1
	v_pk_fma_f32 v[0:1], v[6:7], v[0:1], v[4:5] op_sel_hi:[0,1,1]
	v_pk_mul_f32 v[4:5], v[0:1], v[2:3] op_sel_hi:[1,0]
	s_nop 0
	v_pk_fma_f32 v[0:1], v[0:1], v[2:3], v[4:5] op_sel:[1,1,0] op_sel_hi:[0,1,1] neg_lo:[0,1,0]
	s_nop 1
	v_mov_b32_dpp v2, v0 quad_perm:[1,0,3,2] row_mask:0xf bank_mask:0xf bound_ctrl:1
	v_mov_b32_dpp v3, v1 quad_perm:[1,0,3,2] row_mask:0xf bank_mask:0xf bound_ctrl:1
	v_pk_fma_f32 v[82:83], v[8:9], v[0:1], v[2:3] op_sel_hi:[0,1,1]
	s_cbranch_scc1 .LBB0_345
; __device__ __forceinline__ float bflo(unsigned w) { return __uint_as_float(w << 16); }
; __device__ __forceinline__ float bfhi(unsigned w) { return __uint_as_float(w & 0xffff0000u); }
; __device__ __forceinline__ float lx1(float v) { return __int_as_float(__builtin_amdgcn_update_dpp(0, __float_as_int(v), 0xB1, 0xF, 0xF, true)); }
; __device__ __forceinline__ void fft_inverse(f2 (&x)[32], LAS f2* X, int t, LAS const float* W1, LAS const M2C* MC) {
;     ...
;     for (int p = 0; p < 32; ++p) {
;         f2 v = x[p], pr;
;         pr = (f2){lx1(v.x), lx1(v.y)}; v = cmulrc(pr + v * c.s1, t2);
; template <int VAR> __device__ __forceinline__ void hyena_conv_phase(const Frame& F, const bf16* ZT, const bf16* GT, const float* conv_w, const float* conv_b, const float* skip, float* gscr, float* zscr, bf16* UT) {
;     ...
;             } else {
; #pragma unroll
;                 for (int p = 0; p < 32; ++p) { const unsigned w = gpre[p]; x[p] = cmulr(x[p], (f2){bflo(w), bfhi(w)}); }
	v_lshlrev_b32_e32 v0, 16, v161
	v_and_b32_e32 v1, 0xffff0000, v161
	v_pk_mul_f32 v[2:3], v[14:15], v[0:1] op_sel_hi:[1,0]
	s_mov_b32 s96, s63
	v_pk_fma_f32 v[86:87], v[14:15], v[0:1], v[2:3] op_sel:[1,1,0] op_sel_hi:[0,1,1] neg_lo:[0,1,0]
	v_lshlrev_b32_e32 v0, 16, v162
	v_and_b32_e32 v1, 0xffff0000, v162
	v_pk_mul_f32 v[2:3], v[22:23], v[0:1] op_sel_hi:[1,0]
	v_mov_b32_dpp v216, v86 quad_perm:[1,0,3,2] row_mask:0xf bank_mask:0xf bound_ctrl:1
	v_pk_fma_f32 v[90:91], v[22:23], v[0:1], v[2:3] op_sel:[1,1,0] op_sel_hi:[0,1,1] neg_lo:[0,1,0]
	v_lshlrev_b32_e32 v0, 16, v163
	v_and_b32_e32 v1, 0xffff0000, v163
	v_pk_mul_f32 v[2:3], v[24:25], v[0:1] op_sel_hi:[1,0]
	v_mov_b32_dpp v217, v87 quad_perm:[1,0,3,2] row_mask:0xf bank_mask:0xf bound_ctrl:1
	v_pk_fma_f32 v[98:99], v[24:25], v[0:1], v[2:3] op_sel:[1,1,0] op_sel_hi:[0,1,1] neg_lo:[0,1,0]
	v_lshlrev_b32_e32 v0, 16, v164
	v_and_b32_e32 v1, 0xffff0000, v164
	v_pk_mul_f32 v[2:3], v[26:27], v[0:1] op_sel_hi:[1,0]
	s_mov_b32 s97, s62
	v_pk_fma_f32 v[96:97], v[26:27], v[0:1], v[2:3] op_sel:[1,1,0] op_sel_hi:[0,1,1] neg_lo:[0,1,0]
	v_lshlrev_b32_e32 v0, 16, v165
	v_and_b32_e32 v1, 0xffff0000, v165
	v_pk_mul_f32 v[2:3], v[28:29], v[0:1] op_sel_hi:[1,0]
	s_mov_b32 s94, s63
	v_pk_fma_f32 v[108:109], v[28:29], v[0:1], v[2:3] op_sel:[1,1,0] op_sel_hi:[0,1,1] neg_lo:[0,1,0]
	v_lshlrev_b32_e32 v0, 16, v166
	v_and_b32_e32 v1, 0xffff0000, v166
	v_pk_mul_f32 v[2:3], v[30:31], v[0:1] op_sel_hi:[1,0]
	s_mov_b32 s6, s55
	v_pk_fma_f32 v[104:105], v[30:31], v[0:1], v[2:3] op_sel:[1,1,0] op_sel_hi:[0,1,1] neg_lo:[0,1,0]
	v_lshlrev_b32_e32 v0, 16, v167
	v_and_b32_e32 v1, 0xffff0000, v167
	v_pk_mul_f32 v[2:3], v[32:33], v[0:1] op_sel_hi:[1,0]
	s_mov_b32 s7, s54
	v_pk_fma_f32 v[114:115], v[32:33], v[0:1], v[2:3] op_sel:[1,1,0] op_sel_hi:[0,1,1] neg_lo:[0,1,0]
	v_lshlrev_b32_e32 v0, 16, v168
	v_and_b32_e32 v1, 0xffff0000, v168
	v_pk_mul_f32 v[2:3], v[34:35], v[0:1] op_sel_hi:[1,0]
	s_mov_b32 s84, s55
	v_pk_fma_f32 v[112:113], v[34:35], v[0:1], v[2:3] op_sel:[1,1,0] op_sel_hi:[0,1,1] neg_lo:[0,1,0]
	v_lshlrev_b32_e32 v0, 16, v169
	v_and_b32_e32 v1, 0xffff0000, v169
	v_pk_mul_f32 v[2:3], v[36:37], v[0:1] op_sel_hi:[1,0]
	s_mov_b32 s76, s47
	v_pk_fma_f32 v[126:127], v[36:37], v[0:1], v[2:3] op_sel:[1,1,0] op_sel_hi:[0,1,1] neg_lo:[0,1,0]
	v_lshlrev_b32_e32 v0, 16, v170
	v_and_b32_e32 v1, 0xffff0000, v170
	v_pk_mul_f32 v[2:3], v[38:39], v[0:1] op_sel_hi:[1,0]
	s_mov_b32 s77, s46
	v_pk_fma_f32 v[122:123], v[38:39], v[0:1], v[2:3] op_sel:[1,1,0] op_sel_hi:[0,1,1] neg_lo:[0,1,0]
	v_lshlrev_b32_e32 v0, 16, v171
	v_and_b32_e32 v1, 0xffff0000, v171
	v_pk_mul_f32 v[2:3], v[40:41], v[0:1] op_sel_hi:[1,0]
	s_mov_b32 s20, s59
	v_pk_fma_f32 v[132:133], v[40:41], v[0:1], v[2:3] op_sel:[1,1,0] op_sel_hi:[0,1,1] neg_lo:[0,1,0]
	v_lshlrev_b32_e32 v0, 16, v172
	v_and_b32_e32 v1, 0xffff0000, v172
	v_pk_mul_f32 v[2:3], v[42:43], v[0:1] op_sel_hi:[1,0]
	s_mov_b32 s21, s58
	v_pk_fma_f32 v[130:131], v[42:43], v[0:1], v[2:3] op_sel:[1,1,0] op_sel_hi:[0,1,1] neg_lo:[0,1,0]
	v_lshlrev_b32_e32 v0, 16, v173
	v_and_b32_e32 v1, 0xffff0000, v173
	v_pk_mul_f32 v[2:3], v[44:45], v[0:1] op_sel_hi:[1,0]
	s_mov_b32 s86, s59
	v_pk_fma_f32 v[142:143], v[44:45], v[0:1], v[2:3] op_sel:[1,1,0] op_sel_hi:[0,1,1] neg_lo:[0,1,0]
	v_lshlrev_b32_e32 v0, 16, v174
	v_and_b32_e32 v1, 0xffff0000, v174
	v_pk_mul_f32 v[2:3], v[46:47], v[0:1] op_sel_hi:[1,0]
	s_mov_b32 s10, s47
	v_pk_fma_f32 v[138:139], v[46:47], v[0:1], v[2:3] op_sel:[1,1,0] op_sel_hi:[0,1,1] neg_lo:[0,1,0]
	v_lshlrev_b32_e32 v0, 16, v175
	v_and_b32_e32 v1, 0xffff0000, v175
	v_pk_mul_f32 v[2:3], v[48:49], v[0:1] op_sel_hi:[1,0]
	v_lshl_add_u64 v[84:85], v[12:13], 4, s[8:9]
	v_pk_fma_f32 v[148:149], v[48:49], v[0:1], v[2:3] op_sel:[1,1,0] op_sel_hi:[0,1,1] neg_lo:[0,1,0]
	v_lshlrev_b32_e32 v0, 16, v176
	v_and_b32_e32 v1, 0xffff0000, v176
	v_pk_mul_f32 v[2:3], v[50:51], v[0:1] op_sel_hi:[1,0]
	s_and_b64 vcc, exec, s[92:93]
	v_pk_fma_f32 v[146:147], v[50:51], v[0:1], v[2:3] op_sel:[1,1,0] op_sel_hi:[0,1,1] neg_lo:[0,1,0]
	v_lshlrev_b32_e32 v0, 16, v177
	v_and_b32_e32 v1, 0xffff0000, v177
	v_pk_mul_f32 v[2:3], v[52:53], v[0:1] op_sel_hi:[1,0]
	s_nop 0
	v_pk_fma_f32 v[144:145], v[52:53], v[0:1], v[2:3] op_sel:[1,1,0] op_sel_hi:[0,1,1] neg_lo:[0,1,0]
	v_lshlrev_b32_e32 v0, 16, v178
	v_and_b32_e32 v1, 0xffff0000, v178
	v_pk_mul_f32 v[2:3], v[54:55], v[0:1] op_sel_hi:[1,0]
	s_nop 0
	v_pk_fma_f32 v[140:141], v[54:55], v[0:1], v[2:3] op_sel:[1,1,0] op_sel_hi:[0,1,1] neg_lo:[0,1,0]
	v_lshlrev_b32_e32 v0, 16, v179
	v_and_b32_e32 v1, 0xffff0000, v179
	v_pk_mul_f32 v[2:3], v[56:57], v[0:1] op_sel_hi:[1,0]
	s_nop 0
	v_pk_fma_f32 v[136:137], v[56:57], v[0:1], v[2:3] op_sel:[1,1,0] op_sel_hi:[0,1,1] neg_lo:[0,1,0]
	v_lshlrev_b32_e32 v0, 16, v180
	v_and_b32_e32 v1, 0xffff0000, v180
	v_pk_mul_f32 v[2:3], v[58:59], v[0:1] op_sel_hi:[1,0]
	s_nop 0
	v_pk_fma_f32 v[134:135], v[58:59], v[0:1], v[2:3] op_sel:[1,1,0] op_sel_hi:[0,1,1] neg_lo:[0,1,0]
	v_lshlrev_b32_e32 v0, 16, v181
	v_and_b32_e32 v1, 0xffff0000, v181
	v_pk_mul_f32 v[2:3], v[60:61], v[0:1] op_sel_hi:[1,0]
	s_nop 0
	v_pk_fma_f32 v[128:129], v[60:61], v[0:1], v[2:3] op_sel:[1,1,0] op_sel_hi:[0,1,1] neg_lo:[0,1,0]
	v_lshlrev_b32_e32 v0, 16, v182
	v_and_b32_e32 v1, 0xffff0000, v182
	v_pk_mul_f32 v[2:3], v[62:63], v[0:1] op_sel_hi:[1,0]
	s_nop 0
	v_pk_fma_f32 v[124:125], v[62:63], v[0:1], v[2:3] op_sel:[1,1,0] op_sel_hi:[0,1,1] neg_lo:[0,1,0]
	v_lshlrev_b32_e32 v0, 16, v183
	v_and_b32_e32 v1, 0xffff0000, v183
	v_pk_mul_f32 v[2:3], v[64:65], v[0:1] op_sel_hi:[1,0]
	s_nop 0
	v_pk_fma_f32 v[120:121], v[64:65], v[0:1], v[2:3] op_sel:[1,1,0] op_sel_hi:[0,1,1] neg_lo:[0,1,0]
; __device__ __forceinline__ float bflo(unsigned w) { return __uint_as_float(w << 16); }
; __device__ __forceinline__ float bfhi(unsigned w) { return __uint_as_float(w & 0xffff0000u); }
; __device__ __forceinline__ float lx1(float v) { return __int_as_float(__builtin_amdgcn_update_dpp(0, __float_as_int(v), 0xB1, 0xF, 0xF, true)); }
; __device__ __forceinline__ float lx2(float v) { return __int_as_float(__builtin_amdgcn_update_dpp(0, __float_as_int(v), 0x4E, 0xF, 0xF, true)); }
; __device__ __forceinline__ float lx4(float v) { return __int_as_float(__builtin_amdgcn_ds_swizzle(__float_as_int(v), 0x101F)); }
; __device__ __forceinline__ float lx8(float v) { return __int_as_float(__builtin_amdgcn_update_dpp(0, __float_as_int(v), 0x128, 0xF, 0xF, true)); }
; __device__ __forceinline__ void fft_inverse(f2 (&x)[32], LAS f2* X, int t, LAS const float* W1, LAS const M2C* MC) {
;     const M2C c = m2c_load(MC); const f2 t8 = (f2){c.t8r, c.t8i}, t4 = (f2){c.t4r, c.t4i}, t2 = (f2){c.t2r, c.t2i};
; #pragma unroll
;     for (int p = 0; p < 32; ++p) {
;         f2 v = x[p], pr;
;         pr = (f2){lx1(v.x), lx1(v.y)}; v = cmulrc(pr + v * c.s1, t2);
;         pr = (f2){lx2(v.x), lx2(v.y)}; v = cmulrc(pr + v * c.s2, t4);
;         pr = (f2){lx4(v.x), lx4(v.y)}; v = cmulrc(pr + v * c.s4, t8);
;         pr = (f2){lx8(v.x), lx8(v.y)}; x[p] = pr + v * c.s8;
;     }
; template <int VAR> __device__ __forceinline__ void hyena_conv_phase(const Frame& F, const bf16* ZT, const bf16* GT, const float* conv_w, const float* conv_b, const float* skip, float* gscr, float* zscr, bf16* UT) {
;     ...
;             } else {
; #pragma unroll
;                 for (int p = 0; p < 32; ++p) { const unsigned w = gpre[p]; x[p] = cmulr(x[p], (f2){bflo(w), bfhi(w)}); }
	v_lshlrev_b32_e32 v0, 16, v184
	v_and_b32_e32 v1, 0xffff0000, v184
	v_pk_mul_f32 v[2:3], v[66:67], v[0:1] op_sel_hi:[1,0]
	s_nop 0
	v_pk_fma_f32 v[118:119], v[66:67], v[0:1], v[2:3] op_sel:[1,1,0] op_sel_hi:[0,1,1] neg_lo:[0,1,0]
	v_lshlrev_b32_e32 v0, 16, v185
	v_and_b32_e32 v1, 0xffff0000, v185
	v_pk_mul_f32 v[2:3], v[68:69], v[0:1] op_sel_hi:[1,0]
	s_nop 0
	v_pk_fma_f32 v[116:117], v[68:69], v[0:1], v[2:3] op_sel:[1,1,0] op_sel_hi:[0,1,1] neg_lo:[0,1,0]
	v_lshlrev_b32_e32 v0, 16, v186
	v_and_b32_e32 v1, 0xffff0000, v186
	v_pk_mul_f32 v[2:3], v[70:71], v[0:1] op_sel_hi:[1,0]
	s_nop 0
	v_pk_fma_f32 v[110:111], v[70:71], v[0:1], v[2:3] op_sel:[1,1,0] op_sel_hi:[0,1,1] neg_lo:[0,1,0]
	v_lshlrev_b32_e32 v0, 16, v187
	v_and_b32_e32 v1, 0xffff0000, v187
	v_pk_mul_f32 v[2:3], v[72:73], v[0:1] op_sel_hi:[1,0]
	s_nop 0
	v_pk_fma_f32 v[106:107], v[72:73], v[0:1], v[2:3] op_sel:[1,1,0] op_sel_hi:[0,1,1] neg_lo:[0,1,0]
	v_lshlrev_b32_e32 v0, 16, v188
	v_and_b32_e32 v1, 0xffff0000, v188
	v_pk_mul_f32 v[2:3], v[74:75], v[0:1] op_sel_hi:[1,0]
	s_nop 0
	v_pk_fma_f32 v[102:103], v[74:75], v[0:1], v[2:3] op_sel:[1,1,0] op_sel_hi:[0,1,1] neg_lo:[0,1,0]
	v_lshlrev_b32_e32 v0, 16, v189
	v_and_b32_e32 v1, 0xffff0000, v189
	v_pk_mul_f32 v[2:3], v[76:77], v[0:1] op_sel_hi:[1,0]
	s_nop 0
	v_pk_fma_f32 v[100:101], v[76:77], v[0:1], v[2:3] op_sel:[1,1,0] op_sel_hi:[0,1,1] neg_lo:[0,1,0]
	v_lshlrev_b32_e32 v0, 16, v190
	v_and_b32_e32 v1, 0xffff0000, v190
	v_pk_mul_f32 v[2:3], v[78:79], v[0:1] op_sel_hi:[1,0]
	s_nop 0
	v_pk_fma_f32 v[94:95], v[78:79], v[0:1], v[2:3] op_sel:[1,1,0] op_sel_hi:[0,1,1] neg_lo:[0,1,0]
	v_lshlrev_b32_e32 v0, 16, v191
	v_and_b32_e32 v1, 0xffff0000, v191
	v_pk_mul_f32 v[2:3], v[80:81], v[0:1] op_sel_hi:[1,0]
	s_nop 0
	v_pk_fma_f32 v[92:93], v[80:81], v[0:1], v[2:3] op_sel:[1,1,0] op_sel_hi:[0,1,1] neg_lo:[0,1,0]
	v_lshlrev_b32_e32 v0, 16, v192
	v_and_b32_e32 v1, 0xffff0000, v192
	v_pk_mul_f32 v[2:3], v[82:83], v[0:1] op_sel_hi:[1,0]
	s_nop 0
	v_pk_fma_f32 v[88:89], v[82:83], v[0:1], v[2:3] op_sel:[1,1,0] op_sel_hi:[0,1,1] neg_lo:[0,1,0]
	ds_read_b128 v[0:3], v151
	ds_read_b128 v[4:7], v151 offset:16
	ds_read_b128 v[8:11], v151 offset:32
	s_waitcnt lgkmcnt(2)
	s_nop 0
	v_xor_b32_e32 v1, 0x80000000, v1
	s_waitcnt lgkmcnt(0)
	v_mov_b32_e32 v16, v11
	v_pk_fma_f32 v[86:87], v[86:87], v[16:17], v[216:217] op_sel_hi:[1,0,1]
	s_nop 0
	v_pk_mul_f32 v[216:217], v[86:87], v[6:7] op_sel_hi:[1,0]
	s_nop 0
	v_pk_fma_f32 v[86:87], v[86:87], v[6:7], v[216:217] op_sel:[1,1,0] op_sel_hi:[0,1,1] neg_hi:[0,1,0]
	s_nop 1
	v_mov_b32_dpp v216, v86 quad_perm:[2,3,0,1] row_mask:0xf bank_mask:0xf bound_ctrl:1
	v_mov_b32_dpp v217, v87 quad_perm:[2,3,0,1] row_mask:0xf bank_mask:0xf bound_ctrl:1
	v_pk_fma_f32 v[86:87], v[10:11], v[86:87], v[216:217] op_sel_hi:[0,1,1]
	v_pk_mul_f32 v[216:217], v[86:87], v[4:5] op_sel_hi:[1,0]
	s_nop 0
	v_pk_fma_f32 v[86:87], v[86:87], v[4:5], v[216:217] op_sel:[1,1,0] op_sel_hi:[0,1,1] neg_hi:[0,1,0]
	ds_swizzle_b32 v216, v86 offset:swizzle(SWAP,4)
	ds_swizzle_b32 v217, v87 offset:swizzle(SWAP,4)
	s_waitcnt lgkmcnt(0)
	v_pk_fma_f32 v[86:87], v[8:9], v[86:87], v[216:217] op_sel:[1,0,0]
	s_nop 0
	v_pk_mul_f32 v[216:217], v[86:87], v[2:3] op_sel_hi:[1,0]
	s_nop 0
	v_pk_fma_f32 v[86:87], v[86:87], v[2:3], v[216:217] op_sel:[1,1,0] op_sel_hi:[0,1,1] neg_hi:[0,1,0]
	s_nop 1
	v_mov_b32_dpp v216, v86 row_ror:8 row_mask:0xf bank_mask:0xf bound_ctrl:1
	v_mov_b32_dpp v217, v87 row_ror:8 row_mask:0xf bank_mask:0xf bound_ctrl:1
	v_pk_fma_f32 v[86:87], v[8:9], v[86:87], v[216:217] op_sel_hi:[0,1,1]
	v_mov_b32_dpp v216, v90 quad_perm:[1,0,3,2] row_mask:0xf bank_mask:0xf bound_ctrl:1
	v_mov_b32_dpp v217, v91 quad_perm:[1,0,3,2] row_mask:0xf bank_mask:0xf bound_ctrl:1
	v_pk_fma_f32 v[90:91], v[90:91], v[16:17], v[216:217] op_sel_hi:[1,0,1]
	s_nop 0
	v_pk_mul_f32 v[216:217], v[90:91], v[6:7] op_sel_hi:[1,0]
	s_nop 0
	v_pk_fma_f32 v[90:91], v[90:91], v[6:7], v[216:217] op_sel:[1,1,0] op_sel_hi:[0,1,1] neg_hi:[0,1,0]
	s_nop 1
	v_mov_b32_dpp v216, v90 quad_perm:[2,3,0,1] row_mask:0xf bank_mask:0xf bound_ctrl:1
	v_mov_b32_dpp v217, v91 quad_perm:[2,3,0,1] row_mask:0xf bank_mask:0xf bound_ctrl:1
	v_pk_fma_f32 v[90:91], v[10:11], v[90:91], v[216:217] op_sel_hi:[0,1,1]
	v_pk_mul_f32 v[216:217], v[90:91], v[4:5] op_sel_hi:[1,0]
	s_nop 0
	v_pk_fma_f32 v[90:91], v[90:91], v[4:5], v[216:217] op_sel:[1,1,0] op_sel_hi:[0,1,1] neg_hi:[0,1,0]
	ds_swizzle_b32 v216, v90 offset:swizzle(SWAP,4)
	ds_swizzle_b32 v217, v91 offset:swizzle(SWAP,4)
	s_waitcnt lgkmcnt(0)
	v_pk_fma_f32 v[90:91], v[8:9], v[90:91], v[216:217] op_sel:[1,0,0]
	s_nop 0
	v_pk_mul_f32 v[216:217], v[90:91], v[2:3] op_sel_hi:[1,0]
	s_nop 0
	v_pk_fma_f32 v[90:91], v[90:91], v[2:3], v[216:217] op_sel:[1,1,0] op_sel_hi:[0,1,1] neg_hi:[0,1,0]
	s_nop 1
	v_mov_b32_dpp v216, v90 row_ror:8 row_mask:0xf bank_mask:0xf bound_ctrl:1
	v_mov_b32_dpp v217, v91 row_ror:8 row_mask:0xf bank_mask:0xf bound_ctrl:1
	v_pk_fma_f32 v[90:91], v[8:9], v[90:91], v[216:217] op_sel_hi:[0,1,1]
	v_mov_b32_dpp v216, v98 quad_perm:[1,0,3,2] row_mask:0xf bank_mask:0xf bound_ctrl:1
	v_mov_b32_dpp v217, v99 quad_perm:[1,0,3,2] row_mask:0xf bank_mask:0xf bound_ctrl:1
	v_pk_fma_f32 v[98:99], v[98:99], v[16:17], v[216:217] op_sel_hi:[1,0,1]
	s_nop 0
	v_pk_mul_f32 v[216:217], v[98:99], v[6:7] op_sel_hi:[1,0]
	s_nop 0
	v_pk_fma_f32 v[98:99], v[98:99], v[6:7], v[216:217] op_sel:[1,1,0] op_sel_hi:[0,1,1] neg_hi:[0,1,0]
	s_nop 1
	v_mov_b32_dpp v216, v98 quad_perm:[2,3,0,1] row_mask:0xf bank_mask:0xf bound_ctrl:1
	v_mov_b32_dpp v217, v99 quad_perm:[2,3,0,1] row_mask:0xf bank_mask:0xf bound_ctrl:1
	v_pk_fma_f32 v[98:99], v[10:11], v[98:99], v[216:217] op_sel_hi:[0,1,1]
	v_pk_mul_f32 v[216:217], v[98:99], v[4:5] op_sel_hi:[1,0]
	s_nop 0
	v_pk_fma_f32 v[98:99], v[98:99], v[4:5], v[216:217] op_sel:[1,1,0] op_sel_hi:[0,1,1] neg_hi:[0,1,0]
	ds_swizzle_b32 v216, v98 offset:swizzle(SWAP,4)
	ds_swizzle_b32 v217, v99 offset:swizzle(SWAP,4)
	s_waitcnt lgkmcnt(0)
; __device__ __forceinline__ float lx1(float v) { return __int_as_float(__builtin_amdgcn_update_dpp(0, __float_as_int(v), 0xB1, 0xF, 0xF, true)); }
; __device__ __forceinline__ float lx2(float v) { return __int_as_float(__builtin_amdgcn_update_dpp(0, __float_as_int(v), 0x4E, 0xF, 0xF, true)); }
; __device__ __forceinline__ float lx4(float v) { return __int_as_float(__builtin_amdgcn_ds_swizzle(__float_as_int(v), 0x101F)); }
; __device__ __forceinline__ float lx8(float v) { return __int_as_float(__builtin_amdgcn_update_dpp(0, __float_as_int(v), 0x128, 0xF, 0xF, true)); }
; __device__ __forceinline__ void fft_inverse(f2 (&x)[32], LAS f2* X, int t, LAS const float* W1, LAS const M2C* MC) {
;     ...
;     for (int p = 0; p < 32; ++p) {
;         f2 v = x[p], pr;
;         pr = (f2){lx1(v.x), lx1(v.y)}; v = cmulrc(pr + v * c.s1, t2);
;         pr = (f2){lx2(v.x), lx2(v.y)}; v = cmulrc(pr + v * c.s2, t4);
;         pr = (f2){lx4(v.x), lx4(v.y)}; v = cmulrc(pr + v * c.s4, t8);
;         pr = (f2){lx8(v.x), lx8(v.y)}; x[p] = pr + v * c.s8;
;     }
	v_pk_fma_f32 v[98:99], v[8:9], v[98:99], v[216:217] op_sel:[1,0,0]
	s_nop 0
	v_pk_mul_f32 v[216:217], v[98:99], v[2:3] op_sel_hi:[1,0]
	s_nop 0
	v_pk_fma_f32 v[98:99], v[98:99], v[2:3], v[216:217] op_sel:[1,1,0] op_sel_hi:[0,1,1] neg_hi:[0,1,0]
	s_nop 1
	v_mov_b32_dpp v216, v98 row_ror:8 row_mask:0xf bank_mask:0xf bound_ctrl:1
	v_mov_b32_dpp v217, v99 row_ror:8 row_mask:0xf bank_mask:0xf bound_ctrl:1
	v_pk_fma_f32 v[98:99], v[8:9], v[98:99], v[216:217] op_sel_hi:[0,1,1]
	v_mov_b32_dpp v216, v96 quad_perm:[1,0,3,2] row_mask:0xf bank_mask:0xf bound_ctrl:1
	v_mov_b32_dpp v217, v97 quad_perm:[1,0,3,2] row_mask:0xf bank_mask:0xf bound_ctrl:1
	v_pk_fma_f32 v[96:97], v[96:97], v[16:17], v[216:217] op_sel_hi:[1,0,1]
	s_nop 0
	v_pk_mul_f32 v[216:217], v[96:97], v[6:7] op_sel_hi:[1,0]
	s_nop 0
	v_pk_fma_f32 v[96:97], v[96:97], v[6:7], v[216:217] op_sel:[1,1,0] op_sel_hi:[0,1,1] neg_hi:[0,1,0]
	s_nop 1
	v_mov_b32_dpp v216, v96 quad_perm:[2,3,0,1] row_mask:0xf bank_mask:0xf bound_ctrl:1
	v_mov_b32_dpp v217, v97 quad_perm:[2,3,0,1] row_mask:0xf bank_mask:0xf bound_ctrl:1
	v_pk_fma_f32 v[96:97], v[10:11], v[96:97], v[216:217] op_sel_hi:[0,1,1]
	v_pk_mul_f32 v[216:217], v[96:97], v[4:5] op_sel_hi:[1,0]
	s_nop 0
	v_pk_fma_f32 v[96:97], v[96:97], v[4:5], v[216:217] op_sel:[1,1,0] op_sel_hi:[0,1,1] neg_hi:[0,1,0]
	ds_swizzle_b32 v216, v96 offset:swizzle(SWAP,4)
	ds_swizzle_b32 v217, v97 offset:swizzle(SWAP,4)
	s_waitcnt lgkmcnt(0)
	v_pk_fma_f32 v[96:97], v[8:9], v[96:97], v[216:217] op_sel:[1,0,0]
	s_nop 0
	v_pk_mul_f32 v[216:217], v[96:97], v[2:3] op_sel_hi:[1,0]
	s_nop 0
	v_pk_fma_f32 v[96:97], v[96:97], v[2:3], v[216:217] op_sel:[1,1,0] op_sel_hi:[0,1,1] neg_hi:[0,1,0]
	s_nop 1
	v_mov_b32_dpp v216, v96 row_ror:8 row_mask:0xf bank_mask:0xf bound_ctrl:1
	v_mov_b32_dpp v217, v97 row_ror:8 row_mask:0xf bank_mask:0xf bound_ctrl:1
	v_pk_fma_f32 v[96:97], v[8:9], v[96:97], v[216:217] op_sel_hi:[0,1,1]
	v_mov_b32_dpp v216, v108 quad_perm:[1,0,3,2] row_mask:0xf bank_mask:0xf bound_ctrl:1
	v_mov_b32_dpp v217, v109 quad_perm:[1,0,3,2] row_mask:0xf bank_mask:0xf bound_ctrl:1
	v_pk_fma_f32 v[108:109], v[108:109], v[16:17], v[216:217] op_sel_hi:[1,0,1]
	s_nop 0
	v_pk_mul_f32 v[216:217], v[108:109], v[6:7] op_sel_hi:[1,0]
	s_nop 0
	v_pk_fma_f32 v[108:109], v[108:109], v[6:7], v[216:217] op_sel:[1,1,0] op_sel_hi:[0,1,1] neg_hi:[0,1,0]
	s_nop 1
	v_mov_b32_dpp v216, v108 quad_perm:[2,3,0,1] row_mask:0xf bank_mask:0xf bound_ctrl:1
	v_mov_b32_dpp v217, v109 quad_perm:[2,3,0,1] row_mask:0xf bank_mask:0xf bound_ctrl:1
	v_pk_fma_f32 v[108:109], v[10:11], v[108:109], v[216:217] op_sel_hi:[0,1,1]
	v_pk_mul_f32 v[216:217], v[108:109], v[4:5] op_sel_hi:[1,0]
	s_nop 0
	v_pk_fma_f32 v[108:109], v[108:109], v[4:5], v[216:217] op_sel:[1,1,0] op_sel_hi:[0,1,1] neg_hi:[0,1,0]
	ds_swizzle_b32 v216, v108 offset:swizzle(SWAP,4)
	ds_swizzle_b32 v217, v109 offset:swizzle(SWAP,4)
	s_waitcnt lgkmcnt(0)
	v_pk_fma_f32 v[108:109], v[8:9], v[108:109], v[216:217] op_sel:[1,0,0]
	s_nop 0
	v_pk_mul_f32 v[216:217], v[108:109], v[2:3] op_sel_hi:[1,0]
	s_nop 0
	v_pk_fma_f32 v[108:109], v[108:109], v[2:3], v[216:217] op_sel:[1,1,0] op_sel_hi:[0,1,1] neg_hi:[0,1,0]
	s_nop 1
	v_mov_b32_dpp v216, v108 row_ror:8 row_mask:0xf bank_mask:0xf bound_ctrl:1
	v_mov_b32_dpp v217, v109 row_ror:8 row_mask:0xf bank_mask:0xf bound_ctrl:1
	v_pk_fma_f32 v[108:109], v[8:9], v[108:109], v[216:217] op_sel_hi:[0,1,1]
	v_mov_b32_dpp v216, v104 quad_perm:[1,0,3,2] row_mask:0xf bank_mask:0xf bound_ctrl:1
	v_mov_b32_dpp v217, v105 quad_perm:[1,0,3,2] row_mask:0xf bank_mask:0xf bound_ctrl:1
	v_pk_fma_f32 v[104:105], v[104:105], v[16:17], v[216:217] op_sel_hi:[1,0,1]
	s_nop 0
	v_pk_mul_f32 v[216:217], v[104:105], v[6:7] op_sel_hi:[1,0]
	s_nop 0
	v_pk_fma_f32 v[104:105], v[104:105], v[6:7], v[216:217] op_sel:[1,1,0] op_sel_hi:[0,1,1] neg_hi:[0,1,0]
	s_nop 1
	v_mov_b32_dpp v216, v104 quad_perm:[2,3,0,1] row_mask:0xf bank_mask:0xf bound_ctrl:1
	v_mov_b32_dpp v217, v105 quad_perm:[2,3,0,1] row_mask:0xf bank_mask:0xf bound_ctrl:1
	v_pk_fma_f32 v[104:105], v[10:11], v[104:105], v[216:217] op_sel_hi:[0,1,1]
	v_pk_mul_f32 v[216:217], v[104:105], v[4:5] op_sel_hi:[1,0]
	s_nop 0
	v_pk_fma_f32 v[104:105], v[104:105], v[4:5], v[216:217] op_sel:[1,1,0] op_sel_hi:[0,1,1] neg_hi:[0,1,0]
	ds_swizzle_b32 v216, v104 offset:swizzle(SWAP,4)
	ds_swizzle_b32 v217, v105 offset:swizzle(SWAP,4)
	s_waitcnt lgkmcnt(0)
	v_pk_fma_f32 v[104:105], v[8:9], v[104:105], v[216:217] op_sel:[1,0,0]
	s_nop 0
	v_pk_mul_f32 v[216:217], v[104:105], v[2:3] op_sel_hi:[1,0]
	s_nop 0
	v_pk_fma_f32 v[104:105], v[104:105], v[2:3], v[216:217] op_sel:[1,1,0] op_sel_hi:[0,1,1] neg_hi:[0,1,0]
	s_nop 1
	v_mov_b32_dpp v216, v104 row_ror:8 row_mask:0xf bank_mask:0xf bound_ctrl:1
	v_mov_b32_dpp v217, v105 row_ror:8 row_mask:0xf bank_mask:0xf bound_ctrl:1
	v_pk_fma_f32 v[104:105], v[8:9], v[104:105], v[216:217] op_sel_hi:[0,1,1]
	v_mov_b32_dpp v216, v114 quad_perm:[1,0,3,2] row_mask:0xf bank_mask:0xf bound_ctrl:1
	v_mov_b32_dpp v217, v115 quad_perm:[1,0,3,2] row_mask:0xf bank_mask:0xf bound_ctrl:1
	v_pk_fma_f32 v[114:115], v[114:115], v[16:17], v[216:217] op_sel_hi:[1,0,1]
	s_nop 0
	v_pk_mul_f32 v[216:217], v[114:115], v[6:7] op_sel_hi:[1,0]
	s_nop 0
	v_pk_fma_f32 v[114:115], v[114:115], v[6:7], v[216:217] op_sel:[1,1,0] op_sel_hi:[0,1,1] neg_hi:[0,1,0]
	s_nop 1
	v_mov_b32_dpp v216, v114 quad_perm:[2,3,0,1] row_mask:0xf bank_mask:0xf bound_ctrl:1
	v_mov_b32_dpp v217, v115 quad_perm:[2,3,0,1] row_mask:0xf bank_mask:0xf bound_ctrl:1
	v_pk_fma_f32 v[114:115], v[10:11], v[114:115], v[216:217] op_sel_hi:[0,1,1]
	v_pk_mul_f32 v[216:217], v[114:115], v[4:5] op_sel_hi:[1,0]
	s_nop 0
	v_pk_fma_f32 v[114:115], v[114:115], v[4:5], v[216:217] op_sel:[1,1,0] op_sel_hi:[0,1,1] neg_hi:[0,1,0]
	ds_swizzle_b32 v216, v114 offset:swizzle(SWAP,4)
	ds_swizzle_b32 v217, v115 offset:swizzle(SWAP,4)
	s_waitcnt lgkmcnt(0)
; __device__ __forceinline__ float lx1(float v) { return __int_as_float(__builtin_amdgcn_update_dpp(0, __float_as_int(v), 0xB1, 0xF, 0xF, true)); }
; __device__ __forceinline__ float lx2(float v) { return __int_as_float(__builtin_amdgcn_update_dpp(0, __float_as_int(v), 0x4E, 0xF, 0xF, true)); }
; __device__ __forceinline__ float lx4(float v) { return __int_as_float(__builtin_amdgcn_ds_swizzle(__float_as_int(v), 0x101F)); }
; __device__ __forceinline__ float lx8(float v) { return __int_as_float(__builtin_amdgcn_update_dpp(0, __float_as_int(v), 0x128, 0xF, 0xF, true)); }
; __device__ __forceinline__ void fft_inverse(f2 (&x)[32], LAS f2* X, int t, LAS const float* W1, LAS const M2C* MC) {
;     ...
;     for (int p = 0; p < 32; ++p) {
;         f2 v = x[p], pr;
;         pr = (f2){lx1(v.x), lx1(v.y)}; v = cmulrc(pr + v * c.s1, t2);
;         pr = (f2){lx2(v.x), lx2(v.y)}; v = cmulrc(pr + v * c.s2, t4);
;         pr = (f2){lx4(v.x), lx4(v.y)}; v = cmulrc(pr + v * c.s4, t8);
;         pr = (f2){lx8(v.x), lx8(v.y)}; x[p] = pr + v * c.s8;
;     }
	v_pk_fma_f32 v[114:115], v[8:9], v[114:115], v[216:217] op_sel:[1,0,0]
	s_nop 0
	v_pk_mul_f32 v[216:217], v[114:115], v[2:3] op_sel_hi:[1,0]
	s_nop 0
	v_pk_fma_f32 v[114:115], v[114:115], v[2:3], v[216:217] op_sel:[1,1,0] op_sel_hi:[0,1,1] neg_hi:[0,1,0]
	s_nop 1
	v_mov_b32_dpp v216, v114 row_ror:8 row_mask:0xf bank_mask:0xf bound_ctrl:1
	v_mov_b32_dpp v217, v115 row_ror:8 row_mask:0xf bank_mask:0xf bound_ctrl:1
	v_pk_fma_f32 v[114:115], v[8:9], v[114:115], v[216:217] op_sel_hi:[0,1,1]
	v_mov_b32_dpp v216, v112 quad_perm:[1,0,3,2] row_mask:0xf bank_mask:0xf bound_ctrl:1
	v_mov_b32_dpp v217, v113 quad_perm:[1,0,3,2] row_mask:0xf bank_mask:0xf bound_ctrl:1
	v_pk_fma_f32 v[112:113], v[112:113], v[16:17], v[216:217] op_sel_hi:[1,0,1]
	s_nop 0
	v_pk_mul_f32 v[216:217], v[112:113], v[6:7] op_sel_hi:[1,0]
	s_nop 0
	v_pk_fma_f32 v[112:113], v[112:113], v[6:7], v[216:217] op_sel:[1,1,0] op_sel_hi:[0,1,1] neg_hi:[0,1,0]
	s_nop 1
	v_mov_b32_dpp v216, v112 quad_perm:[2,3,0,1] row_mask:0xf bank_mask:0xf bound_ctrl:1
	v_mov_b32_dpp v217, v113 quad_perm:[2,3,0,1] row_mask:0xf bank_mask:0xf bound_ctrl:1
	v_pk_fma_f32 v[112:113], v[10:11], v[112:113], v[216:217] op_sel_hi:[0,1,1]
	v_pk_mul_f32 v[216:217], v[112:113], v[4:5] op_sel_hi:[1,0]
	s_nop 0
	v_pk_fma_f32 v[112:113], v[112:113], v[4:5], v[216:217] op_sel:[1,1,0] op_sel_hi:[0,1,1] neg_hi:[0,1,0]
	ds_swizzle_b32 v216, v112 offset:swizzle(SWAP,4)
	ds_swizzle_b32 v217, v113 offset:swizzle(SWAP,4)
	s_waitcnt lgkmcnt(0)
	v_pk_fma_f32 v[112:113], v[8:9], v[112:113], v[216:217] op_sel:[1,0,0]
	s_nop 0
	v_pk_mul_f32 v[216:217], v[112:113], v[2:3] op_sel_hi:[1,0]
	s_nop 0
	v_pk_fma_f32 v[112:113], v[112:113], v[2:3], v[216:217] op_sel:[1,1,0] op_sel_hi:[0,1,1] neg_hi:[0,1,0]
	s_nop 1
	v_mov_b32_dpp v216, v112 row_ror:8 row_mask:0xf bank_mask:0xf bound_ctrl:1
	v_mov_b32_dpp v217, v113 row_ror:8 row_mask:0xf bank_mask:0xf bound_ctrl:1
	v_pk_fma_f32 v[112:113], v[8:9], v[112:113], v[216:217] op_sel_hi:[0,1,1]
	v_mov_b32_dpp v216, v126 quad_perm:[1,0,3,2] row_mask:0xf bank_mask:0xf bound_ctrl:1
	v_mov_b32_dpp v217, v127 quad_perm:[1,0,3,2] row_mask:0xf bank_mask:0xf bound_ctrl:1
	v_pk_fma_f32 v[126:127], v[126:127], v[16:17], v[216:217] op_sel_hi:[1,0,1]
	s_nop 0
	v_pk_mul_f32 v[216:217], v[126:127], v[6:7] op_sel_hi:[1,0]
	s_nop 0
	v_pk_fma_f32 v[126:127], v[126:127], v[6:7], v[216:217] op_sel:[1,1,0] op_sel_hi:[0,1,1] neg_hi:[0,1,0]
	s_nop 1
	v_mov_b32_dpp v216, v126 quad_perm:[2,3,0,1] row_mask:0xf bank_mask:0xf bound_ctrl:1
	v_mov_b32_dpp v217, v127 quad_perm:[2,3,0,1] row_mask:0xf bank_mask:0xf bound_ctrl:1
	v_pk_fma_f32 v[126:127], v[10:11], v[126:127], v[216:217] op_sel_hi:[0,1,1]
	v_pk_mul_f32 v[216:217], v[126:127], v[4:5] op_sel_hi:[1,0]
	s_nop 0
	v_pk_fma_f32 v[126:127], v[126:127], v[4:5], v[216:217] op_sel:[1,1,0] op_sel_hi:[0,1,1] neg_hi:[0,1,0]
	ds_swizzle_b32 v216, v126 offset:swizzle(SWAP,4)
	ds_swizzle_b32 v217, v127 offset:swizzle(SWAP,4)
	s_waitcnt lgkmcnt(0)
	v_pk_fma_f32 v[126:127], v[8:9], v[126:127], v[216:217] op_sel:[1,0,0]
	s_nop 0
	v_pk_mul_f32 v[216:217], v[126:127], v[2:3] op_sel_hi:[1,0]
	s_nop 0
	v_pk_fma_f32 v[126:127], v[126:127], v[2:3], v[216:217] op_sel:[1,1,0] op_sel_hi:[0,1,1] neg_hi:[0,1,0]
	s_nop 1
	v_mov_b32_dpp v216, v126 row_ror:8 row_mask:0xf bank_mask:0xf bound_ctrl:1
	v_mov_b32_dpp v217, v127 row_ror:8 row_mask:0xf bank_mask:0xf bound_ctrl:1
	v_pk_fma_f32 v[126:127], v[8:9], v[126:127], v[216:217] op_sel_hi:[0,1,1]
	v_mov_b32_dpp v216, v122 quad_perm:[1,0,3,2] row_mask:0xf bank_mask:0xf bound_ctrl:1
	v_mov_b32_dpp v217, v123 quad_perm:[1,0,3,2] row_mask:0xf bank_mask:0xf bound_ctrl:1
	v_pk_fma_f32 v[122:123], v[122:123], v[16:17], v[216:217] op_sel_hi:[1,0,1]
	s_nop 0
	v_pk_mul_f32 v[216:217], v[122:123], v[6:7] op_sel_hi:[1,0]
	s_nop 0
	v_pk_fma_f32 v[122:123], v[122:123], v[6:7], v[216:217] op_sel:[1,1,0] op_sel_hi:[0,1,1] neg_hi:[0,1,0]
	s_nop 1
	v_mov_b32_dpp v216, v122 quad_perm:[2,3,0,1] row_mask:0xf bank_mask:0xf bound_ctrl:1
	v_mov_b32_dpp v217, v123 quad_perm:[2,3,0,1] row_mask:0xf bank_mask:0xf bound_ctrl:1
	v_pk_fma_f32 v[122:123], v[10:11], v[122:123], v[216:217] op_sel_hi:[0,1,1]
	v_pk_mul_f32 v[216:217], v[122:123], v[4:5] op_sel_hi:[1,0]
	s_nop 0
	v_pk_fma_f32 v[122:123], v[122:123], v[4:5], v[216:217] op_sel:[1,1,0] op_sel_hi:[0,1,1] neg_hi:[0,1,0]
	ds_swizzle_b32 v216, v122 offset:swizzle(SWAP,4)
	ds_swizzle_b32 v217, v123 offset:swizzle(SWAP,4)
	s_waitcnt lgkmcnt(0)
	v_pk_fma_f32 v[122:123], v[8:9], v[122:123], v[216:217] op_sel:[1,0,0]
	s_nop 0
	v_pk_mul_f32 v[216:217], v[122:123], v[2:3] op_sel_hi:[1,0]
	s_nop 0
	v_pk_fma_f32 v[122:123], v[122:123], v[2:3], v[216:217] op_sel:[1,1,0] op_sel_hi:[0,1,1] neg_hi:[0,1,0]
	s_nop 1
	v_mov_b32_dpp v216, v122 row_ror:8 row_mask:0xf bank_mask:0xf bound_ctrl:1
	v_mov_b32_dpp v217, v123 row_ror:8 row_mask:0xf bank_mask:0xf bound_ctrl:1
	v_pk_fma_f32 v[122:123], v[8:9], v[122:123], v[216:217] op_sel_hi:[0,1,1]
	v_mov_b32_dpp v216, v132 quad_perm:[1,0,3,2] row_mask:0xf bank_mask:0xf bound_ctrl:1
	v_mov_b32_dpp v217, v133 quad_perm:[1,0,3,2] row_mask:0xf bank_mask:0xf bound_ctrl:1
	v_pk_fma_f32 v[132:133], v[132:133], v[16:17], v[216:217] op_sel_hi:[1,0,1]
	s_nop 0
	v_pk_mul_f32 v[216:217], v[132:133], v[6:7] op_sel_hi:[1,0]
	s_nop 0
	v_pk_fma_f32 v[132:133], v[132:133], v[6:7], v[216:217] op_sel:[1,1,0] op_sel_hi:[0,1,1] neg_hi:[0,1,0]
	s_nop 1
	v_mov_b32_dpp v216, v132 quad_perm:[2,3,0,1] row_mask:0xf bank_mask:0xf bound_ctrl:1
	v_mov_b32_dpp v217, v133 quad_perm:[2,3,0,1] row_mask:0xf bank_mask:0xf bound_ctrl:1
	v_pk_fma_f32 v[132:133], v[10:11], v[132:133], v[216:217] op_sel_hi:[0,1,1]
	v_pk_mul_f32 v[216:217], v[132:133], v[4:5] op_sel_hi:[1,0]
	s_nop 0
	v_pk_fma_f32 v[132:133], v[132:133], v[4:5], v[216:217] op_sel:[1,1,0] op_sel_hi:[0,1,1] neg_hi:[0,1,0]
	ds_swizzle_b32 v216, v132 offset:swizzle(SWAP,4)
	ds_swizzle_b32 v217, v133 offset:swizzle(SWAP,4)
	s_waitcnt lgkmcnt(0)
; __device__ __forceinline__ float lx1(float v) { return __int_as_float(__builtin_amdgcn_update_dpp(0, __float_as_int(v), 0xB1, 0xF, 0xF, true)); }
; __device__ __forceinline__ float lx2(float v) { return __int_as_float(__builtin_amdgcn_update_dpp(0, __float_as_int(v), 0x4E, 0xF, 0xF, true)); }
; __device__ __forceinline__ float lx4(float v) { return __int_as_float(__builtin_amdgcn_ds_swizzle(__float_as_int(v), 0x101F)); }
; __device__ __forceinline__ float lx8(float v) { return __int_as_float(__builtin_amdgcn_update_dpp(0, __float_as_int(v), 0x128, 0xF, 0xF, true)); }
; __device__ __forceinline__ void fft_inverse(f2 (&x)[32], LAS f2* X, int t, LAS const float* W1, LAS const M2C* MC) {
;     ...
;     for (int p = 0; p < 32; ++p) {
;         f2 v = x[p], pr;
;         pr = (f2){lx1(v.x), lx1(v.y)}; v = cmulrc(pr + v * c.s1, t2);
;         pr = (f2){lx2(v.x), lx2(v.y)}; v = cmulrc(pr + v * c.s2, t4);
;         pr = (f2){lx4(v.x), lx4(v.y)}; v = cmulrc(pr + v * c.s4, t8);
;         pr = (f2){lx8(v.x), lx8(v.y)}; x[p] = pr + v * c.s8;
;     }
	v_pk_fma_f32 v[132:133], v[8:9], v[132:133], v[216:217] op_sel:[1,0,0]
	s_nop 0
	v_pk_mul_f32 v[216:217], v[132:133], v[2:3] op_sel_hi:[1,0]
	s_nop 0
	v_pk_fma_f32 v[132:133], v[132:133], v[2:3], v[216:217] op_sel:[1,1,0] op_sel_hi:[0,1,1] neg_hi:[0,1,0]
	s_nop 1
	v_mov_b32_dpp v216, v132 row_ror:8 row_mask:0xf bank_mask:0xf bound_ctrl:1
	v_mov_b32_dpp v217, v133 row_ror:8 row_mask:0xf bank_mask:0xf bound_ctrl:1
	v_pk_fma_f32 v[132:133], v[8:9], v[132:133], v[216:217] op_sel_hi:[0,1,1]
	v_mov_b32_dpp v216, v130 quad_perm:[1,0,3,2] row_mask:0xf bank_mask:0xf bound_ctrl:1
	v_mov_b32_dpp v217, v131 quad_perm:[1,0,3,2] row_mask:0xf bank_mask:0xf bound_ctrl:1
	v_pk_fma_f32 v[130:131], v[130:131], v[16:17], v[216:217] op_sel_hi:[1,0,1]
	s_nop 0
	v_pk_mul_f32 v[216:217], v[130:131], v[6:7] op_sel_hi:[1,0]
	s_nop 0
	v_pk_fma_f32 v[130:131], v[130:131], v[6:7], v[216:217] op_sel:[1,1,0] op_sel_hi:[0,1,1] neg_hi:[0,1,0]
	s_nop 1
	v_mov_b32_dpp v216, v130 quad_perm:[2,3,0,1] row_mask:0xf bank_mask:0xf bound_ctrl:1
	v_mov_b32_dpp v217, v131 quad_perm:[2,3,0,1] row_mask:0xf bank_mask:0xf bound_ctrl:1
	v_pk_fma_f32 v[130:131], v[10:11], v[130:131], v[216:217] op_sel_hi:[0,1,1]
	v_pk_mul_f32 v[216:217], v[130:131], v[4:5] op_sel_hi:[1,0]
	s_nop 0
	v_pk_fma_f32 v[130:131], v[130:131], v[4:5], v[216:217] op_sel:[1,1,0] op_sel_hi:[0,1,1] neg_hi:[0,1,0]
	ds_swizzle_b32 v216, v130 offset:swizzle(SWAP,4)
	ds_swizzle_b32 v217, v131 offset:swizzle(SWAP,4)
	s_waitcnt lgkmcnt(0)
	v_pk_fma_f32 v[130:131], v[8:9], v[130:131], v[216:217] op_sel:[1,0,0]
	s_nop 0
	v_pk_mul_f32 v[216:217], v[130:131], v[2:3] op_sel_hi:[1,0]
	s_nop 0
	v_pk_fma_f32 v[130:131], v[130:131], v[2:3], v[216:217] op_sel:[1,1,0] op_sel_hi:[0,1,1] neg_hi:[0,1,0]
	s_nop 1
	v_mov_b32_dpp v216, v130 row_ror:8 row_mask:0xf bank_mask:0xf bound_ctrl:1
	v_mov_b32_dpp v217, v131 row_ror:8 row_mask:0xf bank_mask:0xf bound_ctrl:1
	v_pk_fma_f32 v[130:131], v[8:9], v[130:131], v[216:217] op_sel_hi:[0,1,1]
	v_mov_b32_dpp v216, v142 quad_perm:[1,0,3,2] row_mask:0xf bank_mask:0xf bound_ctrl:1
	v_mov_b32_dpp v217, v143 quad_perm:[1,0,3,2] row_mask:0xf bank_mask:0xf bound_ctrl:1
	v_pk_fma_f32 v[142:143], v[142:143], v[16:17], v[216:217] op_sel_hi:[1,0,1]
	s_nop 0
	v_pk_mul_f32 v[216:217], v[142:143], v[6:7] op_sel_hi:[1,0]
	s_nop 0
	v_pk_fma_f32 v[142:143], v[142:143], v[6:7], v[216:217] op_sel:[1,1,0] op_sel_hi:[0,1,1] neg_hi:[0,1,0]
	s_nop 1
	v_mov_b32_dpp v216, v142 quad_perm:[2,3,0,1] row_mask:0xf bank_mask:0xf bound_ctrl:1
	v_mov_b32_dpp v217, v143 quad_perm:[2,3,0,1] row_mask:0xf bank_mask:0xf bound_ctrl:1
	v_pk_fma_f32 v[142:143], v[10:11], v[142:143], v[216:217] op_sel_hi:[0,1,1]
	v_pk_mul_f32 v[216:217], v[142:143], v[4:5] op_sel_hi:[1,0]
	s_nop 0
	v_pk_fma_f32 v[142:143], v[142:143], v[4:5], v[216:217] op_sel:[1,1,0] op_sel_hi:[0,1,1] neg_hi:[0,1,0]
	ds_swizzle_b32 v216, v142 offset:swizzle(SWAP,4)
	ds_swizzle_b32 v217, v143 offset:swizzle(SWAP,4)
	s_waitcnt lgkmcnt(0)
	v_pk_fma_f32 v[142:143], v[8:9], v[142:143], v[216:217] op_sel:[1,0,0]
	s_nop 0
	v_pk_mul_f32 v[216:217], v[142:143], v[2:3] op_sel_hi:[1,0]
	s_nop 0
	v_pk_fma_f32 v[142:143], v[142:143], v[2:3], v[216:217] op_sel:[1,1,0] op_sel_hi:[0,1,1] neg_hi:[0,1,0]
	s_nop 1
	v_mov_b32_dpp v216, v142 row_ror:8 row_mask:0xf bank_mask:0xf bound_ctrl:1
	v_mov_b32_dpp v217, v143 row_ror:8 row_mask:0xf bank_mask:0xf bound_ctrl:1
	v_pk_fma_f32 v[142:143], v[8:9], v[142:143], v[216:217] op_sel_hi:[0,1,1]
	v_mov_b32_dpp v216, v138 quad_perm:[1,0,3,2] row_mask:0xf bank_mask:0xf bound_ctrl:1
	v_mov_b32_dpp v217, v139 quad_perm:[1,0,3,2] row_mask:0xf bank_mask:0xf bound_ctrl:1
	v_pk_fma_f32 v[138:139], v[138:139], v[16:17], v[216:217] op_sel_hi:[1,0,1]
	s_nop 0
	v_pk_mul_f32 v[216:217], v[138:139], v[6:7] op_sel_hi:[1,0]
	s_nop 0
	v_pk_fma_f32 v[138:139], v[138:139], v[6:7], v[216:217] op_sel:[1,1,0] op_sel_hi:[0,1,1] neg_hi:[0,1,0]
	s_nop 1
	v_mov_b32_dpp v216, v138 quad_perm:[2,3,0,1] row_mask:0xf bank_mask:0xf bound_ctrl:1
	v_mov_b32_dpp v217, v139 quad_perm:[2,3,0,1] row_mask:0xf bank_mask:0xf bound_ctrl:1
	v_pk_fma_f32 v[138:139], v[10:11], v[138:139], v[216:217] op_sel_hi:[0,1,1]
	v_pk_mul_f32 v[216:217], v[138:139], v[4:5] op_sel_hi:[1,0]
	s_nop 0
	v_pk_fma_f32 v[138:139], v[138:139], v[4:5], v[216:217] op_sel:[1,1,0] op_sel_hi:[0,1,1] neg_hi:[0,1,0]
	ds_swizzle_b32 v216, v138 offset:swizzle(SWAP,4)
	ds_swizzle_b32 v217, v139 offset:swizzle(SWAP,4)
	s_waitcnt lgkmcnt(0)
	v_pk_fma_f32 v[138:139], v[8:9], v[138:139], v[216:217] op_sel:[1,0,0]
	s_nop 0
	v_pk_mul_f32 v[216:217], v[138:139], v[2:3] op_sel_hi:[1,0]
	s_nop 0
	v_pk_fma_f32 v[138:139], v[138:139], v[2:3], v[216:217] op_sel:[1,1,0] op_sel_hi:[0,1,1] neg_hi:[0,1,0]
	s_nop 1
	v_mov_b32_dpp v216, v138 row_ror:8 row_mask:0xf bank_mask:0xf bound_ctrl:1
	v_mov_b32_dpp v217, v139 row_ror:8 row_mask:0xf bank_mask:0xf bound_ctrl:1
	v_pk_fma_f32 v[138:139], v[8:9], v[138:139], v[216:217] op_sel_hi:[0,1,1]
	v_mov_b32_dpp v216, v148 quad_perm:[1,0,3,2] row_mask:0xf bank_mask:0xf bound_ctrl:1
	v_mov_b32_dpp v217, v149 quad_perm:[1,0,3,2] row_mask:0xf bank_mask:0xf bound_ctrl:1
	v_pk_fma_f32 v[148:149], v[148:149], v[16:17], v[216:217] op_sel_hi:[1,0,1]
	s_nop 0
	v_pk_mul_f32 v[216:217], v[148:149], v[6:7] op_sel_hi:[1,0]
	s_nop 0
	v_pk_fma_f32 v[148:149], v[148:149], v[6:7], v[216:217] op_sel:[1,1,0] op_sel_hi:[0,1,1] neg_hi:[0,1,0]
	s_nop 1
	v_mov_b32_dpp v216, v148 quad_perm:[2,3,0,1] row_mask:0xf bank_mask:0xf bound_ctrl:1
	v_mov_b32_dpp v217, v149 quad_perm:[2,3,0,1] row_mask:0xf bank_mask:0xf bound_ctrl:1
	v_pk_fma_f32 v[148:149], v[10:11], v[148:149], v[216:217] op_sel_hi:[0,1,1]
	v_pk_mul_f32 v[216:217], v[148:149], v[4:5] op_sel_hi:[1,0]
	s_nop 0
	v_pk_fma_f32 v[148:149], v[148:149], v[4:5], v[216:217] op_sel:[1,1,0] op_sel_hi:[0,1,1] neg_hi:[0,1,0]
	ds_swizzle_b32 v216, v148 offset:swizzle(SWAP,4)
	ds_swizzle_b32 v217, v149 offset:swizzle(SWAP,4)
	s_waitcnt lgkmcnt(0)
; __device__ __forceinline__ float lx1(float v) { return __int_as_float(__builtin_amdgcn_update_dpp(0, __float_as_int(v), 0xB1, 0xF, 0xF, true)); }
; __device__ __forceinline__ float lx2(float v) { return __int_as_float(__builtin_amdgcn_update_dpp(0, __float_as_int(v), 0x4E, 0xF, 0xF, true)); }
; __device__ __forceinline__ float lx4(float v) { return __int_as_float(__builtin_amdgcn_ds_swizzle(__float_as_int(v), 0x101F)); }
; __device__ __forceinline__ float lx8(float v) { return __int_as_float(__builtin_amdgcn_update_dpp(0, __float_as_int(v), 0x128, 0xF, 0xF, true)); }
; __device__ __forceinline__ void fft_inverse(f2 (&x)[32], LAS f2* X, int t, LAS const float* W1, LAS const M2C* MC) {
;     ...
;     for (int p = 0; p < 32; ++p) {
;         f2 v = x[p], pr;
;         pr = (f2){lx1(v.x), lx1(v.y)}; v = cmulrc(pr + v * c.s1, t2);
;         pr = (f2){lx2(v.x), lx2(v.y)}; v = cmulrc(pr + v * c.s2, t4);
;         pr = (f2){lx4(v.x), lx4(v.y)}; v = cmulrc(pr + v * c.s4, t8);
;         pr = (f2){lx8(v.x), lx8(v.y)}; x[p] = pr + v * c.s8;
;     }
	v_pk_fma_f32 v[148:149], v[8:9], v[148:149], v[216:217] op_sel:[1,0,0]
	s_nop 0
	v_pk_mul_f32 v[216:217], v[148:149], v[2:3] op_sel_hi:[1,0]
	s_nop 0
	v_pk_fma_f32 v[148:149], v[148:149], v[2:3], v[216:217] op_sel:[1,1,0] op_sel_hi:[0,1,1] neg_hi:[0,1,0]
	s_nop 1
	v_mov_b32_dpp v216, v148 row_ror:8 row_mask:0xf bank_mask:0xf bound_ctrl:1
	v_mov_b32_dpp v217, v149 row_ror:8 row_mask:0xf bank_mask:0xf bound_ctrl:1
	v_pk_fma_f32 v[148:149], v[8:9], v[148:149], v[216:217] op_sel_hi:[0,1,1]
	v_mov_b32_dpp v216, v146 quad_perm:[1,0,3,2] row_mask:0xf bank_mask:0xf bound_ctrl:1
	v_mov_b32_dpp v217, v147 quad_perm:[1,0,3,2] row_mask:0xf bank_mask:0xf bound_ctrl:1
	v_pk_fma_f32 v[146:147], v[146:147], v[16:17], v[216:217] op_sel_hi:[1,0,1]
	s_nop 0
	v_pk_mul_f32 v[216:217], v[146:147], v[6:7] op_sel_hi:[1,0]
	s_nop 0
	v_pk_fma_f32 v[146:147], v[146:147], v[6:7], v[216:217] op_sel:[1,1,0] op_sel_hi:[0,1,1] neg_hi:[0,1,0]
	s_nop 1
	v_mov_b32_dpp v216, v146 quad_perm:[2,3,0,1] row_mask:0xf bank_mask:0xf bound_ctrl:1
	v_mov_b32_dpp v217, v147 quad_perm:[2,3,0,1] row_mask:0xf bank_mask:0xf bound_ctrl:1
	v_pk_fma_f32 v[146:147], v[10:11], v[146:147], v[216:217] op_sel_hi:[0,1,1]
	v_pk_mul_f32 v[216:217], v[146:147], v[4:5] op_sel_hi:[1,0]
	s_nop 0
	v_pk_fma_f32 v[146:147], v[146:147], v[4:5], v[216:217] op_sel:[1,1,0] op_sel_hi:[0,1,1] neg_hi:[0,1,0]
	ds_swizzle_b32 v216, v146 offset:swizzle(SWAP,4)
	ds_swizzle_b32 v217, v147 offset:swizzle(SWAP,4)
	s_waitcnt lgkmcnt(0)
	v_pk_fma_f32 v[146:147], v[8:9], v[146:147], v[216:217] op_sel:[1,0,0]
	s_nop 0
	v_pk_mul_f32 v[216:217], v[146:147], v[2:3] op_sel_hi:[1,0]
	s_nop 0
	v_pk_fma_f32 v[146:147], v[146:147], v[2:3], v[216:217] op_sel:[1,1,0] op_sel_hi:[0,1,1] neg_hi:[0,1,0]
	s_nop 1
	v_mov_b32_dpp v216, v146 row_ror:8 row_mask:0xf bank_mask:0xf bound_ctrl:1
	v_mov_b32_dpp v217, v147 row_ror:8 row_mask:0xf bank_mask:0xf bound_ctrl:1
	v_pk_fma_f32 v[146:147], v[8:9], v[146:147], v[216:217] op_sel_hi:[0,1,1]
	v_mov_b32_dpp v216, v144 quad_perm:[1,0,3,2] row_mask:0xf bank_mask:0xf bound_ctrl:1
	v_mov_b32_dpp v217, v145 quad_perm:[1,0,3,2] row_mask:0xf bank_mask:0xf bound_ctrl:1
	v_pk_fma_f32 v[144:145], v[144:145], v[16:17], v[216:217] op_sel_hi:[1,0,1]
	s_nop 0
	v_pk_mul_f32 v[216:217], v[144:145], v[6:7] op_sel_hi:[1,0]
	s_nop 0
	v_pk_fma_f32 v[144:145], v[144:145], v[6:7], v[216:217] op_sel:[1,1,0] op_sel_hi:[0,1,1] neg_hi:[0,1,0]
	s_nop 1
	v_mov_b32_dpp v216, v144 quad_perm:[2,3,0,1] row_mask:0xf bank_mask:0xf bound_ctrl:1
	v_mov_b32_dpp v217, v145 quad_perm:[2,3,0,1] row_mask:0xf bank_mask:0xf bound_ctrl:1
	v_pk_fma_f32 v[144:145], v[10:11], v[144:145], v[216:217] op_sel_hi:[0,1,1]
	v_pk_mul_f32 v[216:217], v[144:145], v[4:5] op_sel_hi:[1,0]
	s_nop 0
	v_pk_fma_f32 v[144:145], v[144:145], v[4:5], v[216:217] op_sel:[1,1,0] op_sel_hi:[0,1,1] neg_hi:[0,1,0]
	ds_swizzle_b32 v216, v144 offset:swizzle(SWAP,4)
	ds_swizzle_b32 v217, v145 offset:swizzle(SWAP,4)
	s_waitcnt lgkmcnt(0)
	v_pk_fma_f32 v[144:145], v[8:9], v[144:145], v[216:217] op_sel:[1,0,0]
	s_nop 0
	v_pk_mul_f32 v[216:217], v[144:145], v[2:3] op_sel_hi:[1,0]
	s_nop 0
	v_pk_fma_f32 v[144:145], v[144:145], v[2:3], v[216:217] op_sel:[1,1,0] op_sel_hi:[0,1,1] neg_hi:[0,1,0]
	s_nop 1
	v_mov_b32_dpp v216, v144 row_ror:8 row_mask:0xf bank_mask:0xf bound_ctrl:1
	v_mov_b32_dpp v217, v145 row_ror:8 row_mask:0xf bank_mask:0xf bound_ctrl:1
	v_pk_fma_f32 v[144:145], v[8:9], v[144:145], v[216:217] op_sel_hi:[0,1,1]
	v_mov_b32_dpp v216, v140 quad_perm:[1,0,3,2] row_mask:0xf bank_mask:0xf bound_ctrl:1
	v_mov_b32_dpp v217, v141 quad_perm:[1,0,3,2] row_mask:0xf bank_mask:0xf bound_ctrl:1
	v_pk_fma_f32 v[140:141], v[140:141], v[16:17], v[216:217] op_sel_hi:[1,0,1]
	s_nop 0
	v_pk_mul_f32 v[216:217], v[140:141], v[6:7] op_sel_hi:[1,0]
	s_nop 0
	v_pk_fma_f32 v[140:141], v[140:141], v[6:7], v[216:217] op_sel:[1,1,0] op_sel_hi:[0,1,1] neg_hi:[0,1,0]
	s_nop 1
	v_mov_b32_dpp v216, v140 quad_perm:[2,3,0,1] row_mask:0xf bank_mask:0xf bound_ctrl:1
	v_mov_b32_dpp v217, v141 quad_perm:[2,3,0,1] row_mask:0xf bank_mask:0xf bound_ctrl:1
	v_pk_fma_f32 v[140:141], v[10:11], v[140:141], v[216:217] op_sel_hi:[0,1,1]
	v_pk_mul_f32 v[216:217], v[140:141], v[4:5] op_sel_hi:[1,0]
	s_nop 0
	v_pk_fma_f32 v[140:141], v[140:141], v[4:5], v[216:217] op_sel:[1,1,0] op_sel_hi:[0,1,1] neg_hi:[0,1,0]
	ds_swizzle_b32 v216, v140 offset:swizzle(SWAP,4)
	ds_swizzle_b32 v217, v141 offset:swizzle(SWAP,4)
	s_waitcnt lgkmcnt(0)
	v_pk_fma_f32 v[140:141], v[8:9], v[140:141], v[216:217] op_sel:[1,0,0]
	s_nop 0
	v_pk_mul_f32 v[216:217], v[140:141], v[2:3] op_sel_hi:[1,0]
	s_nop 0
	v_pk_fma_f32 v[140:141], v[140:141], v[2:3], v[216:217] op_sel:[1,1,0] op_sel_hi:[0,1,1] neg_hi:[0,1,0]
	s_nop 1
	v_mov_b32_dpp v216, v140 row_ror:8 row_mask:0xf bank_mask:0xf bound_ctrl:1
	v_mov_b32_dpp v217, v141 row_ror:8 row_mask:0xf bank_mask:0xf bound_ctrl:1
	v_pk_fma_f32 v[140:141], v[8:9], v[140:141], v[216:217] op_sel_hi:[0,1,1]
	v_mov_b32_dpp v216, v136 quad_perm:[1,0,3,2] row_mask:0xf bank_mask:0xf bound_ctrl:1
	v_mov_b32_dpp v217, v137 quad_perm:[1,0,3,2] row_mask:0xf bank_mask:0xf bound_ctrl:1
	v_pk_fma_f32 v[136:137], v[136:137], v[16:17], v[216:217] op_sel_hi:[1,0,1]
	s_nop 0
	v_pk_mul_f32 v[216:217], v[136:137], v[6:7] op_sel_hi:[1,0]
	s_nop 0
	v_pk_fma_f32 v[136:137], v[136:137], v[6:7], v[216:217] op_sel:[1,1,0] op_sel_hi:[0,1,1] neg_hi:[0,1,0]
	s_nop 1
	v_mov_b32_dpp v216, v136 quad_perm:[2,3,0,1] row_mask:0xf bank_mask:0xf bound_ctrl:1
	v_mov_b32_dpp v217, v137 quad_perm:[2,3,0,1] row_mask:0xf bank_mask:0xf bound_ctrl:1
	v_pk_fma_f32 v[136:137], v[10:11], v[136:137], v[216:217] op_sel_hi:[0,1,1]
	v_pk_mul_f32 v[216:217], v[136:137], v[4:5] op_sel_hi:[1,0]
	s_nop 0
	v_pk_fma_f32 v[136:137], v[136:137], v[4:5], v[216:217] op_sel:[1,1,0] op_sel_hi:[0,1,1] neg_hi:[0,1,0]
	ds_swizzle_b32 v216, v136 offset:swizzle(SWAP,4)
	ds_swizzle_b32 v217, v137 offset:swizzle(SWAP,4)
	s_waitcnt lgkmcnt(0)
; __device__ __forceinline__ float lx1(float v) { return __int_as_float(__builtin_amdgcn_update_dpp(0, __float_as_int(v), 0xB1, 0xF, 0xF, true)); }
; __device__ __forceinline__ float lx2(float v) { return __int_as_float(__builtin_amdgcn_update_dpp(0, __float_as_int(v), 0x4E, 0xF, 0xF, true)); }
; __device__ __forceinline__ float lx4(float v) { return __int_as_float(__builtin_amdgcn_ds_swizzle(__float_as_int(v), 0x101F)); }
; __device__ __forceinline__ float lx8(float v) { return __int_as_float(__builtin_amdgcn_update_dpp(0, __float_as_int(v), 0x128, 0xF, 0xF, true)); }
; __device__ __forceinline__ void fft_inverse(f2 (&x)[32], LAS f2* X, int t, LAS const float* W1, LAS const M2C* MC) {
;     ...
;     for (int p = 0; p < 32; ++p) {
;         f2 v = x[p], pr;
;         pr = (f2){lx1(v.x), lx1(v.y)}; v = cmulrc(pr + v * c.s1, t2);
;         pr = (f2){lx2(v.x), lx2(v.y)}; v = cmulrc(pr + v * c.s2, t4);
;         pr = (f2){lx4(v.x), lx4(v.y)}; v = cmulrc(pr + v * c.s4, t8);
;         pr = (f2){lx8(v.x), lx8(v.y)}; x[p] = pr + v * c.s8;
;     }
	v_pk_fma_f32 v[136:137], v[8:9], v[136:137], v[216:217] op_sel:[1,0,0]
	s_nop 0
	v_pk_mul_f32 v[216:217], v[136:137], v[2:3] op_sel_hi:[1,0]
	s_nop 0
	v_pk_fma_f32 v[136:137], v[136:137], v[2:3], v[216:217] op_sel:[1,1,0] op_sel_hi:[0,1,1] neg_hi:[0,1,0]
	s_nop 1
	v_mov_b32_dpp v216, v136 row_ror:8 row_mask:0xf bank_mask:0xf bound_ctrl:1
	v_mov_b32_dpp v217, v137 row_ror:8 row_mask:0xf bank_mask:0xf bound_ctrl:1
	v_pk_fma_f32 v[136:137], v[8:9], v[136:137], v[216:217] op_sel_hi:[0,1,1]
	v_mov_b32_dpp v216, v134 quad_perm:[1,0,3,2] row_mask:0xf bank_mask:0xf bound_ctrl:1
	v_mov_b32_dpp v217, v135 quad_perm:[1,0,3,2] row_mask:0xf bank_mask:0xf bound_ctrl:1
	v_pk_fma_f32 v[134:135], v[134:135], v[16:17], v[216:217] op_sel_hi:[1,0,1]
	s_nop 0
	v_pk_mul_f32 v[216:217], v[134:135], v[6:7] op_sel_hi:[1,0]
	s_nop 0
	v_pk_fma_f32 v[134:135], v[134:135], v[6:7], v[216:217] op_sel:[1,1,0] op_sel_hi:[0,1,1] neg_hi:[0,1,0]
	s_nop 1
	v_mov_b32_dpp v216, v134 quad_perm:[2,3,0,1] row_mask:0xf bank_mask:0xf bound_ctrl:1
	v_mov_b32_dpp v217, v135 quad_perm:[2,3,0,1] row_mask:0xf bank_mask:0xf bound_ctrl:1
	v_pk_fma_f32 v[134:135], v[10:11], v[134:135], v[216:217] op_sel_hi:[0,1,1]
	v_pk_mul_f32 v[216:217], v[134:135], v[4:5] op_sel_hi:[1,0]
	s_nop 0
	v_pk_fma_f32 v[134:135], v[134:135], v[4:5], v[216:217] op_sel:[1,1,0] op_sel_hi:[0,1,1] neg_hi:[0,1,0]
	ds_swizzle_b32 v216, v134 offset:swizzle(SWAP,4)
	ds_swizzle_b32 v217, v135 offset:swizzle(SWAP,4)
	s_waitcnt lgkmcnt(0)
	v_pk_fma_f32 v[134:135], v[8:9], v[134:135], v[216:217] op_sel:[1,0,0]
	s_nop 0
	v_pk_mul_f32 v[216:217], v[134:135], v[2:3] op_sel_hi:[1,0]
	s_nop 0
	v_pk_fma_f32 v[134:135], v[134:135], v[2:3], v[216:217] op_sel:[1,1,0] op_sel_hi:[0,1,1] neg_hi:[0,1,0]
	s_nop 1
	v_mov_b32_dpp v216, v134 row_ror:8 row_mask:0xf bank_mask:0xf bound_ctrl:1
	v_mov_b32_dpp v217, v135 row_ror:8 row_mask:0xf bank_mask:0xf bound_ctrl:1
	v_pk_fma_f32 v[134:135], v[8:9], v[134:135], v[216:217] op_sel_hi:[0,1,1]
	v_mov_b32_dpp v216, v128 quad_perm:[1,0,3,2] row_mask:0xf bank_mask:0xf bound_ctrl:1
	v_mov_b32_dpp v217, v129 quad_perm:[1,0,3,2] row_mask:0xf bank_mask:0xf bound_ctrl:1
	v_pk_fma_f32 v[128:129], v[128:129], v[16:17], v[216:217] op_sel_hi:[1,0,1]
	s_nop 0
	v_pk_mul_f32 v[216:217], v[128:129], v[6:7] op_sel_hi:[1,0]
	s_nop 0
	v_pk_fma_f32 v[128:129], v[128:129], v[6:7], v[216:217] op_sel:[1,1,0] op_sel_hi:[0,1,1] neg_hi:[0,1,0]
	s_nop 1
	v_mov_b32_dpp v216, v128 quad_perm:[2,3,0,1] row_mask:0xf bank_mask:0xf bound_ctrl:1
	v_mov_b32_dpp v217, v129 quad_perm:[2,3,0,1] row_mask:0xf bank_mask:0xf bound_ctrl:1
	v_pk_fma_f32 v[128:129], v[10:11], v[128:129], v[216:217] op_sel_hi:[0,1,1]
	v_pk_mul_f32 v[216:217], v[128:129], v[4:5] op_sel_hi:[1,0]
	s_nop 0
	v_pk_fma_f32 v[128:129], v[128:129], v[4:5], v[216:217] op_sel:[1,1,0] op_sel_hi:[0,1,1] neg_hi:[0,1,0]
	ds_swizzle_b32 v216, v128 offset:swizzle(SWAP,4)
	ds_swizzle_b32 v217, v129 offset:swizzle(SWAP,4)
	s_waitcnt lgkmcnt(0)
	v_pk_fma_f32 v[128:129], v[8:9], v[128:129], v[216:217] op_sel:[1,0,0]
	s_nop 0
	v_pk_mul_f32 v[216:217], v[128:129], v[2:3] op_sel_hi:[1,0]
	s_nop 0
	v_pk_fma_f32 v[128:129], v[128:129], v[2:3], v[216:217] op_sel:[1,1,0] op_sel_hi:[0,1,1] neg_hi:[0,1,0]
	s_nop 1
	v_mov_b32_dpp v216, v128 row_ror:8 row_mask:0xf bank_mask:0xf bound_ctrl:1
	v_mov_b32_dpp v217, v129 row_ror:8 row_mask:0xf bank_mask:0xf bound_ctrl:1
	v_pk_fma_f32 v[128:129], v[8:9], v[128:129], v[216:217] op_sel_hi:[0,1,1]
	v_mov_b32_dpp v216, v124 quad_perm:[1,0,3,2] row_mask:0xf bank_mask:0xf bound_ctrl:1
	v_mov_b32_dpp v217, v125 quad_perm:[1,0,3,2] row_mask:0xf bank_mask:0xf bound_ctrl:1
	v_pk_fma_f32 v[124:125], v[124:125], v[16:17], v[216:217] op_sel_hi:[1,0,1]
	s_nop 0
	v_pk_mul_f32 v[216:217], v[124:125], v[6:7] op_sel_hi:[1,0]
	s_nop 0
	v_pk_fma_f32 v[124:125], v[124:125], v[6:7], v[216:217] op_sel:[1,1,0] op_sel_hi:[0,1,1] neg_hi:[0,1,0]
	s_nop 1
	v_mov_b32_dpp v216, v124 quad_perm:[2,3,0,1] row_mask:0xf bank_mask:0xf bound_ctrl:1
	v_mov_b32_dpp v217, v125 quad_perm:[2,3,0,1] row_mask:0xf bank_mask:0xf bound_ctrl:1
	v_pk_fma_f32 v[124:125], v[10:11], v[124:125], v[216:217] op_sel_hi:[0,1,1]
	v_pk_mul_f32 v[216:217], v[124:125], v[4:5] op_sel_hi:[1,0]
	s_nop 0
	v_pk_fma_f32 v[124:125], v[124:125], v[4:5], v[216:217] op_sel:[1,1,0] op_sel_hi:[0,1,1] neg_hi:[0,1,0]
	ds_swizzle_b32 v216, v124 offset:swizzle(SWAP,4)
	ds_swizzle_b32 v217, v125 offset:swizzle(SWAP,4)
	s_waitcnt lgkmcnt(0)
	v_pk_fma_f32 v[124:125], v[8:9], v[124:125], v[216:217] op_sel:[1,0,0]
	s_nop 0
	v_pk_mul_f32 v[216:217], v[124:125], v[2:3] op_sel_hi:[1,0]
	s_nop 0
	v_pk_fma_f32 v[124:125], v[124:125], v[2:3], v[216:217] op_sel:[1,1,0] op_sel_hi:[0,1,1] neg_hi:[0,1,0]
	s_nop 1
	v_mov_b32_dpp v216, v124 row_ror:8 row_mask:0xf bank_mask:0xf bound_ctrl:1
	v_mov_b32_dpp v217, v125 row_ror:8 row_mask:0xf bank_mask:0xf bound_ctrl:1
	v_pk_fma_f32 v[124:125], v[8:9], v[124:125], v[216:217] op_sel_hi:[0,1,1]
	v_mov_b32_dpp v216, v120 quad_perm:[1,0,3,2] row_mask:0xf bank_mask:0xf bound_ctrl:1
	v_mov_b32_dpp v217, v121 quad_perm:[1,0,3,2] row_mask:0xf bank_mask:0xf bound_ctrl:1
	v_pk_fma_f32 v[120:121], v[120:121], v[16:17], v[216:217] op_sel_hi:[1,0,1]
	s_nop 0
	v_pk_mul_f32 v[216:217], v[120:121], v[6:7] op_sel_hi:[1,0]
	s_nop 0
	v_pk_fma_f32 v[120:121], v[120:121], v[6:7], v[216:217] op_sel:[1,1,0] op_sel_hi:[0,1,1] neg_hi:[0,1,0]
	s_nop 1
	v_mov_b32_dpp v216, v120 quad_perm:[2,3,0,1] row_mask:0xf bank_mask:0xf bound_ctrl:1
	v_mov_b32_dpp v217, v121 quad_perm:[2,3,0,1] row_mask:0xf bank_mask:0xf bound_ctrl:1
	v_pk_fma_f32 v[120:121], v[10:11], v[120:121], v[216:217] op_sel_hi:[0,1,1]
	v_pk_mul_f32 v[216:217], v[120:121], v[4:5] op_sel_hi:[1,0]
	s_nop 0
	v_pk_fma_f32 v[120:121], v[120:121], v[4:5], v[216:217] op_sel:[1,1,0] op_sel_hi:[0,1,1] neg_hi:[0,1,0]
	ds_swizzle_b32 v216, v120 offset:swizzle(SWAP,4)
	ds_swizzle_b32 v217, v121 offset:swizzle(SWAP,4)
	s_waitcnt lgkmcnt(0)
; __device__ __forceinline__ float lx1(float v) { return __int_as_float(__builtin_amdgcn_update_dpp(0, __float_as_int(v), 0xB1, 0xF, 0xF, true)); }
; __device__ __forceinline__ float lx2(float v) { return __int_as_float(__builtin_amdgcn_update_dpp(0, __float_as_int(v), 0x4E, 0xF, 0xF, true)); }
; __device__ __forceinline__ float lx4(float v) { return __int_as_float(__builtin_amdgcn_ds_swizzle(__float_as_int(v), 0x101F)); }
; __device__ __forceinline__ float lx8(float v) { return __int_as_float(__builtin_amdgcn_update_dpp(0, __float_as_int(v), 0x128, 0xF, 0xF, true)); }
; __device__ __forceinline__ void fft_inverse(f2 (&x)[32], LAS f2* X, int t, LAS const float* W1, LAS const M2C* MC) {
;     ...
;     for (int p = 0; p < 32; ++p) {
;         f2 v = x[p], pr;
;         pr = (f2){lx1(v.x), lx1(v.y)}; v = cmulrc(pr + v * c.s1, t2);
;         pr = (f2){lx2(v.x), lx2(v.y)}; v = cmulrc(pr + v * c.s2, t4);
;         pr = (f2){lx4(v.x), lx4(v.y)}; v = cmulrc(pr + v * c.s4, t8);
;         pr = (f2){lx8(v.x), lx8(v.y)}; x[p] = pr + v * c.s8;
;     }
	v_pk_fma_f32 v[120:121], v[8:9], v[120:121], v[216:217] op_sel:[1,0,0]
	s_nop 0
	v_pk_mul_f32 v[216:217], v[120:121], v[2:3] op_sel_hi:[1,0]
	s_nop 0
	v_pk_fma_f32 v[120:121], v[120:121], v[2:3], v[216:217] op_sel:[1,1,0] op_sel_hi:[0,1,1] neg_hi:[0,1,0]
	s_nop 1
	v_mov_b32_dpp v216, v120 row_ror:8 row_mask:0xf bank_mask:0xf bound_ctrl:1
	v_mov_b32_dpp v217, v121 row_ror:8 row_mask:0xf bank_mask:0xf bound_ctrl:1
	v_pk_fma_f32 v[120:121], v[8:9], v[120:121], v[216:217] op_sel_hi:[0,1,1]
	v_mov_b32_dpp v216, v118 quad_perm:[1,0,3,2] row_mask:0xf bank_mask:0xf bound_ctrl:1
	v_mov_b32_dpp v217, v119 quad_perm:[1,0,3,2] row_mask:0xf bank_mask:0xf bound_ctrl:1
	v_pk_fma_f32 v[118:119], v[118:119], v[16:17], v[216:217] op_sel_hi:[1,0,1]
	s_nop 0
	v_pk_mul_f32 v[216:217], v[118:119], v[6:7] op_sel_hi:[1,0]
	s_nop 0
	v_pk_fma_f32 v[118:119], v[118:119], v[6:7], v[216:217] op_sel:[1,1,0] op_sel_hi:[0,1,1] neg_hi:[0,1,0]
	s_nop 1
	v_mov_b32_dpp v216, v118 quad_perm:[2,3,0,1] row_mask:0xf bank_mask:0xf bound_ctrl:1
	v_mov_b32_dpp v217, v119 quad_perm:[2,3,0,1] row_mask:0xf bank_mask:0xf bound_ctrl:1
	v_pk_fma_f32 v[118:119], v[10:11], v[118:119], v[216:217] op_sel_hi:[0,1,1]
	v_pk_mul_f32 v[216:217], v[118:119], v[4:5] op_sel_hi:[1,0]
	s_nop 0
	v_pk_fma_f32 v[118:119], v[118:119], v[4:5], v[216:217] op_sel:[1,1,0] op_sel_hi:[0,1,1] neg_hi:[0,1,0]
	ds_swizzle_b32 v216, v118 offset:swizzle(SWAP,4)
	ds_swizzle_b32 v217, v119 offset:swizzle(SWAP,4)
	s_waitcnt lgkmcnt(0)
	v_pk_fma_f32 v[118:119], v[8:9], v[118:119], v[216:217] op_sel:[1,0,0]
	s_nop 0
	v_pk_mul_f32 v[216:217], v[118:119], v[2:3] op_sel_hi:[1,0]
	s_nop 0
	v_pk_fma_f32 v[118:119], v[118:119], v[2:3], v[216:217] op_sel:[1,1,0] op_sel_hi:[0,1,1] neg_hi:[0,1,0]
	s_nop 1
	v_mov_b32_dpp v216, v118 row_ror:8 row_mask:0xf bank_mask:0xf bound_ctrl:1
	v_mov_b32_dpp v217, v119 row_ror:8 row_mask:0xf bank_mask:0xf bound_ctrl:1
	v_pk_fma_f32 v[118:119], v[8:9], v[118:119], v[216:217] op_sel_hi:[0,1,1]
	v_mov_b32_dpp v216, v116 quad_perm:[1,0,3,2] row_mask:0xf bank_mask:0xf bound_ctrl:1
	v_mov_b32_dpp v217, v117 quad_perm:[1,0,3,2] row_mask:0xf bank_mask:0xf bound_ctrl:1
	v_pk_fma_f32 v[116:117], v[116:117], v[16:17], v[216:217] op_sel_hi:[1,0,1]
	s_nop 0
	v_pk_mul_f32 v[216:217], v[116:117], v[6:7] op_sel_hi:[1,0]
	s_nop 0
	v_pk_fma_f32 v[116:117], v[116:117], v[6:7], v[216:217] op_sel:[1,1,0] op_sel_hi:[0,1,1] neg_hi:[0,1,0]
	s_nop 1
	v_mov_b32_dpp v216, v116 quad_perm:[2,3,0,1] row_mask:0xf bank_mask:0xf bound_ctrl:1
	v_mov_b32_dpp v217, v117 quad_perm:[2,3,0,1] row_mask:0xf bank_mask:0xf bound_ctrl:1
	v_pk_fma_f32 v[116:117], v[10:11], v[116:117], v[216:217] op_sel_hi:[0,1,1]
	v_pk_mul_f32 v[216:217], v[116:117], v[4:5] op_sel_hi:[1,0]
	s_nop 0
	v_pk_fma_f32 v[116:117], v[116:117], v[4:5], v[216:217] op_sel:[1,1,0] op_sel_hi:[0,1,1] neg_hi:[0,1,0]
	ds_swizzle_b32 v216, v116 offset:swizzle(SWAP,4)
	ds_swizzle_b32 v217, v117 offset:swizzle(SWAP,4)
	s_waitcnt lgkmcnt(0)
	v_pk_fma_f32 v[116:117], v[8:9], v[116:117], v[216:217] op_sel:[1,0,0]
	s_nop 0
	v_pk_mul_f32 v[216:217], v[116:117], v[2:3] op_sel_hi:[1,0]
	s_nop 0
	v_pk_fma_f32 v[116:117], v[116:117], v[2:3], v[216:217] op_sel:[1,1,0] op_sel_hi:[0,1,1] neg_hi:[0,1,0]
	s_nop 1
	v_mov_b32_dpp v216, v116 row_ror:8 row_mask:0xf bank_mask:0xf bound_ctrl:1
	v_mov_b32_dpp v217, v117 row_ror:8 row_mask:0xf bank_mask:0xf bound_ctrl:1
	v_pk_fma_f32 v[116:117], v[8:9], v[116:117], v[216:217] op_sel_hi:[0,1,1]
	v_mov_b32_dpp v216, v110 quad_perm:[1,0,3,2] row_mask:0xf bank_mask:0xf bound_ctrl:1
	v_mov_b32_dpp v217, v111 quad_perm:[1,0,3,2] row_mask:0xf bank_mask:0xf bound_ctrl:1
	v_pk_fma_f32 v[110:111], v[110:111], v[16:17], v[216:217] op_sel_hi:[1,0,1]
	s_nop 0
	v_pk_mul_f32 v[216:217], v[110:111], v[6:7] op_sel_hi:[1,0]
	s_nop 0
	v_pk_fma_f32 v[110:111], v[110:111], v[6:7], v[216:217] op_sel:[1,1,0] op_sel_hi:[0,1,1] neg_hi:[0,1,0]
	s_nop 1
	v_mov_b32_dpp v216, v110 quad_perm:[2,3,0,1] row_mask:0xf bank_mask:0xf bound_ctrl:1
	v_mov_b32_dpp v217, v111 quad_perm:[2,3,0,1] row_mask:0xf bank_mask:0xf bound_ctrl:1
	v_pk_fma_f32 v[110:111], v[10:11], v[110:111], v[216:217] op_sel_hi:[0,1,1]
	v_pk_mul_f32 v[216:217], v[110:111], v[4:5] op_sel_hi:[1,0]
	s_nop 0
	v_pk_fma_f32 v[110:111], v[110:111], v[4:5], v[216:217] op_sel:[1,1,0] op_sel_hi:[0,1,1] neg_hi:[0,1,0]
	ds_swizzle_b32 v216, v110 offset:swizzle(SWAP,4)
	ds_swizzle_b32 v217, v111 offset:swizzle(SWAP,4)
	s_waitcnt lgkmcnt(0)
	v_pk_fma_f32 v[110:111], v[8:9], v[110:111], v[216:217] op_sel:[1,0,0]
	s_nop 0
	v_pk_mul_f32 v[216:217], v[110:111], v[2:3] op_sel_hi:[1,0]
	s_nop 0
	v_pk_fma_f32 v[110:111], v[110:111], v[2:3], v[216:217] op_sel:[1,1,0] op_sel_hi:[0,1,1] neg_hi:[0,1,0]
	s_nop 1
	v_mov_b32_dpp v216, v110 row_ror:8 row_mask:0xf bank_mask:0xf bound_ctrl:1
	v_mov_b32_dpp v217, v111 row_ror:8 row_mask:0xf bank_mask:0xf bound_ctrl:1
	v_pk_fma_f32 v[110:111], v[8:9], v[110:111], v[216:217] op_sel_hi:[0,1,1]
	v_mov_b32_dpp v216, v106 quad_perm:[1,0,3,2] row_mask:0xf bank_mask:0xf bound_ctrl:1
	v_mov_b32_dpp v217, v107 quad_perm:[1,0,3,2] row_mask:0xf bank_mask:0xf bound_ctrl:1
	v_pk_fma_f32 v[106:107], v[106:107], v[16:17], v[216:217] op_sel_hi:[1,0,1]
	s_nop 0
	v_pk_mul_f32 v[216:217], v[106:107], v[6:7] op_sel_hi:[1,0]
	s_nop 0
	v_pk_fma_f32 v[106:107], v[106:107], v[6:7], v[216:217] op_sel:[1,1,0] op_sel_hi:[0,1,1] neg_hi:[0,1,0]
	s_nop 1
	v_mov_b32_dpp v216, v106 quad_perm:[2,3,0,1] row_mask:0xf bank_mask:0xf bound_ctrl:1
	v_mov_b32_dpp v217, v107 quad_perm:[2,3,0,1] row_mask:0xf bank_mask:0xf bound_ctrl:1
	v_pk_fma_f32 v[106:107], v[10:11], v[106:107], v[216:217] op_sel_hi:[0,1,1]
	v_pk_mul_f32 v[216:217], v[106:107], v[4:5] op_sel_hi:[1,0]
	s_nop 0
	v_pk_fma_f32 v[106:107], v[106:107], v[4:5], v[216:217] op_sel:[1,1,0] op_sel_hi:[0,1,1] neg_hi:[0,1,0]
	ds_swizzle_b32 v216, v106 offset:swizzle(SWAP,4)
	ds_swizzle_b32 v217, v107 offset:swizzle(SWAP,4)
	s_waitcnt lgkmcnt(0)
; __device__ __forceinline__ float lx1(float v) { return __int_as_float(__builtin_amdgcn_update_dpp(0, __float_as_int(v), 0xB1, 0xF, 0xF, true)); }
; __device__ __forceinline__ float lx2(float v) { return __int_as_float(__builtin_amdgcn_update_dpp(0, __float_as_int(v), 0x4E, 0xF, 0xF, true)); }
; __device__ __forceinline__ float lx4(float v) { return __int_as_float(__builtin_amdgcn_ds_swizzle(__float_as_int(v), 0x101F)); }
; __device__ __forceinline__ float lx8(float v) { return __int_as_float(__builtin_amdgcn_update_dpp(0, __float_as_int(v), 0x128, 0xF, 0xF, true)); }
; __device__ __forceinline__ void fft_inverse(f2 (&x)[32], LAS f2* X, int t, LAS const float* W1, LAS const M2C* MC) {
;     ...
;     for (int p = 0; p < 32; ++p) {
;         f2 v = x[p], pr;
;         pr = (f2){lx1(v.x), lx1(v.y)}; v = cmulrc(pr + v * c.s1, t2);
;         pr = (f2){lx2(v.x), lx2(v.y)}; v = cmulrc(pr + v * c.s2, t4);
;         pr = (f2){lx4(v.x), lx4(v.y)}; v = cmulrc(pr + v * c.s4, t8);
;         pr = (f2){lx8(v.x), lx8(v.y)}; x[p] = pr + v * c.s8;
;     }
	v_pk_fma_f32 v[106:107], v[8:9], v[106:107], v[216:217] op_sel:[1,0,0]
	s_nop 0
	v_pk_mul_f32 v[216:217], v[106:107], v[2:3] op_sel_hi:[1,0]
	s_nop 0
	v_pk_fma_f32 v[106:107], v[106:107], v[2:3], v[216:217] op_sel:[1,1,0] op_sel_hi:[0,1,1] neg_hi:[0,1,0]
	s_nop 1
	v_mov_b32_dpp v216, v106 row_ror:8 row_mask:0xf bank_mask:0xf bound_ctrl:1
	v_mov_b32_dpp v217, v107 row_ror:8 row_mask:0xf bank_mask:0xf bound_ctrl:1
	v_pk_fma_f32 v[106:107], v[8:9], v[106:107], v[216:217] op_sel_hi:[0,1,1]
	v_mov_b32_dpp v216, v102 quad_perm:[1,0,3,2] row_mask:0xf bank_mask:0xf bound_ctrl:1
	v_mov_b32_dpp v217, v103 quad_perm:[1,0,3,2] row_mask:0xf bank_mask:0xf bound_ctrl:1
	v_pk_fma_f32 v[102:103], v[102:103], v[16:17], v[216:217] op_sel_hi:[1,0,1]
	s_nop 0
	v_pk_mul_f32 v[216:217], v[102:103], v[6:7] op_sel_hi:[1,0]
	s_nop 0
	v_pk_fma_f32 v[102:103], v[102:103], v[6:7], v[216:217] op_sel:[1,1,0] op_sel_hi:[0,1,1] neg_hi:[0,1,0]
	s_nop 1
	v_mov_b32_dpp v216, v102 quad_perm:[2,3,0,1] row_mask:0xf bank_mask:0xf bound_ctrl:1
	v_mov_b32_dpp v217, v103 quad_perm:[2,3,0,1] row_mask:0xf bank_mask:0xf bound_ctrl:1
	v_pk_fma_f32 v[102:103], v[10:11], v[102:103], v[216:217] op_sel_hi:[0,1,1]
	v_pk_mul_f32 v[216:217], v[102:103], v[4:5] op_sel_hi:[1,0]
	s_nop 0
	v_pk_fma_f32 v[102:103], v[102:103], v[4:5], v[216:217] op_sel:[1,1,0] op_sel_hi:[0,1,1] neg_hi:[0,1,0]
	ds_swizzle_b32 v216, v102 offset:swizzle(SWAP,4)
	ds_swizzle_b32 v217, v103 offset:swizzle(SWAP,4)
	s_waitcnt lgkmcnt(0)
	v_pk_fma_f32 v[102:103], v[8:9], v[102:103], v[216:217] op_sel:[1,0,0]
	s_nop 0
	v_pk_mul_f32 v[216:217], v[102:103], v[2:3] op_sel_hi:[1,0]
	s_nop 0
	v_pk_fma_f32 v[102:103], v[102:103], v[2:3], v[216:217] op_sel:[1,1,0] op_sel_hi:[0,1,1] neg_hi:[0,1,0]
	s_nop 1
	v_mov_b32_dpp v216, v102 row_ror:8 row_mask:0xf bank_mask:0xf bound_ctrl:1
	v_mov_b32_dpp v217, v103 row_ror:8 row_mask:0xf bank_mask:0xf bound_ctrl:1
	v_pk_fma_f32 v[102:103], v[8:9], v[102:103], v[216:217] op_sel_hi:[0,1,1]
	v_mov_b32_dpp v216, v100 quad_perm:[1,0,3,2] row_mask:0xf bank_mask:0xf bound_ctrl:1
	v_mov_b32_dpp v217, v101 quad_perm:[1,0,3,2] row_mask:0xf bank_mask:0xf bound_ctrl:1
	v_pk_fma_f32 v[100:101], v[100:101], v[16:17], v[216:217] op_sel_hi:[1,0,1]
	s_nop 0
	v_pk_mul_f32 v[216:217], v[100:101], v[6:7] op_sel_hi:[1,0]
	s_nop 0
	v_pk_fma_f32 v[100:101], v[100:101], v[6:7], v[216:217] op_sel:[1,1,0] op_sel_hi:[0,1,1] neg_hi:[0,1,0]
	s_nop 1
	v_mov_b32_dpp v216, v100 quad_perm:[2,3,0,1] row_mask:0xf bank_mask:0xf bound_ctrl:1
	v_mov_b32_dpp v217, v101 quad_perm:[2,3,0,1] row_mask:0xf bank_mask:0xf bound_ctrl:1
	v_pk_fma_f32 v[100:101], v[10:11], v[100:101], v[216:217] op_sel_hi:[0,1,1]
	v_pk_mul_f32 v[216:217], v[100:101], v[4:5] op_sel_hi:[1,0]
	s_nop 0
	v_pk_fma_f32 v[100:101], v[100:101], v[4:5], v[216:217] op_sel:[1,1,0] op_sel_hi:[0,1,1] neg_hi:[0,1,0]
	ds_swizzle_b32 v216, v100 offset:swizzle(SWAP,4)
	ds_swizzle_b32 v217, v101 offset:swizzle(SWAP,4)
	s_waitcnt lgkmcnt(0)
	v_pk_fma_f32 v[100:101], v[8:9], v[100:101], v[216:217] op_sel:[1,0,0]
	s_nop 0
	v_pk_mul_f32 v[216:217], v[100:101], v[2:3] op_sel_hi:[1,0]
	s_nop 0
	v_pk_fma_f32 v[100:101], v[100:101], v[2:3], v[216:217] op_sel:[1,1,0] op_sel_hi:[0,1,1] neg_hi:[0,1,0]
	s_nop 1
	v_mov_b32_dpp v216, v100 row_ror:8 row_mask:0xf bank_mask:0xf bound_ctrl:1
	v_mov_b32_dpp v217, v101 row_ror:8 row_mask:0xf bank_mask:0xf bound_ctrl:1
	v_pk_fma_f32 v[100:101], v[8:9], v[100:101], v[216:217] op_sel_hi:[0,1,1]
	v_mov_b32_dpp v216, v94 quad_perm:[1,0,3,2] row_mask:0xf bank_mask:0xf bound_ctrl:1
	v_mov_b32_dpp v217, v95 quad_perm:[1,0,3,2] row_mask:0xf bank_mask:0xf bound_ctrl:1
	v_pk_fma_f32 v[94:95], v[94:95], v[16:17], v[216:217] op_sel_hi:[1,0,1]
	s_nop 0
	v_pk_mul_f32 v[216:217], v[94:95], v[6:7] op_sel_hi:[1,0]
	s_nop 0
	v_pk_fma_f32 v[94:95], v[94:95], v[6:7], v[216:217] op_sel:[1,1,0] op_sel_hi:[0,1,1] neg_hi:[0,1,0]
	s_nop 1
	v_mov_b32_dpp v216, v94 quad_perm:[2,3,0,1] row_mask:0xf bank_mask:0xf bound_ctrl:1
	v_mov_b32_dpp v217, v95 quad_perm:[2,3,0,1] row_mask:0xf bank_mask:0xf bound_ctrl:1
	v_pk_fma_f32 v[94:95], v[10:11], v[94:95], v[216:217] op_sel_hi:[0,1,1]
	v_pk_mul_f32 v[216:217], v[94:95], v[4:5] op_sel_hi:[1,0]
	s_nop 0
	v_pk_fma_f32 v[94:95], v[94:95], v[4:5], v[216:217] op_sel:[1,1,0] op_sel_hi:[0,1,1] neg_hi:[0,1,0]
	ds_swizzle_b32 v216, v94 offset:swizzle(SWAP,4)
	ds_swizzle_b32 v217, v95 offset:swizzle(SWAP,4)
	s_waitcnt lgkmcnt(0)
	v_pk_fma_f32 v[94:95], v[8:9], v[94:95], v[216:217] op_sel:[1,0,0]
	s_nop 0
	v_pk_mul_f32 v[216:217], v[94:95], v[2:3] op_sel_hi:[1,0]
	s_nop 0
	v_pk_fma_f32 v[94:95], v[94:95], v[2:3], v[216:217] op_sel:[1,1,0] op_sel_hi:[0,1,1] neg_hi:[0,1,0]
	s_nop 1
	v_mov_b32_dpp v216, v94 row_ror:8 row_mask:0xf bank_mask:0xf bound_ctrl:1
	v_mov_b32_dpp v217, v95 row_ror:8 row_mask:0xf bank_mask:0xf bound_ctrl:1
	v_pk_fma_f32 v[94:95], v[8:9], v[94:95], v[216:217] op_sel_hi:[0,1,1]
	v_mov_b32_dpp v216, v92 quad_perm:[1,0,3,2] row_mask:0xf bank_mask:0xf bound_ctrl:1
	v_mov_b32_dpp v217, v93 quad_perm:[1,0,3,2] row_mask:0xf bank_mask:0xf bound_ctrl:1
	v_pk_fma_f32 v[92:93], v[92:93], v[16:17], v[216:217] op_sel_hi:[1,0,1]
	s_nop 0
	v_pk_mul_f32 v[216:217], v[92:93], v[6:7] op_sel_hi:[1,0]
	s_nop 0
	v_pk_fma_f32 v[92:93], v[92:93], v[6:7], v[216:217] op_sel:[1,1,0] op_sel_hi:[0,1,1] neg_hi:[0,1,0]
	s_nop 1
	v_mov_b32_dpp v216, v92 quad_perm:[2,3,0,1] row_mask:0xf bank_mask:0xf bound_ctrl:1
	v_mov_b32_dpp v217, v93 quad_perm:[2,3,0,1] row_mask:0xf bank_mask:0xf bound_ctrl:1
	v_pk_fma_f32 v[92:93], v[10:11], v[92:93], v[216:217] op_sel_hi:[0,1,1]
	v_pk_mul_f32 v[216:217], v[92:93], v[4:5] op_sel_hi:[1,0]
	s_nop 0
	v_pk_fma_f32 v[92:93], v[92:93], v[4:5], v[216:217] op_sel:[1,1,0] op_sel_hi:[0,1,1] neg_hi:[0,1,0]
	ds_swizzle_b32 v216, v92 offset:swizzle(SWAP,4)
	ds_swizzle_b32 v217, v93 offset:swizzle(SWAP,4)
	s_waitcnt lgkmcnt(0)
; __device__ __forceinline__ float lx1(float v) { return __int_as_float(__builtin_amdgcn_update_dpp(0, __float_as_int(v), 0xB1, 0xF, 0xF, true)); }
; __device__ __forceinline__ float lx2(float v) { return __int_as_float(__builtin_amdgcn_update_dpp(0, __float_as_int(v), 0x4E, 0xF, 0xF, true)); }
; __device__ __forceinline__ float lx4(float v) { return __int_as_float(__builtin_amdgcn_ds_swizzle(__float_as_int(v), 0x101F)); }
; __device__ __forceinline__ float lx8(float v) { return __int_as_float(__builtin_amdgcn_update_dpp(0, __float_as_int(v), 0x128, 0xF, 0xF, true)); }
; template <bool CONJ> __device__ __forceinline__ void twiddle32(f2 (&x)[32], float wr, float wi) {
;     asm volatile("" : "+v"(wr), "+v"(wi));
;     f2 c = (f2){wr, CONJ ? -wi : wi}; const f2 w = c;
; #pragma unroll
;     for (int k = 1; k < 32; ++k) { const int p = brev5(k); x[p] = cmulr(x[p], c); if (k < 31) c = cmulr(c, w); }
; }
; __device__ __forceinline__ void fft_inverse(f2 (&x)[32], LAS f2* X, int t, LAS const float* W1, LAS const M2C* MC) {
;     ...
;     for (int p = 0; p < 32; ++p) {
;         f2 v = x[p], pr;
;         pr = (f2){lx1(v.x), lx1(v.y)}; v = cmulrc(pr + v * c.s1, t2);
;         pr = (f2){lx2(v.x), lx2(v.y)}; v = cmulrc(pr + v * c.s2, t4);
;         pr = (f2){lx4(v.x), lx4(v.y)}; v = cmulrc(pr + v * c.s4, t8);
;         pr = (f2){lx8(v.x), lx8(v.y)}; x[p] = pr + v * c.s8;
;     }
;     twiddle32<true>(x, c.w2r, c.w2i);
	v_pk_fma_f32 v[92:93], v[8:9], v[92:93], v[216:217] op_sel:[1,0,0]
	s_nop 0
	v_pk_mul_f32 v[216:217], v[92:93], v[2:3] op_sel_hi:[1,0]
	s_nop 0
	v_pk_fma_f32 v[92:93], v[92:93], v[2:3], v[216:217] op_sel:[1,1,0] op_sel_hi:[0,1,1] neg_hi:[0,1,0]
	s_nop 1
	v_mov_b32_dpp v216, v92 row_ror:8 row_mask:0xf bank_mask:0xf bound_ctrl:1
	v_mov_b32_dpp v217, v93 row_ror:8 row_mask:0xf bank_mask:0xf bound_ctrl:1
	v_pk_fma_f32 v[92:93], v[8:9], v[92:93], v[216:217] op_sel_hi:[0,1,1]
	v_mov_b32_dpp v216, v88 quad_perm:[1,0,3,2] row_mask:0xf bank_mask:0xf bound_ctrl:1
	v_mov_b32_dpp v217, v89 quad_perm:[1,0,3,2] row_mask:0xf bank_mask:0xf bound_ctrl:1
	v_pk_fma_f32 v[88:89], v[88:89], v[16:17], v[216:217] op_sel_hi:[1,0,1]
	s_nop 0
	v_pk_mul_f32 v[216:217], v[88:89], v[6:7] op_sel_hi:[1,0]
	s_nop 0
	v_pk_fma_f32 v[6:7], v[88:89], v[6:7], v[216:217] op_sel:[1,1,0] op_sel_hi:[0,1,1] neg_hi:[0,1,0]
	s_nop 1
	v_mov_b32_dpp v88, v6 quad_perm:[2,3,0,1] row_mask:0xf bank_mask:0xf bound_ctrl:1
	v_mov_b32_dpp v89, v7 quad_perm:[2,3,0,1] row_mask:0xf bank_mask:0xf bound_ctrl:1
	v_pk_fma_f32 v[6:7], v[10:11], v[6:7], v[88:89] op_sel_hi:[0,1,1]
	v_pk_mul_f32 v[10:11], v[6:7], v[4:5] op_sel_hi:[1,0]
	s_nop 0
	v_pk_fma_f32 v[4:5], v[6:7], v[4:5], v[10:11] op_sel:[1,1,0] op_sel_hi:[0,1,1] neg_hi:[0,1,0]
	ds_swizzle_b32 v6, v4 offset:swizzle(SWAP,4)
	ds_swizzle_b32 v7, v5 offset:swizzle(SWAP,4)
	s_waitcnt lgkmcnt(0)
	v_pk_fma_f32 v[4:5], v[8:9], v[4:5], v[6:7] op_sel:[1,0,0]
	s_nop 0
	v_pk_mul_f32 v[6:7], v[4:5], v[2:3] op_sel_hi:[1,0]
	s_nop 0
	v_pk_fma_f32 v[2:3], v[4:5], v[2:3], v[6:7] op_sel:[1,1,0] op_sel_hi:[0,1,1] neg_hi:[0,1,0]
	v_pk_mul_f32 v[6:7], v[0:1], v[0:1] op_sel_hi:[1,0]
	s_nop 0
	v_pk_fma_f32 v[6:7], v[0:1], v[0:1], v[6:7] op_sel:[1,1,0] op_sel_hi:[0,1,1] neg_lo:[0,1,0]
	s_nop 0
	v_mov_b32_dpp v4, v2 row_ror:8 row_mask:0xf bank_mask:0xf bound_ctrl:1
	v_mov_b32_dpp v5, v3 row_ror:8 row_mask:0xf bank_mask:0xf bound_ctrl:1
	v_pk_fma_f32 v[2:3], v[8:9], v[2:3], v[4:5] op_sel_hi:[0,1,1]
	v_pk_mul_f32 v[8:9], v[126:127], v[6:7] op_sel_hi:[1,0]
	v_pk_mul_f32 v[10:11], v[6:7], v[0:1] op_sel_hi:[1,0]
	v_pk_mul_f32 v[4:5], v[144:145], v[0:1] op_sel_hi:[1,0]
	s_nop 0
	v_pk_fma_f32 v[8:9], v[126:127], v[6:7], v[8:9] op_sel:[1,1,0] op_sel_hi:[0,1,1] neg_lo:[0,1,0]
	v_pk_fma_f32 v[6:7], v[6:7], v[0:1], v[10:11] op_sel:[1,1,0] op_sel_hi:[0,1,1] neg_lo:[0,1,0]
	v_pk_fma_f32 v[4:5], v[144:145], v[0:1], v[4:5] op_sel:[1,1,0] op_sel_hi:[0,1,1] neg_lo:[0,1,0]
	s_nop 0
	v_pk_mul_f32 v[10:11], v[116:117], v[6:7] op_sel_hi:[1,0]
	v_pk_mul_f32 v[88:89], v[6:7], v[0:1] op_sel_hi:[1,0]
	s_nop 0
	v_pk_fma_f32 v[10:11], v[116:117], v[6:7], v[10:11] op_sel:[1,1,0] op_sel_hi:[0,1,1] neg_lo:[0,1,0]
	v_pk_fma_f32 v[6:7], v[6:7], v[0:1], v[88:89] op_sel:[1,1,0] op_sel_hi:[0,1,1] neg_lo:[0,1,0]
	s_nop 0
	v_pk_mul_f32 v[88:89], v[108:109], v[6:7] op_sel_hi:[1,0]
	s_nop 0
	v_pk_fma_f32 v[88:89], v[108:109], v[6:7], v[88:89] op_sel:[1,1,0] op_sel_hi:[0,1,1] neg_lo:[0,1,0]
	v_pk_mul_f32 v[108:109], v[6:7], v[0:1] op_sel_hi:[1,0]
	s_nop 0
	v_pk_fma_f32 v[6:7], v[6:7], v[0:1], v[108:109] op_sel:[1,1,0] op_sel_hi:[0,1,1] neg_lo:[0,1,0]
	s_nop 0
	v_pk_mul_f32 v[108:109], v[128:129], v[6:7] op_sel_hi:[1,0]
	v_pk_mul_f32 v[116:117], v[6:7], v[0:1] op_sel_hi:[1,0]
	s_nop 0
	v_pk_fma_f32 v[108:109], v[128:129], v[6:7], v[108:109] op_sel:[1,1,0] op_sel_hi:[0,1,1] neg_lo:[0,1,0]
	v_pk_fma_f32 v[6:7], v[6:7], v[0:1], v[116:117] op_sel:[1,1,0] op_sel_hi:[0,1,1] neg_lo:[0,1,0]
	s_nop 0
	v_pk_mul_f32 v[116:117], v[142:143], v[6:7] op_sel_hi:[1,0]
	v_pk_mul_f32 v[126:127], v[6:7], v[0:1] op_sel_hi:[1,0]
	s_nop 0
	v_pk_fma_f32 v[116:117], v[142:143], v[6:7], v[116:117] op_sel:[1,1,0] op_sel_hi:[0,1,1] neg_lo:[0,1,0]
	v_pk_fma_f32 v[6:7], v[6:7], v[0:1], v[126:127] op_sel:[1,1,0] op_sel_hi:[0,1,1] neg_lo:[0,1,0]
	s_nop 0
	v_pk_mul_f32 v[126:127], v[100:101], v[6:7] op_sel_hi:[1,0]
	s_nop 0
	v_pk_fma_f32 v[100:101], v[100:101], v[6:7], v[126:127] op_sel:[1,1,0] op_sel_hi:[0,1,1] neg_lo:[0,1,0]
	v_pk_mul_f32 v[126:127], v[6:7], v[0:1] op_sel_hi:[1,0]
	s_nop 0
	v_pk_fma_f32 v[6:7], v[6:7], v[0:1], v[126:127] op_sel:[1,1,0] op_sel_hi:[0,1,1] neg_lo:[0,1,0]
	s_nop 0
	v_pk_mul_f32 v[126:127], v[98:99], v[6:7] op_sel_hi:[1,0]
	s_nop 0
	v_pk_fma_f32 v[98:99], v[98:99], v[6:7], v[126:127] op_sel:[1,1,0] op_sel_hi:[0,1,1] neg_lo:[0,1,0]
	v_pk_mul_f32 v[126:127], v[6:7], v[0:1] op_sel_hi:[1,0]
	s_nop 0
	v_pk_fma_f32 v[6:7], v[6:7], v[0:1], v[126:127] op_sel:[1,1,0] op_sel_hi:[0,1,1] neg_lo:[0,1,0]
	s_nop 0
	v_pk_mul_f32 v[126:127], v[136:137], v[6:7] op_sel_hi:[1,0]
	v_pk_mul_f32 v[128:129], v[6:7], v[0:1] op_sel_hi:[1,0]
	s_nop 0
	v_pk_fma_f32 v[126:127], v[136:137], v[6:7], v[126:127] op_sel:[1,1,0] op_sel_hi:[0,1,1] neg_lo:[0,1,0]
	v_pk_fma_f32 v[6:7], v[6:7], v[0:1], v[128:129] op_sel:[1,1,0] op_sel_hi:[0,1,1] neg_lo:[0,1,0]
	s_nop 0
	v_pk_mul_f32 v[128:129], v[132:133], v[6:7] op_sel_hi:[1,0]
	s_nop 0
	v_pk_fma_f32 v[128:129], v[132:133], v[6:7], v[128:129] op_sel:[1,1,0] op_sel_hi:[0,1,1] neg_lo:[0,1,0]
	v_pk_mul_f32 v[132:133], v[6:7], v[0:1] op_sel_hi:[1,0]
	s_nop 0
	v_pk_fma_f32 v[6:7], v[6:7], v[0:1], v[132:133] op_sel:[1,1,0] op_sel_hi:[0,1,1] neg_lo:[0,1,0]
	s_nop 0
	v_pk_mul_f32 v[132:133], v[106:107], v[6:7] op_sel_hi:[1,0]
	s_nop 0
	v_pk_fma_f32 v[106:107], v[106:107], v[6:7], v[132:133] op_sel:[1,1,0] op_sel_hi:[0,1,1] neg_lo:[0,1,0]
	v_pk_mul_f32 v[132:133], v[6:7], v[0:1] op_sel_hi:[1,0]
	s_nop 0
	v_pk_fma_f32 v[6:7], v[6:7], v[0:1], v[132:133] op_sel:[1,1,0] op_sel_hi:[0,1,1] neg_lo:[0,1,0]
	s_nop 0
	v_pk_mul_f32 v[132:133], v[114:115], v[6:7] op_sel_hi:[1,0]
	s_nop 0
; template <bool CONJ> __device__ __forceinline__ void twiddle32(f2 (&x)[32], float wr, float wi) {
;     asm volatile("" : "+v"(wr), "+v"(wi));
;     f2 c = (f2){wr, CONJ ? -wi : wi}; const f2 w = c;
; #pragma unroll
;     for (int k = 1; k < 32; ++k) { const int p = brev5(k); x[p] = cmulr(x[p], c); if (k < 31) c = cmulr(c, w); }
; }
	v_pk_fma_f32 v[114:115], v[114:115], v[6:7], v[132:133] op_sel:[1,1,0] op_sel_hi:[0,1,1] neg_lo:[0,1,0]
	v_pk_mul_f32 v[132:133], v[6:7], v[0:1] op_sel_hi:[1,0]
	s_nop 0
	v_pk_fma_f32 v[6:7], v[6:7], v[0:1], v[132:133] op_sel:[1,1,0] op_sel_hi:[0,1,1] neg_lo:[0,1,0]
	s_nop 0
	v_pk_mul_f32 v[132:133], v[120:121], v[6:7] op_sel_hi:[1,0]
	s_nop 0
	v_pk_fma_f32 v[120:121], v[120:121], v[6:7], v[132:133] op_sel:[1,1,0] op_sel_hi:[0,1,1] neg_lo:[0,1,0]
	v_pk_mul_f32 v[132:133], v[6:7], v[0:1] op_sel_hi:[1,0]
	s_nop 0
	v_pk_fma_f32 v[6:7], v[6:7], v[0:1], v[132:133] op_sel:[1,1,0] op_sel_hi:[0,1,1] neg_lo:[0,1,0]
	s_nop 0
	v_pk_mul_f32 v[132:133], v[148:149], v[6:7] op_sel_hi:[1,0]
	v_pk_mul_f32 v[136:137], v[6:7], v[0:1] op_sel_hi:[1,0]
	s_nop 0
	v_pk_fma_f32 v[132:133], v[148:149], v[6:7], v[132:133] op_sel:[1,1,0] op_sel_hi:[0,1,1] neg_lo:[0,1,0]
	v_pk_fma_f32 v[6:7], v[6:7], v[0:1], v[136:137] op_sel:[1,1,0] op_sel_hi:[0,1,1] neg_lo:[0,1,0]
	s_nop 0
	v_pk_mul_f32 v[136:137], v[92:93], v[6:7] op_sel_hi:[1,0]
	s_nop 0
	v_pk_fma_f32 v[92:93], v[92:93], v[6:7], v[136:137] op_sel:[1,1,0] op_sel_hi:[0,1,1] neg_lo:[0,1,0]
	v_pk_mul_f32 v[136:137], v[6:7], v[0:1] op_sel_hi:[1,0]
	s_nop 0
	v_pk_fma_f32 v[6:7], v[6:7], v[0:1], v[136:137] op_sel:[1,1,0] op_sel_hi:[0,1,1] neg_lo:[0,1,0]
	s_nop 0
	v_pk_mul_f32 v[136:137], v[90:91], v[6:7] op_sel_hi:[1,0]
	s_nop 0
	v_pk_fma_f32 v[90:91], v[90:91], v[6:7], v[136:137] op_sel:[1,1,0] op_sel_hi:[0,1,1] neg_lo:[0,1,0]
	v_pk_mul_f32 v[136:137], v[6:7], v[0:1] op_sel_hi:[1,0]
	s_nop 0
	v_pk_fma_f32 v[6:7], v[6:7], v[0:1], v[136:137] op_sel:[1,1,0] op_sel_hi:[0,1,1] neg_lo:[0,1,0]
	s_nop 0
	v_pk_mul_f32 v[136:137], v[140:141], v[6:7] op_sel_hi:[1,0]
	s_nop 0
	v_pk_fma_f32 v[136:137], v[140:141], v[6:7], v[136:137] op_sel:[1,1,0] op_sel_hi:[0,1,1] neg_lo:[0,1,0]
	v_pk_mul_f32 v[140:141], v[6:7], v[0:1] op_sel_hi:[1,0]
	s_nop 0
	v_pk_fma_f32 v[6:7], v[6:7], v[0:1], v[140:141] op_sel:[1,1,0] op_sel_hi:[0,1,1] neg_lo:[0,1,0]
	s_nop 0
	v_pk_mul_f32 v[140:141], v[122:123], v[6:7] op_sel_hi:[1,0]
	s_nop 0
	v_pk_fma_f32 v[122:123], v[122:123], v[6:7], v[140:141] op_sel:[1,1,0] op_sel_hi:[0,1,1] neg_lo:[0,1,0]
	v_pk_mul_f32 v[140:141], v[6:7], v[0:1] op_sel_hi:[1,0]
	s_nop 0
	v_pk_fma_f32 v[6:7], v[6:7], v[0:1], v[140:141] op_sel:[1,1,0] op_sel_hi:[0,1,1] neg_lo:[0,1,0]
	s_nop 0
	v_pk_mul_f32 v[140:141], v[110:111], v[6:7] op_sel_hi:[1,0]
	s_nop 0
	v_pk_fma_f32 v[110:111], v[110:111], v[6:7], v[140:141] op_sel:[1,1,0] op_sel_hi:[0,1,1] neg_lo:[0,1,0]
	v_pk_mul_f32 v[140:141], v[6:7], v[0:1] op_sel_hi:[1,0]
	s_nop 0
	v_pk_fma_f32 v[6:7], v[6:7], v[0:1], v[140:141] op_sel:[1,1,0] op_sel_hi:[0,1,1] neg_lo:[0,1,0]
	s_nop 0
	v_pk_mul_f32 v[140:141], v[104:105], v[6:7] op_sel_hi:[1,0]
	s_nop 0
	v_pk_fma_f32 v[104:105], v[104:105], v[6:7], v[140:141] op_sel:[1,1,0] op_sel_hi:[0,1,1] neg_lo:[0,1,0]
	v_pk_mul_f32 v[140:141], v[6:7], v[0:1] op_sel_hi:[1,0]
	s_nop 0
	v_pk_fma_f32 v[6:7], v[6:7], v[0:1], v[140:141] op_sel:[1,1,0] op_sel_hi:[0,1,1] neg_lo:[0,1,0]
	s_nop 0
	v_pk_mul_f32 v[140:141], v[124:125], v[6:7] op_sel_hi:[1,0]
	s_nop 0
	v_pk_fma_f32 v[124:125], v[124:125], v[6:7], v[140:141] op_sel:[1,1,0] op_sel_hi:[0,1,1] neg_lo:[0,1,0]
	v_pk_mul_f32 v[140:141], v[6:7], v[0:1] op_sel_hi:[1,0]
	s_nop 0
	v_pk_fma_f32 v[6:7], v[6:7], v[0:1], v[140:141] op_sel:[1,1,0] op_sel_hi:[0,1,1] neg_lo:[0,1,0]
	s_nop 0
	v_pk_mul_f32 v[140:141], v[138:139], v[6:7] op_sel_hi:[1,0]
	s_nop 0
	v_pk_fma_f32 v[138:139], v[138:139], v[6:7], v[140:141] op_sel:[1,1,0] op_sel_hi:[0,1,1] neg_lo:[0,1,0]
	v_pk_mul_f32 v[140:141], v[6:7], v[0:1] op_sel_hi:[1,0]
	s_nop 0
	v_pk_fma_f32 v[6:7], v[6:7], v[0:1], v[140:141] op_sel:[1,1,0] op_sel_hi:[0,1,1] neg_lo:[0,1,0]
	s_nop 0
	v_pk_mul_f32 v[140:141], v[94:95], v[6:7] op_sel_hi:[1,0]
	s_nop 0
	v_pk_fma_f32 v[94:95], v[94:95], v[6:7], v[140:141] op_sel:[1,1,0] op_sel_hi:[0,1,1] neg_lo:[0,1,0]
	v_pk_mul_f32 v[140:141], v[6:7], v[0:1] op_sel_hi:[1,0]
	s_nop 0
	v_pk_fma_f32 v[6:7], v[6:7], v[0:1], v[140:141] op_sel:[1,1,0] op_sel_hi:[0,1,1] neg_lo:[0,1,0]
	s_nop 0
	v_pk_mul_f32 v[140:141], v[96:97], v[6:7] op_sel_hi:[1,0]
	s_nop 0
	v_pk_fma_f32 v[96:97], v[96:97], v[6:7], v[140:141] op_sel:[1,1,0] op_sel_hi:[0,1,1] neg_lo:[0,1,0]
	v_pk_mul_f32 v[140:141], v[6:7], v[0:1] op_sel_hi:[1,0]
	s_nop 0
	v_pk_fma_f32 v[6:7], v[6:7], v[0:1], v[140:141] op_sel:[1,1,0] op_sel_hi:[0,1,1] neg_lo:[0,1,0]
	s_nop 0
	v_pk_mul_f32 v[140:141], v[134:135], v[6:7] op_sel_hi:[1,0]
	s_nop 0
	v_pk_fma_f32 v[134:135], v[134:135], v[6:7], v[140:141] op_sel:[1,1,0] op_sel_hi:[0,1,1] neg_lo:[0,1,0]
	v_pk_mul_f32 v[140:141], v[6:7], v[0:1] op_sel_hi:[1,0]
	s_nop 0
	v_pk_fma_f32 v[6:7], v[6:7], v[0:1], v[140:141] op_sel:[1,1,0] op_sel_hi:[0,1,1] neg_lo:[0,1,0]
	s_nop 0
	v_pk_mul_f32 v[140:141], v[130:131], v[6:7] op_sel_hi:[1,0]
	s_nop 0
	v_pk_fma_f32 v[130:131], v[130:131], v[6:7], v[140:141] op_sel:[1,1,0] op_sel_hi:[0,1,1] neg_lo:[0,1,0]
	v_pk_mul_f32 v[140:141], v[6:7], v[0:1] op_sel_hi:[1,0]
	s_nop 0
	v_pk_fma_f32 v[6:7], v[6:7], v[0:1], v[140:141] op_sel:[1,1,0] op_sel_hi:[0,1,1] neg_lo:[0,1,0]
	s_nop 0
	v_pk_mul_f32 v[140:141], v[102:103], v[6:7] op_sel_hi:[1,0]
	s_nop 0
	v_pk_fma_f32 v[102:103], v[102:103], v[6:7], v[140:141] op_sel:[1,1,0] op_sel_hi:[0,1,1] neg_lo:[0,1,0]
	v_pk_mul_f32 v[140:141], v[6:7], v[0:1] op_sel_hi:[1,0]
	s_nop 0
	v_pk_fma_f32 v[6:7], v[6:7], v[0:1], v[140:141] op_sel:[1,1,0] op_sel_hi:[0,1,1] neg_lo:[0,1,0]
	s_nop 0
	v_pk_mul_f32 v[140:141], v[112:113], v[6:7] op_sel_hi:[1,0]
	s_nop 0
	v_pk_fma_f32 v[112:113], v[112:113], v[6:7], v[140:141] op_sel:[1,1,0] op_sel_hi:[0,1,1] neg_lo:[0,1,0]
; __device__ __forceinline__ f2 cmulc(f2 a, float wr, float wi) { const f2 s = __builtin_shufflevector(a, a, 1, 0); return s * (f2){wi, -wi} + a * (f2){wr, wr}; }
; __device__ __forceinline__ void ifft32(f2 (&x)[32]) {
;     constexpr float TWR[32] = {TWR_LIST}; constexpr float TWI[32] = {TWI_LIST};
; #pragma unroll
;     for (int h = 1; h <= 16; h <<= 1) {
; #pragma unroll
;         for (int i0 = 0; i0 < 32; i0 += 2 * h) {
; #pragma unroll
;             for (int j = 0; j < h; ++j) {
;                 const int i = i0 + j, k = i + h, m = j * (32 / h);
;                 const f2 a = x[i], y = x[k];
;                 f2 b;
;                 if (m == 0) b = y;
;                 else if (m == 16) b = (f2){-y.y, y.x};
;                 else b = cmulc(y, TWR[m], TWI[m]);
;                 x[i] = a + b; x[k] = a - b;
;             }
;         }
;     }
; }
; template <bool CONJ> __device__ __forceinline__ void twiddle32(f2 (&x)[32], float wr, float wi) {
;     asm volatile("" : "+v"(wr), "+v"(wi));
;     f2 c = (f2){wr, CONJ ? -wi : wi}; const f2 w = c;
; #pragma unroll
;     for (int k = 1; k < 32; ++k) { const int p = brev5(k); x[p] = cmulr(x[p], c); if (k < 31) c = cmulr(c, w); }
; }
	v_pk_mul_f32 v[140:141], v[6:7], v[0:1] op_sel_hi:[1,0]
	s_nop 0
	v_pk_fma_f32 v[6:7], v[6:7], v[0:1], v[140:141] op_sel:[1,1,0] op_sel_hi:[0,1,1] neg_lo:[0,1,0]
	s_nop 0
	v_pk_mul_f32 v[140:141], v[118:119], v[6:7] op_sel_hi:[1,0]
	s_nop 0
	v_pk_fma_f32 v[118:119], v[118:119], v[6:7], v[140:141] op_sel:[1,1,0] op_sel_hi:[0,1,1] neg_lo:[0,1,0]
	v_pk_mul_f32 v[140:141], v[6:7], v[0:1] op_sel_hi:[1,0]
	s_nop 0
	v_pk_fma_f32 v[6:7], v[6:7], v[0:1], v[140:141] op_sel:[1,1,0] op_sel_hi:[0,1,1] neg_lo:[0,1,0]
	s_nop 0
	v_pk_mul_f32 v[140:141], v[146:147], v[6:7] op_sel_hi:[1,0]
	v_pk_mul_f32 v[142:143], v[6:7], v[0:1] op_sel_hi:[1,0]
	s_nop 0
	v_pk_fma_f32 v[140:141], v[146:147], v[6:7], v[140:141] op_sel:[1,1,0] op_sel_hi:[0,1,1] neg_lo:[0,1,0]
	v_pk_fma_f32 v[0:1], v[6:7], v[0:1], v[142:143] op_sel:[1,1,0] op_sel_hi:[0,1,1] neg_lo:[0,1,0]
	s_nop 0
	v_pk_mul_f32 v[6:7], v[2:3], v[0:1] op_sel_hi:[1,0]
	s_nop 0
	v_pk_fma_f32 v[0:1], v[2:3], v[0:1], v[6:7] op_sel:[1,1,0] op_sel_hi:[0,1,1] neg_lo:[0,1,0]
	v_pk_add_f32 v[2:3], v[86:87], v[90:91]
	v_pk_add_f32 v[6:7], v[86:87], v[90:91] neg_lo:[0,1] neg_hi:[0,1]
	v_pk_add_f32 v[86:87], v[98:99], v[96:97]
	v_pk_add_f32 v[90:91], v[98:99], v[96:97] neg_lo:[0,1] neg_hi:[0,1]
	v_pk_add_f32 v[96:97], v[88:89], v[104:105]
	v_pk_add_f32 v[88:89], v[88:89], v[104:105] neg_lo:[0,1] neg_hi:[0,1]
	v_pk_add_f32 v[98:99], v[114:115], v[112:113]
	v_pk_add_f32 v[104:105], v[114:115], v[112:113] neg_lo:[0,1] neg_hi:[0,1]
	v_pk_add_f32 v[112:113], v[8:9], v[122:123]
	v_pk_add_f32 v[8:9], v[8:9], v[122:123] neg_lo:[0,1] neg_hi:[0,1]
	v_pk_add_f32 v[114:115], v[128:129], v[130:131]
	v_pk_add_f32 v[122:123], v[128:129], v[130:131] neg_lo:[0,1] neg_hi:[0,1]
	v_pk_add_f32 v[128:129], v[116:117], v[138:139]
	v_pk_add_f32 v[116:117], v[116:117], v[138:139] neg_lo:[0,1] neg_hi:[0,1]
	v_pk_add_f32 v[138:139], v[4:5], v[136:137]
	v_pk_add_f32 v[4:5], v[4:5], v[136:137] neg_lo:[0,1] neg_hi:[0,1]
	v_pk_add_f32 v[136:137], v[126:127], v[134:135]
	v_pk_add_f32 v[126:127], v[126:127], v[134:135] neg_lo:[0,1] neg_hi:[0,1]
	v_pk_add_f32 v[134:135], v[108:109], v[124:125]
	v_pk_add_f32 v[108:109], v[108:109], v[124:125] neg_lo:[0,1] neg_hi:[0,1]
	v_pk_add_f32 v[124:125], v[120:121], v[118:119]
	v_pk_add_f32 v[118:119], v[120:121], v[118:119] neg_lo:[0,1] neg_hi:[0,1]
	v_pk_add_f32 v[120:121], v[10:11], v[110:111]
	v_pk_add_f32 v[10:11], v[10:11], v[110:111] neg_lo:[0,1] neg_hi:[0,1]
	v_pk_add_f32 v[110:111], v[106:107], v[102:103]
	v_pk_add_f32 v[102:103], v[106:107], v[102:103] neg_lo:[0,1] neg_hi:[0,1]
	v_pk_add_f32 v[106:107], v[100:101], v[94:95]
	v_pk_add_f32 v[94:95], v[100:101], v[94:95] neg_lo:[0,1] neg_hi:[0,1]
	v_pk_add_f32 v[100:101], v[92:93], v[0:1]
	v_pk_add_f32 v[0:1], v[92:93], v[0:1] neg_lo:[0,1] neg_hi:[0,1]
	v_pk_add_f32 v[92:93], v[2:3], v[86:87]
	v_pk_add_f32 v[2:3], v[2:3], v[86:87] neg_lo:[0,1] neg_hi:[0,1]
	v_xor_b32_e32 v86, 0x80000000, v91
	v_mov_b32_e32 v87, v90
	v_pk_add_f32 v[90:91], v[6:7], v[86:87]
	v_pk_add_f32 v[6:7], v[6:7], v[86:87] neg_lo:[0,1] neg_hi:[0,1]
	v_pk_add_f32 v[86:87], v[96:97], v[98:99]
	v_pk_add_f32 v[96:97], v[96:97], v[98:99] neg_lo:[0,1] neg_hi:[0,1]
	v_xor_b32_e32 v98, 0x80000000, v105
	v_mov_b32_e32 v99, v104
	v_pk_add_f32 v[130:131], v[132:133], v[140:141]
	v_pk_add_f32 v[132:133], v[132:133], v[140:141] neg_lo:[0,1] neg_hi:[0,1]
	v_pk_add_f32 v[104:105], v[88:89], v[98:99]
	v_pk_add_f32 v[88:89], v[88:89], v[98:99] neg_lo:[0,1] neg_hi:[0,1]
	v_pk_add_f32 v[98:99], v[112:113], v[114:115]
	v_pk_add_f32 v[112:113], v[112:113], v[114:115] neg_lo:[0,1] neg_hi:[0,1]
	v_xor_b32_e32 v114, 0x80000000, v123
	v_mov_b32_e32 v115, v122
	v_pk_add_f32 v[122:123], v[8:9], v[114:115]
	v_pk_add_f32 v[8:9], v[8:9], v[114:115] neg_lo:[0,1] neg_hi:[0,1]
	v_pk_add_f32 v[114:115], v[128:129], v[130:131]
	v_pk_add_f32 v[128:129], v[128:129], v[130:131] neg_lo:[0,1] neg_hi:[0,1]
	v_xor_b32_e32 v130, 0x80000000, v133
	v_mov_b32_e32 v131, v132
	v_pk_add_f32 v[132:133], v[116:117], v[130:131]
	v_pk_add_f32 v[116:117], v[116:117], v[130:131] neg_lo:[0,1] neg_hi:[0,1]
	v_pk_add_f32 v[130:131], v[138:139], v[136:137]
	v_pk_add_f32 v[136:137], v[138:139], v[136:137] neg_lo:[0,1] neg_hi:[0,1]
	v_xor_b32_e32 v138, 0x80000000, v127
	v_mov_b32_e32 v139, v126
	v_pk_add_f32 v[126:127], v[4:5], v[138:139]
	v_pk_add_f32 v[4:5], v[4:5], v[138:139] neg_lo:[0,1] neg_hi:[0,1]
	v_pk_add_f32 v[138:139], v[134:135], v[124:125]
	v_pk_add_f32 v[124:125], v[134:135], v[124:125] neg_lo:[0,1] neg_hi:[0,1]
	v_xor_b32_e32 v134, 0x80000000, v119
	v_mov_b32_e32 v135, v118
	v_pk_add_f32 v[118:119], v[108:109], v[134:135]
	v_pk_add_f32 v[108:109], v[108:109], v[134:135] neg_lo:[0,1] neg_hi:[0,1]
	v_pk_add_f32 v[134:135], v[120:121], v[110:111]
	v_pk_add_f32 v[110:111], v[120:121], v[110:111] neg_lo:[0,1] neg_hi:[0,1]
	v_xor_b32_e32 v120, 0x80000000, v103
	v_mov_b32_e32 v121, v102
	v_pk_add_f32 v[102:103], v[10:11], v[120:121]
	v_pk_add_f32 v[10:11], v[10:11], v[120:121] neg_lo:[0,1] neg_hi:[0,1]
	v_pk_add_f32 v[120:121], v[106:107], v[100:101]
	v_pk_add_f32 v[100:101], v[106:107], v[100:101] neg_lo:[0,1] neg_hi:[0,1]
	v_xor_b32_e32 v106, 0x80000000, v1
	v_mov_b32_e32 v107, v0
	v_pk_add_f32 v[0:1], v[94:95], v[106:107]
	v_pk_add_f32 v[94:95], v[94:95], v[106:107] neg_lo:[0,1] neg_hi:[0,1]
	v_pk_add_f32 v[106:107], v[92:93], v[86:87]
	v_pk_add_f32 v[86:87], v[92:93], v[86:87] neg_lo:[0,1] neg_hi:[0,1]
	v_pk_mul_f32 v[92:93], v[104:105], s[96:97]
	s_nop 0
	v_pk_fma_f32 v[92:93], v[104:105], s[94:95], v[92:93] op_sel:[0,0,1] op_sel_hi:[1,0,0]
	s_nop 0
	v_pk_add_f32 v[104:105], v[90:91], v[92:93]
	v_pk_add_f32 v[90:91], v[90:91], v[92:93] neg_lo:[0,1] neg_hi:[0,1]
; __device__ __forceinline__ f2 cmulc(f2 a, float wr, float wi) { const f2 s = __builtin_shufflevector(a, a, 1, 0); return s * (f2){wi, -wi} + a * (f2){wr, wr}; }
; __device__ __forceinline__ void ifft32(f2 (&x)[32]) {
;     constexpr float TWR[32] = {TWR_LIST}; constexpr float TWI[32] = {TWI_LIST};
; #pragma unroll
;     for (int h = 1; h <= 16; h <<= 1) {
; #pragma unroll
;         for (int i0 = 0; i0 < 32; i0 += 2 * h) {
; #pragma unroll
;             for (int j = 0; j < h; ++j) {
;                 const int i = i0 + j, k = i + h, m = j * (32 / h);
;                 const f2 a = x[i], y = x[k];
;                 f2 b;
;                 if (m == 0) b = y;
;                 else if (m == 16) b = (f2){-y.y, y.x};
;                 else b = cmulc(y, TWR[m], TWI[m]);
;                 x[i] = a + b; x[k] = a - b;
;             }
;         }
;     }
; }
	v_xor_b32_e32 v92, 0x80000000, v97
	v_mov_b32_e32 v93, v96
	v_pk_add_f32 v[96:97], v[2:3], v[92:93]
	v_pk_add_f32 v[2:3], v[2:3], v[92:93] neg_lo:[0,1] neg_hi:[0,1]
	v_pk_mul_f32 v[92:93], v[88:89], s[96:97]
	s_nop 0
	v_pk_fma_f32 v[88:89], v[88:89], s[94:95], v[92:93] op_sel:[0,0,1] op_sel_hi:[1,0,0] neg_lo:[1,0,0] neg_hi:[1,0,0]
	s_nop 0
	v_pk_add_f32 v[92:93], v[6:7], v[88:89]
	v_pk_add_f32 v[6:7], v[6:7], v[88:89] neg_lo:[0,1] neg_hi:[0,1]
	v_pk_add_f32 v[88:89], v[98:99], v[114:115]
	v_pk_add_f32 v[98:99], v[98:99], v[114:115] neg_lo:[0,1] neg_hi:[0,1]
	v_pk_mul_f32 v[114:115], v[132:133], s[96:97]
	s_nop 0
	v_pk_fma_f32 v[114:115], v[132:133], s[94:95], v[114:115] op_sel:[0,0,1] op_sel_hi:[1,0,0]
	s_nop 0
	v_pk_add_f32 v[132:133], v[122:123], v[114:115]
	v_pk_add_f32 v[114:115], v[122:123], v[114:115] neg_lo:[0,1] neg_hi:[0,1]
	v_xor_b32_e32 v122, 0x80000000, v129
	v_mov_b32_e32 v123, v128
	v_pk_add_f32 v[128:129], v[112:113], v[122:123]
	v_pk_add_f32 v[112:113], v[112:113], v[122:123] neg_lo:[0,1] neg_hi:[0,1]
	v_pk_mul_f32 v[122:123], v[116:117], s[96:97]
	s_nop 0
	v_pk_fma_f32 v[116:117], v[116:117], s[94:95], v[122:123] op_sel:[0,0,1] op_sel_hi:[1,0,0] neg_lo:[1,0,0] neg_hi:[1,0,0]
	s_nop 0
	v_pk_add_f32 v[122:123], v[8:9], v[116:117]
	v_pk_add_f32 v[8:9], v[8:9], v[116:117] neg_lo:[0,1] neg_hi:[0,1]
	v_pk_add_f32 v[116:117], v[130:131], v[138:139]
	v_pk_add_f32 v[130:131], v[130:131], v[138:139] neg_lo:[0,1] neg_hi:[0,1]
	v_pk_mul_f32 v[138:139], v[118:119], s[96:97]
	s_nop 0
	v_pk_fma_f32 v[118:119], v[118:119], s[94:95], v[138:139] op_sel:[0,0,1] op_sel_hi:[1,0,0]
	s_nop 0
	v_pk_add_f32 v[138:139], v[126:127], v[118:119]
	v_pk_add_f32 v[118:119], v[126:127], v[118:119] neg_lo:[0,1] neg_hi:[0,1]
	v_xor_b32_e32 v126, 0x80000000, v125
	v_mov_b32_e32 v127, v124
	v_pk_add_f32 v[124:125], v[136:137], v[126:127]
	v_pk_add_f32 v[126:127], v[136:137], v[126:127] neg_lo:[0,1] neg_hi:[0,1]
	v_pk_mul_f32 v[136:137], v[108:109], s[96:97]
	s_nop 0
	v_pk_fma_f32 v[108:109], v[108:109], s[94:95], v[136:137] op_sel:[0,0,1] op_sel_hi:[1,0,0] neg_lo:[1,0,0] neg_hi:[1,0,0]
	s_nop 0
	v_pk_add_f32 v[136:137], v[4:5], v[108:109]
	v_pk_add_f32 v[4:5], v[4:5], v[108:109] neg_lo:[0,1] neg_hi:[0,1]
	v_pk_add_f32 v[108:109], v[134:135], v[120:121]
	v_pk_add_f32 v[120:121], v[134:135], v[120:121] neg_lo:[0,1] neg_hi:[0,1]
	v_pk_mul_f32 v[134:135], v[0:1], s[96:97]
	s_nop 0
	v_pk_fma_f32 v[0:1], v[0:1], s[94:95], v[134:135] op_sel:[0,0,1] op_sel_hi:[1,0,0]
	s_nop 0
	v_pk_add_f32 v[134:135], v[102:103], v[0:1]
	v_pk_add_f32 v[0:1], v[102:103], v[0:1] neg_lo:[0,1] neg_hi:[0,1]
	v_xor_b32_e32 v102, 0x80000000, v101
	v_mov_b32_e32 v103, v100
	v_pk_add_f32 v[100:101], v[110:111], v[102:103]
	v_pk_add_f32 v[102:103], v[110:111], v[102:103] neg_lo:[0,1] neg_hi:[0,1]
	v_pk_mul_f32 v[110:111], v[94:95], s[96:97]
	s_nop 0
	v_pk_fma_f32 v[94:95], v[94:95], s[94:95], v[110:111] op_sel:[0,0,1] op_sel_hi:[1,0,0] neg_lo:[1,0,0] neg_hi:[1,0,0]
	s_nop 0
	v_pk_add_f32 v[110:111], v[10:11], v[94:95]
	v_pk_add_f32 v[10:11], v[10:11], v[94:95] neg_lo:[0,1] neg_hi:[0,1]
	v_pk_add_f32 v[94:95], v[106:107], v[88:89]
	v_pk_add_f32 v[88:89], v[106:107], v[88:89] neg_lo:[0,1] neg_hi:[0,1]
	v_pk_mul_f32 v[106:107], v[132:133], s[6:7]
	s_nop 0
	v_pk_fma_f32 v[106:107], v[132:133], s[56:57], v[106:107] op_sel:[0,0,1] op_sel_hi:[1,0,0]
	s_mov_b32 s57, s66
	v_pk_add_f32 v[132:133], v[104:105], v[106:107]
	v_pk_add_f32 v[104:105], v[104:105], v[106:107] neg_lo:[0,1] neg_hi:[0,1]
	v_pk_mul_f32 v[106:107], v[128:129], s[96:97]
	s_nop 0
	v_pk_fma_f32 v[106:107], v[128:129], s[94:95], v[106:107] op_sel:[0,0,1] op_sel_hi:[1,0,0]
	s_nop 0
	v_pk_add_f32 v[128:129], v[96:97], v[106:107]
	v_pk_add_f32 v[96:97], v[96:97], v[106:107] neg_lo:[0,1] neg_hi:[0,1]
	v_pk_mul_f32 v[106:107], v[122:123], s[56:57]
	s_nop 0
	v_pk_fma_f32 v[106:107], v[122:123], s[84:85], v[106:107] op_sel:[0,0,1] op_sel_hi:[1,0,0]
	s_nop 0
	v_pk_add_f32 v[122:123], v[92:93], v[106:107]
	v_pk_add_f32 v[92:93], v[92:93], v[106:107] neg_lo:[0,1] neg_hi:[0,1]
	v_xor_b32_e32 v106, 0x80000000, v99
	v_mov_b32_e32 v107, v98
	v_pk_add_f32 v[98:99], v[86:87], v[106:107]
	v_pk_add_f32 v[86:87], v[86:87], v[106:107] neg_lo:[0,1] neg_hi:[0,1]
	v_pk_mul_f32 v[106:107], v[114:115], s[56:57]
	s_nop 0
	v_pk_fma_f32 v[106:107], v[114:115], s[84:85], v[106:107] op_sel:[0,0,1] op_sel_hi:[1,0,0] neg_lo:[1,0,0] neg_hi:[1,0,0]
	s_nop 0
	v_pk_add_f32 v[114:115], v[90:91], v[106:107]
	v_pk_add_f32 v[90:91], v[90:91], v[106:107] neg_lo:[0,1] neg_hi:[0,1]
	v_pk_mul_f32 v[106:107], v[112:113], s[96:97]
	s_nop 0
	v_pk_fma_f32 v[106:107], v[112:113], s[94:95], v[106:107] op_sel:[0,0,1] op_sel_hi:[1,0,0] neg_lo:[1,0,0] neg_hi:[1,0,0]
	s_nop 0
	v_pk_add_f32 v[112:113], v[2:3], v[106:107]
	v_pk_add_f32 v[2:3], v[2:3], v[106:107] neg_lo:[0,1] neg_hi:[0,1]
	v_pk_mul_f32 v[106:107], v[8:9], s[6:7]
	s_nop 0
	v_pk_fma_f32 v[8:9], v[8:9], s[56:57], v[106:107] op_sel:[0,0,1] op_sel_hi:[1,0,0] neg_lo:[1,0,0] neg_hi:[1,0,0]
	s_nop 0
	v_pk_add_f32 v[106:107], v[6:7], v[8:9]
	v_pk_add_f32 v[6:7], v[6:7], v[8:9] neg_lo:[0,1] neg_hi:[0,1]
	v_pk_add_f32 v[8:9], v[116:117], v[108:109]
	v_pk_add_f32 v[108:109], v[116:117], v[108:109] neg_lo:[0,1] neg_hi:[0,1]
	v_pk_mul_f32 v[116:117], v[134:135], s[6:7]
	s_nop 0
	v_pk_fma_f32 v[116:117], v[134:135], s[56:57], v[116:117] op_sel:[0,0,1] op_sel_hi:[1,0,0]
	s_nop 0
	v_pk_add_f32 v[134:135], v[138:139], v[116:117]
	v_pk_add_f32 v[116:117], v[138:139], v[116:117] neg_lo:[0,1] neg_hi:[0,1]
	v_pk_mul_f32 v[138:139], v[100:101], s[96:97]
	s_nop 0
	v_pk_fma_f32 v[100:101], v[100:101], s[94:95], v[138:139] op_sel:[0,0,1] op_sel_hi:[1,0,0]
; #define LAS __attribute__((address_space(3)))
; __device__ __forceinline__ f2 cmulc(f2 a, float wr, float wi) { const f2 s = __builtin_shufflevector(a, a, 1, 0); return s * (f2){wi, -wi} + a * (f2){wr, wr}; }
; __device__ __forceinline__ void ifft32(f2 (&x)[32]) {
;     constexpr float TWR[32] = {TWR_LIST}; constexpr float TWI[32] = {TWI_LIST};
; #pragma unroll
;     for (int h = 1; h <= 16; h <<= 1) {
; #pragma unroll
;         for (int i0 = 0; i0 < 32; i0 += 2 * h) {
; #pragma unroll
;             for (int j = 0; j < h; ++j) {
;                 const int i = i0 + j, k = i + h, m = j * (32 / h);
;                 const f2 a = x[i], y = x[k];
;                 f2 b;
;                 if (m == 0) b = y;
;                 else if (m == 16) b = (f2){-y.y, y.x};
;                 else b = cmulc(y, TWR[m], TWI[m]);
;                 x[i] = a + b; x[k] = a - b;
;             }
;         }
;     }
; }
; __device__ __forceinline__ void fft_inverse(f2 (&x)[32], LAS f2* X, int t, LAS const float* W1, LAS const M2C* MC) {
;     ...
;     LAS f2* wp = X + (t >> 4) * XP + (t & 15); LAS const f2* rp = X + t; LAS f2* wp1 = wp + 256; LAS const f2* rp1 = rp + 16 * XP;
;     asm volatile("" : "+v"(wp), "+v"(rp), "+v"(wp1), "+v"(rp1));
; #pragma unroll
;     for (int m = 0; m < 16; ++m) { wp[16 * m] = x[m]; wp1[16 * m] = x[m + 16]; }
	s_nop 0
	v_pk_add_f32 v[138:139], v[124:125], v[100:101]
	v_pk_add_f32 v[100:101], v[124:125], v[100:101] neg_lo:[0,1] neg_hi:[0,1]
	v_pk_mul_f32 v[124:125], v[110:111], s[56:57]
	s_nop 0
	v_pk_fma_f32 v[110:111], v[110:111], s[84:85], v[124:125] op_sel:[0,0,1] op_sel_hi:[1,0,0]
	s_nop 0
	v_pk_add_f32 v[124:125], v[136:137], v[110:111]
	v_pk_add_f32 v[110:111], v[136:137], v[110:111] neg_lo:[0,1] neg_hi:[0,1]
	v_xor_b32_e32 v136, 0x80000000, v121
	v_mov_b32_e32 v137, v120
	v_pk_add_f32 v[120:121], v[130:131], v[136:137]
	v_pk_add_f32 v[130:131], v[130:131], v[136:137] neg_lo:[0,1] neg_hi:[0,1]
	v_pk_mul_f32 v[136:137], v[0:1], s[56:57]
	s_nop 0
	v_pk_fma_f32 v[0:1], v[0:1], s[84:85], v[136:137] op_sel:[0,0,1] op_sel_hi:[1,0,0] neg_lo:[1,0,0] neg_hi:[1,0,0]
	s_nop 0
	v_pk_add_f32 v[136:137], v[118:119], v[0:1]
	v_pk_add_f32 v[0:1], v[118:119], v[0:1] neg_lo:[0,1] neg_hi:[0,1]
	v_pk_mul_f32 v[118:119], v[102:103], s[96:97]
	s_nop 0
	v_pk_fma_f32 v[102:103], v[102:103], s[94:95], v[118:119] op_sel:[0,0,1] op_sel_hi:[1,0,0] neg_lo:[1,0,0] neg_hi:[1,0,0]
	s_nop 0
	v_pk_add_f32 v[118:119], v[126:127], v[102:103]
	v_pk_add_f32 v[102:103], v[126:127], v[102:103] neg_lo:[0,1] neg_hi:[0,1]
	v_pk_mul_f32 v[126:127], v[10:11], s[6:7]
	s_nop 0
	v_pk_fma_f32 v[10:11], v[10:11], s[56:57], v[126:127] op_sel:[0,0,1] op_sel_hi:[1,0,0] neg_lo:[1,0,0] neg_hi:[1,0,0]
	s_nop 0
	v_pk_add_f32 v[126:127], v[4:5], v[10:11]
	v_pk_add_f32 v[4:5], v[4:5], v[10:11] neg_lo:[0,1] neg_hi:[0,1]
	v_pk_add_f32 v[10:11], v[94:95], v[8:9]
	ds_write_b64 v214, v[10:11]
	v_pk_add_f32 v[8:9], v[94:95], v[8:9] neg_lo:[0,1] neg_hi:[0,1]
	ds_write_b64 v215, v[8:9]
	v_pk_mul_f32 v[94:95], v[134:135], s[76:77]
	s_nop 0
	v_pk_fma_f32 v[94:95], v[134:135], s[52:53], v[94:95] op_sel:[0,0,1] op_sel_hi:[1,0,0]
	s_mov_b32 s53, s78
	v_pk_add_f32 v[134:135], v[132:133], v[94:95]
	ds_write_b64 v214, v[134:135] offset:128
	v_pk_add_f32 v[94:95], v[132:133], v[94:95] neg_lo:[0,1] neg_hi:[0,1]
	ds_write_b64 v215, v[94:95] offset:128
	v_pk_mul_f32 v[132:133], v[138:139], s[6:7]
	s_nop 0
	v_pk_fma_f32 v[132:133], v[138:139], s[56:57], v[132:133] op_sel:[0,0,1] op_sel_hi:[1,0,0]
	s_nop 0
	v_pk_add_f32 v[138:139], v[128:129], v[132:133]
	ds_write_b64 v214, v[138:139] offset:256
	v_pk_add_f32 v[128:129], v[128:129], v[132:133] neg_lo:[0,1] neg_hi:[0,1]
	ds_write_b64 v215, v[128:129] offset:256
	v_pk_mul_f32 v[132:133], v[124:125], s[20:21]
	s_nop 0
	v_pk_fma_f32 v[124:125], v[124:125], s[60:61], v[132:133] op_sel:[0,0,1] op_sel_hi:[1,0,0]
	s_mov_b32 s61, s64
	v_pk_add_f32 v[132:133], v[122:123], v[124:125]
	ds_write_b64 v214, v[132:133] offset:384
	v_pk_add_f32 v[122:123], v[122:123], v[124:125] neg_lo:[0,1] neg_hi:[0,1]
	ds_write_b64 v215, v[122:123] offset:384
	v_pk_mul_f32 v[124:125], v[120:121], s[96:97]
	s_nop 0
	v_pk_fma_f32 v[120:121], v[120:121], s[94:95], v[124:125] op_sel:[0,0,1] op_sel_hi:[1,0,0]
	s_nop 0
	v_pk_add_f32 v[124:125], v[98:99], v[120:121]
	ds_write_b64 v214, v[124:125] offset:512
	v_pk_add_f32 v[98:99], v[98:99], v[120:121] neg_lo:[0,1] neg_hi:[0,1]
	ds_write_b64 v215, v[98:99] offset:512
	v_pk_mul_f32 v[120:121], v[136:137], s[60:61]
	s_nop 0
	v_pk_fma_f32 v[120:121], v[136:137], s[86:87], v[120:121] op_sel:[0,0,1] op_sel_hi:[1,0,0]
	s_nop 0
	v_pk_add_f32 v[136:137], v[114:115], v[120:121]
	ds_write_b64 v214, v[136:137] offset:640
	v_pk_add_f32 v[114:115], v[114:115], v[120:121] neg_lo:[0,1] neg_hi:[0,1]
	ds_write_b64 v215, v[114:115] offset:640
	v_pk_mul_f32 v[120:121], v[118:119], s[56:57]
	s_nop 0
	v_pk_fma_f32 v[118:119], v[118:119], s[84:85], v[120:121] op_sel:[0,0,1] op_sel_hi:[1,0,0]
	s_nop 0
	v_pk_add_f32 v[120:121], v[112:113], v[118:119]
	ds_write_b64 v214, v[120:121] offset:768
	v_pk_add_f32 v[112:113], v[112:113], v[118:119] neg_lo:[0,1] neg_hi:[0,1]
	ds_write_b64 v215, v[112:113] offset:768
	v_pk_mul_f32 v[118:119], v[126:127], s[52:53]
	s_nop 0
	v_pk_fma_f32 v[118:119], v[126:127], s[10:11], v[118:119] op_sel:[0,0,1] op_sel_hi:[1,0,0]
	s_nop 0
	v_pk_add_f32 v[126:127], v[106:107], v[118:119]
	ds_write_b64 v214, v[126:127] offset:896
	v_pk_add_f32 v[106:107], v[106:107], v[118:119] neg_lo:[0,1] neg_hi:[0,1]
	ds_write_b64 v215, v[106:107] offset:896
	v_xor_b32_e32 v118, 0x80000000, v109
	v_mov_b32_e32 v119, v108
	v_pk_add_f32 v[108:109], v[88:89], v[118:119]
	ds_write_b64 v214, v[108:109] offset:1024
	v_pk_add_f32 v[88:89], v[88:89], v[118:119] neg_lo:[0,1] neg_hi:[0,1]
	ds_write_b64 v215, v[88:89] offset:1024
	v_pk_mul_f32 v[118:119], v[116:117], s[52:53]
	s_nop 0
	v_pk_fma_f32 v[116:117], v[116:117], s[10:11], v[118:119] op_sel:[0,0,1] op_sel_hi:[1,0,0] neg_lo:[1,0,0] neg_hi:[1,0,0]
	s_nop 0
	v_pk_add_f32 v[118:119], v[104:105], v[116:117]
	ds_write_b64 v214, v[118:119] offset:1152
	v_pk_add_f32 v[104:105], v[104:105], v[116:117] neg_lo:[0,1] neg_hi:[0,1]
	ds_write_b64 v215, v[104:105] offset:1152
	v_pk_mul_f32 v[116:117], v[100:101], s[56:57]
	s_nop 0
	v_pk_fma_f32 v[100:101], v[100:101], s[84:85], v[116:117] op_sel:[0,0,1] op_sel_hi:[1,0,0] neg_lo:[1,0,0] neg_hi:[1,0,0]
	s_nop 0
	v_pk_add_f32 v[116:117], v[96:97], v[100:101]
	ds_write_b64 v214, v[116:117] offset:1280
	v_pk_add_f32 v[96:97], v[96:97], v[100:101] neg_lo:[0,1] neg_hi:[0,1]
	ds_write_b64 v215, v[96:97] offset:1280
	v_pk_mul_f32 v[100:101], v[110:111], s[60:61]
	s_nop 0
	v_pk_fma_f32 v[100:101], v[110:111], s[86:87], v[100:101] op_sel:[0,0,1] op_sel_hi:[1,0,0] neg_lo:[1,0,0] neg_hi:[1,0,0]
	s_nop 0
	v_pk_add_f32 v[110:111], v[92:93], v[100:101]
	ds_write_b64 v214, v[110:111] offset:1408
	v_pk_add_f32 v[92:93], v[92:93], v[100:101] neg_lo:[0,1] neg_hi:[0,1]
	ds_write_b64 v215, v[92:93] offset:1408
; #define LAS __attribute__((address_space(3)))
; #define LBAR() do { asm volatile("s_waitcnt lgkmcnt(0)" ::: "memory"); __builtin_amdgcn_s_barrier(); asm volatile("" ::: "memory"); } while (0)
; template <bool CONJ> __device__ __forceinline__ void twiddle32(f2 (&x)[32], float wr, float wi) {
;     asm volatile("" : "+v"(wr), "+v"(wi));
;     f2 c = (f2){wr, CONJ ? -wi : wi}; const f2 w = c;
; #pragma unroll
;     for (int k = 1; k < 32; ++k) { const int p = brev5(k); x[p] = cmulr(x[p], c); if (k < 31) c = cmulr(c, w); }
; }
; __device__ __forceinline__ void fft_inverse(f2 (&x)[32], LAS f2* X, int t, LAS const float* W1, LAS const M2C* MC) {
;     ...
;     LAS f2* wp = X + (t >> 4) * XP + (t & 15); LAS const f2* rp = X + t; LAS f2* wp1 = wp + 256; LAS const f2* rp1 = rp + 16 * XP;
;     asm volatile("" : "+v"(wp), "+v"(rp), "+v"(wp1), "+v"(rp1));
; #pragma unroll
;     for (int m = 0; m < 16; ++m) { wp[16 * m] = x[m]; wp1[16 * m] = x[m + 16]; }
;     LBAR();
; #pragma unroll
;     for (int k = 0; k < 16; ++k) { x[brev5(k)] = rp[k * XP]; x[brev5(k + 16)] = rp1[k * XP]; }
;     LBAR();
;     { const float wr = W1[0], wi = W1[1]; twiddle32<true>(x, wr * wr - wi * wi, 2.f * wr * wi); }
	v_pk_mul_f32 v[100:101], v[130:131], s[96:97]
	s_nop 0
	v_pk_fma_f32 v[100:101], v[130:131], s[94:95], v[100:101] op_sel:[0,0,1] op_sel_hi:[1,0,0] neg_lo:[1,0,0] neg_hi:[1,0,0]
	s_nop 0
	v_pk_add_f32 v[130:131], v[86:87], v[100:101]
	ds_write_b64 v214, v[130:131] offset:1536
	v_pk_add_f32 v[86:87], v[86:87], v[100:101] neg_lo:[0,1] neg_hi:[0,1]
	ds_write_b64 v215, v[86:87] offset:1536
	v_pk_mul_f32 v[100:101], v[0:1], s[20:21]
	s_nop 0
	v_pk_fma_f32 v[0:1], v[0:1], s[60:61], v[100:101] op_sel:[0,0,1] op_sel_hi:[1,0,0] neg_lo:[1,0,0] neg_hi:[1,0,0]
	s_nop 0
	v_pk_add_f32 v[100:101], v[90:91], v[0:1]
	ds_write_b64 v214, v[100:101] offset:1664
	v_pk_add_f32 v[0:1], v[90:91], v[0:1] neg_lo:[0,1] neg_hi:[0,1]
	ds_write_b64 v215, v[0:1] offset:1664
	v_pk_mul_f32 v[90:91], v[102:103], s[6:7]
	s_nop 0
	v_pk_fma_f32 v[90:91], v[102:103], s[56:57], v[90:91] op_sel:[0,0,1] op_sel_hi:[1,0,0] neg_lo:[1,0,0] neg_hi:[1,0,0]
	s_nop 0
	v_pk_add_f32 v[102:103], v[2:3], v[90:91]
	ds_write_b64 v214, v[102:103] offset:1792
	v_pk_add_f32 v[2:3], v[2:3], v[90:91] neg_lo:[0,1] neg_hi:[0,1]
	ds_write_b64 v215, v[2:3] offset:1792
	v_pk_mul_f32 v[90:91], v[4:5], s[76:77]
	s_nop 0
	v_pk_fma_f32 v[4:5], v[4:5], s[52:53], v[90:91] op_sel:[0,0,1] op_sel_hi:[1,0,0] neg_lo:[1,0,0] neg_hi:[1,0,0]
	s_nop 0
	v_pk_add_f32 v[90:91], v[6:7], v[4:5]
	ds_write_b64 v214, v[90:91] offset:1920
	v_pk_add_f32 v[4:5], v[6:7], v[4:5] neg_lo:[0,1] neg_hi:[0,1]
	ds_write_b64 v215, v[4:5] offset:1920
	s_waitcnt lgkmcnt(0)
	s_barrier
	ds_read_b64 v[0:1], v213
	ds_read_b64 v[2:3], v213 offset:4224
	ds_read_b64 v[4:5], v213 offset:8448
	ds_read_b64 v[6:7], v213 offset:12672
	ds_read_b64 v[8:9], v213 offset:16896
	ds_read_b64 v[10:11], v213 offset:21120
	ds_read_b64 v[86:87], v213 offset:25344
	ds_read_b64 v[88:89], v213 offset:29568
	ds_read_b64 v[90:91], v213 offset:33792
	ds_read_b64 v[92:93], v213 offset:38016
	ds_read_b64 v[94:95], v213 offset:42240
	ds_read_b64 v[96:97], v213 offset:46464
	ds_read_b64 v[98:99], v213 offset:50688
	ds_read_b64 v[100:101], v213 offset:54912
	ds_read_b64 v[102:103], v213 offset:59136
	ds_read_b64 v[104:105], v213 offset:63360
	ds_read_b64 v[106:107], v212
	ds_read_b64 v[108:109], v212 offset:4224
	ds_read_b64 v[110:111], v212 offset:8448
	ds_read_b64 v[112:113], v212 offset:12672
	ds_read_b64 v[114:115], v212 offset:16896
	ds_read_b64 v[116:117], v212 offset:21120
	ds_read_b64 v[118:119], v212 offset:25344
	ds_read_b64 v[120:121], v212 offset:29568
	ds_read_b64 v[122:123], v212 offset:33792
	ds_read_b64 v[124:125], v212 offset:38016
	ds_read_b64 v[126:127], v212 offset:42240
	ds_read_b64 v[128:129], v212 offset:46464
	ds_read_b64 v[130:131], v212 offset:50688
	ds_read_b64 v[132:133], v212 offset:54912
	ds_read_b64 v[134:135], v212 offset:59136
	ds_read_b64 v[136:137], v212 offset:63360
	s_waitcnt lgkmcnt(0)
	s_barrier
	ds_read_b64 v[138:139], v211
	s_waitcnt lgkmcnt(0)
	v_pk_mul_f32 v[140:141], v[138:139], v[138:139]
	v_add_f32_e32 v13, v138, v138
	v_sub_f32_e32 v140, v140, v141
	v_mul_f32_e32 v13, v13, v139
	s_nop 0
	v_xor_b32_e32 v141, 0x80000000, v13
	v_pk_mul_f32 v[138:139], v[2:3], v[140:141] op_sel_hi:[1,0]
	s_nop 0
	v_pk_fma_f32 v[2:3], v[2:3], v[140:141], v[138:139] op_sel:[1,1,0] op_sel_hi:[0,1,1] neg_lo:[0,1,0]
	v_pk_mul_f32 v[138:139], v[140:141], v[140:141] op_sel_hi:[1,0]
	s_nop 0
	v_pk_fma_f32 v[138:139], v[140:141], v[140:141], v[138:139] op_sel:[1,1,0] op_sel_hi:[0,1,1] neg_lo:[0,1,0]
	s_nop 0
	v_pk_mul_f32 v[142:143], v[4:5], v[138:139] op_sel_hi:[1,0]
	s_nop 0
	v_pk_fma_f32 v[4:5], v[4:5], v[138:139], v[142:143] op_sel:[1,1,0] op_sel_hi:[0,1,1] neg_lo:[0,1,0]
	v_pk_mul_f32 v[142:143], v[138:139], v[140:141] op_sel_hi:[1,0]
	s_nop 0
	v_pk_fma_f32 v[138:139], v[138:139], v[140:141], v[142:143] op_sel:[1,1,0] op_sel_hi:[0,1,1] neg_lo:[0,1,0]
	s_nop 0
	v_pk_mul_f32 v[142:143], v[6:7], v[138:139] op_sel_hi:[1,0]
	s_nop 0
	v_pk_fma_f32 v[6:7], v[6:7], v[138:139], v[142:143] op_sel:[1,1,0] op_sel_hi:[0,1,1] neg_lo:[0,1,0]
	v_pk_mul_f32 v[142:143], v[138:139], v[140:141] op_sel_hi:[1,0]
	s_nop 0
	v_pk_fma_f32 v[138:139], v[138:139], v[140:141], v[142:143] op_sel:[1,1,0] op_sel_hi:[0,1,1] neg_lo:[0,1,0]
	s_nop 0
	v_pk_mul_f32 v[142:143], v[8:9], v[138:139] op_sel_hi:[1,0]
	s_nop 0
	v_pk_fma_f32 v[8:9], v[8:9], v[138:139], v[142:143] op_sel:[1,1,0] op_sel_hi:[0,1,1] neg_lo:[0,1,0]
	v_pk_mul_f32 v[142:143], v[138:139], v[140:141] op_sel_hi:[1,0]
	s_nop 0
	v_pk_fma_f32 v[138:139], v[138:139], v[140:141], v[142:143] op_sel:[1,1,0] op_sel_hi:[0,1,1] neg_lo:[0,1,0]
	s_nop 0
	v_pk_mul_f32 v[142:143], v[10:11], v[138:139] op_sel_hi:[1,0]
	s_nop 0
	v_pk_fma_f32 v[10:11], v[10:11], v[138:139], v[142:143] op_sel:[1,1,0] op_sel_hi:[0,1,1] neg_lo:[0,1,0]
	v_pk_mul_f32 v[142:143], v[138:139], v[140:141] op_sel_hi:[1,0]
	s_nop 0
	v_pk_fma_f32 v[138:139], v[138:139], v[140:141], v[142:143] op_sel:[1,1,0] op_sel_hi:[0,1,1] neg_lo:[0,1,0]
	s_nop 0
	v_pk_mul_f32 v[142:143], v[86:87], v[138:139] op_sel_hi:[1,0]
	s_nop 0
	v_pk_fma_f32 v[86:87], v[86:87], v[138:139], v[142:143] op_sel:[1,1,0] op_sel_hi:[0,1,1] neg_lo:[0,1,0]
	v_pk_mul_f32 v[142:143], v[138:139], v[140:141] op_sel_hi:[1,0]
	s_nop 0
	v_pk_fma_f32 v[138:139], v[138:139], v[140:141], v[142:143] op_sel:[1,1,0] op_sel_hi:[0,1,1] neg_lo:[0,1,0]
	s_nop 0
	v_pk_mul_f32 v[142:143], v[88:89], v[138:139] op_sel_hi:[1,0]
	s_nop 0
	v_pk_fma_f32 v[88:89], v[88:89], v[138:139], v[142:143] op_sel:[1,1,0] op_sel_hi:[0,1,1] neg_lo:[0,1,0]
	v_pk_mul_f32 v[142:143], v[138:139], v[140:141] op_sel_hi:[1,0]
	s_nop 0
	v_pk_fma_f32 v[138:139], v[138:139], v[140:141], v[142:143] op_sel:[1,1,0] op_sel_hi:[0,1,1] neg_lo:[0,1,0]
; template <bool CONJ> __device__ __forceinline__ void twiddle32(f2 (&x)[32], float wr, float wi) {
;     asm volatile("" : "+v"(wr), "+v"(wi));
;     f2 c = (f2){wr, CONJ ? -wi : wi}; const f2 w = c;
; #pragma unroll
;     for (int k = 1; k < 32; ++k) { const int p = brev5(k); x[p] = cmulr(x[p], c); if (k < 31) c = cmulr(c, w); }
; }
	s_nop 0
	v_pk_mul_f32 v[142:143], v[90:91], v[138:139] op_sel_hi:[1,0]
	s_nop 0
	v_pk_fma_f32 v[90:91], v[90:91], v[138:139], v[142:143] op_sel:[1,1,0] op_sel_hi:[0,1,1] neg_lo:[0,1,0]
	v_pk_mul_f32 v[142:143], v[138:139], v[140:141] op_sel_hi:[1,0]
	s_nop 0
	v_pk_fma_f32 v[138:139], v[138:139], v[140:141], v[142:143] op_sel:[1,1,0] op_sel_hi:[0,1,1] neg_lo:[0,1,0]
	s_nop 0
	v_pk_mul_f32 v[142:143], v[92:93], v[138:139] op_sel_hi:[1,0]
	s_nop 0
	v_pk_fma_f32 v[92:93], v[92:93], v[138:139], v[142:143] op_sel:[1,1,0] op_sel_hi:[0,1,1] neg_lo:[0,1,0]
	v_pk_mul_f32 v[142:143], v[138:139], v[140:141] op_sel_hi:[1,0]
	s_nop 0
	v_pk_fma_f32 v[138:139], v[138:139], v[140:141], v[142:143] op_sel:[1,1,0] op_sel_hi:[0,1,1] neg_lo:[0,1,0]
	s_nop 0
	v_pk_mul_f32 v[142:143], v[94:95], v[138:139] op_sel_hi:[1,0]
	s_nop 0
	v_pk_fma_f32 v[94:95], v[94:95], v[138:139], v[142:143] op_sel:[1,1,0] op_sel_hi:[0,1,1] neg_lo:[0,1,0]
	v_pk_mul_f32 v[142:143], v[138:139], v[140:141] op_sel_hi:[1,0]
	s_nop 0
	v_pk_fma_f32 v[138:139], v[138:139], v[140:141], v[142:143] op_sel:[1,1,0] op_sel_hi:[0,1,1] neg_lo:[0,1,0]
	s_nop 0
	v_pk_mul_f32 v[142:143], v[96:97], v[138:139] op_sel_hi:[1,0]
	s_nop 0
	v_pk_fma_f32 v[96:97], v[96:97], v[138:139], v[142:143] op_sel:[1,1,0] op_sel_hi:[0,1,1] neg_lo:[0,1,0]
	v_pk_mul_f32 v[142:143], v[138:139], v[140:141] op_sel_hi:[1,0]
	s_nop 0
	v_pk_fma_f32 v[138:139], v[138:139], v[140:141], v[142:143] op_sel:[1,1,0] op_sel_hi:[0,1,1] neg_lo:[0,1,0]
	s_nop 0
	v_pk_mul_f32 v[142:143], v[98:99], v[138:139] op_sel_hi:[1,0]
	s_nop 0
	v_pk_fma_f32 v[98:99], v[98:99], v[138:139], v[142:143] op_sel:[1,1,0] op_sel_hi:[0,1,1] neg_lo:[0,1,0]
	v_pk_mul_f32 v[142:143], v[138:139], v[140:141] op_sel_hi:[1,0]
	s_nop 0
	v_pk_fma_f32 v[138:139], v[138:139], v[140:141], v[142:143] op_sel:[1,1,0] op_sel_hi:[0,1,1] neg_lo:[0,1,0]
	s_nop 0
	v_pk_mul_f32 v[142:143], v[100:101], v[138:139] op_sel_hi:[1,0]
	s_nop 0
	v_pk_fma_f32 v[100:101], v[100:101], v[138:139], v[142:143] op_sel:[1,1,0] op_sel_hi:[0,1,1] neg_lo:[0,1,0]
	v_pk_mul_f32 v[142:143], v[138:139], v[140:141] op_sel_hi:[1,0]
	s_nop 0
	v_pk_fma_f32 v[138:139], v[138:139], v[140:141], v[142:143] op_sel:[1,1,0] op_sel_hi:[0,1,1] neg_lo:[0,1,0]
	s_nop 0
	v_pk_mul_f32 v[142:143], v[102:103], v[138:139] op_sel_hi:[1,0]
	s_nop 0
	v_pk_fma_f32 v[102:103], v[102:103], v[138:139], v[142:143] op_sel:[1,1,0] op_sel_hi:[0,1,1] neg_lo:[0,1,0]
	v_pk_mul_f32 v[142:143], v[138:139], v[140:141] op_sel_hi:[1,0]
	s_nop 0
	v_pk_fma_f32 v[138:139], v[138:139], v[140:141], v[142:143] op_sel:[1,1,0] op_sel_hi:[0,1,1] neg_lo:[0,1,0]
	s_nop 0
	v_pk_mul_f32 v[142:143], v[104:105], v[138:139] op_sel_hi:[1,0]
	s_nop 0
	v_pk_fma_f32 v[104:105], v[104:105], v[138:139], v[142:143] op_sel:[1,1,0] op_sel_hi:[0,1,1] neg_lo:[0,1,0]
	v_pk_mul_f32 v[142:143], v[138:139], v[140:141] op_sel_hi:[1,0]
	s_nop 0
	v_pk_fma_f32 v[138:139], v[138:139], v[140:141], v[142:143] op_sel:[1,1,0] op_sel_hi:[0,1,1] neg_lo:[0,1,0]
	s_nop 0
	v_pk_mul_f32 v[142:143], v[106:107], v[138:139] op_sel_hi:[1,0]
	s_nop 0
	v_pk_fma_f32 v[106:107], v[106:107], v[138:139], v[142:143] op_sel:[1,1,0] op_sel_hi:[0,1,1] neg_lo:[0,1,0]
	v_pk_mul_f32 v[142:143], v[138:139], v[140:141] op_sel_hi:[1,0]
	s_nop 0
	v_pk_fma_f32 v[138:139], v[138:139], v[140:141], v[142:143] op_sel:[1,1,0] op_sel_hi:[0,1,1] neg_lo:[0,1,0]
	s_nop 0
	v_pk_mul_f32 v[142:143], v[108:109], v[138:139] op_sel_hi:[1,0]
	s_nop 0
	v_pk_fma_f32 v[108:109], v[108:109], v[138:139], v[142:143] op_sel:[1,1,0] op_sel_hi:[0,1,1] neg_lo:[0,1,0]
	v_pk_mul_f32 v[142:143], v[138:139], v[140:141] op_sel_hi:[1,0]
	s_nop 0
	v_pk_fma_f32 v[138:139], v[138:139], v[140:141], v[142:143] op_sel:[1,1,0] op_sel_hi:[0,1,1] neg_lo:[0,1,0]
	s_nop 0
	v_pk_mul_f32 v[142:143], v[110:111], v[138:139] op_sel_hi:[1,0]
	s_nop 0
	v_pk_fma_f32 v[110:111], v[110:111], v[138:139], v[142:143] op_sel:[1,1,0] op_sel_hi:[0,1,1] neg_lo:[0,1,0]
	v_pk_mul_f32 v[142:143], v[138:139], v[140:141] op_sel_hi:[1,0]
	s_nop 0
	v_pk_fma_f32 v[138:139], v[138:139], v[140:141], v[142:143] op_sel:[1,1,0] op_sel_hi:[0,1,1] neg_lo:[0,1,0]
	s_nop 0
	v_pk_mul_f32 v[142:143], v[112:113], v[138:139] op_sel_hi:[1,0]
	s_nop 0
	v_pk_fma_f32 v[112:113], v[112:113], v[138:139], v[142:143] op_sel:[1,1,0] op_sel_hi:[0,1,1] neg_lo:[0,1,0]
	v_pk_mul_f32 v[142:143], v[138:139], v[140:141] op_sel_hi:[1,0]
	s_nop 0
	v_pk_fma_f32 v[138:139], v[138:139], v[140:141], v[142:143] op_sel:[1,1,0] op_sel_hi:[0,1,1] neg_lo:[0,1,0]
	s_nop 0
	v_pk_mul_f32 v[142:143], v[114:115], v[138:139] op_sel_hi:[1,0]
	s_nop 0
	v_pk_fma_f32 v[114:115], v[114:115], v[138:139], v[142:143] op_sel:[1,1,0] op_sel_hi:[0,1,1] neg_lo:[0,1,0]
	v_pk_mul_f32 v[142:143], v[138:139], v[140:141] op_sel_hi:[1,0]
	s_nop 0
	v_pk_fma_f32 v[138:139], v[138:139], v[140:141], v[142:143] op_sel:[1,1,0] op_sel_hi:[0,1,1] neg_lo:[0,1,0]
	s_nop 0
	v_pk_mul_f32 v[142:143], v[116:117], v[138:139] op_sel_hi:[1,0]
	s_nop 0
	v_pk_fma_f32 v[116:117], v[116:117], v[138:139], v[142:143] op_sel:[1,1,0] op_sel_hi:[0,1,1] neg_lo:[0,1,0]
	v_pk_mul_f32 v[142:143], v[138:139], v[140:141] op_sel_hi:[1,0]
	s_nop 0
	v_pk_fma_f32 v[138:139], v[138:139], v[140:141], v[142:143] op_sel:[1,1,0] op_sel_hi:[0,1,1] neg_lo:[0,1,0]
	s_nop 0
	v_pk_mul_f32 v[142:143], v[118:119], v[138:139] op_sel_hi:[1,0]
	s_nop 0
	v_pk_fma_f32 v[118:119], v[118:119], v[138:139], v[142:143] op_sel:[1,1,0] op_sel_hi:[0,1,1] neg_lo:[0,1,0]
	v_pk_mul_f32 v[142:143], v[138:139], v[140:141] op_sel_hi:[1,0]
	s_nop 0
	v_pk_fma_f32 v[138:139], v[138:139], v[140:141], v[142:143] op_sel:[1,1,0] op_sel_hi:[0,1,1] neg_lo:[0,1,0]
	s_nop 0
	v_pk_mul_f32 v[142:143], v[120:121], v[138:139] op_sel_hi:[1,0]
; __device__ __forceinline__ f2 cmulc(f2 a, float wr, float wi) { const f2 s = __builtin_shufflevector(a, a, 1, 0); return s * (f2){wi, -wi} + a * (f2){wr, wr}; }
; __device__ __forceinline__ void ifft32(f2 (&x)[32]) {
;     constexpr float TWR[32] = {TWR_LIST}; constexpr float TWI[32] = {TWI_LIST};
; #pragma unroll
;     for (int h = 1; h <= 16; h <<= 1) {
; #pragma unroll
;         for (int i0 = 0; i0 < 32; i0 += 2 * h) {
; #pragma unroll
;             for (int j = 0; j < h; ++j) {
;                 const int i = i0 + j, k = i + h, m = j * (32 / h);
;                 const f2 a = x[i], y = x[k];
;                 f2 b;
;                 if (m == 0) b = y;
;                 else if (m == 16) b = (f2){-y.y, y.x};
;                 else b = cmulc(y, TWR[m], TWI[m]);
;                 x[i] = a + b; x[k] = a - b;
;             }
;         }
;     }
; }
; template <bool CONJ> __device__ __forceinline__ void twiddle32(f2 (&x)[32], float wr, float wi) {
;     asm volatile("" : "+v"(wr), "+v"(wi));
;     f2 c = (f2){wr, CONJ ? -wi : wi}; const f2 w = c;
; #pragma unroll
;     for (int k = 1; k < 32; ++k) { const int p = brev5(k); x[p] = cmulr(x[p], c); if (k < 31) c = cmulr(c, w); }
; }
	s_nop 0
	v_pk_fma_f32 v[120:121], v[120:121], v[138:139], v[142:143] op_sel:[1,1,0] op_sel_hi:[0,1,1] neg_lo:[0,1,0]
	v_pk_mul_f32 v[142:143], v[138:139], v[140:141] op_sel_hi:[1,0]
	s_nop 0
	v_pk_fma_f32 v[138:139], v[138:139], v[140:141], v[142:143] op_sel:[1,1,0] op_sel_hi:[0,1,1] neg_lo:[0,1,0]
	s_nop 0
	v_pk_mul_f32 v[142:143], v[122:123], v[138:139] op_sel_hi:[1,0]
	s_nop 0
	v_pk_fma_f32 v[122:123], v[122:123], v[138:139], v[142:143] op_sel:[1,1,0] op_sel_hi:[0,1,1] neg_lo:[0,1,0]
	v_pk_mul_f32 v[142:143], v[138:139], v[140:141] op_sel_hi:[1,0]
	s_nop 0
	v_pk_fma_f32 v[138:139], v[138:139], v[140:141], v[142:143] op_sel:[1,1,0] op_sel_hi:[0,1,1] neg_lo:[0,1,0]
	s_nop 0
	v_pk_mul_f32 v[142:143], v[124:125], v[138:139] op_sel_hi:[1,0]
	s_nop 0
	v_pk_fma_f32 v[124:125], v[124:125], v[138:139], v[142:143] op_sel:[1,1,0] op_sel_hi:[0,1,1] neg_lo:[0,1,0]
	v_pk_mul_f32 v[142:143], v[138:139], v[140:141] op_sel_hi:[1,0]
	s_nop 0
	v_pk_fma_f32 v[138:139], v[138:139], v[140:141], v[142:143] op_sel:[1,1,0] op_sel_hi:[0,1,1] neg_lo:[0,1,0]
	s_nop 0
	v_pk_mul_f32 v[142:143], v[126:127], v[138:139] op_sel_hi:[1,0]
	s_nop 0
	v_pk_fma_f32 v[126:127], v[126:127], v[138:139], v[142:143] op_sel:[1,1,0] op_sel_hi:[0,1,1] neg_lo:[0,1,0]
	v_pk_mul_f32 v[142:143], v[138:139], v[140:141] op_sel_hi:[1,0]
	s_nop 0
	v_pk_fma_f32 v[138:139], v[138:139], v[140:141], v[142:143] op_sel:[1,1,0] op_sel_hi:[0,1,1] neg_lo:[0,1,0]
	s_nop 0
	v_pk_mul_f32 v[142:143], v[128:129], v[138:139] op_sel_hi:[1,0]
	s_nop 0
	v_pk_fma_f32 v[128:129], v[128:129], v[138:139], v[142:143] op_sel:[1,1,0] op_sel_hi:[0,1,1] neg_lo:[0,1,0]
	v_pk_mul_f32 v[142:143], v[138:139], v[140:141] op_sel_hi:[1,0]
	s_nop 0
	v_pk_fma_f32 v[138:139], v[138:139], v[140:141], v[142:143] op_sel:[1,1,0] op_sel_hi:[0,1,1] neg_lo:[0,1,0]
	s_nop 0
	v_pk_mul_f32 v[142:143], v[130:131], v[138:139] op_sel_hi:[1,0]
	s_nop 0
	v_pk_fma_f32 v[130:131], v[130:131], v[138:139], v[142:143] op_sel:[1,1,0] op_sel_hi:[0,1,1] neg_lo:[0,1,0]
	v_pk_mul_f32 v[142:143], v[138:139], v[140:141] op_sel_hi:[1,0]
	s_nop 0
	v_pk_fma_f32 v[138:139], v[138:139], v[140:141], v[142:143] op_sel:[1,1,0] op_sel_hi:[0,1,1] neg_lo:[0,1,0]
	s_nop 0
	v_pk_mul_f32 v[142:143], v[132:133], v[138:139] op_sel_hi:[1,0]
	s_nop 0
	v_pk_fma_f32 v[132:133], v[132:133], v[138:139], v[142:143] op_sel:[1,1,0] op_sel_hi:[0,1,1] neg_lo:[0,1,0]
	v_pk_mul_f32 v[142:143], v[138:139], v[140:141] op_sel_hi:[1,0]
	s_nop 0
	v_pk_fma_f32 v[138:139], v[138:139], v[140:141], v[142:143] op_sel:[1,1,0] op_sel_hi:[0,1,1] neg_lo:[0,1,0]
	s_nop 0
	v_pk_mul_f32 v[142:143], v[134:135], v[138:139] op_sel_hi:[1,0]
	s_nop 0
	v_pk_fma_f32 v[134:135], v[134:135], v[138:139], v[142:143] op_sel:[1,1,0] op_sel_hi:[0,1,1] neg_lo:[0,1,0]
	v_pk_mul_f32 v[142:143], v[138:139], v[140:141] op_sel_hi:[1,0]
	s_nop 0
	v_pk_fma_f32 v[138:139], v[138:139], v[140:141], v[142:143] op_sel:[1,1,0] op_sel_hi:[0,1,1] neg_lo:[0,1,0]
	s_nop 0
	v_pk_mul_f32 v[140:141], v[136:137], v[138:139] op_sel_hi:[1,0]
	s_nop 0
	v_pk_fma_f32 v[136:137], v[136:137], v[138:139], v[140:141] op_sel:[1,1,0] op_sel_hi:[0,1,1] neg_lo:[0,1,0]
	v_pk_add_f32 v[138:139], v[0:1], v[106:107]
	v_pk_add_f32 v[0:1], v[0:1], v[106:107] neg_lo:[0,1] neg_hi:[0,1]
	v_pk_add_f32 v[106:107], v[90:91], v[122:123]
	v_pk_add_f32 v[90:91], v[90:91], v[122:123] neg_lo:[0,1] neg_hi:[0,1]
	v_pk_add_f32 v[122:123], v[8:9], v[114:115]
	v_pk_add_f32 v[8:9], v[8:9], v[114:115] neg_lo:[0,1] neg_hi:[0,1]
	v_pk_add_f32 v[114:115], v[98:99], v[130:131]
	v_pk_add_f32 v[98:99], v[98:99], v[130:131] neg_lo:[0,1] neg_hi:[0,1]
	v_pk_add_f32 v[130:131], v[4:5], v[110:111]
	v_pk_add_f32 v[4:5], v[4:5], v[110:111] neg_lo:[0,1] neg_hi:[0,1]
	v_pk_add_f32 v[110:111], v[94:95], v[126:127]
	v_pk_add_f32 v[94:95], v[94:95], v[126:127] neg_lo:[0,1] neg_hi:[0,1]
	v_pk_add_f32 v[126:127], v[86:87], v[118:119]
	v_pk_add_f32 v[86:87], v[86:87], v[118:119] neg_lo:[0,1] neg_hi:[0,1]
	v_pk_add_f32 v[118:119], v[102:103], v[134:135]
	v_pk_add_f32 v[102:103], v[102:103], v[134:135] neg_lo:[0,1] neg_hi:[0,1]
	v_pk_add_f32 v[134:135], v[2:3], v[108:109]
	v_pk_add_f32 v[2:3], v[2:3], v[108:109] neg_lo:[0,1] neg_hi:[0,1]
	v_pk_add_f32 v[108:109], v[92:93], v[124:125]
	v_pk_add_f32 v[92:93], v[92:93], v[124:125] neg_lo:[0,1] neg_hi:[0,1]
	v_pk_add_f32 v[124:125], v[10:11], v[116:117]
	v_pk_add_f32 v[10:11], v[10:11], v[116:117] neg_lo:[0,1] neg_hi:[0,1]
	v_pk_add_f32 v[116:117], v[100:101], v[132:133]
	v_pk_add_f32 v[100:101], v[100:101], v[132:133] neg_lo:[0,1] neg_hi:[0,1]
	v_pk_add_f32 v[132:133], v[6:7], v[112:113]
	v_pk_add_f32 v[6:7], v[6:7], v[112:113] neg_lo:[0,1] neg_hi:[0,1]
	v_pk_add_f32 v[112:113], v[96:97], v[128:129]
	v_pk_add_f32 v[96:97], v[96:97], v[128:129] neg_lo:[0,1] neg_hi:[0,1]
	v_pk_add_f32 v[128:129], v[88:89], v[120:121]
	v_pk_add_f32 v[88:89], v[88:89], v[120:121] neg_lo:[0,1] neg_hi:[0,1]
	v_pk_add_f32 v[120:121], v[104:105], v[136:137]
	v_pk_add_f32 v[104:105], v[104:105], v[136:137] neg_lo:[0,1] neg_hi:[0,1]
	v_pk_add_f32 v[136:137], v[138:139], v[106:107]
	v_pk_add_f32 v[106:107], v[138:139], v[106:107] neg_lo:[0,1] neg_hi:[0,1]
	v_xor_b32_e32 v138, 0x80000000, v91
	v_mov_b32_e32 v139, v90
	v_pk_add_f32 v[90:91], v[0:1], v[138:139]
	v_pk_add_f32 v[0:1], v[0:1], v[138:139] neg_lo:[0,1] neg_hi:[0,1]
	v_pk_add_f32 v[138:139], v[122:123], v[114:115]
	v_pk_add_f32 v[114:115], v[122:123], v[114:115] neg_lo:[0,1] neg_hi:[0,1]
	v_xor_b32_e32 v122, 0x80000000, v99
	v_mov_b32_e32 v123, v98
	v_pk_add_f32 v[98:99], v[8:9], v[122:123]
	v_pk_add_f32 v[8:9], v[8:9], v[122:123] neg_lo:[0,1] neg_hi:[0,1]
	v_pk_add_f32 v[122:123], v[130:131], v[110:111]
; __device__ __forceinline__ f2 cmulc(f2 a, float wr, float wi) { const f2 s = __builtin_shufflevector(a, a, 1, 0); return s * (f2){wi, -wi} + a * (f2){wr, wr}; }
; __device__ __forceinline__ void ifft32(f2 (&x)[32]) {
;     constexpr float TWR[32] = {TWR_LIST}; constexpr float TWI[32] = {TWI_LIST};
; #pragma unroll
;     for (int h = 1; h <= 16; h <<= 1) {
; #pragma unroll
;         for (int i0 = 0; i0 < 32; i0 += 2 * h) {
; #pragma unroll
;             for (int j = 0; j < h; ++j) {
;                 const int i = i0 + j, k = i + h, m = j * (32 / h);
;                 const f2 a = x[i], y = x[k];
;                 f2 b;
;                 if (m == 0) b = y;
;                 else if (m == 16) b = (f2){-y.y, y.x};
;                 else b = cmulc(y, TWR[m], TWI[m]);
;                 x[i] = a + b; x[k] = a - b;
;             }
;         }
;     }
; }
	v_pk_add_f32 v[110:111], v[130:131], v[110:111] neg_lo:[0,1] neg_hi:[0,1]
	v_xor_b32_e32 v130, 0x80000000, v95
	v_mov_b32_e32 v131, v94
	v_pk_add_f32 v[94:95], v[4:5], v[130:131]
	v_pk_add_f32 v[4:5], v[4:5], v[130:131] neg_lo:[0,1] neg_hi:[0,1]
	v_pk_add_f32 v[130:131], v[126:127], v[118:119]
	v_pk_add_f32 v[118:119], v[126:127], v[118:119] neg_lo:[0,1] neg_hi:[0,1]
	v_xor_b32_e32 v126, 0x80000000, v103
	v_mov_b32_e32 v127, v102
	v_pk_add_f32 v[102:103], v[86:87], v[126:127]
	v_pk_add_f32 v[86:87], v[86:87], v[126:127] neg_lo:[0,1] neg_hi:[0,1]
	v_pk_add_f32 v[126:127], v[134:135], v[108:109]
	v_pk_add_f32 v[108:109], v[134:135], v[108:109] neg_lo:[0,1] neg_hi:[0,1]
	v_xor_b32_e32 v134, 0x80000000, v93
	v_mov_b32_e32 v135, v92
	v_pk_add_f32 v[92:93], v[2:3], v[134:135]
	v_pk_add_f32 v[2:3], v[2:3], v[134:135] neg_lo:[0,1] neg_hi:[0,1]
	v_pk_add_f32 v[134:135], v[124:125], v[116:117]
	v_pk_add_f32 v[116:117], v[124:125], v[116:117] neg_lo:[0,1] neg_hi:[0,1]
	v_xor_b32_e32 v124, 0x80000000, v101
	v_mov_b32_e32 v125, v100
	v_pk_add_f32 v[100:101], v[10:11], v[124:125]
	v_pk_add_f32 v[10:11], v[10:11], v[124:125] neg_lo:[0,1] neg_hi:[0,1]
	v_pk_add_f32 v[124:125], v[132:133], v[112:113]
	v_pk_add_f32 v[112:113], v[132:133], v[112:113] neg_lo:[0,1] neg_hi:[0,1]
	v_xor_b32_e32 v132, 0x80000000, v97
	v_mov_b32_e32 v133, v96
	v_pk_add_f32 v[96:97], v[6:7], v[132:133]
	v_pk_add_f32 v[6:7], v[6:7], v[132:133] neg_lo:[0,1] neg_hi:[0,1]
	v_pk_add_f32 v[132:133], v[128:129], v[120:121]
	v_pk_add_f32 v[120:121], v[128:129], v[120:121] neg_lo:[0,1] neg_hi:[0,1]
	v_xor_b32_e32 v128, 0x80000000, v105
	v_mov_b32_e32 v129, v104
	v_pk_add_f32 v[104:105], v[88:89], v[128:129]
	v_pk_add_f32 v[88:89], v[88:89], v[128:129] neg_lo:[0,1] neg_hi:[0,1]
	v_pk_add_f32 v[128:129], v[136:137], v[138:139]
	v_pk_add_f32 v[136:137], v[136:137], v[138:139] neg_lo:[0,1] neg_hi:[0,1]
	v_pk_mul_f32 v[138:139], v[98:99], s[96:97]
	s_nop 0
	v_pk_fma_f32 v[98:99], v[98:99], s[94:95], v[138:139] op_sel:[0,0,1] op_sel_hi:[1,0,0]
	s_nop 0
	v_pk_add_f32 v[138:139], v[90:91], v[98:99]
	v_pk_add_f32 v[90:91], v[90:91], v[98:99] neg_lo:[0,1] neg_hi:[0,1]
	v_xor_b32_e32 v98, 0x80000000, v115
	v_mov_b32_e32 v99, v114
	v_pk_add_f32 v[114:115], v[106:107], v[98:99]
	v_pk_add_f32 v[98:99], v[106:107], v[98:99] neg_lo:[0,1] neg_hi:[0,1]
	v_pk_mul_f32 v[106:107], v[8:9], s[96:97]
	s_nop 0
	v_pk_fma_f32 v[8:9], v[8:9], s[94:95], v[106:107] op_sel:[0,0,1] op_sel_hi:[1,0,0] neg_lo:[1,0,0] neg_hi:[1,0,0]
	s_nop 0
	v_pk_add_f32 v[106:107], v[0:1], v[8:9]
	v_pk_add_f32 v[0:1], v[0:1], v[8:9] neg_lo:[0,1] neg_hi:[0,1]
	v_pk_add_f32 v[8:9], v[122:123], v[130:131]
	v_pk_add_f32 v[122:123], v[122:123], v[130:131] neg_lo:[0,1] neg_hi:[0,1]
	v_pk_mul_f32 v[130:131], v[102:103], s[96:97]
	s_nop 0
	v_pk_fma_f32 v[102:103], v[102:103], s[94:95], v[130:131] op_sel:[0,0,1] op_sel_hi:[1,0,0]
	s_nop 0
	v_pk_add_f32 v[130:131], v[94:95], v[102:103]
	v_pk_add_f32 v[94:95], v[94:95], v[102:103] neg_lo:[0,1] neg_hi:[0,1]
	v_xor_b32_e32 v102, 0x80000000, v119
	v_mov_b32_e32 v103, v118
	v_pk_add_f32 v[118:119], v[110:111], v[102:103]
	v_pk_add_f32 v[102:103], v[110:111], v[102:103] neg_lo:[0,1] neg_hi:[0,1]
	v_pk_mul_f32 v[110:111], v[86:87], s[96:97]
	s_nop 0
	v_pk_fma_f32 v[86:87], v[86:87], s[94:95], v[110:111] op_sel:[0,0,1] op_sel_hi:[1,0,0] neg_lo:[1,0,0] neg_hi:[1,0,0]
	s_nop 0
	v_pk_add_f32 v[110:111], v[4:5], v[86:87]
	v_pk_add_f32 v[4:5], v[4:5], v[86:87] neg_lo:[0,1] neg_hi:[0,1]
	v_pk_add_f32 v[86:87], v[126:127], v[134:135]
	v_pk_add_f32 v[126:127], v[126:127], v[134:135] neg_lo:[0,1] neg_hi:[0,1]
	v_pk_mul_f32 v[134:135], v[100:101], s[96:97]
	s_nop 0
	v_pk_fma_f32 v[100:101], v[100:101], s[94:95], v[134:135] op_sel:[0,0,1] op_sel_hi:[1,0,0]
	s_nop 0
	v_pk_add_f32 v[134:135], v[92:93], v[100:101]
	v_pk_add_f32 v[92:93], v[92:93], v[100:101] neg_lo:[0,1] neg_hi:[0,1]
	v_xor_b32_e32 v100, 0x80000000, v117
	v_mov_b32_e32 v101, v116
	v_pk_add_f32 v[116:117], v[108:109], v[100:101]
	v_pk_add_f32 v[100:101], v[108:109], v[100:101] neg_lo:[0,1] neg_hi:[0,1]
	v_pk_mul_f32 v[108:109], v[10:11], s[96:97]
	s_nop 0
	v_pk_fma_f32 v[10:11], v[10:11], s[94:95], v[108:109] op_sel:[0,0,1] op_sel_hi:[1,0,0] neg_lo:[1,0,0] neg_hi:[1,0,0]
	s_nop 0
	v_pk_add_f32 v[108:109], v[2:3], v[10:11]
	v_pk_add_f32 v[2:3], v[2:3], v[10:11] neg_lo:[0,1] neg_hi:[0,1]
	v_pk_add_f32 v[10:11], v[124:125], v[132:133]
	v_pk_add_f32 v[124:125], v[124:125], v[132:133] neg_lo:[0,1] neg_hi:[0,1]
	v_pk_mul_f32 v[132:133], v[104:105], s[96:97]
	s_nop 0
	v_pk_fma_f32 v[104:105], v[104:105], s[94:95], v[132:133] op_sel:[0,0,1] op_sel_hi:[1,0,0]
	s_nop 0
	v_pk_add_f32 v[132:133], v[96:97], v[104:105]
	v_pk_add_f32 v[96:97], v[96:97], v[104:105] neg_lo:[0,1] neg_hi:[0,1]
	v_xor_b32_e32 v104, 0x80000000, v121
	v_mov_b32_e32 v105, v120
	v_pk_add_f32 v[120:121], v[112:113], v[104:105]
	v_pk_add_f32 v[104:105], v[112:113], v[104:105] neg_lo:[0,1] neg_hi:[0,1]
	v_pk_mul_f32 v[112:113], v[88:89], s[96:97]
	s_nop 0
	v_pk_fma_f32 v[88:89], v[88:89], s[94:95], v[112:113] op_sel:[0,0,1] op_sel_hi:[1,0,0] neg_lo:[1,0,0] neg_hi:[1,0,0]
	s_nop 0
	v_pk_add_f32 v[112:113], v[6:7], v[88:89]
	v_pk_add_f32 v[6:7], v[6:7], v[88:89] neg_lo:[0,1] neg_hi:[0,1]
	v_pk_add_f32 v[88:89], v[128:129], v[8:9]
	v_pk_add_f32 v[8:9], v[128:129], v[8:9] neg_lo:[0,1] neg_hi:[0,1]
	v_pk_mul_f32 v[128:129], v[130:131], s[6:7]
	s_nop 0
	v_pk_fma_f32 v[128:129], v[130:131], s[56:57], v[128:129] op_sel:[0,0,1] op_sel_hi:[1,0,0]
	s_nop 0
	v_pk_add_f32 v[130:131], v[138:139], v[128:129]
	v_pk_add_f32 v[138:139], v[138:139], v[128:129] neg_lo:[0,1] neg_hi:[0,1]
	v_pk_mul_f32 v[128:129], v[118:119], s[96:97]
; __device__ __forceinline__ f2 cmulc(f2 a, float wr, float wi) { const f2 s = __builtin_shufflevector(a, a, 1, 0); return s * (f2){wi, -wi} + a * (f2){wr, wr}; }
; __device__ __forceinline__ void ifft32(f2 (&x)[32]) {
;     constexpr float TWR[32] = {TWR_LIST}; constexpr float TWI[32] = {TWI_LIST};
; #pragma unroll
;     for (int h = 1; h <= 16; h <<= 1) {
; #pragma unroll
;         for (int i0 = 0; i0 < 32; i0 += 2 * h) {
; #pragma unroll
;             for (int j = 0; j < h; ++j) {
;                 const int i = i0 + j, k = i + h, m = j * (32 / h);
;                 const f2 a = x[i], y = x[k];
;                 f2 b;
;                 if (m == 0) b = y;
;                 else if (m == 16) b = (f2){-y.y, y.x};
;                 else b = cmulc(y, TWR[m], TWI[m]);
;                 x[i] = a + b; x[k] = a - b;
;             }
;         }
;     }
; }
	s_nop 0
	v_pk_fma_f32 v[118:119], v[118:119], s[94:95], v[128:129] op_sel:[0,0,1] op_sel_hi:[1,0,0]
	s_nop 0
	v_pk_add_f32 v[140:141], v[114:115], v[118:119]
	v_pk_add_f32 v[142:143], v[114:115], v[118:119] neg_lo:[0,1] neg_hi:[0,1]
	v_pk_mul_f32 v[118:119], v[94:95], s[56:57]
	v_pk_mul_f32 v[114:115], v[110:111], s[56:57]
	v_pk_fma_f32 v[94:95], v[94:95], s[84:85], v[118:119] op_sel:[0,0,1] op_sel_hi:[1,0,0] neg_lo:[1,0,0] neg_hi:[1,0,0]
	v_pk_fma_f32 v[110:111], v[110:111], s[84:85], v[114:115] op_sel:[0,0,1] op_sel_hi:[1,0,0]
	v_pk_add_f32 v[144:145], v[90:91], v[94:95]
	v_pk_add_f32 v[146:147], v[90:91], v[94:95] neg_lo:[0,1] neg_hi:[0,1]
	v_pk_mul_f32 v[90:91], v[102:103], s[96:97]
	v_pk_add_f32 v[114:115], v[106:107], v[110:111]
	v_pk_fma_f32 v[90:91], v[102:103], s[94:95], v[90:91] op_sel:[0,0,1] op_sel_hi:[1,0,0] neg_lo:[1,0,0] neg_hi:[1,0,0]
	v_pk_add_f32 v[106:107], v[106:107], v[110:111] neg_lo:[0,1] neg_hi:[0,1]
	v_pk_add_f32 v[94:95], v[98:99], v[90:91]
	v_pk_add_f32 v[148:149], v[98:99], v[90:91] neg_lo:[0,1] neg_hi:[0,1]
	v_pk_mul_f32 v[90:91], v[4:5], s[6:7]
	v_xor_b32_e32 v110, 0x80000000, v123
	v_pk_fma_f32 v[4:5], v[4:5], s[56:57], v[90:91] op_sel:[0,0,1] op_sel_hi:[1,0,0] neg_lo:[1,0,0] neg_hi:[1,0,0]
	v_pk_mul_f32 v[90:91], v[120:121], s[96:97]
	v_pk_add_f32 v[212:213], v[0:1], v[4:5]
	v_pk_fma_f32 v[90:91], v[120:121], s[94:95], v[90:91] op_sel:[0,0,1] op_sel_hi:[1,0,0]
	v_pk_add_f32 v[214:215], v[0:1], v[4:5] neg_lo:[0,1] neg_hi:[0,1]
	v_pk_add_f32 v[102:103], v[116:117], v[90:91]
	v_pk_add_f32 v[120:121], v[116:117], v[90:91] neg_lo:[0,1] neg_hi:[0,1]
	v_pk_mul_f32 v[90:91], v[112:113], s[56:57]
	v_pk_add_f32 v[0:1], v[86:87], v[10:11]
	v_pk_fma_f32 v[90:91], v[112:113], s[84:85], v[90:91] op_sel:[0,0,1] op_sel_hi:[1,0,0]
	v_pk_add_f32 v[4:5], v[86:87], v[10:11] neg_lo:[0,1] neg_hi:[0,1]
	v_pk_mul_f32 v[10:11], v[132:133], s[6:7]
	v_pk_add_f32 v[112:113], v[108:109], v[90:91]
	v_pk_add_f32 v[108:109], v[108:109], v[90:91] neg_lo:[0,1] neg_hi:[0,1]
	v_xor_b32_e32 v90, 0x80000000, v125
	v_mov_b32_e32 v91, v124
	v_pk_fma_f32 v[10:11], v[132:133], s[56:57], v[10:11] op_sel:[0,0,1] op_sel_hi:[1,0,0]
	v_pk_add_f32 v[116:117], v[126:127], v[90:91]
	v_pk_add_f32 v[216:217], v[126:127], v[90:91] neg_lo:[0,1] neg_hi:[0,1]
	v_pk_mul_f32 v[90:91], v[96:97], s[56:57]
	v_pk_add_f32 v[86:87], v[134:135], v[10:11]
	v_pk_fma_f32 v[90:91], v[96:97], s[84:85], v[90:91] op_sel:[0,0,1] op_sel_hi:[1,0,0] neg_lo:[1,0,0] neg_hi:[1,0,0]
	v_pk_add_f32 v[128:129], v[88:89], v[0:1]
	v_pk_add_f32 v[96:97], v[92:93], v[90:91]
	v_pk_add_f32 v[218:219], v[92:93], v[90:91] neg_lo:[0,1] neg_hi:[0,1]
	v_pk_mul_f32 v[90:91], v[104:105], s[96:97]
	v_pk_add_f32 v[98:99], v[88:89], v[0:1] neg_lo:[0,1] neg_hi:[0,1]
	v_pk_mul_f32 v[0:1], v[86:87], s[76:77]
	v_pk_fma_f32 v[90:91], v[104:105], s[94:95], v[90:91] op_sel:[0,0,1] op_sel_hi:[1,0,0] neg_lo:[1,0,0] neg_hi:[1,0,0]
	v_pk_fma_f32 v[0:1], v[86:87], s[52:53], v[0:1] op_sel:[0,0,1] op_sel_hi:[1,0,0]
	v_pk_add_f32 v[92:93], v[100:101], v[90:91]
	v_pk_add_f32 v[222:223], v[100:101], v[90:91] neg_lo:[0,1] neg_hi:[0,1]
	v_pk_add_f32 v[132:133], v[130:131], v[0:1]
	v_pk_add_f32 v[100:101], v[130:131], v[0:1] neg_lo:[0,1] neg_hi:[0,1]
	v_pk_mul_f32 v[0:1], v[102:103], s[6:7]
	v_pk_add_f32 v[10:11], v[134:135], v[10:11] neg_lo:[0,1] neg_hi:[0,1]
	v_pk_fma_f32 v[0:1], v[102:103], s[56:57], v[0:1] op_sel:[0,0,1] op_sel_hi:[1,0,0]
	v_mov_b32_e32 v111, v122
	v_pk_add_f32 v[134:135], v[140:141], v[0:1]
	v_pk_add_f32 v[102:103], v[140:141], v[0:1] neg_lo:[0,1] neg_hi:[0,1]
	v_pk_mul_f32 v[0:1], v[112:113], s[20:21]
	v_pk_add_f32 v[122:123], v[136:137], v[110:111]
	v_pk_fma_f32 v[0:1], v[112:113], s[60:61], v[0:1] op_sel:[0,0,1] op_sel_hi:[1,0,0]
	v_pk_add_f32 v[110:111], v[136:137], v[110:111] neg_lo:[0,1] neg_hi:[0,1]
	v_pk_add_f32 v[136:137], v[114:115], v[0:1]
	v_pk_add_f32 v[104:105], v[114:115], v[0:1] neg_lo:[0,1] neg_hi:[0,1]
	v_pk_mul_f32 v[0:1], v[116:117], s[96:97]
	v_pk_mul_f32 v[90:91], v[6:7], s[6:7]
	v_pk_fma_f32 v[0:1], v[116:117], s[94:95], v[0:1] op_sel:[0,0,1] op_sel_hi:[1,0,0]
	v_pk_fma_f32 v[6:7], v[6:7], s[56:57], v[90:91] op_sel:[0,0,1] op_sel_hi:[1,0,0] neg_lo:[1,0,0] neg_hi:[1,0,0]
	v_pk_add_f32 v[118:119], v[122:123], v[0:1]
	v_pk_add_f32 v[86:87], v[122:123], v[0:1] neg_lo:[0,1] neg_hi:[0,1]
	v_pk_mul_f32 v[0:1], v[96:97], s[60:61]
	v_pk_add_f32 v[124:125], v[2:3], v[6:7]
	v_pk_fma_f32 v[0:1], v[96:97], s[86:87], v[0:1] op_sel:[0,0,1] op_sel_hi:[1,0,0]
	v_pk_add_f32 v[6:7], v[2:3], v[6:7] neg_lo:[0,1] neg_hi:[0,1]
	v_pk_add_f32 v[122:123], v[144:145], v[0:1]
	v_pk_add_f32 v[90:91], v[144:145], v[0:1] neg_lo:[0,1] neg_hi:[0,1]
	v_pk_mul_f32 v[0:1], v[92:93], s[56:57]
	v_pk_mul_f32 v[2:3], v[218:219], s[20:21]
	v_pk_fma_f32 v[0:1], v[92:93], s[84:85], v[0:1] op_sel:[0,0,1] op_sel_hi:[1,0,0]
	v_pk_mul_f32 v[112:113], v[6:7], s[76:77]
	v_pk_add_f32 v[126:127], v[94:95], v[0:1]
	v_pk_add_f32 v[94:95], v[94:95], v[0:1] neg_lo:[0,1] neg_hi:[0,1]
	v_pk_mul_f32 v[0:1], v[124:125], s[52:53]
	v_pk_fma_f32 v[2:3], v[218:219], s[60:61], v[2:3] op_sel:[0,0,1] op_sel_hi:[1,0,0] neg_lo:[1,0,0] neg_hi:[1,0,0]
	v_pk_fma_f32 v[0:1], v[124:125], s[10:11], v[0:1] op_sel:[0,0,1] op_sel_hi:[1,0,0]
	v_pk_fma_f32 v[6:7], v[6:7], s[52:53], v[112:113] op_sel:[0,0,1] op_sel_hi:[1,0,0] neg_lo:[1,0,0] neg_hi:[1,0,0]
	v_pk_add_f32 v[130:131], v[212:213], v[0:1]
	v_pk_add_f32 v[96:97], v[212:213], v[0:1] neg_lo:[0,1] neg_hi:[0,1]
	v_xor_b32_e32 v0, 0x80000000, v5
	v_mov_b32_e32 v1, v4
	v_pk_add_f32 v[114:115], v[8:9], v[0:1]
	v_pk_add_f32 v[8:9], v[8:9], v[0:1] neg_lo:[0,1] neg_hi:[0,1]
	v_pk_mul_f32 v[0:1], v[10:11], s[52:53]
; #define LAS __attribute__((address_space(3)))
; __device__ __forceinline__ float bflo(unsigned w) { return __uint_as_float(w << 16); }
; __device__ __forceinline__ float bfhi(unsigned w) { return __uint_as_float(w & 0xffff0000u); }
; __device__ __forceinline__ void ifft32(f2 (&x)[32]) {
;     constexpr float TWR[32] = {TWR_LIST}; constexpr float TWI[32] = {TWI_LIST};
; #pragma unroll
;     for (int h = 1; h <= 16; h <<= 1) {
; #pragma unroll
;         for (int i0 = 0; i0 < 32; i0 += 2 * h) {
; #pragma unroll
;             for (int j = 0; j < h; ++j) {
;                 const int i = i0 + j, k = i + h, m = j * (32 / h);
;                 const f2 a = x[i], y = x[k];
;                 f2 b;
;                 if (m == 0) b = y;
;                 else if (m == 16) b = (f2){-y.y, y.x};
;                 else b = cmulc(y, TWR[m], TWI[m]);
;                 x[i] = a + b; x[k] = a - b;
;             }
;         }
;     }
; }
; template <bool CONJ> __device__ __forceinline__ void twiddleN(f2 (&x)[32], float wr, float wi) {
;     float sr = 0.995184727f, si = CONJ ? 0.098017140f : -0.098017140f;
;     asm volatile("" : "+v"(wr), "+v"(wi), "+v"(sr), "+v"(si));
;     f2 e = (f2){wr, CONJ ? -wi : wi}; const f2 st = (f2){sr, si};
; #pragma unroll
;     for (int n1 = 0; n1 < 32; ++n1) { x[n1] = cmulr(x[n1], e); if (n1 < 31) e = cmulr(e, st); }
; }
; template <int VAR> __device__ __forceinline__ void hyena_conv_phase(const Frame& F, const bf16* ZT, const bf16* GT, const float* conv_w, const float* conv_b, const float* skip, float* gscr, float* zscr, bf16* UT) {
;     ...
;                     twiddleN<true>(x, W1[0], W1[1]);
;                     LAS float* x0p = X + t; LAS float* x1p = X + SEQL + t; asm volatile("" : "+v"(x0p), "+v"(x1p));
; #pragma unroll
;                     for (int g = 0; g < 8; ++g) { const v4u w = *py; py += 512; asm volatile("" : "+v"(py));
;                         x0p[512 * (4 * g)] = x[4 * g].x + bflo(w.x); x1p[512 * (4 * g)] = x[4 * g].y + bfhi(w.x); x0p[512 * (4 * g + 1)] = x[4 * g + 1].x + bflo(w.y); x1p[512 * (4 * g + 1)] = x[4 * g + 1].y + bfhi(w.y);
;                         x0p[512 * (4 * g + 2)] = x[4 * g + 2].x + bflo(w.z); x1p[512 * (4 * g + 2)] = x[4 * g + 2].y + bfhi(w.z); x0p[512 * (4 * g + 3)] = x[4 * g + 3].x + bflo(w.w); x1p[512 * (4 * g + 3)] = x[4 * g + 3].y + bfhi(w.w); }
	v_pk_mul_f32 v[4:5], v[222:223], s[6:7]
	v_pk_fma_f32 v[0:1], v[10:11], s[10:11], v[0:1] op_sel:[0,0,1] op_sel_hi:[1,0,0] neg_lo:[1,0,0] neg_hi:[1,0,0]
	v_pk_fma_f32 v[4:5], v[222:223], s[56:57], v[4:5] op_sel:[0,0,1] op_sel_hi:[1,0,0] neg_lo:[1,0,0] neg_hi:[1,0,0]
	v_pk_add_f32 v[116:117], v[138:139], v[0:1]
	v_pk_add_f32 v[10:11], v[138:139], v[0:1] neg_lo:[0,1] neg_hi:[0,1]
	v_pk_mul_f32 v[0:1], v[120:121], s[56:57]
	v_pk_add_f32 v[112:113], v[214:215], v[6:7]
	v_pk_fma_f32 v[0:1], v[120:121], s[84:85], v[0:1] op_sel:[0,0,1] op_sel_hi:[1,0,0] neg_lo:[1,0,0] neg_hi:[1,0,0]
	v_pk_add_f32 v[6:7], v[214:215], v[6:7] neg_lo:[0,1] neg_hi:[0,1]
	v_pk_add_f32 v[120:121], v[142:143], v[0:1]
	v_pk_add_f32 v[88:89], v[142:143], v[0:1] neg_lo:[0,1] neg_hi:[0,1]
	v_pk_mul_f32 v[0:1], v[108:109], s[60:61]
	s_mov_b64 s[6:7], -1
	v_pk_fma_f32 v[0:1], v[108:109], s[86:87], v[0:1] op_sel:[0,0,1] op_sel_hi:[1,0,0] neg_lo:[1,0,0] neg_hi:[1,0,0]
	v_pk_add_f32 v[108:109], v[146:147], v[2:3]
	v_pk_add_f32 v[124:125], v[106:107], v[0:1]
	v_pk_add_f32 v[92:93], v[106:107], v[0:1] neg_lo:[0,1] neg_hi:[0,1]
	v_pk_mul_f32 v[0:1], v[216:217], s[96:97]
	v_pk_add_f32 v[2:3], v[146:147], v[2:3] neg_lo:[0,1] neg_hi:[0,1]
	v_pk_fma_f32 v[0:1], v[216:217], s[94:95], v[0:1] op_sel:[0,0,1] op_sel_hi:[1,0,0] neg_lo:[1,0,0] neg_hi:[1,0,0]
	v_lshl_add_u64 v[138:139], v[84:85], 0, s[26:27]
	v_pk_add_f32 v[106:107], v[110:111], v[0:1]
	v_pk_add_f32 v[0:1], v[110:111], v[0:1] neg_lo:[0,1] neg_hi:[0,1]
	v_pk_add_f32 v[110:111], v[148:149], v[4:5]
	v_pk_add_f32 v[4:5], v[148:149], v[4:5] neg_lo:[0,1] neg_hi:[0,1]
	s_cbranch_vccz .LBB0_342
	v_lshlrev_b32_e32 v13, 2, v12
	ds_read_b64 v[142:143], v211
	v_mov_b32_e32 v141, 0x3dc8bd36
	v_mov_b32_e32 v140, 0x3f7ec46d
	v_add_u32_e32 v12, 0, v13
	v_add_u32_e32 v13, s85, v13
	s_waitcnt lgkmcnt(0)
	global_load_dwordx4 v[144:147], v[84:85], off
	v_mov_b64_e32 v[148:149], v[138:139]
	global_load_dwordx4 v[212:215], v[148:149], off
	v_xor_b32_e32 v143, 0x80000000, v143
	v_pk_mul_f32 v[216:217], v[128:129], v[142:143] op_sel_hi:[1,0]
	v_pk_mul_f32 v[218:219], v[142:143], v[140:141] op_sel_hi:[1,0]
	v_lshl_add_u64 v[148:149], v[148:149], 0, s[26:27]
	v_pk_fma_f32 v[216:217], v[128:129], v[142:143], v[216:217] op_sel:[1,1,0] op_sel_hi:[0,1,1] neg_lo:[0,1,0]
	v_pk_fma_f32 v[142:143], v[142:143], v[140:141], v[218:219] op_sel:[1,1,0] op_sel_hi:[0,1,1] neg_lo:[0,1,0]
	s_mov_b64 s[6:7], 0
	v_pk_mul_f32 v[218:219], v[132:133], v[142:143] op_sel_hi:[1,0]
	v_pk_mul_f32 v[222:223], v[142:143], v[140:141] op_sel_hi:[1,0]
	s_waitcnt vmcnt(1)
	v_lshlrev_b32_e32 v16, 16, v144
	v_pk_fma_f32 v[218:219], v[132:133], v[142:143], v[218:219] op_sel:[1,1,0] op_sel_hi:[0,1,1] neg_lo:[0,1,0]
	v_pk_fma_f32 v[142:143], v[142:143], v[140:141], v[222:223] op_sel:[1,1,0] op_sel_hi:[0,1,1] neg_lo:[0,1,0]
	v_lshlrev_b32_e32 v211, 16, v147
	v_pk_mul_f32 v[222:223], v[134:135], v[142:143] op_sel_hi:[1,0]
	v_pk_mul_f32 v[224:225], v[142:143], v[140:141] op_sel_hi:[1,0]
	v_and_b32_e32 v147, 0xffff0000, v147
	v_pk_fma_f32 v[222:223], v[134:135], v[142:143], v[222:223] op_sel:[1,1,0] op_sel_hi:[0,1,1] neg_lo:[0,1,0]
	v_pk_fma_f32 v[142:143], v[142:143], v[140:141], v[224:225] op_sel:[1,1,0] op_sel_hi:[0,1,1] neg_lo:[0,1,0]
	v_add_f32_e32 v16, v216, v16
	v_pk_mul_f32 v[224:225], v[136:137], v[142:143] op_sel_hi:[1,0]
	v_pk_mul_f32 v[226:227], v[142:143], v[140:141] op_sel_hi:[1,0]
	s_waitcnt vmcnt(0)
	v_lshlrev_b32_e32 v216, 16, v212
	v_pk_fma_f32 v[224:225], v[136:137], v[142:143], v[224:225] op_sel:[1,1,0] op_sel_hi:[0,1,1] neg_lo:[0,1,0]
	v_pk_fma_f32 v[142:143], v[142:143], v[140:141], v[226:227] op_sel:[1,1,0] op_sel_hi:[0,1,1] neg_lo:[0,1,0]
	v_and_b32_e32 v212, 0xffff0000, v212
	v_pk_mul_f32 v[226:227], v[118:119], v[142:143] op_sel_hi:[1,0]
	v_pk_mul_f32 v[228:229], v[142:143], v[140:141] op_sel_hi:[1,0]
	v_add_f32_e32 v211, v224, v211
	v_pk_fma_f32 v[226:227], v[118:119], v[142:143], v[226:227] op_sel:[1,1,0] op_sel_hi:[0,1,1] neg_lo:[0,1,0]
	v_pk_fma_f32 v[142:143], v[142:143], v[140:141], v[228:229] op_sel:[1,1,0] op_sel_hi:[0,1,1] neg_lo:[0,1,0]
	v_add_f32_e32 v147, v225, v147
	v_pk_mul_f32 v[228:229], v[122:123], v[142:143] op_sel_hi:[1,0]
	v_pk_mul_f32 v[230:231], v[142:143], v[140:141] op_sel_hi:[1,0]
	v_add_f32_e32 v212, v227, v212
	v_pk_fma_f32 v[228:229], v[122:123], v[142:143], v[228:229] op_sel:[1,1,0] op_sel_hi:[0,1,1] neg_lo:[0,1,0]
	v_pk_fma_f32 v[142:143], v[142:143], v[140:141], v[230:231] op_sel:[1,1,0] op_sel_hi:[0,1,1] neg_lo:[0,1,0]
	s_nop 0
	v_pk_mul_f32 v[230:231], v[126:127], v[142:143] op_sel_hi:[1,0]
	v_pk_mul_f32 v[232:233], v[142:143], v[140:141] op_sel_hi:[1,0]
	s_nop 0
	v_pk_fma_f32 v[230:231], v[126:127], v[142:143], v[230:231] op_sel:[1,1,0] op_sel_hi:[0,1,1] neg_lo:[0,1,0]
	v_pk_fma_f32 v[232:233], v[142:143], v[140:141], v[232:233] op_sel:[1,1,0] op_sel_hi:[0,1,1] neg_lo:[0,1,0]
	s_nop 0
	v_pk_mul_f32 v[142:143], v[130:131], v[232:233] op_sel_hi:[1,0]
	s_nop 0
	v_pk_fma_f32 v[234:235], v[130:131], v[232:233], v[142:143] op_sel:[1,1,0] op_sel_hi:[0,1,1] neg_lo:[0,1,0]
	v_and_b32_e32 v142, 0xffff0000, v144
	v_lshlrev_b32_e32 v143, 16, v145
	v_and_b32_e32 v144, 0xffff0000, v145
	v_lshlrev_b32_e32 v145, 16, v146
	v_and_b32_e32 v146, 0xffff0000, v146
	v_add_f32_e32 v146, v223, v146
	v_add_f32_e32 v142, v217, v142
	v_add_f32_e32 v143, v218, v143
	v_add_f32_e32 v144, v219, v144
	v_add_f32_e32 v145, v222, v145
	ds_write_b32 v12, v16
	ds_write_b32 v13, v142
	ds_write_b32 v12, v143 offset:2048
	ds_write_b32 v13, v144 offset:2048
	ds_write_b32 v12, v145 offset:4096
	ds_write_b32 v13, v146 offset:4096
	ds_write_b32 v12, v211 offset:6144
	ds_write_b32 v13, v147 offset:6144
	v_lshlrev_b32_e32 v16, 16, v213
	v_and_b32_e32 v146, 0xffff0000, v213
	v_lshlrev_b32_e32 v213, 16, v215
	global_load_dwordx4 v[142:145], v[148:149], off
	v_lshlrev_b32_e32 v147, 16, v214
	v_and_b32_e32 v211, 0xffff0000, v214
	v_and_b32_e32 v214, 0xffff0000, v215
	v_add_f32_e32 v215, v226, v216
	v_add_f32_e32 v213, v234, v213
	v_add_f32_e32 v16, v228, v16
	v_add_f32_e32 v146, v229, v146
	v_add_f32_e32 v147, v230, v147
	v_add_f32_e32 v211, v231, v211
	v_add_f32_e32 v214, v235, v214
	ds_write_b32 v12, v215 offset:8192
	ds_write_b32 v13, v212 offset:8192
	ds_write_b32 v12, v16 offset:10240
	ds_write_b32 v13, v146 offset:10240
	ds_write_b32 v12, v147 offset:12288
	ds_write_b32 v13, v211 offset:12288
	ds_write_b32 v12, v213 offset:14336
	ds_write_b32 v13, v214 offset:14336
	v_lshl_add_u64 v[212:213], v[148:149], 0, s[26:27]
	global_load_dwordx4 v[146:149], v[212:213], off
	v_pk_mul_f32 v[214:215], v[232:233], v[140:141] op_sel_hi:[1,0]
	v_lshl_add_u64 v[212:213], v[212:213], 0, s[26:27]
	v_pk_fma_f32 v[214:215], v[232:233], v[140:141], v[214:215] op_sel:[1,1,0] op_sel_hi:[0,1,1] neg_lo:[0,1,0]
	s_waitcnt vmcnt(1)
; #define LAS __attribute__((address_space(3)))
; __device__ __forceinline__ float bflo(unsigned w) { return __uint_as_float(w << 16); }
; __device__ __forceinline__ float bfhi(unsigned w) { return __uint_as_float(w & 0xffff0000u); }
; template <bool CONJ> __device__ __forceinline__ void twiddleN(f2 (&x)[32], float wr, float wi) {
;     float sr = 0.995184727f, si = CONJ ? 0.098017140f : -0.098017140f;
;     asm volatile("" : "+v"(wr), "+v"(wi), "+v"(sr), "+v"(si));
;     f2 e = (f2){wr, CONJ ? -wi : wi}; const f2 st = (f2){sr, si};
; #pragma unroll
;     for (int n1 = 0; n1 < 32; ++n1) { x[n1] = cmulr(x[n1], e); if (n1 < 31) e = cmulr(e, st); }
; }
; template <int VAR> __device__ __forceinline__ void hyena_conv_phase(const Frame& F, const bf16* ZT, const bf16* GT, const float* conv_w, const float* conv_b, const float* skip, float* gscr, float* zscr, bf16* UT) {
;     ...
;                     twiddleN<true>(x, W1[0], W1[1]);
;                     LAS float* x0p = X + t; LAS float* x1p = X + SEQL + t; asm volatile("" : "+v"(x0p), "+v"(x1p));
; #pragma unroll
;                     for (int g = 0; g < 8; ++g) { const v4u w = *py; py += 512; asm volatile("" : "+v"(py));
;                         x0p[512 * (4 * g)] = x[4 * g].x + bflo(w.x); x1p[512 * (4 * g)] = x[4 * g].y + bfhi(w.x); x0p[512 * (4 * g + 1)] = x[4 * g + 1].x + bflo(w.y); x1p[512 * (4 * g + 1)] = x[4 * g + 1].y + bfhi(w.y);
;                         x0p[512 * (4 * g + 2)] = x[4 * g + 2].x + bflo(w.z); x1p[512 * (4 * g + 2)] = x[4 * g + 2].y + bfhi(w.z); x0p[512 * (4 * g + 3)] = x[4 * g + 3].x + bflo(w.w); x1p[512 * (4 * g + 3)] = x[4 * g + 3].y + bfhi(w.w); }
	v_lshlrev_b32_e32 v16, 16, v142
	v_pk_mul_f32 v[216:217], v[114:115], v[214:215] op_sel_hi:[1,0]
	v_pk_mul_f32 v[218:219], v[214:215], v[140:141] op_sel_hi:[1,0]
	v_and_b32_e32 v142, 0xffff0000, v142
	v_pk_fma_f32 v[216:217], v[114:115], v[214:215], v[216:217] op_sel:[1,1,0] op_sel_hi:[0,1,1] neg_lo:[0,1,0]
	v_pk_fma_f32 v[214:215], v[214:215], v[140:141], v[218:219] op_sel:[1,1,0] op_sel_hi:[0,1,1] neg_lo:[0,1,0]
	v_lshlrev_b32_e32 v211, 16, v143
	v_pk_mul_f32 v[218:219], v[116:117], v[214:215] op_sel_hi:[1,0]
	v_pk_mul_f32 v[222:223], v[214:215], v[140:141] op_sel_hi:[1,0]
	v_and_b32_e32 v143, 0xffff0000, v143
	v_pk_fma_f32 v[218:219], v[116:117], v[214:215], v[218:219] op_sel:[1,1,0] op_sel_hi:[0,1,1] neg_lo:[0,1,0]
	v_pk_fma_f32 v[214:215], v[214:215], v[140:141], v[222:223] op_sel:[1,1,0] op_sel_hi:[0,1,1] neg_lo:[0,1,0]
	v_lshlrev_b32_e32 v234, 16, v144
	v_pk_mul_f32 v[222:223], v[120:121], v[214:215] op_sel_hi:[1,0]
	v_pk_mul_f32 v[224:225], v[214:215], v[140:141] op_sel_hi:[1,0]
	v_and_b32_e32 v144, 0xffff0000, v144
	v_pk_fma_f32 v[222:223], v[120:121], v[214:215], v[222:223] op_sel:[1,1,0] op_sel_hi:[0,1,1] neg_lo:[0,1,0]
	v_pk_fma_f32 v[214:215], v[214:215], v[140:141], v[224:225] op_sel:[1,1,0] op_sel_hi:[0,1,1] neg_lo:[0,1,0]
	v_lshlrev_b32_e32 v235, 16, v145
	v_pk_mul_f32 v[224:225], v[124:125], v[214:215] op_sel_hi:[1,0]
	v_pk_mul_f32 v[226:227], v[214:215], v[140:141] op_sel_hi:[1,0]
	v_and_b32_e32 v145, 0xffff0000, v145
	v_pk_fma_f32 v[224:225], v[124:125], v[214:215], v[224:225] op_sel:[1,1,0] op_sel_hi:[0,1,1] neg_lo:[0,1,0]
	v_pk_fma_f32 v[214:215], v[214:215], v[140:141], v[226:227] op_sel:[1,1,0] op_sel_hi:[0,1,1] neg_lo:[0,1,0]
	v_add_f32_e32 v16, v216, v16
	v_pk_mul_f32 v[226:227], v[106:107], v[214:215] op_sel_hi:[1,0]
	v_pk_mul_f32 v[228:229], v[214:215], v[140:141] op_sel_hi:[1,0]
	v_add_f32_e32 v142, v217, v142
	v_pk_fma_f32 v[226:227], v[106:107], v[214:215], v[226:227] op_sel:[1,1,0] op_sel_hi:[0,1,1] neg_lo:[0,1,0]
	v_pk_fma_f32 v[214:215], v[214:215], v[140:141], v[228:229] op_sel:[1,1,0] op_sel_hi:[0,1,1] neg_lo:[0,1,0]
	v_add_f32_e32 v211, v218, v211
	v_pk_mul_f32 v[228:229], v[108:109], v[214:215] op_sel_hi:[1,0]
	v_pk_mul_f32 v[230:231], v[214:215], v[140:141] op_sel_hi:[1,0]
	v_add_f32_e32 v143, v219, v143
	v_pk_fma_f32 v[228:229], v[108:109], v[214:215], v[228:229] op_sel:[1,1,0] op_sel_hi:[0,1,1] neg_lo:[0,1,0]
	v_pk_fma_f32 v[214:215], v[214:215], v[140:141], v[230:231] op_sel:[1,1,0] op_sel_hi:[0,1,1] neg_lo:[0,1,0]
	v_add_f32_e32 v216, v222, v234
	v_pk_mul_f32 v[230:231], v[110:111], v[214:215] op_sel_hi:[1,0]
	v_pk_mul_f32 v[232:233], v[214:215], v[140:141] op_sel_hi:[1,0]
	v_add_f32_e32 v144, v223, v144
	v_add_f32_e32 v217, v224, v235
	v_add_f32_e32 v145, v225, v145
	v_pk_fma_f32 v[230:231], v[110:111], v[214:215], v[230:231] op_sel:[1,1,0] op_sel_hi:[0,1,1] neg_lo:[0,1,0]
	v_pk_fma_f32 v[214:215], v[214:215], v[140:141], v[232:233] op_sel:[1,1,0] op_sel_hi:[0,1,1] neg_lo:[0,1,0]
	ds_write_b32 v12, v16 offset:16384
	ds_write_b32 v13, v142 offset:16384
	ds_write_b32 v12, v211 offset:18432
	ds_write_b32 v13, v143 offset:18432
	ds_write_b32 v12, v216 offset:20480
	ds_write_b32 v13, v144 offset:20480
	ds_write_b32 v12, v217 offset:22528
	ds_write_b32 v13, v145 offset:22528
	v_pk_mul_f32 v[232:233], v[112:113], v[214:215] op_sel_hi:[1,0]
	s_waitcnt vmcnt(0)
	v_lshlrev_b32_e32 v16, 16, v146
	v_and_b32_e32 v146, 0xffff0000, v146
	global_load_dwordx4 v[142:145], v[212:213], off
	v_lshlrev_b32_e32 v211, 16, v147
	v_and_b32_e32 v147, 0xffff0000, v147
	v_lshlrev_b32_e32 v216, 16, v148
	v_and_b32_e32 v148, 0xffff0000, v148
	v_lshlrev_b32_e32 v217, 16, v149
	v_and_b32_e32 v149, 0xffff0000, v149
	v_pk_fma_f32 v[232:233], v[112:113], v[214:215], v[232:233] op_sel:[1,1,0] op_sel_hi:[0,1,1] neg_lo:[0,1,0]
	v_add_f32_e32 v16, v226, v16
	v_add_f32_e32 v146, v227, v146
	v_add_f32_e32 v147, v229, v147
	v_add_f32_e32 v148, v231, v148
	v_add_f32_e32 v149, v233, v149
	v_lshl_add_u64 v[212:213], v[212:213], 0, s[26:27]
	v_add_f32_e32 v211, v228, v211
	v_add_f32_e32 v216, v230, v216
	v_add_f32_e32 v217, v232, v217
	ds_write_b32 v12, v16 offset:24576
	ds_write_b32 v13, v146 offset:24576
	ds_write_b32 v12, v211 offset:26624
	ds_write_b32 v13, v147 offset:26624
	ds_write_b32 v12, v216 offset:28672
	ds_write_b32 v13, v148 offset:28672
	ds_write_b32 v12, v217 offset:30720
	ds_write_b32 v13, v149 offset:30720
	global_load_dwordx4 v[146:149], v[212:213], off
	v_pk_mul_f32 v[216:217], v[214:215], v[140:141] op_sel_hi:[1,0]
	v_lshl_add_u64 v[212:213], v[212:213], 0, s[26:27]
	v_pk_fma_f32 v[214:215], v[214:215], v[140:141], v[216:217] op_sel:[1,1,0] op_sel_hi:[0,1,1] neg_lo:[0,1,0]
	s_waitcnt vmcnt(1)
; #define LAS __attribute__((address_space(3)))
; __device__ __forceinline__ float bflo(unsigned w) { return __uint_as_float(w << 16); }
; __device__ __forceinline__ float bfhi(unsigned w) { return __uint_as_float(w & 0xffff0000u); }
; template <bool CONJ> __device__ __forceinline__ void twiddleN(f2 (&x)[32], float wr, float wi) {
;     float sr = 0.995184727f, si = CONJ ? 0.098017140f : -0.098017140f;
;     asm volatile("" : "+v"(wr), "+v"(wi), "+v"(sr), "+v"(si));
;     f2 e = (f2){wr, CONJ ? -wi : wi}; const f2 st = (f2){sr, si};
; #pragma unroll
;     for (int n1 = 0; n1 < 32; ++n1) { x[n1] = cmulr(x[n1], e); if (n1 < 31) e = cmulr(e, st); }
; }
; template <int VAR> __device__ __forceinline__ void hyena_conv_phase(const Frame& F, const bf16* ZT, const bf16* GT, const float* conv_w, const float* conv_b, const float* skip, float* gscr, float* zscr, bf16* UT) {
;     ...
;                     twiddleN<true>(x, W1[0], W1[1]);
;                     LAS float* x0p = X + t; LAS float* x1p = X + SEQL + t; asm volatile("" : "+v"(x0p), "+v"(x1p));
; #pragma unroll
;                     for (int g = 0; g < 8; ++g) { const v4u w = *py; py += 512; asm volatile("" : "+v"(py));
;                         x0p[512 * (4 * g)] = x[4 * g].x + bflo(w.x); x1p[512 * (4 * g)] = x[4 * g].y + bfhi(w.x); x0p[512 * (4 * g + 1)] = x[4 * g + 1].x + bflo(w.y); x1p[512 * (4 * g + 1)] = x[4 * g + 1].y + bfhi(w.y);
;                         x0p[512 * (4 * g + 2)] = x[4 * g + 2].x + bflo(w.z); x1p[512 * (4 * g + 2)] = x[4 * g + 2].y + bfhi(w.z); x0p[512 * (4 * g + 3)] = x[4 * g + 3].x + bflo(w.w); x1p[512 * (4 * g + 3)] = x[4 * g + 3].y + bfhi(w.w); }
	v_lshlrev_b32_e32 v16, 16, v142
	v_pk_mul_f32 v[216:217], v[98:99], v[214:215] op_sel_hi:[1,0]
	v_pk_mul_f32 v[218:219], v[214:215], v[140:141] op_sel_hi:[1,0]
	v_and_b32_e32 v142, 0xffff0000, v142
	v_pk_fma_f32 v[216:217], v[98:99], v[214:215], v[216:217] op_sel:[1,1,0] op_sel_hi:[0,1,1] neg_lo:[0,1,0]
	v_pk_fma_f32 v[214:215], v[214:215], v[140:141], v[218:219] op_sel:[1,1,0] op_sel_hi:[0,1,1] neg_lo:[0,1,0]
	v_lshlrev_b32_e32 v211, 16, v143
	v_pk_mul_f32 v[218:219], v[100:101], v[214:215] op_sel_hi:[1,0]
	v_pk_mul_f32 v[222:223], v[214:215], v[140:141] op_sel_hi:[1,0]
	v_and_b32_e32 v143, 0xffff0000, v143
	v_pk_fma_f32 v[218:219], v[100:101], v[214:215], v[218:219] op_sel:[1,1,0] op_sel_hi:[0,1,1] neg_lo:[0,1,0]
	v_pk_fma_f32 v[214:215], v[214:215], v[140:141], v[222:223] op_sel:[1,1,0] op_sel_hi:[0,1,1] neg_lo:[0,1,0]
	v_lshlrev_b32_e32 v234, 16, v144
	v_pk_mul_f32 v[222:223], v[102:103], v[214:215] op_sel_hi:[1,0]
	v_pk_mul_f32 v[224:225], v[214:215], v[140:141] op_sel_hi:[1,0]
	v_and_b32_e32 v144, 0xffff0000, v144
	v_pk_fma_f32 v[222:223], v[102:103], v[214:215], v[222:223] op_sel:[1,1,0] op_sel_hi:[0,1,1] neg_lo:[0,1,0]
	v_pk_fma_f32 v[214:215], v[214:215], v[140:141], v[224:225] op_sel:[1,1,0] op_sel_hi:[0,1,1] neg_lo:[0,1,0]
	v_lshlrev_b32_e32 v235, 16, v145
	v_pk_mul_f32 v[224:225], v[104:105], v[214:215] op_sel_hi:[1,0]
	v_pk_mul_f32 v[226:227], v[214:215], v[140:141] op_sel_hi:[1,0]
	v_and_b32_e32 v145, 0xffff0000, v145
	v_pk_fma_f32 v[224:225], v[104:105], v[214:215], v[224:225] op_sel:[1,1,0] op_sel_hi:[0,1,1] neg_lo:[0,1,0]
	v_pk_fma_f32 v[214:215], v[214:215], v[140:141], v[226:227] op_sel:[1,1,0] op_sel_hi:[0,1,1] neg_lo:[0,1,0]
	v_add_f32_e32 v16, v216, v16
	v_pk_mul_f32 v[226:227], v[86:87], v[214:215] op_sel_hi:[1,0]
	v_pk_mul_f32 v[228:229], v[214:215], v[140:141] op_sel_hi:[1,0]
	v_add_f32_e32 v142, v217, v142
	v_pk_fma_f32 v[226:227], v[86:87], v[214:215], v[226:227] op_sel:[1,1,0] op_sel_hi:[0,1,1] neg_lo:[0,1,0]
	v_pk_fma_f32 v[214:215], v[214:215], v[140:141], v[228:229] op_sel:[1,1,0] op_sel_hi:[0,1,1] neg_lo:[0,1,0]
	v_add_f32_e32 v211, v218, v211
	v_pk_mul_f32 v[228:229], v[90:91], v[214:215] op_sel_hi:[1,0]
	v_pk_mul_f32 v[230:231], v[214:215], v[140:141] op_sel_hi:[1,0]
	v_add_f32_e32 v143, v219, v143
	v_pk_fma_f32 v[228:229], v[90:91], v[214:215], v[228:229] op_sel:[1,1,0] op_sel_hi:[0,1,1] neg_lo:[0,1,0]
	v_pk_fma_f32 v[214:215], v[214:215], v[140:141], v[230:231] op_sel:[1,1,0] op_sel_hi:[0,1,1] neg_lo:[0,1,0]
	v_add_f32_e32 v216, v222, v234
	v_pk_mul_f32 v[230:231], v[94:95], v[214:215] op_sel_hi:[1,0]
	v_pk_mul_f32 v[232:233], v[214:215], v[140:141] op_sel_hi:[1,0]
	v_add_f32_e32 v144, v223, v144
	v_add_f32_e32 v217, v224, v235
	v_add_f32_e32 v145, v225, v145
	v_pk_fma_f32 v[230:231], v[94:95], v[214:215], v[230:231] op_sel:[1,1,0] op_sel_hi:[0,1,1] neg_lo:[0,1,0]
	v_pk_fma_f32 v[214:215], v[214:215], v[140:141], v[232:233] op_sel:[1,1,0] op_sel_hi:[0,1,1] neg_lo:[0,1,0]
	ds_write_b32 v12, v16 offset:32768
	ds_write_b32 v13, v142 offset:32768
	ds_write_b32 v12, v211 offset:34816
	ds_write_b32 v13, v143 offset:34816
	ds_write_b32 v12, v216 offset:36864
	ds_write_b32 v13, v144 offset:36864
	ds_write_b32 v12, v217 offset:38912
	ds_write_b32 v13, v145 offset:38912
	v_pk_mul_f32 v[232:233], v[96:97], v[214:215] op_sel_hi:[1,0]
	s_waitcnt vmcnt(0)
	v_lshlrev_b32_e32 v16, 16, v146
	v_and_b32_e32 v146, 0xffff0000, v146
	global_load_dwordx4 v[142:145], v[212:213], off
	v_lshlrev_b32_e32 v211, 16, v147
	v_and_b32_e32 v147, 0xffff0000, v147
	v_lshlrev_b32_e32 v216, 16, v148
	v_and_b32_e32 v148, 0xffff0000, v148
	v_lshlrev_b32_e32 v217, 16, v149
	v_and_b32_e32 v149, 0xffff0000, v149
	v_pk_fma_f32 v[232:233], v[96:97], v[214:215], v[232:233] op_sel:[1,1,0] op_sel_hi:[0,1,1] neg_lo:[0,1,0]
	v_add_f32_e32 v16, v226, v16
	v_add_f32_e32 v146, v227, v146
	v_add_f32_e32 v147, v229, v147
	v_add_f32_e32 v148, v231, v148
	v_add_f32_e32 v149, v233, v149
	v_lshl_add_u64 v[212:213], v[212:213], 0, s[26:27]
	v_add_f32_e32 v211, v228, v211
	v_add_f32_e32 v216, v230, v216
	v_add_f32_e32 v217, v232, v217
	ds_write_b32 v12, v16 offset:40960
	ds_write_b32 v13, v146 offset:40960
	ds_write_b32 v12, v211 offset:43008
	ds_write_b32 v13, v147 offset:43008
	ds_write_b32 v12, v216 offset:45056
	ds_write_b32 v13, v148 offset:45056
	ds_write_b32 v12, v217 offset:47104
	ds_write_b32 v13, v149 offset:47104
	global_load_dwordx4 v[146:149], v[212:213], off
	v_pk_mul_f32 v[216:217], v[214:215], v[140:141] op_sel_hi:[1,0]
	v_lshl_add_u64 v[212:213], v[212:213], 0, s[26:27]
	v_pk_fma_f32 v[214:215], v[214:215], v[140:141], v[216:217] op_sel:[1,1,0] op_sel_hi:[0,1,1] neg_lo:[0,1,0]
	s_waitcnt vmcnt(1)
; #define LAS __attribute__((address_space(3)))
; __device__ __forceinline__ float bflo(unsigned w) { return __uint_as_float(w << 16); }
; __device__ __forceinline__ float bfhi(unsigned w) { return __uint_as_float(w & 0xffff0000u); }
; template <bool CONJ> __device__ __forceinline__ void twiddleN(f2 (&x)[32], float wr, float wi) {
;     float sr = 0.995184727f, si = CONJ ? 0.098017140f : -0.098017140f;
;     asm volatile("" : "+v"(wr), "+v"(wi), "+v"(sr), "+v"(si));
;     f2 e = (f2){wr, CONJ ? -wi : wi}; const f2 st = (f2){sr, si};
; #pragma unroll
;     for (int n1 = 0; n1 < 32; ++n1) { x[n1] = cmulr(x[n1], e); if (n1 < 31) e = cmulr(e, st); }
; }
; template <int VAR> __device__ __forceinline__ void hyena_conv_phase(const Frame& F, const bf16* ZT, const bf16* GT, const float* conv_w, const float* conv_b, const float* skip, float* gscr, float* zscr, bf16* UT) {
;     ...
;                     twiddleN<true>(x, W1[0], W1[1]);
;                     LAS float* x0p = X + t; LAS float* x1p = X + SEQL + t; asm volatile("" : "+v"(x0p), "+v"(x1p));
; #pragma unroll
;                     for (int g = 0; g < 8; ++g) { const v4u w = *py; py += 512; asm volatile("" : "+v"(py));
;                         x0p[512 * (4 * g)] = x[4 * g].x + bflo(w.x); x1p[512 * (4 * g)] = x[4 * g].y + bfhi(w.x); x0p[512 * (4 * g + 1)] = x[4 * g + 1].x + bflo(w.y); x1p[512 * (4 * g + 1)] = x[4 * g + 1].y + bfhi(w.y);
;                         x0p[512 * (4 * g + 2)] = x[4 * g + 2].x + bflo(w.z); x1p[512 * (4 * g + 2)] = x[4 * g + 2].y + bfhi(w.z); x0p[512 * (4 * g + 3)] = x[4 * g + 3].x + bflo(w.w); x1p[512 * (4 * g + 3)] = x[4 * g + 3].y + bfhi(w.w); }
	v_lshlrev_b32_e32 v16, 16, v142
	v_pk_mul_f32 v[216:217], v[8:9], v[214:215] op_sel_hi:[1,0]
	v_pk_mul_f32 v[218:219], v[214:215], v[140:141] op_sel_hi:[1,0]
	v_and_b32_e32 v142, 0xffff0000, v142
	v_pk_fma_f32 v[216:217], v[8:9], v[214:215], v[216:217] op_sel:[1,1,0] op_sel_hi:[0,1,1] neg_lo:[0,1,0]
	v_pk_fma_f32 v[214:215], v[214:215], v[140:141], v[218:219] op_sel:[1,1,0] op_sel_hi:[0,1,1] neg_lo:[0,1,0]
	v_lshlrev_b32_e32 v211, 16, v143
	v_pk_mul_f32 v[218:219], v[10:11], v[214:215] op_sel_hi:[1,0]
	v_pk_mul_f32 v[222:223], v[214:215], v[140:141] op_sel_hi:[1,0]
	v_and_b32_e32 v143, 0xffff0000, v143
	v_pk_fma_f32 v[218:219], v[10:11], v[214:215], v[218:219] op_sel:[1,1,0] op_sel_hi:[0,1,1] neg_lo:[0,1,0]
	v_pk_fma_f32 v[214:215], v[214:215], v[140:141], v[222:223] op_sel:[1,1,0] op_sel_hi:[0,1,1] neg_lo:[0,1,0]
	v_add_f32_e32 v16, v216, v16
	v_pk_mul_f32 v[222:223], v[88:89], v[214:215] op_sel_hi:[1,0]
	v_pk_mul_f32 v[224:225], v[214:215], v[140:141] op_sel_hi:[1,0]
	v_add_f32_e32 v142, v217, v142
	v_pk_fma_f32 v[222:223], v[88:89], v[214:215], v[222:223] op_sel:[1,1,0] op_sel_hi:[0,1,1] neg_lo:[0,1,0]
	v_pk_fma_f32 v[214:215], v[214:215], v[140:141], v[224:225] op_sel:[1,1,0] op_sel_hi:[0,1,1] neg_lo:[0,1,0]
	v_add_f32_e32 v211, v218, v211
	v_pk_mul_f32 v[224:225], v[92:93], v[214:215] op_sel_hi:[1,0]
	v_pk_mul_f32 v[226:227], v[214:215], v[140:141] op_sel_hi:[1,0]
	v_add_f32_e32 v143, v219, v143
	v_pk_fma_f32 v[224:225], v[92:93], v[214:215], v[224:225] op_sel:[1,1,0] op_sel_hi:[0,1,1] neg_lo:[0,1,0]
	v_pk_fma_f32 v[214:215], v[214:215], v[140:141], v[226:227] op_sel:[1,1,0] op_sel_hi:[0,1,1] neg_lo:[0,1,0]
	s_nop 0
	v_pk_mul_f32 v[226:227], v[0:1], v[214:215] op_sel_hi:[1,0]
	v_pk_mul_f32 v[228:229], v[214:215], v[140:141] op_sel_hi:[1,0]
	s_nop 0
	v_pk_fma_f32 v[226:227], v[0:1], v[214:215], v[226:227] op_sel:[1,1,0] op_sel_hi:[0,1,1] neg_lo:[0,1,0]
	v_pk_fma_f32 v[214:215], v[214:215], v[140:141], v[228:229] op_sel:[1,1,0] op_sel_hi:[0,1,1] neg_lo:[0,1,0]
	s_nop 0
	v_pk_mul_f32 v[228:229], v[2:3], v[214:215] op_sel_hi:[1,0]
	v_pk_mul_f32 v[230:231], v[214:215], v[140:141] op_sel_hi:[1,0]
	s_nop 0
	v_pk_fma_f32 v[228:229], v[2:3], v[214:215], v[228:229] op_sel:[1,1,0] op_sel_hi:[0,1,1] neg_lo:[0,1,0]
	v_pk_fma_f32 v[214:215], v[214:215], v[140:141], v[230:231] op_sel:[1,1,0] op_sel_hi:[0,1,1] neg_lo:[0,1,0]
	s_nop 0
	v_pk_mul_f32 v[230:231], v[4:5], v[214:215] op_sel_hi:[1,0]
	v_pk_mul_f32 v[232:233], v[214:215], v[140:141] op_sel_hi:[1,0]
	s_nop 0
	v_pk_fma_f32 v[230:231], v[4:5], v[214:215], v[230:231] op_sel:[1,1,0] op_sel_hi:[0,1,1] neg_lo:[0,1,0]
	v_pk_fma_f32 v[140:141], v[214:215], v[140:141], v[232:233] op_sel:[1,1,0] op_sel_hi:[0,1,1] neg_lo:[0,1,0]
	s_nop 0
	v_pk_mul_f32 v[214:215], v[6:7], v[140:141] op_sel_hi:[1,0]
	s_nop 0
	v_pk_fma_f32 v[140:141], v[6:7], v[140:141], v[214:215] op_sel:[1,1,0] op_sel_hi:[0,1,1] neg_lo:[0,1,0]
	v_lshlrev_b32_e32 v214, 16, v144
	v_and_b32_e32 v144, 0xffff0000, v144
	v_lshlrev_b32_e32 v215, 16, v145
	v_and_b32_e32 v145, 0xffff0000, v145
	v_add_f32_e32 v214, v222, v214
	v_add_f32_e32 v144, v223, v144
	v_add_f32_e32 v215, v224, v215
	v_add_f32_e32 v145, v225, v145
	ds_write_b32 v12, v16 offset:49152
	ds_write_b32 v13, v142 offset:49152
	ds_write_b32 v12, v211 offset:51200
	ds_write_b32 v13, v143 offset:51200
	ds_write_b32 v12, v214 offset:53248
	ds_write_b32 v13, v144 offset:53248
	ds_write_b32 v12, v215 offset:55296
	ds_write_b32 v13, v145 offset:55296
	s_waitcnt vmcnt(0)
	v_lshlrev_b32_e32 v16, 16, v146
	v_and_b32_e32 v142, 0xffff0000, v146
	v_lshlrev_b32_e32 v143, 16, v147
	v_and_b32_e32 v144, 0xffff0000, v147
	v_add_f32_e32 v16, v226, v16
	v_add_f32_e32 v142, v227, v142
	v_add_f32_e32 v143, v228, v143
	v_add_f32_e32 v144, v229, v144
	ds_write_b32 v12, v16 offset:57344
	ds_write_b32 v13, v142 offset:57344
	ds_write_b32 v12, v143 offset:59392
	ds_write_b32 v13, v144 offset:59392
	v_lshlrev_b32_e32 v16, 16, v148
	v_add_f32_e32 v16, v230, v16
	ds_write_b32 v12, v16 offset:61440
	v_and_b32_e32 v16, 0xffff0000, v148
	v_add_f32_e32 v16, v231, v16
	ds_write_b32 v13, v16 offset:61440
	v_lshlrev_b32_e32 v16, 16, v149
	v_add_f32_e32 v16, v140, v16
	ds_write_b32 v12, v16 offset:63488
	v_and_b32_e32 v12, 0xffff0000, v149
	v_add_f32_e32 v12, v141, v12
	ds_write_b32 v13, v12 offset:63488

; #define LAS __attribute__((address_space(3)))
; __device__ __forceinline__ void na_phase(const Frame& F, const bf16* QH, const bf16* VB, const float* rpb, bf16* U) {
;     ...
;     LAS float* RP = (LAS float*)F.lds;
;     for (int i = F.tid; i < 16 * 465; i += 512) RP[i] = rpb[i];
;     __syncthreads();
;     const int lane = F.lane, n = lane & 15, q4 = lane >> 4;
;     const int vcu = (F.G % 8 == 0) ? (F.bid % 8) * (F.G / 8) + F.bid / 8 : F.bid;
;     for (int br = vcu; br < MB * 256; br += F.G) {
;         const int b = br >> 8, r = br & 255;
;         const int rs = min(max(r - 4, 0), 248);
; #pragma unroll 1
;         for (int it = 0; it < 8; ++it) {
;             const int hj = it * 8 + F.wave, h = hj >> 2, j = hj & 3;
;             const int c0 = (j == 0) ? 0 : (j == 1) ? 8 : (j == 2) ? 24 : 32;
;             const int qcol = 16 * j + n, cs = min(max(qcol - 8, 0), 48);
;             const size_t tokq = (size_t)b * SEQL + r * 64 + qcol;
;             bf16x8 qf[2];
; #pragma unroll
;             for (int ks = 0; ks < 2; ++ks) qf[ks] = *(const bf16x8*)(QH + (((size_t)h * 2 + ks) * MTOK + tokq) * 32 + q4 * 8);
;             f32x4 acc[16];
; #pragma unroll
;             for (int blk = 0; blk < 16; ++blk) { const int i = blk >> 1, hf = blk & 1;
;                 const size_t tokk = (size_t)b * SEQL + (rs + i) * 64 + c0 + 8 * (n >> 2) + 4 * hf + (n & 3);
;                 const bf16* kp = KH + ((size_t)h * 2 * MTOK + tokk) * 32 + q4 * 8; const bf16x8 k0 = *(const bf16x8*)kp, k1 = *(const bf16x8*)(kp + (size_t)MTOK * 32);
;                 f32x4 a = (f32x4){0.f, 0.f, 0.f, 0.f};
;                 a = __builtin_amdgcn_mfma_f32_16x16x32_bf16(k0, qf[0], a, 0, 0, 0);
;                 a = __builtin_amdgcn_mfma_f32_16x16x32_bf16(k1, qf[1], a, 0, 0, 0);
;                 acc[blk] = a; }
;             float mx = -3.0e38f;
;             int cofs[8]; bool okk[8];
; #pragma unroll
;             for (int k8 = 0; k8 < 8; ++k8) { const int kc = c0 + 8 * q4 + 4 * (k8 >> 2) + (k8 & 3); okk[k8] = (kc >= cs) && (kc < cs + 16); cofs[k8] = min(max(kc - qcol + 15, 0), 30); }
; #pragma unroll
.LBB0_899:
	s_cmp_lt_i32 s72, 10
	s_cselect_b64 s[4:5], -1, 0
	s_and_b64 s[36:37], s[4:5], s[0:1]
	s_andn2_b64 vcc, exec, s[36:37]
	s_cbranch_vccnz .LBB0_913
	v_lshlrev_b32_e32 v4, 2, v221
	v_add_u32_e32 v3, 0, v4
	s_waitcnt lgkmcnt(0)
	v_add_u32_e32 v6, 0x1000, v4
	v_add_u32_e32 v7, 0x2000, v4
	v_add_u32_e32 v8, 0x3000, v4
	v_add_u32_e32 v9, 0x4000, v4
	v_add_u32_e32 v26, 0x5000, v4
	v_add_u32_e32 v27, 0x6000, v4
	v_add_u32_e32 v28, 0x7000, v4
	global_load_dword v10, v4, s[24:25]
	global_load_dword v11, v4, s[24:25] offset:2048
	global_load_dword v12, v6, s[24:25]
	global_load_dword v13, v6, s[24:25] offset:2048
	global_load_dword v14, v7, s[24:25]
	global_load_dword v15, v7, s[24:25] offset:2048
	global_load_dword v16, v8, s[24:25]
	global_load_dword v17, v8, s[24:25] offset:2048
	global_load_dword v18, v9, s[24:25]
	global_load_dword v19, v9, s[24:25] offset:2048
	global_load_dword v20, v26, s[24:25]
	global_load_dword v21, v26, s[24:25] offset:2048
	global_load_dword v22, v27, s[24:25]
	global_load_dword v23, v27, s[24:25] offset:2048
	v_cmp_gt_u32_e32 vcc, 0x110, v221
	s_nop 1
	s_and_saveexec_b64 s[0:1], vcc
	global_load_dword v24, v28, s[24:25]
	s_mov_b64 exec, s[0:1]
	s_waitcnt vmcnt(0)
	ds_write_b32 v3, v10
	ds_write_b32 v3, v11 offset:2048
	ds_write_b32 v3, v12 offset:4096
	ds_write_b32 v3, v13 offset:6144
	ds_write_b32 v3, v14 offset:8192
	ds_write_b32 v3, v15 offset:10240
	ds_write_b32 v3, v16 offset:12288
	ds_write_b32 v3, v17 offset:14336
	ds_write_b32 v3, v18 offset:16384
	ds_write_b32 v3, v19 offset:18432
	ds_write_b32 v3, v20 offset:20480
	ds_write_b32 v3, v21 offset:22528
	ds_write_b32 v3, v22 offset:24576
	ds_write_b32 v3, v23 offset:26624
	s_and_saveexec_b64 s[0:1], vcc
	ds_write_b32 v3, v24 offset:28672
	s_mov_b64 exec, s[0:1]
	s_ashr_i32 s1, s2, 31
	s_lshr_b32 s1, s1, 29
	s_add_i32 s1, s2, s1
	s_ashr_i32 s3, s1, 3
	s_and_b32 s1, s1, -8
	s_sub_i32 s1, s2, s1
	s_ashr_i32 s4, s74, 3
	s_mul_i32 s1, s4, s1
	s_and_b32 s0, s74, 7
	s_add_i32 s1, s1, s3
	s_cmp_eq_u32 s0, 0
	s_cselect_b32 s3, s1, s2
	s_mov_b32 s47, 0
	s_cmpk_lt_i32 s3, 0x200
	s_waitcnt lgkmcnt(0)
	s_barrier
	s_cbranch_scc0 .LBB0_912
	v_mbcnt_lo_u32_b32 v3, -1, 0
	v_readlane_b32 s0, v248, 14
	v_mbcnt_hi_u32_b32 v3, -1, v3
	s_bfe_u32 s6, s0, 0x20006
	v_and_b32_e32 v5, 64, v3
	s_lshl_b32 s8, s6, 4
	v_xor_b32_e32 v4, 16, v3
	v_add_u32_e32 v5, 64, v5
	s_cmp_eq_u32 s6, 2
	v_cmp_lt_i32_e32 vcc, v4, v5
	v_and_b32_e32 v0, 15, v221
	v_lshrrev_b32_e32 v72, 4, v220
	s_cselect_b32 s7, 24, 32
	v_cndmask_b32_e32 v4, v3, v4, vcc
	s_lshr_b32 s46, s0, 8
	v_or_b32_e32 v1, s8, v0
	v_lshlrev_b32_e32 v48, 3, v72
	v_lshlrev_b32_e32 v73, 2, v4
	v_xor_b32_e32 v4, 32, v3
	s_lshl_b64 s[0:1], s[46:47], 22
	v_sub_u32_e64 v1, v1, 8 clamp
	v_cmp_lt_i32_e32 vcc, v4, v5
	v_lshl_or_b32 v52, v0, 4, s0
	v_mov_b32_e32 v53, s1
	v_add_u32_e32 v75, s8, v0
	v_sub_u32_e32 v0, v48, v0
	s_mul_i32 s1, s46, 0x744
	v_min_u32_e32 v49, 48, v1
	v_mov_b32_e32 v51, 0
	v_lshlrev_b32_e32 v1, 1, v221
	v_and_b32_e32 v2, 3, v221
	v_cndmask_b32_e32 v3, v3, v4, vcc
	v_lshl_or_b32 v50, s46, 7, v48
	s_mov_b64 s[4:5], 0x8000040
	v_subrev_u32_e32 v76, s8, v0
	s_add_i32 s33, s1, 0
	v_add_u32_e32 v57, 16, v49
	v_lshlrev_b32_e32 v74, 2, v3
	v_lshl_add_u64 v[54:55], v[50:51], 0, s[4:5]
	s_addk_i32 s33, 0x364
	v_and_or_b32 v56, v1, 24, v2
	v_and_or_b32 v58, v221, 48, s0
	v_mov_b32_e32 v59, v53
	v_add_u32_e32 v77, 1, v76
	v_add_u32_e32 v78, 2, v76
	v_add_u32_e32 v79, 3, v76
	v_add_u32_e32 v80, 4, v76
	v_add_u32_e32 v81, 5, v76
	v_add_u32_e32 v82, 6, v76
	v_add_u32_e32 v83, 7, v76
	s_movk_i32 s52, 0x7c
	s_brev_b32 s53, 8
	s_mov_b32 s54, 0x10200000
	s_mov_b32 s55, 0x10001000
	s_mov_b32 s56, 0x10201000
	s_mov_b32 s57, 0x10002000
	s_mov_b32 s58, 0x10202000
	s_mov_b32 s59, 0x10003000
	s_mov_b32 s60, 0x10203000
	s_mov_b32 s61, 0x10004000
	s_mov_b32 s62, 0x10204000
	s_mov_b32 s63, 0x10005000
	s_mov_b32 s64, 0x10205000
	s_mov_b32 s65, 0x10006000
	s_mov_b32 s66, 0x10206000
	s_mov_b32 s67, 0x10007000
	s_mov_b32 s76, 0x10207000
	s_mov_b32 s77, 0xff61b1e6
	v_mov_b32_e32 v84, 0xff61b1e6
	s_brev_b32 s78, 40
	s_mov_b32 s79, 0x14002000
	s_mov_b32 s80, 0x14004000
	s_mov_b32 s81, 0x14006000
	s_mov_b32 s82, 0x14008000
	s_mov_b32 s83, 0x1400a000
	s_mov_b32 s84, 0x1400c000
	s_mov_b32 s85, 0x1400e000
	s_mov_b64 s[48:49], 0x800000
	s_mov_b64 s[50:51], 0x100
	s_mov_b32 s86, s3
	s_branch .LBB0_905
